# P13: window loads issued before the chunk's rstd pass (gamma load first), on v16
# speedup vs baseline: 1.0015x; 1.0015x over previous
; #define LDX(tok) ({ const u32x2 _q = *(const u32x2*)(xb + (size_t)(tok) * D + cq * 4); (f32x4){bf_lo(_q.x), bf_hi(_q.x), bf_lo(_q.y), bf_hi(_q.y)} * rs[(tok) - t0 + 8]; })
; __global__ void __launch_bounds__(512, 2) fwd_megakernel(Params Pk) {
;     ...
;         for (int ch = bx; ch < NCH; ch += G) {
;             const int t0 = ch * 64; const int sbeg = t0 < TP ? 0 : TP + ((t0 - TP) / DSEQ) * DSEQ, send = t0 < TP ? TP : sbeg + DSEQ;
;             if (tid < 80) { const int tok = t0 - 8 + tid; rs[tid] = (tok >= sbeg && tok < send) ? row_rstd(rowss, tok, 4) : 0.f; }
;             __syncthreads();
;             const int cq = tid & 255, half = tid >> 8, hw = 1 << (cq >> 6), ta = t0 + 32 * half;
;             const f32x4 gv = *(const f32x4*)(g1 + cq * 4);
;             f32x4 S = (f32x4){0.f, 0.f, 0.f, 0.f};
;     ...
;             for (int s = ta - hw; s <= ta + hw - 2; ++s) if (s >= sbeg && s < send) S += LDX(s);
.LBB0_1558:
	s_lshl_b32 s12, s14, 6
	s_and_b32 s6, s12, 0x7ffff800
	s_add_i32 s7, s6, 0x800
	s_cmpk_lt_i32 s14, 0x100
	s_cselect_b32 s16, 0, s6
	s_cselect_b32 s17, 0x4000, s7
	global_load_dwordx4 v[52:55], v[6:7], off
	v_lshrrev_b32_e32 v40, 6, v220
	v_and_b32_e32 v41, 0xff, v220
	v_lshlrev_b32_e32 v41, 3, v41
	v_readfirstlane_b32 s20, v40
	s_add_i32 s25, s17, -1
	s_nop 3
	s_lshr_b32 s21, s20, 2
	s_and_b32 s22, s20, 3
	s_lshl_b32 s23, s21, 5
	s_add_i32 s23, s12, s23
	s_lshl_b32 s24, s23, 11
	s_add_u32 s28, s0, s24
	s_addc_u32 s29, s1, 0
	s_add_u32 s28, s28, 0x4000000
	s_addc_u32 s29, s29, 0
	s_lshl_b32 s24, s21, 7
	v_mov_b32_e32 v42, s24
	s_cmp_eq_u32 s22, 0
	s_cbranch_scc1 .Lp13_ld1
	s_cmp_eq_u32 s22, 1
	s_cbranch_scc1 .Lp13_ld2
	s_cmp_eq_u32 s22, 2
	s_cbranch_scc1 .Lp13_ld4
	s_branch .Lp13_ld8
.Lp13_ld1:
	s_add_i32 s26, s23, -1
	s_max_i32 s26, s26, s16
	s_min_i32 s26, s26, s25
	s_lshl_b32 s26, s26, 11
	s_add_u32 s30, s0, s26
	s_addc_u32 s31, s1, 0
	global_load_dwordx2 v[60:61], v41, s[30:31]
	s_add_i32 s26, s23, 0
	s_max_i32 s26, s26, s16
	s_min_i32 s26, s26, s25
	s_lshl_b32 s26, s26, 11
	s_add_u32 s32, s0, s26
	s_addc_u32 s33, s1, 0
	global_load_dwordx2 v[62:63], v41, s[32:33]
	s_add_i32 s26, s23, 1
	s_max_i32 s26, s26, s16
	s_min_i32 s26, s26, s25
	s_lshl_b32 s26, s26, 11
	s_add_u32 s34, s0, s26
	s_addc_u32 s35, s1, 0
	global_load_dwordx2 v[64:65], v41, s[34:35]
	s_add_i32 s26, s23, 2
	s_max_i32 s26, s26, s16
	s_min_i32 s26, s26, s25
	s_lshl_b32 s26, s26, 11
	s_add_u32 s36, s0, s26
	s_addc_u32 s37, s1, 0
	global_load_dwordx2 v[66:67], v41, s[36:37]
	s_add_i32 s26, s23, 3
	s_max_i32 s26, s26, s16
	s_min_i32 s26, s26, s25
	s_lshl_b32 s26, s26, 11
	s_add_u32 s38, s0, s26
	s_addc_u32 s39, s1, 0
	global_load_dwordx2 v[68:69], v41, s[38:39]
	s_add_i32 s26, s23, 4
	s_max_i32 s26, s26, s16
	s_min_i32 s26, s26, s25
	s_lshl_b32 s26, s26, 11
	s_add_u32 s40, s0, s26
	s_addc_u32 s41, s1, 0
	global_load_dwordx2 v[70:71], v41, s[40:41]
	s_add_i32 s26, s23, 5
	s_max_i32 s26, s26, s16
	s_min_i32 s26, s26, s25
	s_lshl_b32 s26, s26, 11
	s_add_u32 s42, s0, s26
	s_addc_u32 s43, s1, 0
	global_load_dwordx2 v[72:73], v41, s[42:43]
	s_add_i32 s26, s23, 6
	s_max_i32 s26, s26, s16
	s_min_i32 s26, s26, s25
	s_lshl_b32 s26, s26, 11
	s_add_u32 s44, s0, s26
	s_addc_u32 s45, s1, 0
	global_load_dwordx2 v[74:75], v41, s[44:45]
	s_add_i32 s26, s23, 7
	s_max_i32 s26, s26, s16
	s_min_i32 s26, s26, s25
	s_lshl_b32 s26, s26, 11
	s_add_u32 s30, s0, s26
	s_addc_u32 s31, s1, 0
	global_load_dwordx2 v[76:77], v41, s[30:31]
	s_add_i32 s26, s23, 8
	s_max_i32 s26, s26, s16
	s_min_i32 s26, s26, s25
	s_lshl_b32 s26, s26, 11
	s_add_u32 s32, s0, s26
	s_addc_u32 s33, s1, 0
	global_load_dwordx2 v[78:79], v41, s[32:33]
	s_add_i32 s26, s23, 9
	s_max_i32 s26, s26, s16
	s_min_i32 s26, s26, s25
	s_lshl_b32 s26, s26, 11
	s_add_u32 s34, s0, s26
	s_addc_u32 s35, s1, 0
	global_load_dwordx2 v[80:81], v41, s[34:35]
	s_add_i32 s26, s23, 10
	s_max_i32 s26, s26, s16
	s_min_i32 s26, s26, s25
	s_lshl_b32 s26, s26, 11
	s_add_u32 s36, s0, s26
	s_addc_u32 s37, s1, 0
	global_load_dwordx2 v[82:83], v41, s[36:37]
	s_add_i32 s26, s23, 11
	s_max_i32 s26, s26, s16
	s_min_i32 s26, s26, s25
	s_lshl_b32 s26, s26, 11
	s_add_u32 s38, s0, s26
	s_addc_u32 s39, s1, 0
	global_load_dwordx2 v[84:85], v41, s[38:39]
	s_add_i32 s26, s23, 12
	s_max_i32 s26, s26, s16
	s_min_i32 s26, s26, s25
	s_lshl_b32 s26, s26, 11
	s_add_u32 s40, s0, s26
	s_addc_u32 s41, s1, 0
	global_load_dwordx2 v[86:87], v41, s[40:41]
	s_add_i32 s26, s23, 13
	s_max_i32 s26, s26, s16
	s_min_i32 s26, s26, s25
	s_lshl_b32 s26, s26, 11
	s_add_u32 s42, s0, s26
	s_addc_u32 s43, s1, 0
	global_load_dwordx2 v[88:89], v41, s[42:43]
	s_add_i32 s26, s23, 14
	s_max_i32 s26, s26, s16
	s_min_i32 s26, s26, s25
	s_lshl_b32 s26, s26, 11
	s_add_u32 s44, s0, s26
	s_addc_u32 s45, s1, 0
	global_load_dwordx2 v[90:91], v41, s[44:45]
	s_add_i32 s26, s23, 15
	s_max_i32 s26, s26, s16
	s_min_i32 s26, s26, s25
	s_lshl_b32 s26, s26, 11
	s_add_u32 s30, s0, s26
	s_addc_u32 s31, s1, 0
	global_load_dwordx2 v[92:93], v41, s[30:31]
	s_add_i32 s26, s23, 16
	s_max_i32 s26, s26, s16
	s_min_i32 s26, s26, s25
	s_lshl_b32 s26, s26, 11
	s_add_u32 s32, s0, s26
	s_addc_u32 s33, s1, 0
	global_load_dwordx2 v[94:95], v41, s[32:33]
	s_add_i32 s26, s23, 17
	s_max_i32 s26, s26, s16
	s_min_i32 s26, s26, s25
	s_lshl_b32 s26, s26, 11
	s_add_u32 s34, s0, s26
	s_addc_u32 s35, s1, 0
	global_load_dwordx2 v[96:97], v41, s[34:35]
	s_add_i32 s26, s23, 18
	s_max_i32 s26, s26, s16
	s_min_i32 s26, s26, s25
	s_lshl_b32 s26, s26, 11
	s_add_u32 s36, s0, s26
	s_addc_u32 s37, s1, 0
	global_load_dwordx2 v[98:99], v41, s[36:37]
	s_add_i32 s26, s23, 19
	s_max_i32 s26, s26, s16
	s_min_i32 s26, s26, s25
	s_lshl_b32 s26, s26, 11
	s_add_u32 s38, s0, s26
	s_addc_u32 s39, s1, 0
	global_load_dwordx2 v[100:101], v41, s[38:39]
	s_add_i32 s26, s23, 20
	s_max_i32 s26, s26, s16
	s_min_i32 s26, s26, s25
	s_lshl_b32 s26, s26, 11
	s_add_u32 s40, s0, s26
	s_addc_u32 s41, s1, 0
	global_load_dwordx2 v[102:103], v41, s[40:41]
	s_add_i32 s26, s23, 21
	s_max_i32 s26, s26, s16
	s_min_i32 s26, s26, s25
	s_lshl_b32 s26, s26, 11
	s_add_u32 s42, s0, s26
	s_addc_u32 s43, s1, 0
	global_load_dwordx2 v[104:105], v41, s[42:43]
	s_add_i32 s26, s23, 22
	s_max_i32 s26, s26, s16
	s_min_i32 s26, s26, s25
	s_lshl_b32 s26, s26, 11
	s_add_u32 s44, s0, s26
	s_addc_u32 s45, s1, 0
	global_load_dwordx2 v[106:107], v41, s[44:45]
	s_add_i32 s26, s23, 23
	s_max_i32 s26, s26, s16
	s_min_i32 s26, s26, s25
	s_lshl_b32 s26, s26, 11
	s_add_u32 s30, s0, s26
	s_addc_u32 s31, s1, 0
	global_load_dwordx2 v[108:109], v41, s[30:31]
	s_add_i32 s26, s23, 24
	s_max_i32 s26, s26, s16
; #define LDX(tok) ({ const u32x2 _q = *(const u32x2*)(xb + (size_t)(tok) * D + cq * 4); (f32x4){bf_lo(_q.x), bf_hi(_q.x), bf_lo(_q.y), bf_hi(_q.y)} * rs[(tok) - t0 + 8]; })
; __global__ void __launch_bounds__(512, 2) fwd_megakernel(Params Pk) {
;     ...
;             for (int s = ta - hw; s <= ta + hw - 2; ++s) if (s >= sbeg && s < send) S += LDX(s);
;             for (int t = ta; t < ta + 32; ++t) {
;                 const int sin_ = t + hw - 1; if (sin_ < send) S += LDX(sin_);
	s_min_i32 s26, s26, s25
	s_lshl_b32 s26, s26, 11
	s_add_u32 s32, s0, s26
	s_addc_u32 s33, s1, 0
	global_load_dwordx2 v[110:111], v41, s[32:33]
	s_add_i32 s26, s23, 25
	s_max_i32 s26, s26, s16
	s_min_i32 s26, s26, s25
	s_lshl_b32 s26, s26, 11
	s_add_u32 s34, s0, s26
	s_addc_u32 s35, s1, 0
	global_load_dwordx2 v[112:113], v41, s[34:35]
	s_add_i32 s26, s23, 26
	s_max_i32 s26, s26, s16
	s_min_i32 s26, s26, s25
	s_lshl_b32 s26, s26, 11
	s_add_u32 s36, s0, s26
	s_addc_u32 s37, s1, 0
	global_load_dwordx2 v[114:115], v41, s[36:37]
	s_add_i32 s26, s23, 27
	s_max_i32 s26, s26, s16
	s_min_i32 s26, s26, s25
	s_lshl_b32 s26, s26, 11
	s_add_u32 s38, s0, s26
	s_addc_u32 s39, s1, 0
	global_load_dwordx2 v[116:117], v41, s[38:39]
	s_add_i32 s26, s23, 28
	s_max_i32 s26, s26, s16
	s_min_i32 s26, s26, s25
	s_lshl_b32 s26, s26, 11
	s_add_u32 s40, s0, s26
	s_addc_u32 s41, s1, 0
	global_load_dwordx2 v[118:119], v41, s[40:41]
	s_add_i32 s26, s23, 29
	s_max_i32 s26, s26, s16
	s_min_i32 s26, s26, s25
	s_lshl_b32 s26, s26, 11
	s_add_u32 s42, s0, s26
	s_addc_u32 s43, s1, 0
	global_load_dwordx2 v[120:121], v41, s[42:43]
	s_add_i32 s26, s23, 30
	s_max_i32 s26, s26, s16
	s_min_i32 s26, s26, s25
	s_lshl_b32 s26, s26, 11
	s_add_u32 s44, s0, s26
	s_addc_u32 s45, s1, 0
	global_load_dwordx2 v[122:123], v41, s[44:45]
	s_add_i32 s26, s23, 31
	s_max_i32 s26, s26, s16
	s_min_i32 s26, s26, s25
	s_lshl_b32 s26, s26, 11
	s_add_u32 s30, s0, s26
	s_addc_u32 s31, s1, 0
	global_load_dwordx2 v[124:125], v41, s[30:31]
	s_branch .Lp13_rs
.Lp13_ld2:
	s_add_i32 s26, s23, -2
	s_max_i32 s26, s26, s16
	s_min_i32 s26, s26, s25
	s_lshl_b32 s26, s26, 11
	s_add_u32 s30, s0, s26
	s_addc_u32 s31, s1, 0
	global_load_dwordx2 v[60:61], v41, s[30:31]
	s_add_i32 s26, s23, -1
	s_max_i32 s26, s26, s16
	s_min_i32 s26, s26, s25
	s_lshl_b32 s26, s26, 11
	s_add_u32 s32, s0, s26
	s_addc_u32 s33, s1, 0
	global_load_dwordx2 v[62:63], v41, s[32:33]
	s_add_i32 s26, s23, 0
	s_max_i32 s26, s26, s16
	s_min_i32 s26, s26, s25
	s_lshl_b32 s26, s26, 11
	s_add_u32 s34, s0, s26
	s_addc_u32 s35, s1, 0
	global_load_dwordx2 v[64:65], v41, s[34:35]
	s_add_i32 s26, s23, 1
	s_max_i32 s26, s26, s16
	s_min_i32 s26, s26, s25
	s_lshl_b32 s26, s26, 11
	s_add_u32 s36, s0, s26
	s_addc_u32 s37, s1, 0
	global_load_dwordx2 v[66:67], v41, s[36:37]
	s_add_i32 s26, s23, 2
	s_max_i32 s26, s26, s16
	s_min_i32 s26, s26, s25
	s_lshl_b32 s26, s26, 11
	s_add_u32 s38, s0, s26
	s_addc_u32 s39, s1, 0
	global_load_dwordx2 v[68:69], v41, s[38:39]
	s_add_i32 s26, s23, 3
	s_max_i32 s26, s26, s16
	s_min_i32 s26, s26, s25
	s_lshl_b32 s26, s26, 11
	s_add_u32 s40, s0, s26
	s_addc_u32 s41, s1, 0
	global_load_dwordx2 v[70:71], v41, s[40:41]
	s_add_i32 s26, s23, 4
	s_max_i32 s26, s26, s16
	s_min_i32 s26, s26, s25
	s_lshl_b32 s26, s26, 11
	s_add_u32 s42, s0, s26
	s_addc_u32 s43, s1, 0
	global_load_dwordx2 v[72:73], v41, s[42:43]
	s_add_i32 s26, s23, 5
	s_max_i32 s26, s26, s16
	s_min_i32 s26, s26, s25
	s_lshl_b32 s26, s26, 11
	s_add_u32 s44, s0, s26
	s_addc_u32 s45, s1, 0
	global_load_dwordx2 v[74:75], v41, s[44:45]
	s_add_i32 s26, s23, 6
	s_max_i32 s26, s26, s16
	s_min_i32 s26, s26, s25
	s_lshl_b32 s26, s26, 11
	s_add_u32 s30, s0, s26
	s_addc_u32 s31, s1, 0
	global_load_dwordx2 v[76:77], v41, s[30:31]
	s_add_i32 s26, s23, 7
	s_max_i32 s26, s26, s16
	s_min_i32 s26, s26, s25
	s_lshl_b32 s26, s26, 11
	s_add_u32 s32, s0, s26
	s_addc_u32 s33, s1, 0
	global_load_dwordx2 v[78:79], v41, s[32:33]
	s_add_i32 s26, s23, 8
	s_max_i32 s26, s26, s16
	s_min_i32 s26, s26, s25
	s_lshl_b32 s26, s26, 11
	s_add_u32 s34, s0, s26
	s_addc_u32 s35, s1, 0
	global_load_dwordx2 v[80:81], v41, s[34:35]
	s_add_i32 s26, s23, 9
	s_max_i32 s26, s26, s16
	s_min_i32 s26, s26, s25
	s_lshl_b32 s26, s26, 11
	s_add_u32 s36, s0, s26
	s_addc_u32 s37, s1, 0
	global_load_dwordx2 v[82:83], v41, s[36:37]
	s_add_i32 s26, s23, 10
	s_max_i32 s26, s26, s16
	s_min_i32 s26, s26, s25
	s_lshl_b32 s26, s26, 11
	s_add_u32 s38, s0, s26
	s_addc_u32 s39, s1, 0
	global_load_dwordx2 v[84:85], v41, s[38:39]
	s_add_i32 s26, s23, 11
	s_max_i32 s26, s26, s16
	s_min_i32 s26, s26, s25
	s_lshl_b32 s26, s26, 11
	s_add_u32 s40, s0, s26
	s_addc_u32 s41, s1, 0
	global_load_dwordx2 v[86:87], v41, s[40:41]
	s_add_i32 s26, s23, 12
	s_max_i32 s26, s26, s16
	s_min_i32 s26, s26, s25
	s_lshl_b32 s26, s26, 11
	s_add_u32 s42, s0, s26
	s_addc_u32 s43, s1, 0
	global_load_dwordx2 v[88:89], v41, s[42:43]
	s_add_i32 s26, s23, 13
	s_max_i32 s26, s26, s16
	s_min_i32 s26, s26, s25
	s_lshl_b32 s26, s26, 11
	s_add_u32 s44, s0, s26
	s_addc_u32 s45, s1, 0
	global_load_dwordx2 v[90:91], v41, s[44:45]
	s_add_i32 s26, s23, 14
	s_max_i32 s26, s26, s16
	s_min_i32 s26, s26, s25
	s_lshl_b32 s26, s26, 11
	s_add_u32 s30, s0, s26
	s_addc_u32 s31, s1, 0
	global_load_dwordx2 v[92:93], v41, s[30:31]
	s_add_i32 s26, s23, 15
	s_max_i32 s26, s26, s16
	s_min_i32 s26, s26, s25
	s_lshl_b32 s26, s26, 11
	s_add_u32 s32, s0, s26
	s_addc_u32 s33, s1, 0
	global_load_dwordx2 v[94:95], v41, s[32:33]
	s_add_i32 s26, s23, 16
	s_max_i32 s26, s26, s16
	s_min_i32 s26, s26, s25
	s_lshl_b32 s26, s26, 11
	s_add_u32 s34, s0, s26
	s_addc_u32 s35, s1, 0
	global_load_dwordx2 v[96:97], v41, s[34:35]
	s_add_i32 s26, s23, 17
	s_max_i32 s26, s26, s16
	s_min_i32 s26, s26, s25
	s_lshl_b32 s26, s26, 11
	s_add_u32 s36, s0, s26
	s_addc_u32 s37, s1, 0
	global_load_dwordx2 v[98:99], v41, s[36:37]
	s_add_i32 s26, s23, 18
	s_max_i32 s26, s26, s16
	s_min_i32 s26, s26, s25
	s_lshl_b32 s26, s26, 11
	s_add_u32 s38, s0, s26
	s_addc_u32 s39, s1, 0
	global_load_dwordx2 v[100:101], v41, s[38:39]
	s_add_i32 s26, s23, 19
	s_max_i32 s26, s26, s16
	s_min_i32 s26, s26, s25
	s_lshl_b32 s26, s26, 11
	s_add_u32 s40, s0, s26
; #define LDX(tok) ({ const u32x2 _q = *(const u32x2*)(xb + (size_t)(tok) * D + cq * 4); (f32x4){bf_lo(_q.x), bf_hi(_q.x), bf_lo(_q.y), bf_hi(_q.y)} * rs[(tok) - t0 + 8]; })
; __global__ void __launch_bounds__(512, 2) fwd_megakernel(Params Pk) {
;     ...
;             for (int s = ta - hw; s <= ta + hw - 2; ++s) if (s >= sbeg && s < send) S += LDX(s);
;             for (int t = ta; t < ta + 32; ++t) {
;                 const int sin_ = t + hw - 1; if (sin_ < send) S += LDX(sin_);
	s_addc_u32 s41, s1, 0
	global_load_dwordx2 v[102:103], v41, s[40:41]
	s_add_i32 s26, s23, 20
	s_max_i32 s26, s26, s16
	s_min_i32 s26, s26, s25
	s_lshl_b32 s26, s26, 11
	s_add_u32 s42, s0, s26
	s_addc_u32 s43, s1, 0
	global_load_dwordx2 v[104:105], v41, s[42:43]
	s_add_i32 s26, s23, 21
	s_max_i32 s26, s26, s16
	s_min_i32 s26, s26, s25
	s_lshl_b32 s26, s26, 11
	s_add_u32 s44, s0, s26
	s_addc_u32 s45, s1, 0
	global_load_dwordx2 v[106:107], v41, s[44:45]
	s_add_i32 s26, s23, 22
	s_max_i32 s26, s26, s16
	s_min_i32 s26, s26, s25
	s_lshl_b32 s26, s26, 11
	s_add_u32 s30, s0, s26
	s_addc_u32 s31, s1, 0
	global_load_dwordx2 v[108:109], v41, s[30:31]
	s_add_i32 s26, s23, 23
	s_max_i32 s26, s26, s16
	s_min_i32 s26, s26, s25
	s_lshl_b32 s26, s26, 11
	s_add_u32 s32, s0, s26
	s_addc_u32 s33, s1, 0
	global_load_dwordx2 v[110:111], v41, s[32:33]
	s_add_i32 s26, s23, 24
	s_max_i32 s26, s26, s16
	s_min_i32 s26, s26, s25
	s_lshl_b32 s26, s26, 11
	s_add_u32 s34, s0, s26
	s_addc_u32 s35, s1, 0
	global_load_dwordx2 v[112:113], v41, s[34:35]
	s_add_i32 s26, s23, 25
	s_max_i32 s26, s26, s16
	s_min_i32 s26, s26, s25
	s_lshl_b32 s26, s26, 11
	s_add_u32 s36, s0, s26
	s_addc_u32 s37, s1, 0
	global_load_dwordx2 v[114:115], v41, s[36:37]
	s_add_i32 s26, s23, 26
	s_max_i32 s26, s26, s16
	s_min_i32 s26, s26, s25
	s_lshl_b32 s26, s26, 11
	s_add_u32 s38, s0, s26
	s_addc_u32 s39, s1, 0
	global_load_dwordx2 v[116:117], v41, s[38:39]
	s_add_i32 s26, s23, 27
	s_max_i32 s26, s26, s16
	s_min_i32 s26, s26, s25
	s_lshl_b32 s26, s26, 11
	s_add_u32 s40, s0, s26
	s_addc_u32 s41, s1, 0
	global_load_dwordx2 v[118:119], v41, s[40:41]
	s_add_i32 s26, s23, 28
	s_max_i32 s26, s26, s16
	s_min_i32 s26, s26, s25
	s_lshl_b32 s26, s26, 11
	s_add_u32 s42, s0, s26
	s_addc_u32 s43, s1, 0
	global_load_dwordx2 v[120:121], v41, s[42:43]
	s_add_i32 s26, s23, 29
	s_max_i32 s26, s26, s16
	s_min_i32 s26, s26, s25
	s_lshl_b32 s26, s26, 11
	s_add_u32 s44, s0, s26
	s_addc_u32 s45, s1, 0
	global_load_dwordx2 v[122:123], v41, s[44:45]
	s_add_i32 s26, s23, 30
	s_max_i32 s26, s26, s16
	s_min_i32 s26, s26, s25
	s_lshl_b32 s26, s26, 11
	s_add_u32 s30, s0, s26
	s_addc_u32 s31, s1, 0
	global_load_dwordx2 v[124:125], v41, s[30:31]
	s_add_i32 s26, s23, 31
	s_max_i32 s26, s26, s16
	s_min_i32 s26, s26, s25
	s_lshl_b32 s26, s26, 11
	s_add_u32 s32, s0, s26
	s_addc_u32 s33, s1, 0
	global_load_dwordx2 v[126:127], v41, s[32:33]
	s_add_i32 s26, s23, 32
	s_max_i32 s26, s26, s16
	s_min_i32 s26, s26, s25
	s_lshl_b32 s26, s26, 11
	s_add_u32 s34, s0, s26
	s_addc_u32 s35, s1, 0
	global_load_dwordx2 v[128:129], v41, s[34:35]
	s_branch .Lp13_rs
.Lp13_ld4:
	s_add_i32 s26, s23, -4
	s_max_i32 s26, s26, s16
	s_min_i32 s26, s26, s25
	s_lshl_b32 s26, s26, 11
	s_add_u32 s30, s0, s26
	s_addc_u32 s31, s1, 0
	global_load_dwordx2 v[60:61], v41, s[30:31]
	s_add_i32 s26, s23, -3
	s_max_i32 s26, s26, s16
	s_min_i32 s26, s26, s25
	s_lshl_b32 s26, s26, 11
	s_add_u32 s32, s0, s26
	s_addc_u32 s33, s1, 0
	global_load_dwordx2 v[62:63], v41, s[32:33]
	s_add_i32 s26, s23, -2
	s_max_i32 s26, s26, s16
	s_min_i32 s26, s26, s25
	s_lshl_b32 s26, s26, 11
	s_add_u32 s34, s0, s26
	s_addc_u32 s35, s1, 0
	global_load_dwordx2 v[64:65], v41, s[34:35]
	s_add_i32 s26, s23, -1
	s_max_i32 s26, s26, s16
	s_min_i32 s26, s26, s25
	s_lshl_b32 s26, s26, 11
	s_add_u32 s36, s0, s26
	s_addc_u32 s37, s1, 0
	global_load_dwordx2 v[66:67], v41, s[36:37]
	s_add_i32 s26, s23, 0
	s_max_i32 s26, s26, s16
	s_min_i32 s26, s26, s25
	s_lshl_b32 s26, s26, 11
	s_add_u32 s38, s0, s26
	s_addc_u32 s39, s1, 0
	global_load_dwordx2 v[68:69], v41, s[38:39]
	s_add_i32 s26, s23, 1
	s_max_i32 s26, s26, s16
	s_min_i32 s26, s26, s25
	s_lshl_b32 s26, s26, 11
	s_add_u32 s40, s0, s26
	s_addc_u32 s41, s1, 0
	global_load_dwordx2 v[70:71], v41, s[40:41]
	s_add_i32 s26, s23, 2
	s_max_i32 s26, s26, s16
	s_min_i32 s26, s26, s25
	s_lshl_b32 s26, s26, 11
	s_add_u32 s42, s0, s26
	s_addc_u32 s43, s1, 0
	global_load_dwordx2 v[72:73], v41, s[42:43]
	s_add_i32 s26, s23, 3
	s_max_i32 s26, s26, s16
	s_min_i32 s26, s26, s25
	s_lshl_b32 s26, s26, 11
	s_add_u32 s44, s0, s26
	s_addc_u32 s45, s1, 0
	global_load_dwordx2 v[74:75], v41, s[44:45]
	s_add_i32 s26, s23, 4
	s_max_i32 s26, s26, s16
	s_min_i32 s26, s26, s25
	s_lshl_b32 s26, s26, 11
	s_add_u32 s30, s0, s26
	s_addc_u32 s31, s1, 0
	global_load_dwordx2 v[76:77], v41, s[30:31]
	s_add_i32 s26, s23, 5
	s_max_i32 s26, s26, s16
	s_min_i32 s26, s26, s25
	s_lshl_b32 s26, s26, 11
	s_add_u32 s32, s0, s26
	s_addc_u32 s33, s1, 0
	global_load_dwordx2 v[78:79], v41, s[32:33]
	s_add_i32 s26, s23, 6
	s_max_i32 s26, s26, s16
	s_min_i32 s26, s26, s25
	s_lshl_b32 s26, s26, 11
	s_add_u32 s34, s0, s26
	s_addc_u32 s35, s1, 0
	global_load_dwordx2 v[80:81], v41, s[34:35]
	s_add_i32 s26, s23, 7
	s_max_i32 s26, s26, s16
	s_min_i32 s26, s26, s25
	s_lshl_b32 s26, s26, 11
	s_add_u32 s36, s0, s26
	s_addc_u32 s37, s1, 0
	global_load_dwordx2 v[82:83], v41, s[36:37]
	s_add_i32 s26, s23, 8
	s_max_i32 s26, s26, s16
	s_min_i32 s26, s26, s25
	s_lshl_b32 s26, s26, 11
	s_add_u32 s38, s0, s26
	s_addc_u32 s39, s1, 0
	global_load_dwordx2 v[84:85], v41, s[38:39]
	s_add_i32 s26, s23, 9
	s_max_i32 s26, s26, s16
	s_min_i32 s26, s26, s25
	s_lshl_b32 s26, s26, 11
	s_add_u32 s40, s0, s26
	s_addc_u32 s41, s1, 0
	global_load_dwordx2 v[86:87], v41, s[40:41]
	s_add_i32 s26, s23, 10
	s_max_i32 s26, s26, s16
	s_min_i32 s26, s26, s25
	s_lshl_b32 s26, s26, 11
	s_add_u32 s42, s0, s26
	s_addc_u32 s43, s1, 0
	global_load_dwordx2 v[88:89], v41, s[42:43]
	s_add_i32 s26, s23, 11
	s_max_i32 s26, s26, s16
	s_min_i32 s26, s26, s25
	s_lshl_b32 s26, s26, 11
	s_add_u32 s44, s0, s26
	s_addc_u32 s45, s1, 0
	global_load_dwordx2 v[90:91], v41, s[44:45]
; #define LDX(tok) ({ const u32x2 _q = *(const u32x2*)(xb + (size_t)(tok) * D + cq * 4); (f32x4){bf_lo(_q.x), bf_hi(_q.x), bf_lo(_q.y), bf_hi(_q.y)} * rs[(tok) - t0 + 8]; })
; __global__ void __launch_bounds__(512, 2) fwd_megakernel(Params Pk) {
;     ...
;             for (int s = ta - hw; s <= ta + hw - 2; ++s) if (s >= sbeg && s < send) S += LDX(s);
;             for (int t = ta; t < ta + 32; ++t) {
;                 const int sin_ = t + hw - 1; if (sin_ < send) S += LDX(sin_);
	s_add_i32 s26, s23, 12
	s_max_i32 s26, s26, s16
	s_min_i32 s26, s26, s25
	s_lshl_b32 s26, s26, 11
	s_add_u32 s30, s0, s26
	s_addc_u32 s31, s1, 0
	global_load_dwordx2 v[92:93], v41, s[30:31]
	s_add_i32 s26, s23, 13
	s_max_i32 s26, s26, s16
	s_min_i32 s26, s26, s25
	s_lshl_b32 s26, s26, 11
	s_add_u32 s32, s0, s26
	s_addc_u32 s33, s1, 0
	global_load_dwordx2 v[94:95], v41, s[32:33]
	s_add_i32 s26, s23, 14
	s_max_i32 s26, s26, s16
	s_min_i32 s26, s26, s25
	s_lshl_b32 s26, s26, 11
	s_add_u32 s34, s0, s26
	s_addc_u32 s35, s1, 0
	global_load_dwordx2 v[96:97], v41, s[34:35]
	s_add_i32 s26, s23, 15
	s_max_i32 s26, s26, s16
	s_min_i32 s26, s26, s25
	s_lshl_b32 s26, s26, 11
	s_add_u32 s36, s0, s26
	s_addc_u32 s37, s1, 0
	global_load_dwordx2 v[98:99], v41, s[36:37]
	s_add_i32 s26, s23, 16
	s_max_i32 s26, s26, s16
	s_min_i32 s26, s26, s25
	s_lshl_b32 s26, s26, 11
	s_add_u32 s38, s0, s26
	s_addc_u32 s39, s1, 0
	global_load_dwordx2 v[100:101], v41, s[38:39]
	s_add_i32 s26, s23, 17
	s_max_i32 s26, s26, s16
	s_min_i32 s26, s26, s25
	s_lshl_b32 s26, s26, 11
	s_add_u32 s40, s0, s26
	s_addc_u32 s41, s1, 0
	global_load_dwordx2 v[102:103], v41, s[40:41]
	s_add_i32 s26, s23, 18
	s_max_i32 s26, s26, s16
	s_min_i32 s26, s26, s25
	s_lshl_b32 s26, s26, 11
	s_add_u32 s42, s0, s26
	s_addc_u32 s43, s1, 0
	global_load_dwordx2 v[104:105], v41, s[42:43]
	s_add_i32 s26, s23, 19
	s_max_i32 s26, s26, s16
	s_min_i32 s26, s26, s25
	s_lshl_b32 s26, s26, 11
	s_add_u32 s44, s0, s26
	s_addc_u32 s45, s1, 0
	global_load_dwordx2 v[106:107], v41, s[44:45]
	s_add_i32 s26, s23, 20
	s_max_i32 s26, s26, s16
	s_min_i32 s26, s26, s25
	s_lshl_b32 s26, s26, 11
	s_add_u32 s30, s0, s26
	s_addc_u32 s31, s1, 0
	global_load_dwordx2 v[108:109], v41, s[30:31]
	s_add_i32 s26, s23, 21
	s_max_i32 s26, s26, s16
	s_min_i32 s26, s26, s25
	s_lshl_b32 s26, s26, 11
	s_add_u32 s32, s0, s26
	s_addc_u32 s33, s1, 0
	global_load_dwordx2 v[110:111], v41, s[32:33]
	s_add_i32 s26, s23, 22
	s_max_i32 s26, s26, s16
	s_min_i32 s26, s26, s25
	s_lshl_b32 s26, s26, 11
	s_add_u32 s34, s0, s26
	s_addc_u32 s35, s1, 0
	global_load_dwordx2 v[112:113], v41, s[34:35]
	s_add_i32 s26, s23, 23
	s_max_i32 s26, s26, s16
	s_min_i32 s26, s26, s25
	s_lshl_b32 s26, s26, 11
	s_add_u32 s36, s0, s26
	s_addc_u32 s37, s1, 0
	global_load_dwordx2 v[114:115], v41, s[36:37]
	s_add_i32 s26, s23, 24
	s_max_i32 s26, s26, s16
	s_min_i32 s26, s26, s25
	s_lshl_b32 s26, s26, 11
	s_add_u32 s38, s0, s26
	s_addc_u32 s39, s1, 0
	global_load_dwordx2 v[116:117], v41, s[38:39]
	s_add_i32 s26, s23, 25
	s_max_i32 s26, s26, s16
	s_min_i32 s26, s26, s25
	s_lshl_b32 s26, s26, 11
	s_add_u32 s40, s0, s26
	s_addc_u32 s41, s1, 0
	global_load_dwordx2 v[118:119], v41, s[40:41]
	s_add_i32 s26, s23, 26
	s_max_i32 s26, s26, s16
	s_min_i32 s26, s26, s25
	s_lshl_b32 s26, s26, 11
	s_add_u32 s42, s0, s26
	s_addc_u32 s43, s1, 0
	global_load_dwordx2 v[120:121], v41, s[42:43]
	s_add_i32 s26, s23, 27
	s_max_i32 s26, s26, s16
	s_min_i32 s26, s26, s25
	s_lshl_b32 s26, s26, 11
	s_add_u32 s44, s0, s26
	s_addc_u32 s45, s1, 0
	global_load_dwordx2 v[122:123], v41, s[44:45]
	s_add_i32 s26, s23, 28
	s_max_i32 s26, s26, s16
	s_min_i32 s26, s26, s25
	s_lshl_b32 s26, s26, 11
	s_add_u32 s30, s0, s26
	s_addc_u32 s31, s1, 0
	global_load_dwordx2 v[124:125], v41, s[30:31]
	s_add_i32 s26, s23, 29
	s_max_i32 s26, s26, s16
	s_min_i32 s26, s26, s25
	s_lshl_b32 s26, s26, 11
	s_add_u32 s32, s0, s26
	s_addc_u32 s33, s1, 0
	global_load_dwordx2 v[126:127], v41, s[32:33]
	s_add_i32 s26, s23, 30
	s_max_i32 s26, s26, s16
	s_min_i32 s26, s26, s25
	s_lshl_b32 s26, s26, 11
	s_add_u32 s34, s0, s26
	s_addc_u32 s35, s1, 0
	global_load_dwordx2 v[128:129], v41, s[34:35]
	s_add_i32 s26, s23, 31
	s_max_i32 s26, s26, s16
	s_min_i32 s26, s26, s25
	s_lshl_b32 s26, s26, 11
	s_add_u32 s36, s0, s26
	s_addc_u32 s37, s1, 0
	global_load_dwordx2 v[130:131], v41, s[36:37]
	s_add_i32 s26, s23, 32
	s_max_i32 s26, s26, s16
	s_min_i32 s26, s26, s25
	s_lshl_b32 s26, s26, 11
	s_add_u32 s38, s0, s26
	s_addc_u32 s39, s1, 0
	global_load_dwordx2 v[132:133], v41, s[38:39]
	s_add_i32 s26, s23, 33
	s_max_i32 s26, s26, s16
	s_min_i32 s26, s26, s25
	s_lshl_b32 s26, s26, 11
	s_add_u32 s40, s0, s26
	s_addc_u32 s41, s1, 0
	global_load_dwordx2 v[134:135], v41, s[40:41]
	s_add_i32 s26, s23, 34
	s_max_i32 s26, s26, s16
	s_min_i32 s26, s26, s25
	s_lshl_b32 s26, s26, 11
	s_add_u32 s42, s0, s26
	s_addc_u32 s43, s1, 0
	global_load_dwordx2 v[136:137], v41, s[42:43]
	s_branch .Lp13_rs
; #define LDX(tok) ({ const u32x2 _q = *(const u32x2*)(xb + (size_t)(tok) * D + cq * 4); (f32x4){bf_lo(_q.x), bf_hi(_q.x), bf_lo(_q.y), bf_hi(_q.y)} * rs[(tok) - t0 + 8]; })
; __global__ void __launch_bounds__(512, 2) fwd_megakernel(Params Pk) {
;     ...
;             for (int s = ta - hw; s <= ta + hw - 2; ++s) if (s >= sbeg && s < send) S += LDX(s);
;             for (int t = ta; t < ta + 32; ++t) {
;                 const int sin_ = t + hw - 1; if (sin_ < send) S += LDX(sin_);
.Lp13_ld8:
	s_add_i32 s26, s23, -8
	s_max_i32 s26, s26, s16
	s_min_i32 s26, s26, s25
	s_lshl_b32 s26, s26, 11
	s_add_u32 s30, s0, s26
	s_addc_u32 s31, s1, 0
	global_load_dwordx2 v[60:61], v41, s[30:31]
	s_add_i32 s26, s23, -7
	s_max_i32 s26, s26, s16
	s_min_i32 s26, s26, s25
	s_lshl_b32 s26, s26, 11
	s_add_u32 s32, s0, s26
	s_addc_u32 s33, s1, 0
	global_load_dwordx2 v[62:63], v41, s[32:33]
	s_add_i32 s26, s23, -6
	s_max_i32 s26, s26, s16
	s_min_i32 s26, s26, s25
	s_lshl_b32 s26, s26, 11
	s_add_u32 s34, s0, s26
	s_addc_u32 s35, s1, 0
	global_load_dwordx2 v[64:65], v41, s[34:35]
	s_add_i32 s26, s23, -5
	s_max_i32 s26, s26, s16
	s_min_i32 s26, s26, s25
	s_lshl_b32 s26, s26, 11
	s_add_u32 s36, s0, s26
	s_addc_u32 s37, s1, 0
	global_load_dwordx2 v[66:67], v41, s[36:37]
	s_add_i32 s26, s23, -4
	s_max_i32 s26, s26, s16
	s_min_i32 s26, s26, s25
	s_lshl_b32 s26, s26, 11
	s_add_u32 s38, s0, s26
	s_addc_u32 s39, s1, 0
	global_load_dwordx2 v[68:69], v41, s[38:39]
	s_add_i32 s26, s23, -3
	s_max_i32 s26, s26, s16
	s_min_i32 s26, s26, s25
	s_lshl_b32 s26, s26, 11
	s_add_u32 s40, s0, s26
	s_addc_u32 s41, s1, 0
	global_load_dwordx2 v[70:71], v41, s[40:41]
	s_add_i32 s26, s23, -2
	s_max_i32 s26, s26, s16
	s_min_i32 s26, s26, s25
	s_lshl_b32 s26, s26, 11
	s_add_u32 s42, s0, s26
	s_addc_u32 s43, s1, 0
	global_load_dwordx2 v[72:73], v41, s[42:43]
	s_add_i32 s26, s23, -1
	s_max_i32 s26, s26, s16
	s_min_i32 s26, s26, s25
	s_lshl_b32 s26, s26, 11
	s_add_u32 s44, s0, s26
	s_addc_u32 s45, s1, 0
	global_load_dwordx2 v[74:75], v41, s[44:45]
	s_add_i32 s26, s23, 0
	s_max_i32 s26, s26, s16
	s_min_i32 s26, s26, s25
	s_lshl_b32 s26, s26, 11
	s_add_u32 s30, s0, s26
	s_addc_u32 s31, s1, 0
	global_load_dwordx2 v[76:77], v41, s[30:31]
	s_add_i32 s26, s23, 1
	s_max_i32 s26, s26, s16
	s_min_i32 s26, s26, s25
	s_lshl_b32 s26, s26, 11
	s_add_u32 s32, s0, s26
	s_addc_u32 s33, s1, 0
	global_load_dwordx2 v[78:79], v41, s[32:33]
	s_add_i32 s26, s23, 2
	s_max_i32 s26, s26, s16
	s_min_i32 s26, s26, s25
	s_lshl_b32 s26, s26, 11
	s_add_u32 s34, s0, s26
	s_addc_u32 s35, s1, 0
	global_load_dwordx2 v[80:81], v41, s[34:35]
	s_add_i32 s26, s23, 3
	s_max_i32 s26, s26, s16
	s_min_i32 s26, s26, s25
	s_lshl_b32 s26, s26, 11
	s_add_u32 s36, s0, s26
	s_addc_u32 s37, s1, 0
	global_load_dwordx2 v[82:83], v41, s[36:37]
	s_add_i32 s26, s23, 4
	s_max_i32 s26, s26, s16
	s_min_i32 s26, s26, s25
	s_lshl_b32 s26, s26, 11
	s_add_u32 s38, s0, s26
	s_addc_u32 s39, s1, 0
	global_load_dwordx2 v[84:85], v41, s[38:39]
	s_add_i32 s26, s23, 5
	s_max_i32 s26, s26, s16
	s_min_i32 s26, s26, s25
	s_lshl_b32 s26, s26, 11
	s_add_u32 s40, s0, s26
	s_addc_u32 s41, s1, 0
	global_load_dwordx2 v[86:87], v41, s[40:41]
	s_add_i32 s26, s23, 6
	s_max_i32 s26, s26, s16
	s_min_i32 s26, s26, s25
	s_lshl_b32 s26, s26, 11
	s_add_u32 s42, s0, s26
	s_addc_u32 s43, s1, 0
	global_load_dwordx2 v[88:89], v41, s[42:43]
	s_add_i32 s26, s23, 7
	s_max_i32 s26, s26, s16
	s_min_i32 s26, s26, s25
	s_lshl_b32 s26, s26, 11
	s_add_u32 s44, s0, s26
	s_addc_u32 s45, s1, 0
	global_load_dwordx2 v[90:91], v41, s[44:45]
	s_add_i32 s26, s23, 8
	s_max_i32 s26, s26, s16
	s_min_i32 s26, s26, s25
	s_lshl_b32 s26, s26, 11
	s_add_u32 s30, s0, s26
	s_addc_u32 s31, s1, 0
	global_load_dwordx2 v[92:93], v41, s[30:31]
	s_add_i32 s26, s23, 9
	s_max_i32 s26, s26, s16
	s_min_i32 s26, s26, s25
	s_lshl_b32 s26, s26, 11
	s_add_u32 s32, s0, s26
	s_addc_u32 s33, s1, 0
	global_load_dwordx2 v[94:95], v41, s[32:33]
	s_add_i32 s26, s23, 10
	s_max_i32 s26, s26, s16
	s_min_i32 s26, s26, s25
	s_lshl_b32 s26, s26, 11
	s_add_u32 s34, s0, s26
	s_addc_u32 s35, s1, 0
	global_load_dwordx2 v[96:97], v41, s[34:35]
	s_add_i32 s26, s23, 11
	s_max_i32 s26, s26, s16
	s_min_i32 s26, s26, s25
	s_lshl_b32 s26, s26, 11
	s_add_u32 s36, s0, s26
	s_addc_u32 s37, s1, 0
	global_load_dwordx2 v[98:99], v41, s[36:37]
	s_add_i32 s26, s23, 12
	s_max_i32 s26, s26, s16
	s_min_i32 s26, s26, s25
	s_lshl_b32 s26, s26, 11
	s_add_u32 s38, s0, s26
	s_addc_u32 s39, s1, 0
	global_load_dwordx2 v[100:101], v41, s[38:39]
	s_add_i32 s26, s23, 13
	s_max_i32 s26, s26, s16
	s_min_i32 s26, s26, s25
	s_lshl_b32 s26, s26, 11
	s_add_u32 s40, s0, s26
	s_addc_u32 s41, s1, 0
	global_load_dwordx2 v[102:103], v41, s[40:41]
	s_add_i32 s26, s23, 14
	s_max_i32 s26, s26, s16
	s_min_i32 s26, s26, s25
	s_lshl_b32 s26, s26, 11
	s_add_u32 s42, s0, s26
	s_addc_u32 s43, s1, 0
	global_load_dwordx2 v[104:105], v41, s[42:43]
	s_add_i32 s26, s23, 15
	s_max_i32 s26, s26, s16
	s_min_i32 s26, s26, s25
	s_lshl_b32 s26, s26, 11
	s_add_u32 s44, s0, s26
	s_addc_u32 s45, s1, 0
	global_load_dwordx2 v[106:107], v41, s[44:45]
	s_add_i32 s26, s23, 16
	s_max_i32 s26, s26, s16
	s_min_i32 s26, s26, s25
	s_lshl_b32 s26, s26, 11
	s_add_u32 s30, s0, s26
	s_addc_u32 s31, s1, 0
	global_load_dwordx2 v[108:109], v41, s[30:31]
	s_add_i32 s26, s23, 17
	s_max_i32 s26, s26, s16
	s_min_i32 s26, s26, s25
	s_lshl_b32 s26, s26, 11
	s_add_u32 s32, s0, s26
	s_addc_u32 s33, s1, 0
	global_load_dwordx2 v[110:111], v41, s[32:33]
	s_add_i32 s26, s23, 18
	s_max_i32 s26, s26, s16
	s_min_i32 s26, s26, s25
	s_lshl_b32 s26, s26, 11
	s_add_u32 s34, s0, s26
	s_addc_u32 s35, s1, 0
	global_load_dwordx2 v[112:113], v41, s[34:35]
	s_add_i32 s26, s23, 19
; #define LDX(tok) ({ const u32x2 _q = *(const u32x2*)(xb + (size_t)(tok) * D + cq * 4); (f32x4){bf_lo(_q.x), bf_hi(_q.x), bf_lo(_q.y), bf_hi(_q.y)} * rs[(tok) - t0 + 8]; })
; __device__ __forceinline__ float row_rstd(const float* rowss, int row, int nq) {
;     const f32x4* p = (const f32x4*)(rowss + (size_t)row * 32); float s = 0.f;
;     for (int k = 0; k < nq; ++k) { const f32x4 v = p[k]; s += (v[0] + v[1]) + (v[2] + v[3]); }
;     return __builtin_amdgcn_rsqf(s * (1.0f / 1024.0f) + EPS);
; __global__ void __launch_bounds__(512, 2) fwd_megakernel(Params Pk) {
;     ...
;             if (tid < 80) { const int tok = t0 - 8 + tid; rs[tid] = (tok >= sbeg && tok < send) ? row_rstd(rowss, tok, 4) : 0.f; }
;             __syncthreads();
;             const int cq = tid & 255, half = tid >> 8, hw = 1 << (cq >> 6), ta = t0 + 32 * half;
;             const f32x4 gv = *(const f32x4*)(g1 + cq * 4);
;             f32x4 S = (f32x4){0.f, 0.f, 0.f, 0.f};
;     ...
;             for (int s = ta - hw; s <= ta + hw - 2; ++s) if (s >= sbeg && s < send) S += LDX(s);
;             for (int t = ta; t < ta + 32; ++t) {
;                 const int sin_ = t + hw - 1; if (sin_ < send) S += LDX(sin_);
	s_max_i32 s26, s26, s16
	s_min_i32 s26, s26, s25
	s_lshl_b32 s26, s26, 11
	s_add_u32 s36, s0, s26
	s_addc_u32 s37, s1, 0
	global_load_dwordx2 v[114:115], v41, s[36:37]
	s_add_i32 s26, s23, 20
	s_max_i32 s26, s26, s16
	s_min_i32 s26, s26, s25
	s_lshl_b32 s26, s26, 11
	s_add_u32 s38, s0, s26
	s_addc_u32 s39, s1, 0
	global_load_dwordx2 v[116:117], v41, s[38:39]
	s_add_i32 s26, s23, 21
	s_max_i32 s26, s26, s16
	s_min_i32 s26, s26, s25
	s_lshl_b32 s26, s26, 11
	s_add_u32 s40, s0, s26
	s_addc_u32 s41, s1, 0
	global_load_dwordx2 v[118:119], v41, s[40:41]
	s_add_i32 s26, s23, 22
	s_max_i32 s26, s26, s16
	s_min_i32 s26, s26, s25
	s_lshl_b32 s26, s26, 11
	s_add_u32 s42, s0, s26
	s_addc_u32 s43, s1, 0
	global_load_dwordx2 v[120:121], v41, s[42:43]
	s_add_i32 s26, s23, 23
	s_max_i32 s26, s26, s16
	s_min_i32 s26, s26, s25
	s_lshl_b32 s26, s26, 11
	s_add_u32 s44, s0, s26
	s_addc_u32 s45, s1, 0
	global_load_dwordx2 v[122:123], v41, s[44:45]
	s_add_i32 s26, s23, 24
	s_max_i32 s26, s26, s16
	s_min_i32 s26, s26, s25
	s_lshl_b32 s26, s26, 11
	s_add_u32 s30, s0, s26
	s_addc_u32 s31, s1, 0
	global_load_dwordx2 v[124:125], v41, s[30:31]
	s_add_i32 s26, s23, 25
	s_max_i32 s26, s26, s16
	s_min_i32 s26, s26, s25
	s_lshl_b32 s26, s26, 11
	s_add_u32 s32, s0, s26
	s_addc_u32 s33, s1, 0
	global_load_dwordx2 v[126:127], v41, s[32:33]
	s_add_i32 s26, s23, 26
	s_max_i32 s26, s26, s16
	s_min_i32 s26, s26, s25
	s_lshl_b32 s26, s26, 11
	s_add_u32 s34, s0, s26
	s_addc_u32 s35, s1, 0
	global_load_dwordx2 v[128:129], v41, s[34:35]
	s_add_i32 s26, s23, 27
	s_max_i32 s26, s26, s16
	s_min_i32 s26, s26, s25
	s_lshl_b32 s26, s26, 11
	s_add_u32 s36, s0, s26
	s_addc_u32 s37, s1, 0
	global_load_dwordx2 v[130:131], v41, s[36:37]
	s_add_i32 s26, s23, 28
	s_max_i32 s26, s26, s16
	s_min_i32 s26, s26, s25
	s_lshl_b32 s26, s26, 11
	s_add_u32 s38, s0, s26
	s_addc_u32 s39, s1, 0
	global_load_dwordx2 v[132:133], v41, s[38:39]
	s_add_i32 s26, s23, 29
	s_max_i32 s26, s26, s16
	s_min_i32 s26, s26, s25
	s_lshl_b32 s26, s26, 11
	s_add_u32 s40, s0, s26
	s_addc_u32 s41, s1, 0
	global_load_dwordx2 v[134:135], v41, s[40:41]
	s_add_i32 s26, s23, 30
	s_max_i32 s26, s26, s16
	s_min_i32 s26, s26, s25
	s_lshl_b32 s26, s26, 11
	s_add_u32 s42, s0, s26
	s_addc_u32 s43, s1, 0
	global_load_dwordx2 v[136:137], v41, s[42:43]
	s_add_i32 s26, s23, 31
	s_max_i32 s26, s26, s16
	s_min_i32 s26, s26, s25
	s_lshl_b32 s26, s26, 11
	s_add_u32 s44, s0, s26
	s_addc_u32 s45, s1, 0
	global_load_dwordx2 v[138:139], v41, s[44:45]
	s_add_i32 s26, s23, 32
	s_max_i32 s26, s26, s16
	s_min_i32 s26, s26, s25
	s_lshl_b32 s26, s26, 11
	s_add_u32 s30, s0, s26
	s_addc_u32 s31, s1, 0
	global_load_dwordx2 v[140:141], v41, s[30:31]
	s_add_i32 s26, s23, 33
	s_max_i32 s26, s26, s16
	s_min_i32 s26, s26, s25
	s_lshl_b32 s26, s26, 11
	s_add_u32 s32, s0, s26
	s_addc_u32 s33, s1, 0
	global_load_dwordx2 v[142:143], v41, s[32:33]
	s_add_i32 s26, s23, 34
	s_max_i32 s26, s26, s16
	s_min_i32 s26, s26, s25
	s_lshl_b32 s26, s26, 11
	s_add_u32 s34, s0, s26
	s_addc_u32 s35, s1, 0
	global_load_dwordx2 v[144:145], v41, s[34:35]
	s_add_i32 s26, s23, 35
	s_max_i32 s26, s26, s16
	s_min_i32 s26, s26, s25
	s_lshl_b32 s26, s26, 11
	s_add_u32 s36, s0, s26
	s_addc_u32 s37, s1, 0
	global_load_dwordx2 v[146:147], v41, s[36:37]
	s_add_i32 s26, s23, 36
	s_max_i32 s26, s26, s16
	s_min_i32 s26, s26, s25
	s_lshl_b32 s26, s26, 11
	s_add_u32 s38, s0, s26
	s_addc_u32 s39, s1, 0
	global_load_dwordx2 v[148:149], v41, s[38:39]
	s_add_i32 s26, s23, 37
	s_max_i32 s26, s26, s16
	s_min_i32 s26, s26, s25
	s_lshl_b32 s26, s26, 11
	s_add_u32 s40, s0, s26
	s_addc_u32 s41, s1, 0
	global_load_dwordx2 v[150:151], v41, s[40:41]
	s_add_i32 s26, s23, 38
	s_max_i32 s26, s26, s16
	s_min_i32 s26, s26, s25
	s_lshl_b32 s26, s26, 11
	s_add_u32 s42, s0, s26
	s_addc_u32 s43, s1, 0
	global_load_dwordx2 v[152:153], v41, s[42:43]
	s_branch .Lp13_rs
.Lp13_rs:
	s_and_saveexec_b64 s[10:11], s[4:5]
	s_cbranch_execz .LBB0_1562
	v_add_u32_e32 v4, s12, v20
	v_cmp_le_i32_e32 vcc, s16, v4
	v_cmp_gt_i32_e64 s[6:7], s17, v4
	s_and_b64 s[18:19], vcc, s[6:7]
	v_mov_b32_e32 v0, 0
	s_and_saveexec_b64 s[6:7], s[18:19]
	s_cbranch_execz .LBB0_1561
	v_lshlrev_b64 v[0:1], 7, v[4:5]
	v_lshl_add_u64 v[36:37], s[2:3], 0, v[0:1]
	global_load_dwordx4 v[0:3], v[36:37], off
	global_load_dwordx4 v[12:15], v[36:37], off offset:16
	global_load_dwordx4 v[16:19], v[36:37], off offset:32
	global_load_dwordx4 v[32:35], v[36:37], off offset:48
	s_waitcnt vmcnt(3)
	v_mov_b32_e32 v36, v1
	v_mov_b32_e32 v37, v2
	v_mov_b32_e32 v1, v3
	s_waitcnt vmcnt(2)
	v_mov_b32_e32 v2, v13
	v_mov_b32_e32 v3, v14
	v_mov_b32_e32 v13, v15
	v_pk_add_f32 v[0:1], v[36:37], v[0:1]
	v_pk_add_f32 v[2:3], v[2:3], v[12:13]
	v_add_f32_e32 v4, v0, v1
	v_pk_add_f32 v[0:1], v[2:3], v[2:3] op_sel:[0,1] op_sel_hi:[1,0]
	s_waitcnt vmcnt(1)
	v_add_f32_e32 v14, v16, v17
	v_add_f32_e32 v16, v18, v19
	s_waitcnt vmcnt(0)
	v_mov_b32_e32 v19, v32
	v_mov_b32_e32 v15, v34
	v_mov_b32_e32 v17, v35
	v_add_f32_e32 v18, 0, v4
	v_mov_b32_e32 v1, v33
	v_pk_add_f32 v[0:1], v[18:19], v[0:1]
	v_pk_add_f32 v[2:3], v[14:15], v[16:17]
	s_nop 0
	v_pk_add_f32 v[0:1], v[0:1], v[2:3]
	s_nop 0
	v_add_f32_e32 v0, v0, v1
	v_fmamk_f32 v0, v0, 0x3a800000, v31
	v_rsq_f32_e32 v0, v0

; __device__ __forceinline__ unsigned pk2(float lo, float hi) { unsigned r; asm volatile("v_cvt_pk_bf16_f32 %0, %1, %2" : "=v"(r) : "v"(lo), "v"(hi)); return r; }
; __device__ __forceinline__ unsigned pk2(float lo, float hi) { return f2bf(lo) | (f2bf(hi) << 16); }
; #define LDX(tok) ({ const u32x2 _q = *(const u32x2*)(xb + (size_t)(tok) * D + cq * 4); (f32x4){bf_lo(_q.x), bf_hi(_q.x), bf_lo(_q.y), bf_hi(_q.y)} * rs[(tok) - t0 + 8]; })
; __global__ void __launch_bounds__(512, 2) fwd_megakernel(Params Pk) {
;     ...
;             __syncthreads();
;             const int cq = tid & 255, half = tid >> 8, hw = 1 << (cq >> 6), ta = t0 + 32 * half;
;             const f32x4 gv = *(const f32x4*)(g1 + cq * 4);
;             f32x4 S = (f32x4){0.f, 0.f, 0.f, 0.f};
;     ...
;             for (int s = ta - hw; s <= ta + hw - 2; ++s) if (s >= sbeg && s < send) S += LDX(s);
;             for (int t = ta; t < ta + 32; ++t) {
;                 const int sin_ = t + hw - 1; if (sin_ < send) S += LDX(sin_);
;                 const int wl = (t - hw) > sbeg ? (t - hw) : sbeg, wh = (t + hw) < send ? (t + hw) : send; const float inv = 1.0f / (float)(wh - wl);
;                 const f32x4 xt = LDX(t);
;                 const f32x4 pv = (S * inv - xt) * gv;
;                 u32x2 w; w.x = pk2(pv[0], pv[1]); w.y = pk2(pv[2], pv[3]); *(u32x2*)(pbuf + (size_t)t * D + cq * 4) = w;
;                 const int sout = t - hw; if (sout >= sbeg) S -= LDX(sout);
;             }
.LBB0_1562:
	s_or_b64 exec, exec, s[10:11]
	s_waitcnt lgkmcnt(0)
	s_barrier
	s_cmp_eq_u32 s22, 0
	s_cbranch_scc1 .Lp13_hw1
	s_cmp_eq_u32 s22, 1
	s_cbranch_scc1 .Lp13_hw2
	s_cmp_eq_u32 s22, 2
	s_cbranch_scc1 .Lp13_hw4
	s_branch .Lp13_hw8
.Lp13_hw1:
	ds_read_b32 v154, v42 offset:28
	ds_read_b32 v155, v42 offset:32
	ds_read_b32 v156, v42 offset:36
	ds_read_b32 v157, v42 offset:40
	ds_read_b32 v158, v42 offset:44
	ds_read_b32 v159, v42 offset:48
	ds_read_b32 v160, v42 offset:52
	ds_read_b32 v161, v42 offset:56
	ds_read_b32 v162, v42 offset:60
	ds_read_b32 v163, v42 offset:64
	ds_read_b32 v164, v42 offset:68
	ds_read_b32 v165, v42 offset:72
	ds_read_b32 v166, v42 offset:76
	ds_read_b32 v167, v42 offset:80
	ds_read_b32 v168, v42 offset:84
	ds_read_b32 v169, v42 offset:88
	ds_read_b32 v170, v42 offset:92
	ds_read_b32 v171, v42 offset:96
	ds_read_b32 v172, v42 offset:100
	ds_read_b32 v173, v42 offset:104
	ds_read_b32 v174, v42 offset:108
	ds_read_b32 v175, v42 offset:112
	ds_read_b32 v176, v42 offset:116
	ds_read_b32 v177, v42 offset:120
	ds_read_b32 v178, v42 offset:124
	ds_read_b32 v179, v42 offset:128
	ds_read_b32 v180, v42 offset:132
	ds_read_b32 v181, v42 offset:136
	ds_read_b32 v182, v42 offset:140
	ds_read_b32 v183, v42 offset:144
	ds_read_b32 v184, v42 offset:148
	ds_read_b32 v185, v42 offset:152
	ds_read_b32 v186, v42 offset:156
	v_mov_b32_e32 v12, 0
	v_mov_b32_e32 v13, 0
	v_mov_b32_e32 v14, 0
	v_mov_b32_e32 v15, 0
	s_waitcnt lgkmcnt(0)
	s_waitcnt vmcnt(32)
	v_lshlrev_b32_e32 v36, 16, v60
	v_and_b32_e32 v37, 0xffff0000, v60
	v_lshlrev_b32_e32 v32, 16, v61
	v_and_b32_e32 v33, 0xffff0000, v61
	v_pk_fma_f32 v[14:15], v[154:155], v[32:33], v[14:15] op_sel_hi:[0,1,1]
	v_pk_fma_f32 v[12:13], v[154:155], v[36:37], v[12:13] op_sel_hi:[0,1,1]
	s_waitcnt vmcnt(31)
	v_lshlrev_b32_e32 v36, 16, v62
	v_and_b32_e32 v37, 0xffff0000, v62
	v_lshlrev_b32_e32 v32, 16, v63
	v_and_b32_e32 v33, 0xffff0000, v63
	v_pk_fma_f32 v[14:15], v[154:155], v[32:33], v[14:15] op_sel:[1,0,0] op_sel_hi:[1,1,1]
	v_pk_fma_f32 v[12:13], v[154:155], v[36:37], v[12:13] op_sel:[1,0,0] op_sel_hi:[1,1,1]
	s_add_i32 s26, s23, -1
	s_max_i32 s26, s26, s16
	s_add_i32 s27, s23, 1
	s_min_i32 s27, s27, s17
	s_sub_i32 s26, s27, s26
	v_cvt_f32_i32_e32 v35, s26
	v_lshlrev_b32_e32 v44, 16, v62
	v_div_scale_f32 v16, s[10:11], v35, v35, 1.0
	v_rcp_f32_e32 v17, v16
	v_div_scale_f32 v38, vcc, 1.0, v35, 1.0
	v_fma_f32 v39, -v16, v17, 1.0
	v_fmac_f32_e32 v17, v39, v17
	v_mul_f32_e32 v39, v38, v17
	v_fma_f32 v43, -v16, v39, v38
	v_fmac_f32_e32 v39, v43, v17
	v_fma_f32 v16, -v16, v39, v38
	v_and_b32_e32 v45, 0xffff0000, v62
	v_lshlrev_b32_e32 v46, 16, v63
	v_div_fmas_f32 v17, v16, v17, v39
	v_and_b32_e32 v47, 0xffff0000, v63
	v_div_fixup_f32 v38, v17, v35, 1.0
	v_pk_mul_f32 v[46:47], v[154:155], v[46:47] op_sel:[1,0] op_sel_hi:[1,1]
	v_pk_mul_f32 v[44:45], v[154:155], v[44:45] op_sel:[1,0] op_sel_hi:[1,1]
	v_pk_fma_f32 v[44:45], v[38:39], v[12:13], v[44:45] op_sel_hi:[0,1,1] neg_lo:[0,0,1] neg_hi:[0,0,1]
	v_pk_fma_f32 v[46:47], v[38:39], v[14:15], v[46:47] op_sel_hi:[0,1,1] neg_lo:[0,0,1] neg_hi:[0,0,1]
	v_pk_mul_f32 v[44:45], v[52:53], v[44:45]
	v_pk_mul_f32 v[46:47], v[54:55], v[46:47]
	v_cvt_pk_bf16_f32 v48, v44, v45
	v_cvt_pk_bf16_f32 v49, v46, v47
	s_add_u32 s46, s28, 0
	s_addc_u32 s47, s29, 0
	global_store_dwordx2 v41, v[48:49], s[46:47]
	v_lshlrev_b32_e32 v36, 16, v60
	v_and_b32_e32 v37, 0xffff0000, v60
	v_lshlrev_b32_e32 v32, 16, v61
	v_and_b32_e32 v33, 0xffff0000, v61
	v_pk_fma_f32 v[14:15], v[154:155], v[32:33], v[14:15] op_sel_hi:[0,1,1] neg_lo:[1,0,0] neg_hi:[1,0,0]
	v_pk_fma_f32 v[12:13], v[154:155], v[36:37], v[12:13] op_sel_hi:[0,1,1] neg_lo:[1,0,0] neg_hi:[1,0,0]
	s_waitcnt vmcnt(31)
	v_lshlrev_b32_e32 v36, 16, v64
	v_and_b32_e32 v37, 0xffff0000, v64
	v_lshlrev_b32_e32 v32, 16, v65
	v_and_b32_e32 v33, 0xffff0000, v65
	v_pk_fma_f32 v[14:15], v[156:157], v[32:33], v[14:15] op_sel_hi:[0,1,1]
	v_pk_fma_f32 v[12:13], v[156:157], v[36:37], v[12:13] op_sel_hi:[0,1,1]
	s_add_i32 s26, s23, 0
	s_max_i32 s26, s26, s16
	s_add_i32 s27, s23, 2
	s_min_i32 s27, s27, s17
	s_sub_i32 s26, s27, s26
	v_cvt_f32_i32_e32 v35, s26
	v_lshlrev_b32_e32 v44, 16, v64
	v_div_scale_f32 v16, s[10:11], v35, v35, 1.0
	v_rcp_f32_e32 v17, v16
	v_div_scale_f32 v38, vcc, 1.0, v35, 1.0
	v_fma_f32 v39, -v16, v17, 1.0
	v_fmac_f32_e32 v17, v39, v17
	v_mul_f32_e32 v39, v38, v17
	v_fma_f32 v43, -v16, v39, v38
	v_fmac_f32_e32 v39, v43, v17
	v_fma_f32 v16, -v16, v39, v38
	v_and_b32_e32 v45, 0xffff0000, v64
	v_lshlrev_b32_e32 v46, 16, v65
	v_div_fmas_f32 v17, v16, v17, v39
	v_and_b32_e32 v47, 0xffff0000, v65
	v_div_fixup_f32 v38, v17, v35, 1.0
	v_pk_mul_f32 v[46:47], v[156:157], v[46:47] op_sel_hi:[0,1]
	v_pk_mul_f32 v[44:45], v[156:157], v[44:45] op_sel_hi:[0,1]
	v_pk_fma_f32 v[44:45], v[38:39], v[12:13], v[44:45] op_sel_hi:[0,1,1] neg_lo:[0,0,1] neg_hi:[0,0,1]
	v_pk_fma_f32 v[46:47], v[38:39], v[14:15], v[46:47] op_sel_hi:[0,1,1] neg_lo:[0,0,1] neg_hi:[0,0,1]
	v_pk_mul_f32 v[44:45], v[52:53], v[44:45]
	v_pk_mul_f32 v[46:47], v[54:55], v[46:47]
	v_cvt_pk_bf16_f32 v50, v44, v45
	v_cvt_pk_bf16_f32 v51, v46, v47
	global_store_dwordx2 v41, v[50:51], s[46:47] offset:2048
	v_lshlrev_b32_e32 v36, 16, v62
	v_and_b32_e32 v37, 0xffff0000, v62
	v_lshlrev_b32_e32 v32, 16, v63
	v_and_b32_e32 v33, 0xffff0000, v63
	v_pk_fma_f32 v[14:15], v[154:155], v[32:33], v[14:15] op_sel:[1,0,0] op_sel_hi:[1,1,1] neg_lo:[1,0,0] neg_hi:[1,0,0]
	v_pk_fma_f32 v[12:13], v[154:155], v[36:37], v[12:13] op_sel:[1,0,0] op_sel_hi:[1,1,1] neg_lo:[1,0,0] neg_hi:[1,0,0]
	s_waitcnt vmcnt(31)
; __device__ __forceinline__ unsigned pk2(float lo, float hi) { unsigned r; asm volatile("v_cvt_pk_bf16_f32 %0, %1, %2" : "=v"(r) : "v"(lo), "v"(hi)); return r; }
; __device__ __forceinline__ unsigned pk2(float lo, float hi) { return f2bf(lo) | (f2bf(hi) << 16); }
; #define LDX(tok) ({ const u32x2 _q = *(const u32x2*)(xb + (size_t)(tok) * D + cq * 4); (f32x4){bf_lo(_q.x), bf_hi(_q.x), bf_lo(_q.y), bf_hi(_q.y)} * rs[(tok) - t0 + 8]; })
; __global__ void __launch_bounds__(512, 2) fwd_megakernel(Params Pk) {
;     ...
;             for (int t = ta; t < ta + 32; ++t) {
;                 const int sin_ = t + hw - 1; if (sin_ < send) S += LDX(sin_);
;                 const int wl = (t - hw) > sbeg ? (t - hw) : sbeg, wh = (t + hw) < send ? (t + hw) : send; const float inv = 1.0f / (float)(wh - wl);
;                 const f32x4 xt = LDX(t);
;                 const f32x4 pv = (S * inv - xt) * gv;
;                 u32x2 w; w.x = pk2(pv[0], pv[1]); w.y = pk2(pv[2], pv[3]); *(u32x2*)(pbuf + (size_t)t * D + cq * 4) = w;
;                 const int sout = t - hw; if (sout >= sbeg) S -= LDX(sout);
;             }
	v_lshlrev_b32_e32 v36, 16, v66
	v_and_b32_e32 v37, 0xffff0000, v66
	v_lshlrev_b32_e32 v32, 16, v67
	v_and_b32_e32 v33, 0xffff0000, v67
	v_pk_fma_f32 v[14:15], v[156:157], v[32:33], v[14:15] op_sel:[1,0,0] op_sel_hi:[1,1,1]
	v_pk_fma_f32 v[12:13], v[156:157], v[36:37], v[12:13] op_sel:[1,0,0] op_sel_hi:[1,1,1]
	s_add_i32 s26, s23, 1
	s_max_i32 s26, s26, s16
	s_add_i32 s27, s23, 3
	s_min_i32 s27, s27, s17
	s_sub_i32 s26, s27, s26
	v_cvt_f32_i32_e32 v35, s26
	v_lshlrev_b32_e32 v44, 16, v66
	v_div_scale_f32 v16, s[10:11], v35, v35, 1.0
	v_rcp_f32_e32 v17, v16
	v_div_scale_f32 v38, vcc, 1.0, v35, 1.0
	v_fma_f32 v39, -v16, v17, 1.0
	v_fmac_f32_e32 v17, v39, v17
	v_mul_f32_e32 v39, v38, v17
	v_fma_f32 v43, -v16, v39, v38
	v_fmac_f32_e32 v39, v43, v17
	v_fma_f32 v16, -v16, v39, v38
	v_and_b32_e32 v45, 0xffff0000, v66
	v_lshlrev_b32_e32 v46, 16, v67
	v_div_fmas_f32 v17, v16, v17, v39
	v_and_b32_e32 v47, 0xffff0000, v67
	v_div_fixup_f32 v38, v17, v35, 1.0
	v_pk_mul_f32 v[46:47], v[156:157], v[46:47] op_sel:[1,0] op_sel_hi:[1,1]
	v_pk_mul_f32 v[44:45], v[156:157], v[44:45] op_sel:[1,0] op_sel_hi:[1,1]
	v_pk_fma_f32 v[44:45], v[38:39], v[12:13], v[44:45] op_sel_hi:[0,1,1] neg_lo:[0,0,1] neg_hi:[0,0,1]
	v_pk_fma_f32 v[46:47], v[38:39], v[14:15], v[46:47] op_sel_hi:[0,1,1] neg_lo:[0,0,1] neg_hi:[0,0,1]
	v_pk_mul_f32 v[44:45], v[52:53], v[44:45]
	v_pk_mul_f32 v[46:47], v[54:55], v[46:47]
	v_cvt_pk_bf16_f32 v48, v44, v45
	v_cvt_pk_bf16_f32 v49, v46, v47
	s_add_u32 s48, s28, 4096
	s_addc_u32 s49, s29, 0
	global_store_dwordx2 v41, v[48:49], s[48:49]
	v_lshlrev_b32_e32 v36, 16, v64
	v_and_b32_e32 v37, 0xffff0000, v64
	v_lshlrev_b32_e32 v32, 16, v65
	v_and_b32_e32 v33, 0xffff0000, v65
	v_pk_fma_f32 v[14:15], v[156:157], v[32:33], v[14:15] op_sel_hi:[0,1,1] neg_lo:[1,0,0] neg_hi:[1,0,0]
	v_pk_fma_f32 v[12:13], v[156:157], v[36:37], v[12:13] op_sel_hi:[0,1,1] neg_lo:[1,0,0] neg_hi:[1,0,0]
	s_waitcnt vmcnt(31)
	v_lshlrev_b32_e32 v36, 16, v68
	v_and_b32_e32 v37, 0xffff0000, v68
	v_lshlrev_b32_e32 v32, 16, v69
	v_and_b32_e32 v33, 0xffff0000, v69
	v_pk_fma_f32 v[14:15], v[158:159], v[32:33], v[14:15] op_sel_hi:[0,1,1]
	v_pk_fma_f32 v[12:13], v[158:159], v[36:37], v[12:13] op_sel_hi:[0,1,1]
	s_add_i32 s26, s23, 2
	s_max_i32 s26, s26, s16
	s_add_i32 s27, s23, 4
	s_min_i32 s27, s27, s17
	s_sub_i32 s26, s27, s26
	v_cvt_f32_i32_e32 v35, s26
	v_lshlrev_b32_e32 v44, 16, v68
	v_div_scale_f32 v16, s[10:11], v35, v35, 1.0
	v_rcp_f32_e32 v17, v16
	v_div_scale_f32 v38, vcc, 1.0, v35, 1.0
	v_fma_f32 v39, -v16, v17, 1.0
	v_fmac_f32_e32 v17, v39, v17
	v_mul_f32_e32 v39, v38, v17
	v_fma_f32 v43, -v16, v39, v38
	v_fmac_f32_e32 v39, v43, v17
	v_fma_f32 v16, -v16, v39, v38
	v_and_b32_e32 v45, 0xffff0000, v68
	v_lshlrev_b32_e32 v46, 16, v69
	v_div_fmas_f32 v17, v16, v17, v39
	v_and_b32_e32 v47, 0xffff0000, v69
	v_div_fixup_f32 v38, v17, v35, 1.0
	v_pk_mul_f32 v[46:47], v[158:159], v[46:47] op_sel_hi:[0,1]
	v_pk_mul_f32 v[44:45], v[158:159], v[44:45] op_sel_hi:[0,1]
	v_pk_fma_f32 v[44:45], v[38:39], v[12:13], v[44:45] op_sel_hi:[0,1,1] neg_lo:[0,0,1] neg_hi:[0,0,1]
	v_pk_fma_f32 v[46:47], v[38:39], v[14:15], v[46:47] op_sel_hi:[0,1,1] neg_lo:[0,0,1] neg_hi:[0,0,1]
	v_pk_mul_f32 v[44:45], v[52:53], v[44:45]
	v_pk_mul_f32 v[46:47], v[54:55], v[46:47]
	v_cvt_pk_bf16_f32 v50, v44, v45
	v_cvt_pk_bf16_f32 v51, v46, v47
	global_store_dwordx2 v41, v[50:51], s[48:49] offset:2048
	v_lshlrev_b32_e32 v36, 16, v66
	v_and_b32_e32 v37, 0xffff0000, v66
	v_lshlrev_b32_e32 v32, 16, v67
	v_and_b32_e32 v33, 0xffff0000, v67
	v_pk_fma_f32 v[14:15], v[156:157], v[32:33], v[14:15] op_sel:[1,0,0] op_sel_hi:[1,1,1] neg_lo:[1,0,0] neg_hi:[1,0,0]
	v_pk_fma_f32 v[12:13], v[156:157], v[36:37], v[12:13] op_sel:[1,0,0] op_sel_hi:[1,1,1] neg_lo:[1,0,0] neg_hi:[1,0,0]
	s_waitcnt vmcnt(31)
	v_lshlrev_b32_e32 v36, 16, v70
	v_and_b32_e32 v37, 0xffff0000, v70
	v_lshlrev_b32_e32 v32, 16, v71
	v_and_b32_e32 v33, 0xffff0000, v71
	v_pk_fma_f32 v[14:15], v[158:159], v[32:33], v[14:15] op_sel:[1,0,0] op_sel_hi:[1,1,1]
	v_pk_fma_f32 v[12:13], v[158:159], v[36:37], v[12:13] op_sel:[1,0,0] op_sel_hi:[1,1,1]
	s_add_i32 s26, s23, 3
	s_max_i32 s26, s26, s16
	s_add_i32 s27, s23, 5
	s_min_i32 s27, s27, s17
	s_sub_i32 s26, s27, s26
	v_cvt_f32_i32_e32 v35, s26
	v_lshlrev_b32_e32 v44, 16, v70
	v_div_scale_f32 v16, s[10:11], v35, v35, 1.0
	v_rcp_f32_e32 v17, v16
	v_div_scale_f32 v38, vcc, 1.0, v35, 1.0
	v_fma_f32 v39, -v16, v17, 1.0
	v_fmac_f32_e32 v17, v39, v17
	v_mul_f32_e32 v39, v38, v17
	v_fma_f32 v43, -v16, v39, v38
	v_fmac_f32_e32 v39, v43, v17
	v_fma_f32 v16, -v16, v39, v38
	v_and_b32_e32 v45, 0xffff0000, v70
	v_lshlrev_b32_e32 v46, 16, v71
	v_div_fmas_f32 v17, v16, v17, v39
	v_and_b32_e32 v47, 0xffff0000, v71
	v_div_fixup_f32 v38, v17, v35, 1.0
	v_pk_mul_f32 v[46:47], v[158:159], v[46:47] op_sel:[1,0] op_sel_hi:[1,1]
	v_pk_mul_f32 v[44:45], v[158:159], v[44:45] op_sel:[1,0] op_sel_hi:[1,1]
	v_pk_fma_f32 v[44:45], v[38:39], v[12:13], v[44:45] op_sel_hi:[0,1,1] neg_lo:[0,0,1] neg_hi:[0,0,1]
	v_pk_fma_f32 v[46:47], v[38:39], v[14:15], v[46:47] op_sel_hi:[0,1,1] neg_lo:[0,0,1] neg_hi:[0,0,1]
	v_pk_mul_f32 v[44:45], v[52:53], v[44:45]
	v_pk_mul_f32 v[46:47], v[54:55], v[46:47]
	v_cvt_pk_bf16_f32 v48, v44, v45
	v_cvt_pk_bf16_f32 v49, v46, v47
	s_add_u32 s50, s28, 8192
	s_addc_u32 s51, s29, 0
	global_store_dwordx2 v41, v[48:49], s[50:51]
	v_lshlrev_b32_e32 v36, 16, v68
	v_and_b32_e32 v37, 0xffff0000, v68
	v_lshlrev_b32_e32 v32, 16, v69
	v_and_b32_e32 v33, 0xffff0000, v69
	v_pk_fma_f32 v[14:15], v[158:159], v[32:33], v[14:15] op_sel_hi:[0,1,1] neg_lo:[1,0,0] neg_hi:[1,0,0]
	v_pk_fma_f32 v[12:13], v[158:159], v[36:37], v[12:13] op_sel_hi:[0,1,1] neg_lo:[1,0,0] neg_hi:[1,0,0]
	s_waitcnt vmcnt(31)
; __device__ __forceinline__ unsigned pk2(float lo, float hi) { unsigned r; asm volatile("v_cvt_pk_bf16_f32 %0, %1, %2" : "=v"(r) : "v"(lo), "v"(hi)); return r; }
; __device__ __forceinline__ unsigned pk2(float lo, float hi) { return f2bf(lo) | (f2bf(hi) << 16); }
; #define LDX(tok) ({ const u32x2 _q = *(const u32x2*)(xb + (size_t)(tok) * D + cq * 4); (f32x4){bf_lo(_q.x), bf_hi(_q.x), bf_lo(_q.y), bf_hi(_q.y)} * rs[(tok) - t0 + 8]; })
; __global__ void __launch_bounds__(512, 2) fwd_megakernel(Params Pk) {
;     ...
;             for (int t = ta; t < ta + 32; ++t) {
;                 const int sin_ = t + hw - 1; if (sin_ < send) S += LDX(sin_);
;                 const int wl = (t - hw) > sbeg ? (t - hw) : sbeg, wh = (t + hw) < send ? (t + hw) : send; const float inv = 1.0f / (float)(wh - wl);
;                 const f32x4 xt = LDX(t);
;                 const f32x4 pv = (S * inv - xt) * gv;
;                 u32x2 w; w.x = pk2(pv[0], pv[1]); w.y = pk2(pv[2], pv[3]); *(u32x2*)(pbuf + (size_t)t * D + cq * 4) = w;
;                 const int sout = t - hw; if (sout >= sbeg) S -= LDX(sout);
;             }
	v_lshlrev_b32_e32 v36, 16, v72
	v_and_b32_e32 v37, 0xffff0000, v72
	v_lshlrev_b32_e32 v32, 16, v73
	v_and_b32_e32 v33, 0xffff0000, v73
	v_pk_fma_f32 v[14:15], v[160:161], v[32:33], v[14:15] op_sel_hi:[0,1,1]
	v_pk_fma_f32 v[12:13], v[160:161], v[36:37], v[12:13] op_sel_hi:[0,1,1]
	s_add_i32 s26, s23, 4
	s_max_i32 s26, s26, s16
	s_add_i32 s27, s23, 6
	s_min_i32 s27, s27, s17
	s_sub_i32 s26, s27, s26
	v_cvt_f32_i32_e32 v35, s26
	v_lshlrev_b32_e32 v44, 16, v72
	v_div_scale_f32 v16, s[10:11], v35, v35, 1.0
	v_rcp_f32_e32 v17, v16
	v_div_scale_f32 v38, vcc, 1.0, v35, 1.0
	v_fma_f32 v39, -v16, v17, 1.0
	v_fmac_f32_e32 v17, v39, v17
	v_mul_f32_e32 v39, v38, v17
	v_fma_f32 v43, -v16, v39, v38
	v_fmac_f32_e32 v39, v43, v17
	v_fma_f32 v16, -v16, v39, v38
	v_and_b32_e32 v45, 0xffff0000, v72
	v_lshlrev_b32_e32 v46, 16, v73
	v_div_fmas_f32 v17, v16, v17, v39
	v_and_b32_e32 v47, 0xffff0000, v73
	v_div_fixup_f32 v38, v17, v35, 1.0
	v_pk_mul_f32 v[46:47], v[160:161], v[46:47] op_sel_hi:[0,1]
	v_pk_mul_f32 v[44:45], v[160:161], v[44:45] op_sel_hi:[0,1]
	v_pk_fma_f32 v[44:45], v[38:39], v[12:13], v[44:45] op_sel_hi:[0,1,1] neg_lo:[0,0,1] neg_hi:[0,0,1]
	v_pk_fma_f32 v[46:47], v[38:39], v[14:15], v[46:47] op_sel_hi:[0,1,1] neg_lo:[0,0,1] neg_hi:[0,0,1]
	v_pk_mul_f32 v[44:45], v[52:53], v[44:45]
	v_pk_mul_f32 v[46:47], v[54:55], v[46:47]
	v_cvt_pk_bf16_f32 v50, v44, v45
	v_cvt_pk_bf16_f32 v51, v46, v47
	global_store_dwordx2 v41, v[50:51], s[50:51] offset:2048
	v_lshlrev_b32_e32 v36, 16, v70
	v_and_b32_e32 v37, 0xffff0000, v70
	v_lshlrev_b32_e32 v32, 16, v71
	v_and_b32_e32 v33, 0xffff0000, v71
	v_pk_fma_f32 v[14:15], v[158:159], v[32:33], v[14:15] op_sel:[1,0,0] op_sel_hi:[1,1,1] neg_lo:[1,0,0] neg_hi:[1,0,0]
	v_pk_fma_f32 v[12:13], v[158:159], v[36:37], v[12:13] op_sel:[1,0,0] op_sel_hi:[1,1,1] neg_lo:[1,0,0] neg_hi:[1,0,0]
	s_waitcnt vmcnt(31)
	v_lshlrev_b32_e32 v36, 16, v74
	v_and_b32_e32 v37, 0xffff0000, v74
	v_lshlrev_b32_e32 v32, 16, v75
	v_and_b32_e32 v33, 0xffff0000, v75
	v_pk_fma_f32 v[14:15], v[160:161], v[32:33], v[14:15] op_sel:[1,0,0] op_sel_hi:[1,1,1]
	v_pk_fma_f32 v[12:13], v[160:161], v[36:37], v[12:13] op_sel:[1,0,0] op_sel_hi:[1,1,1]
	s_add_i32 s26, s23, 5
	s_max_i32 s26, s26, s16
	s_add_i32 s27, s23, 7
	s_min_i32 s27, s27, s17
	s_sub_i32 s26, s27, s26
	v_cvt_f32_i32_e32 v35, s26
	v_lshlrev_b32_e32 v44, 16, v74
	v_div_scale_f32 v16, s[10:11], v35, v35, 1.0
	v_rcp_f32_e32 v17, v16
	v_div_scale_f32 v38, vcc, 1.0, v35, 1.0
	v_fma_f32 v39, -v16, v17, 1.0
	v_fmac_f32_e32 v17, v39, v17
	v_mul_f32_e32 v39, v38, v17
	v_fma_f32 v43, -v16, v39, v38
	v_fmac_f32_e32 v39, v43, v17
	v_fma_f32 v16, -v16, v39, v38
	v_and_b32_e32 v45, 0xffff0000, v74
	v_lshlrev_b32_e32 v46, 16, v75
	v_div_fmas_f32 v17, v16, v17, v39
	v_and_b32_e32 v47, 0xffff0000, v75
	v_div_fixup_f32 v38, v17, v35, 1.0
	v_pk_mul_f32 v[46:47], v[160:161], v[46:47] op_sel:[1,0] op_sel_hi:[1,1]
	v_pk_mul_f32 v[44:45], v[160:161], v[44:45] op_sel:[1,0] op_sel_hi:[1,1]
	v_pk_fma_f32 v[44:45], v[38:39], v[12:13], v[44:45] op_sel_hi:[0,1,1] neg_lo:[0,0,1] neg_hi:[0,0,1]
	v_pk_fma_f32 v[46:47], v[38:39], v[14:15], v[46:47] op_sel_hi:[0,1,1] neg_lo:[0,0,1] neg_hi:[0,0,1]
	v_pk_mul_f32 v[44:45], v[52:53], v[44:45]
	v_pk_mul_f32 v[46:47], v[54:55], v[46:47]
	v_cvt_pk_bf16_f32 v48, v44, v45
	v_cvt_pk_bf16_f32 v49, v46, v47
	s_add_u32 s52, s28, 12288
	s_addc_u32 s53, s29, 0
	global_store_dwordx2 v41, v[48:49], s[52:53]
	v_lshlrev_b32_e32 v36, 16, v72
	v_and_b32_e32 v37, 0xffff0000, v72
	v_lshlrev_b32_e32 v32, 16, v73
	v_and_b32_e32 v33, 0xffff0000, v73
	v_pk_fma_f32 v[14:15], v[160:161], v[32:33], v[14:15] op_sel_hi:[0,1,1] neg_lo:[1,0,0] neg_hi:[1,0,0]
	v_pk_fma_f32 v[12:13], v[160:161], v[36:37], v[12:13] op_sel_hi:[0,1,1] neg_lo:[1,0,0] neg_hi:[1,0,0]
	s_waitcnt vmcnt(31)
	v_lshlrev_b32_e32 v36, 16, v76
	v_and_b32_e32 v37, 0xffff0000, v76
	v_lshlrev_b32_e32 v32, 16, v77
	v_and_b32_e32 v33, 0xffff0000, v77
	v_pk_fma_f32 v[14:15], v[162:163], v[32:33], v[14:15] op_sel_hi:[0,1,1]
	v_pk_fma_f32 v[12:13], v[162:163], v[36:37], v[12:13] op_sel_hi:[0,1,1]
	s_add_i32 s26, s23, 6
	s_max_i32 s26, s26, s16
	s_add_i32 s27, s23, 8
	s_min_i32 s27, s27, s17
	s_sub_i32 s26, s27, s26
	v_cvt_f32_i32_e32 v35, s26
	v_lshlrev_b32_e32 v44, 16, v76
	v_div_scale_f32 v16, s[10:11], v35, v35, 1.0
	v_rcp_f32_e32 v17, v16
	v_div_scale_f32 v38, vcc, 1.0, v35, 1.0
	v_fma_f32 v39, -v16, v17, 1.0
	v_fmac_f32_e32 v17, v39, v17
	v_mul_f32_e32 v39, v38, v17
	v_fma_f32 v43, -v16, v39, v38
	v_fmac_f32_e32 v39, v43, v17
	v_fma_f32 v16, -v16, v39, v38
	v_and_b32_e32 v45, 0xffff0000, v76
	v_lshlrev_b32_e32 v46, 16, v77
	v_div_fmas_f32 v17, v16, v17, v39
	v_and_b32_e32 v47, 0xffff0000, v77
	v_div_fixup_f32 v38, v17, v35, 1.0
	v_pk_mul_f32 v[46:47], v[162:163], v[46:47] op_sel_hi:[0,1]
	v_pk_mul_f32 v[44:45], v[162:163], v[44:45] op_sel_hi:[0,1]
	v_pk_fma_f32 v[44:45], v[38:39], v[12:13], v[44:45] op_sel_hi:[0,1,1] neg_lo:[0,0,1] neg_hi:[0,0,1]
	v_pk_fma_f32 v[46:47], v[38:39], v[14:15], v[46:47] op_sel_hi:[0,1,1] neg_lo:[0,0,1] neg_hi:[0,0,1]
	v_pk_mul_f32 v[44:45], v[52:53], v[44:45]
	v_pk_mul_f32 v[46:47], v[54:55], v[46:47]
	v_cvt_pk_bf16_f32 v50, v44, v45
	v_cvt_pk_bf16_f32 v51, v46, v47
	global_store_dwordx2 v41, v[50:51], s[52:53] offset:2048
	v_lshlrev_b32_e32 v36, 16, v74
	v_and_b32_e32 v37, 0xffff0000, v74
	v_lshlrev_b32_e32 v32, 16, v75
	v_and_b32_e32 v33, 0xffff0000, v75
	v_pk_fma_f32 v[14:15], v[160:161], v[32:33], v[14:15] op_sel:[1,0,0] op_sel_hi:[1,1,1] neg_lo:[1,0,0] neg_hi:[1,0,0]
	v_pk_fma_f32 v[12:13], v[160:161], v[36:37], v[12:13] op_sel:[1,0,0] op_sel_hi:[1,1,1] neg_lo:[1,0,0] neg_hi:[1,0,0]
	s_waitcnt vmcnt(31)
; __device__ __forceinline__ unsigned pk2(float lo, float hi) { unsigned r; asm volatile("v_cvt_pk_bf16_f32 %0, %1, %2" : "=v"(r) : "v"(lo), "v"(hi)); return r; }
; __device__ __forceinline__ unsigned pk2(float lo, float hi) { return f2bf(lo) | (f2bf(hi) << 16); }
; #define LDX(tok) ({ const u32x2 _q = *(const u32x2*)(xb + (size_t)(tok) * D + cq * 4); (f32x4){bf_lo(_q.x), bf_hi(_q.x), bf_lo(_q.y), bf_hi(_q.y)} * rs[(tok) - t0 + 8]; })
; __global__ void __launch_bounds__(512, 2) fwd_megakernel(Params Pk) {
;     ...
;             for (int t = ta; t < ta + 32; ++t) {
;                 const int sin_ = t + hw - 1; if (sin_ < send) S += LDX(sin_);
;                 const int wl = (t - hw) > sbeg ? (t - hw) : sbeg, wh = (t + hw) < send ? (t + hw) : send; const float inv = 1.0f / (float)(wh - wl);
;                 const f32x4 xt = LDX(t);
;                 const f32x4 pv = (S * inv - xt) * gv;
;                 u32x2 w; w.x = pk2(pv[0], pv[1]); w.y = pk2(pv[2], pv[3]); *(u32x2*)(pbuf + (size_t)t * D + cq * 4) = w;
;                 const int sout = t - hw; if (sout >= sbeg) S -= LDX(sout);
;             }
	v_lshlrev_b32_e32 v36, 16, v78
	v_and_b32_e32 v37, 0xffff0000, v78
	v_lshlrev_b32_e32 v32, 16, v79
	v_and_b32_e32 v33, 0xffff0000, v79
	v_pk_fma_f32 v[14:15], v[162:163], v[32:33], v[14:15] op_sel:[1,0,0] op_sel_hi:[1,1,1]
	v_pk_fma_f32 v[12:13], v[162:163], v[36:37], v[12:13] op_sel:[1,0,0] op_sel_hi:[1,1,1]
	s_add_i32 s26, s23, 7
	s_max_i32 s26, s26, s16
	s_add_i32 s27, s23, 9
	s_min_i32 s27, s27, s17
	s_sub_i32 s26, s27, s26
	v_cvt_f32_i32_e32 v35, s26
	v_lshlrev_b32_e32 v44, 16, v78
	v_div_scale_f32 v16, s[10:11], v35, v35, 1.0
	v_rcp_f32_e32 v17, v16
	v_div_scale_f32 v38, vcc, 1.0, v35, 1.0
	v_fma_f32 v39, -v16, v17, 1.0
	v_fmac_f32_e32 v17, v39, v17
	v_mul_f32_e32 v39, v38, v17
	v_fma_f32 v43, -v16, v39, v38
	v_fmac_f32_e32 v39, v43, v17
	v_fma_f32 v16, -v16, v39, v38
	v_and_b32_e32 v45, 0xffff0000, v78
	v_lshlrev_b32_e32 v46, 16, v79
	v_div_fmas_f32 v17, v16, v17, v39
	v_and_b32_e32 v47, 0xffff0000, v79
	v_div_fixup_f32 v38, v17, v35, 1.0
	v_pk_mul_f32 v[46:47], v[162:163], v[46:47] op_sel:[1,0] op_sel_hi:[1,1]
	v_pk_mul_f32 v[44:45], v[162:163], v[44:45] op_sel:[1,0] op_sel_hi:[1,1]
	v_pk_fma_f32 v[44:45], v[38:39], v[12:13], v[44:45] op_sel_hi:[0,1,1] neg_lo:[0,0,1] neg_hi:[0,0,1]
	v_pk_fma_f32 v[46:47], v[38:39], v[14:15], v[46:47] op_sel_hi:[0,1,1] neg_lo:[0,0,1] neg_hi:[0,0,1]
	v_pk_mul_f32 v[44:45], v[52:53], v[44:45]
	v_pk_mul_f32 v[46:47], v[54:55], v[46:47]
	v_cvt_pk_bf16_f32 v48, v44, v45
	v_cvt_pk_bf16_f32 v49, v46, v47
	s_add_u32 s46, s28, 16384
	s_addc_u32 s47, s29, 0
	global_store_dwordx2 v41, v[48:49], s[46:47]
	v_lshlrev_b32_e32 v36, 16, v76
	v_and_b32_e32 v37, 0xffff0000, v76
	v_lshlrev_b32_e32 v32, 16, v77
	v_and_b32_e32 v33, 0xffff0000, v77
	v_pk_fma_f32 v[14:15], v[162:163], v[32:33], v[14:15] op_sel_hi:[0,1,1] neg_lo:[1,0,0] neg_hi:[1,0,0]
	v_pk_fma_f32 v[12:13], v[162:163], v[36:37], v[12:13] op_sel_hi:[0,1,1] neg_lo:[1,0,0] neg_hi:[1,0,0]
	s_waitcnt vmcnt(31)
	v_lshlrev_b32_e32 v36, 16, v80
	v_and_b32_e32 v37, 0xffff0000, v80
	v_lshlrev_b32_e32 v32, 16, v81
	v_and_b32_e32 v33, 0xffff0000, v81
	v_pk_fma_f32 v[14:15], v[164:165], v[32:33], v[14:15] op_sel_hi:[0,1,1]
	v_pk_fma_f32 v[12:13], v[164:165], v[36:37], v[12:13] op_sel_hi:[0,1,1]
	s_add_i32 s26, s23, 8
	s_max_i32 s26, s26, s16
	s_add_i32 s27, s23, 10
	s_min_i32 s27, s27, s17
	s_sub_i32 s26, s27, s26
	v_cvt_f32_i32_e32 v35, s26
	v_lshlrev_b32_e32 v44, 16, v80
	v_div_scale_f32 v16, s[10:11], v35, v35, 1.0
	v_rcp_f32_e32 v17, v16
	v_div_scale_f32 v38, vcc, 1.0, v35, 1.0
	v_fma_f32 v39, -v16, v17, 1.0
	v_fmac_f32_e32 v17, v39, v17
	v_mul_f32_e32 v39, v38, v17
	v_fma_f32 v43, -v16, v39, v38
	v_fmac_f32_e32 v39, v43, v17
	v_fma_f32 v16, -v16, v39, v38
	v_and_b32_e32 v45, 0xffff0000, v80
	v_lshlrev_b32_e32 v46, 16, v81
	v_div_fmas_f32 v17, v16, v17, v39
	v_and_b32_e32 v47, 0xffff0000, v81
	v_div_fixup_f32 v38, v17, v35, 1.0
	v_pk_mul_f32 v[46:47], v[164:165], v[46:47] op_sel_hi:[0,1]
	v_pk_mul_f32 v[44:45], v[164:165], v[44:45] op_sel_hi:[0,1]
	v_pk_fma_f32 v[44:45], v[38:39], v[12:13], v[44:45] op_sel_hi:[0,1,1] neg_lo:[0,0,1] neg_hi:[0,0,1]
	v_pk_fma_f32 v[46:47], v[38:39], v[14:15], v[46:47] op_sel_hi:[0,1,1] neg_lo:[0,0,1] neg_hi:[0,0,1]
	v_pk_mul_f32 v[44:45], v[52:53], v[44:45]
	v_pk_mul_f32 v[46:47], v[54:55], v[46:47]
	v_cvt_pk_bf16_f32 v50, v44, v45
	v_cvt_pk_bf16_f32 v51, v46, v47
	global_store_dwordx2 v41, v[50:51], s[46:47] offset:2048
	v_lshlrev_b32_e32 v36, 16, v78
	v_and_b32_e32 v37, 0xffff0000, v78
	v_lshlrev_b32_e32 v32, 16, v79
	v_and_b32_e32 v33, 0xffff0000, v79
	v_pk_fma_f32 v[14:15], v[162:163], v[32:33], v[14:15] op_sel:[1,0,0] op_sel_hi:[1,1,1] neg_lo:[1,0,0] neg_hi:[1,0,0]
	v_pk_fma_f32 v[12:13], v[162:163], v[36:37], v[12:13] op_sel:[1,0,0] op_sel_hi:[1,1,1] neg_lo:[1,0,0] neg_hi:[1,0,0]
	s_waitcnt vmcnt(31)
	v_lshlrev_b32_e32 v36, 16, v82
	v_and_b32_e32 v37, 0xffff0000, v82
	v_lshlrev_b32_e32 v32, 16, v83
	v_and_b32_e32 v33, 0xffff0000, v83
	v_pk_fma_f32 v[14:15], v[164:165], v[32:33], v[14:15] op_sel:[1,0,0] op_sel_hi:[1,1,1]
	v_pk_fma_f32 v[12:13], v[164:165], v[36:37], v[12:13] op_sel:[1,0,0] op_sel_hi:[1,1,1]
	s_add_i32 s26, s23, 9
	s_max_i32 s26, s26, s16
	s_add_i32 s27, s23, 11
	s_min_i32 s27, s27, s17
	s_sub_i32 s26, s27, s26
	v_cvt_f32_i32_e32 v35, s26
	v_lshlrev_b32_e32 v44, 16, v82
	v_div_scale_f32 v16, s[10:11], v35, v35, 1.0
	v_rcp_f32_e32 v17, v16
	v_div_scale_f32 v38, vcc, 1.0, v35, 1.0
	v_fma_f32 v39, -v16, v17, 1.0
	v_fmac_f32_e32 v17, v39, v17
	v_mul_f32_e32 v39, v38, v17
	v_fma_f32 v43, -v16, v39, v38
	v_fmac_f32_e32 v39, v43, v17
	v_fma_f32 v16, -v16, v39, v38
	v_and_b32_e32 v45, 0xffff0000, v82
	v_lshlrev_b32_e32 v46, 16, v83
	v_div_fmas_f32 v17, v16, v17, v39
	v_and_b32_e32 v47, 0xffff0000, v83
	v_div_fixup_f32 v38, v17, v35, 1.0
	v_pk_mul_f32 v[46:47], v[164:165], v[46:47] op_sel:[1,0] op_sel_hi:[1,1]
	v_pk_mul_f32 v[44:45], v[164:165], v[44:45] op_sel:[1,0] op_sel_hi:[1,1]
	v_pk_fma_f32 v[44:45], v[38:39], v[12:13], v[44:45] op_sel_hi:[0,1,1] neg_lo:[0,0,1] neg_hi:[0,0,1]
	v_pk_fma_f32 v[46:47], v[38:39], v[14:15], v[46:47] op_sel_hi:[0,1,1] neg_lo:[0,0,1] neg_hi:[0,0,1]
	v_pk_mul_f32 v[44:45], v[52:53], v[44:45]
	v_pk_mul_f32 v[46:47], v[54:55], v[46:47]
	v_cvt_pk_bf16_f32 v48, v44, v45
	v_cvt_pk_bf16_f32 v49, v46, v47
	s_add_u32 s48, s28, 20480
	s_addc_u32 s49, s29, 0
	global_store_dwordx2 v41, v[48:49], s[48:49]
	v_lshlrev_b32_e32 v36, 16, v80
	v_and_b32_e32 v37, 0xffff0000, v80
	v_lshlrev_b32_e32 v32, 16, v81
	v_and_b32_e32 v33, 0xffff0000, v81
	v_pk_fma_f32 v[14:15], v[164:165], v[32:33], v[14:15] op_sel_hi:[0,1,1] neg_lo:[1,0,0] neg_hi:[1,0,0]
	v_pk_fma_f32 v[12:13], v[164:165], v[36:37], v[12:13] op_sel_hi:[0,1,1] neg_lo:[1,0,0] neg_hi:[1,0,0]
	s_waitcnt vmcnt(31)
; __device__ __forceinline__ unsigned pk2(float lo, float hi) { unsigned r; asm volatile("v_cvt_pk_bf16_f32 %0, %1, %2" : "=v"(r) : "v"(lo), "v"(hi)); return r; }
; __device__ __forceinline__ unsigned pk2(float lo, float hi) { return f2bf(lo) | (f2bf(hi) << 16); }
; #define LDX(tok) ({ const u32x2 _q = *(const u32x2*)(xb + (size_t)(tok) * D + cq * 4); (f32x4){bf_lo(_q.x), bf_hi(_q.x), bf_lo(_q.y), bf_hi(_q.y)} * rs[(tok) - t0 + 8]; })
; __global__ void __launch_bounds__(512, 2) fwd_megakernel(Params Pk) {
;     ...
;             for (int t = ta; t < ta + 32; ++t) {
;                 const int sin_ = t + hw - 1; if (sin_ < send) S += LDX(sin_);
;                 const int wl = (t - hw) > sbeg ? (t - hw) : sbeg, wh = (t + hw) < send ? (t + hw) : send; const float inv = 1.0f / (float)(wh - wl);
;                 const f32x4 xt = LDX(t);
;                 const f32x4 pv = (S * inv - xt) * gv;
;                 u32x2 w; w.x = pk2(pv[0], pv[1]); w.y = pk2(pv[2], pv[3]); *(u32x2*)(pbuf + (size_t)t * D + cq * 4) = w;
;                 const int sout = t - hw; if (sout >= sbeg) S -= LDX(sout);
;             }
	v_lshlrev_b32_e32 v36, 16, v84
	v_and_b32_e32 v37, 0xffff0000, v84
	v_lshlrev_b32_e32 v32, 16, v85
	v_and_b32_e32 v33, 0xffff0000, v85
	v_pk_fma_f32 v[14:15], v[166:167], v[32:33], v[14:15] op_sel_hi:[0,1,1]
	v_pk_fma_f32 v[12:13], v[166:167], v[36:37], v[12:13] op_sel_hi:[0,1,1]
	s_add_i32 s26, s23, 10
	s_max_i32 s26, s26, s16
	s_add_i32 s27, s23, 12
	s_min_i32 s27, s27, s17
	s_sub_i32 s26, s27, s26
	v_cvt_f32_i32_e32 v35, s26
	v_lshlrev_b32_e32 v44, 16, v84
	v_div_scale_f32 v16, s[10:11], v35, v35, 1.0
	v_rcp_f32_e32 v17, v16
	v_div_scale_f32 v38, vcc, 1.0, v35, 1.0
	v_fma_f32 v39, -v16, v17, 1.0
	v_fmac_f32_e32 v17, v39, v17
	v_mul_f32_e32 v39, v38, v17
	v_fma_f32 v43, -v16, v39, v38
	v_fmac_f32_e32 v39, v43, v17
	v_fma_f32 v16, -v16, v39, v38
	v_and_b32_e32 v45, 0xffff0000, v84
	v_lshlrev_b32_e32 v46, 16, v85
	v_div_fmas_f32 v17, v16, v17, v39
	v_and_b32_e32 v47, 0xffff0000, v85
	v_div_fixup_f32 v38, v17, v35, 1.0
	v_pk_mul_f32 v[46:47], v[166:167], v[46:47] op_sel_hi:[0,1]
	v_pk_mul_f32 v[44:45], v[166:167], v[44:45] op_sel_hi:[0,1]
	v_pk_fma_f32 v[44:45], v[38:39], v[12:13], v[44:45] op_sel_hi:[0,1,1] neg_lo:[0,0,1] neg_hi:[0,0,1]
	v_pk_fma_f32 v[46:47], v[38:39], v[14:15], v[46:47] op_sel_hi:[0,1,1] neg_lo:[0,0,1] neg_hi:[0,0,1]
	v_pk_mul_f32 v[44:45], v[52:53], v[44:45]
	v_pk_mul_f32 v[46:47], v[54:55], v[46:47]
	v_cvt_pk_bf16_f32 v50, v44, v45
	v_cvt_pk_bf16_f32 v51, v46, v47
	global_store_dwordx2 v41, v[50:51], s[48:49] offset:2048
	v_lshlrev_b32_e32 v36, 16, v82
	v_and_b32_e32 v37, 0xffff0000, v82
	v_lshlrev_b32_e32 v32, 16, v83
	v_and_b32_e32 v33, 0xffff0000, v83
	v_pk_fma_f32 v[14:15], v[164:165], v[32:33], v[14:15] op_sel:[1,0,0] op_sel_hi:[1,1,1] neg_lo:[1,0,0] neg_hi:[1,0,0]
	v_pk_fma_f32 v[12:13], v[164:165], v[36:37], v[12:13] op_sel:[1,0,0] op_sel_hi:[1,1,1] neg_lo:[1,0,0] neg_hi:[1,0,0]
	s_waitcnt vmcnt(31)
	v_lshlrev_b32_e32 v36, 16, v86
	v_and_b32_e32 v37, 0xffff0000, v86
	v_lshlrev_b32_e32 v32, 16, v87
	v_and_b32_e32 v33, 0xffff0000, v87
	v_pk_fma_f32 v[14:15], v[166:167], v[32:33], v[14:15] op_sel:[1,0,0] op_sel_hi:[1,1,1]
	v_pk_fma_f32 v[12:13], v[166:167], v[36:37], v[12:13] op_sel:[1,0,0] op_sel_hi:[1,1,1]
	s_add_i32 s26, s23, 11
	s_max_i32 s26, s26, s16
	s_add_i32 s27, s23, 13
	s_min_i32 s27, s27, s17
	s_sub_i32 s26, s27, s26
	v_cvt_f32_i32_e32 v35, s26
	v_lshlrev_b32_e32 v44, 16, v86
	v_div_scale_f32 v16, s[10:11], v35, v35, 1.0
	v_rcp_f32_e32 v17, v16
	v_div_scale_f32 v38, vcc, 1.0, v35, 1.0
	v_fma_f32 v39, -v16, v17, 1.0
	v_fmac_f32_e32 v17, v39, v17
	v_mul_f32_e32 v39, v38, v17
	v_fma_f32 v43, -v16, v39, v38
	v_fmac_f32_e32 v39, v43, v17
	v_fma_f32 v16, -v16, v39, v38
	v_and_b32_e32 v45, 0xffff0000, v86
	v_lshlrev_b32_e32 v46, 16, v87
	v_div_fmas_f32 v17, v16, v17, v39
	v_and_b32_e32 v47, 0xffff0000, v87
	v_div_fixup_f32 v38, v17, v35, 1.0
	v_pk_mul_f32 v[46:47], v[166:167], v[46:47] op_sel:[1,0] op_sel_hi:[1,1]
	v_pk_mul_f32 v[44:45], v[166:167], v[44:45] op_sel:[1,0] op_sel_hi:[1,1]
	v_pk_fma_f32 v[44:45], v[38:39], v[12:13], v[44:45] op_sel_hi:[0,1,1] neg_lo:[0,0,1] neg_hi:[0,0,1]
	v_pk_fma_f32 v[46:47], v[38:39], v[14:15], v[46:47] op_sel_hi:[0,1,1] neg_lo:[0,0,1] neg_hi:[0,0,1]
	v_pk_mul_f32 v[44:45], v[52:53], v[44:45]
	v_pk_mul_f32 v[46:47], v[54:55], v[46:47]
	v_cvt_pk_bf16_f32 v48, v44, v45
	v_cvt_pk_bf16_f32 v49, v46, v47
	s_add_u32 s50, s28, 24576
	s_addc_u32 s51, s29, 0
	global_store_dwordx2 v41, v[48:49], s[50:51]
	v_lshlrev_b32_e32 v36, 16, v84
	v_and_b32_e32 v37, 0xffff0000, v84
	v_lshlrev_b32_e32 v32, 16, v85
	v_and_b32_e32 v33, 0xffff0000, v85
	v_pk_fma_f32 v[14:15], v[166:167], v[32:33], v[14:15] op_sel_hi:[0,1,1] neg_lo:[1,0,0] neg_hi:[1,0,0]
	v_pk_fma_f32 v[12:13], v[166:167], v[36:37], v[12:13] op_sel_hi:[0,1,1] neg_lo:[1,0,0] neg_hi:[1,0,0]
	s_waitcnt vmcnt(31)
	v_lshlrev_b32_e32 v36, 16, v88
	v_and_b32_e32 v37, 0xffff0000, v88
	v_lshlrev_b32_e32 v32, 16, v89
	v_and_b32_e32 v33, 0xffff0000, v89
	v_pk_fma_f32 v[14:15], v[168:169], v[32:33], v[14:15] op_sel_hi:[0,1,1]
	v_pk_fma_f32 v[12:13], v[168:169], v[36:37], v[12:13] op_sel_hi:[0,1,1]
	s_add_i32 s26, s23, 12
	s_max_i32 s26, s26, s16
	s_add_i32 s27, s23, 14
	s_min_i32 s27, s27, s17
	s_sub_i32 s26, s27, s26
	v_cvt_f32_i32_e32 v35, s26
	v_lshlrev_b32_e32 v44, 16, v88
	v_div_scale_f32 v16, s[10:11], v35, v35, 1.0
	v_rcp_f32_e32 v17, v16
	v_div_scale_f32 v38, vcc, 1.0, v35, 1.0
	v_fma_f32 v39, -v16, v17, 1.0
	v_fmac_f32_e32 v17, v39, v17
	v_mul_f32_e32 v39, v38, v17
	v_fma_f32 v43, -v16, v39, v38
	v_fmac_f32_e32 v39, v43, v17
	v_fma_f32 v16, -v16, v39, v38
	v_and_b32_e32 v45, 0xffff0000, v88
	v_lshlrev_b32_e32 v46, 16, v89
	v_div_fmas_f32 v17, v16, v17, v39
	v_and_b32_e32 v47, 0xffff0000, v89
	v_div_fixup_f32 v38, v17, v35, 1.0
	v_pk_mul_f32 v[46:47], v[168:169], v[46:47] op_sel_hi:[0,1]
	v_pk_mul_f32 v[44:45], v[168:169], v[44:45] op_sel_hi:[0,1]
	v_pk_fma_f32 v[44:45], v[38:39], v[12:13], v[44:45] op_sel_hi:[0,1,1] neg_lo:[0,0,1] neg_hi:[0,0,1]
	v_pk_fma_f32 v[46:47], v[38:39], v[14:15], v[46:47] op_sel_hi:[0,1,1] neg_lo:[0,0,1] neg_hi:[0,0,1]
	v_pk_mul_f32 v[44:45], v[52:53], v[44:45]
	v_pk_mul_f32 v[46:47], v[54:55], v[46:47]
	v_cvt_pk_bf16_f32 v50, v44, v45
	v_cvt_pk_bf16_f32 v51, v46, v47
	global_store_dwordx2 v41, v[50:51], s[50:51] offset:2048
	v_lshlrev_b32_e32 v36, 16, v86
	v_and_b32_e32 v37, 0xffff0000, v86
	v_lshlrev_b32_e32 v32, 16, v87
	v_and_b32_e32 v33, 0xffff0000, v87
	v_pk_fma_f32 v[14:15], v[166:167], v[32:33], v[14:15] op_sel:[1,0,0] op_sel_hi:[1,1,1] neg_lo:[1,0,0] neg_hi:[1,0,0]
	v_pk_fma_f32 v[12:13], v[166:167], v[36:37], v[12:13] op_sel:[1,0,0] op_sel_hi:[1,1,1] neg_lo:[1,0,0] neg_hi:[1,0,0]
	s_waitcnt vmcnt(31)
; __device__ __forceinline__ unsigned pk2(float lo, float hi) { unsigned r; asm volatile("v_cvt_pk_bf16_f32 %0, %1, %2" : "=v"(r) : "v"(lo), "v"(hi)); return r; }
; __device__ __forceinline__ unsigned pk2(float lo, float hi) { return f2bf(lo) | (f2bf(hi) << 16); }
; #define LDX(tok) ({ const u32x2 _q = *(const u32x2*)(xb + (size_t)(tok) * D + cq * 4); (f32x4){bf_lo(_q.x), bf_hi(_q.x), bf_lo(_q.y), bf_hi(_q.y)} * rs[(tok) - t0 + 8]; })
; __global__ void __launch_bounds__(512, 2) fwd_megakernel(Params Pk) {
;     ...
;             for (int t = ta; t < ta + 32; ++t) {
;                 const int sin_ = t + hw - 1; if (sin_ < send) S += LDX(sin_);
;                 const int wl = (t - hw) > sbeg ? (t - hw) : sbeg, wh = (t + hw) < send ? (t + hw) : send; const float inv = 1.0f / (float)(wh - wl);
;                 const f32x4 xt = LDX(t);
;                 const f32x4 pv = (S * inv - xt) * gv;
;                 u32x2 w; w.x = pk2(pv[0], pv[1]); w.y = pk2(pv[2], pv[3]); *(u32x2*)(pbuf + (size_t)t * D + cq * 4) = w;
;                 const int sout = t - hw; if (sout >= sbeg) S -= LDX(sout);
;             }
	v_lshlrev_b32_e32 v36, 16, v90
	v_and_b32_e32 v37, 0xffff0000, v90
	v_lshlrev_b32_e32 v32, 16, v91
	v_and_b32_e32 v33, 0xffff0000, v91
	v_pk_fma_f32 v[14:15], v[168:169], v[32:33], v[14:15] op_sel:[1,0,0] op_sel_hi:[1,1,1]
	v_pk_fma_f32 v[12:13], v[168:169], v[36:37], v[12:13] op_sel:[1,0,0] op_sel_hi:[1,1,1]
	s_add_i32 s26, s23, 13
	s_max_i32 s26, s26, s16
	s_add_i32 s27, s23, 15
	s_min_i32 s27, s27, s17
	s_sub_i32 s26, s27, s26
	v_cvt_f32_i32_e32 v35, s26
	v_lshlrev_b32_e32 v44, 16, v90
	v_div_scale_f32 v16, s[10:11], v35, v35, 1.0
	v_rcp_f32_e32 v17, v16
	v_div_scale_f32 v38, vcc, 1.0, v35, 1.0
	v_fma_f32 v39, -v16, v17, 1.0
	v_fmac_f32_e32 v17, v39, v17
	v_mul_f32_e32 v39, v38, v17
	v_fma_f32 v43, -v16, v39, v38
	v_fmac_f32_e32 v39, v43, v17
	v_fma_f32 v16, -v16, v39, v38
	v_and_b32_e32 v45, 0xffff0000, v90
	v_lshlrev_b32_e32 v46, 16, v91
	v_div_fmas_f32 v17, v16, v17, v39
	v_and_b32_e32 v47, 0xffff0000, v91
	v_div_fixup_f32 v38, v17, v35, 1.0
	v_pk_mul_f32 v[46:47], v[168:169], v[46:47] op_sel:[1,0] op_sel_hi:[1,1]
	v_pk_mul_f32 v[44:45], v[168:169], v[44:45] op_sel:[1,0] op_sel_hi:[1,1]
	v_pk_fma_f32 v[44:45], v[38:39], v[12:13], v[44:45] op_sel_hi:[0,1,1] neg_lo:[0,0,1] neg_hi:[0,0,1]
	v_pk_fma_f32 v[46:47], v[38:39], v[14:15], v[46:47] op_sel_hi:[0,1,1] neg_lo:[0,0,1] neg_hi:[0,0,1]
	v_pk_mul_f32 v[44:45], v[52:53], v[44:45]
	v_pk_mul_f32 v[46:47], v[54:55], v[46:47]
	v_cvt_pk_bf16_f32 v48, v44, v45
	v_cvt_pk_bf16_f32 v49, v46, v47
	s_add_u32 s52, s28, 28672
	s_addc_u32 s53, s29, 0
	global_store_dwordx2 v41, v[48:49], s[52:53]
	v_lshlrev_b32_e32 v36, 16, v88
	v_and_b32_e32 v37, 0xffff0000, v88
	v_lshlrev_b32_e32 v32, 16, v89
	v_and_b32_e32 v33, 0xffff0000, v89
	v_pk_fma_f32 v[14:15], v[168:169], v[32:33], v[14:15] op_sel_hi:[0,1,1] neg_lo:[1,0,0] neg_hi:[1,0,0]
	v_pk_fma_f32 v[12:13], v[168:169], v[36:37], v[12:13] op_sel_hi:[0,1,1] neg_lo:[1,0,0] neg_hi:[1,0,0]
	s_waitcnt vmcnt(31)
	v_lshlrev_b32_e32 v36, 16, v92
	v_and_b32_e32 v37, 0xffff0000, v92
	v_lshlrev_b32_e32 v32, 16, v93
	v_and_b32_e32 v33, 0xffff0000, v93
	v_pk_fma_f32 v[14:15], v[170:171], v[32:33], v[14:15] op_sel_hi:[0,1,1]
	v_pk_fma_f32 v[12:13], v[170:171], v[36:37], v[12:13] op_sel_hi:[0,1,1]
	s_add_i32 s26, s23, 14
	s_max_i32 s26, s26, s16
	s_add_i32 s27, s23, 16
	s_min_i32 s27, s27, s17
	s_sub_i32 s26, s27, s26
	v_cvt_f32_i32_e32 v35, s26
	v_lshlrev_b32_e32 v44, 16, v92
	v_div_scale_f32 v16, s[10:11], v35, v35, 1.0
	v_rcp_f32_e32 v17, v16
	v_div_scale_f32 v38, vcc, 1.0, v35, 1.0
	v_fma_f32 v39, -v16, v17, 1.0
	v_fmac_f32_e32 v17, v39, v17
	v_mul_f32_e32 v39, v38, v17
	v_fma_f32 v43, -v16, v39, v38
	v_fmac_f32_e32 v39, v43, v17
	v_fma_f32 v16, -v16, v39, v38
	v_and_b32_e32 v45, 0xffff0000, v92
	v_lshlrev_b32_e32 v46, 16, v93
	v_div_fmas_f32 v17, v16, v17, v39
	v_and_b32_e32 v47, 0xffff0000, v93
	v_div_fixup_f32 v38, v17, v35, 1.0
	v_pk_mul_f32 v[46:47], v[170:171], v[46:47] op_sel_hi:[0,1]
	v_pk_mul_f32 v[44:45], v[170:171], v[44:45] op_sel_hi:[0,1]
	v_pk_fma_f32 v[44:45], v[38:39], v[12:13], v[44:45] op_sel_hi:[0,1,1] neg_lo:[0,0,1] neg_hi:[0,0,1]
	v_pk_fma_f32 v[46:47], v[38:39], v[14:15], v[46:47] op_sel_hi:[0,1,1] neg_lo:[0,0,1] neg_hi:[0,0,1]
	v_pk_mul_f32 v[44:45], v[52:53], v[44:45]
	v_pk_mul_f32 v[46:47], v[54:55], v[46:47]
	v_cvt_pk_bf16_f32 v50, v44, v45
	v_cvt_pk_bf16_f32 v51, v46, v47
	global_store_dwordx2 v41, v[50:51], s[52:53] offset:2048
	v_lshlrev_b32_e32 v36, 16, v90
	v_and_b32_e32 v37, 0xffff0000, v90
	v_lshlrev_b32_e32 v32, 16, v91
	v_and_b32_e32 v33, 0xffff0000, v91
	v_pk_fma_f32 v[14:15], v[168:169], v[32:33], v[14:15] op_sel:[1,0,0] op_sel_hi:[1,1,1] neg_lo:[1,0,0] neg_hi:[1,0,0]
	v_pk_fma_f32 v[12:13], v[168:169], v[36:37], v[12:13] op_sel:[1,0,0] op_sel_hi:[1,1,1] neg_lo:[1,0,0] neg_hi:[1,0,0]
	s_waitcnt vmcnt(31)
	v_lshlrev_b32_e32 v36, 16, v94
	v_and_b32_e32 v37, 0xffff0000, v94
	v_lshlrev_b32_e32 v32, 16, v95
	v_and_b32_e32 v33, 0xffff0000, v95
	v_pk_fma_f32 v[14:15], v[170:171], v[32:33], v[14:15] op_sel:[1,0,0] op_sel_hi:[1,1,1]
	v_pk_fma_f32 v[12:13], v[170:171], v[36:37], v[12:13] op_sel:[1,0,0] op_sel_hi:[1,1,1]
	s_add_i32 s26, s23, 15
	s_max_i32 s26, s26, s16
	s_add_i32 s27, s23, 17
	s_min_i32 s27, s27, s17
	s_sub_i32 s26, s27, s26
	v_cvt_f32_i32_e32 v35, s26
	v_lshlrev_b32_e32 v44, 16, v94
	v_div_scale_f32 v16, s[10:11], v35, v35, 1.0
	v_rcp_f32_e32 v17, v16
	v_div_scale_f32 v38, vcc, 1.0, v35, 1.0
	v_fma_f32 v39, -v16, v17, 1.0
	v_fmac_f32_e32 v17, v39, v17
	v_mul_f32_e32 v39, v38, v17
	v_fma_f32 v43, -v16, v39, v38
	v_fmac_f32_e32 v39, v43, v17
	v_fma_f32 v16, -v16, v39, v38
	v_and_b32_e32 v45, 0xffff0000, v94
	v_lshlrev_b32_e32 v46, 16, v95
	v_div_fmas_f32 v17, v16, v17, v39
	v_and_b32_e32 v47, 0xffff0000, v95
	v_div_fixup_f32 v38, v17, v35, 1.0
	v_pk_mul_f32 v[46:47], v[170:171], v[46:47] op_sel:[1,0] op_sel_hi:[1,1]
	v_pk_mul_f32 v[44:45], v[170:171], v[44:45] op_sel:[1,0] op_sel_hi:[1,1]
	v_pk_fma_f32 v[44:45], v[38:39], v[12:13], v[44:45] op_sel_hi:[0,1,1] neg_lo:[0,0,1] neg_hi:[0,0,1]
	v_pk_fma_f32 v[46:47], v[38:39], v[14:15], v[46:47] op_sel_hi:[0,1,1] neg_lo:[0,0,1] neg_hi:[0,0,1]
	v_pk_mul_f32 v[44:45], v[52:53], v[44:45]
	v_pk_mul_f32 v[46:47], v[54:55], v[46:47]
	v_cvt_pk_bf16_f32 v48, v44, v45
	v_cvt_pk_bf16_f32 v49, v46, v47
	s_add_u32 s46, s28, 32768
	s_addc_u32 s47, s29, 0
	global_store_dwordx2 v41, v[48:49], s[46:47]
	v_lshlrev_b32_e32 v36, 16, v92
	v_and_b32_e32 v37, 0xffff0000, v92
	v_lshlrev_b32_e32 v32, 16, v93
	v_and_b32_e32 v33, 0xffff0000, v93
	v_pk_fma_f32 v[14:15], v[170:171], v[32:33], v[14:15] op_sel_hi:[0,1,1] neg_lo:[1,0,0] neg_hi:[1,0,0]
	v_pk_fma_f32 v[12:13], v[170:171], v[36:37], v[12:13] op_sel_hi:[0,1,1] neg_lo:[1,0,0] neg_hi:[1,0,0]
	s_waitcnt vmcnt(31)
; __device__ __forceinline__ unsigned pk2(float lo, float hi) { unsigned r; asm volatile("v_cvt_pk_bf16_f32 %0, %1, %2" : "=v"(r) : "v"(lo), "v"(hi)); return r; }
; __device__ __forceinline__ unsigned pk2(float lo, float hi) { return f2bf(lo) | (f2bf(hi) << 16); }
; #define LDX(tok) ({ const u32x2 _q = *(const u32x2*)(xb + (size_t)(tok) * D + cq * 4); (f32x4){bf_lo(_q.x), bf_hi(_q.x), bf_lo(_q.y), bf_hi(_q.y)} * rs[(tok) - t0 + 8]; })
; __global__ void __launch_bounds__(512, 2) fwd_megakernel(Params Pk) {
;     ...
;             for (int t = ta; t < ta + 32; ++t) {
;                 const int sin_ = t + hw - 1; if (sin_ < send) S += LDX(sin_);
;                 const int wl = (t - hw) > sbeg ? (t - hw) : sbeg, wh = (t + hw) < send ? (t + hw) : send; const float inv = 1.0f / (float)(wh - wl);
;                 const f32x4 xt = LDX(t);
;                 const f32x4 pv = (S * inv - xt) * gv;
;                 u32x2 w; w.x = pk2(pv[0], pv[1]); w.y = pk2(pv[2], pv[3]); *(u32x2*)(pbuf + (size_t)t * D + cq * 4) = w;
;                 const int sout = t - hw; if (sout >= sbeg) S -= LDX(sout);
;             }
	v_lshlrev_b32_e32 v36, 16, v96
	v_and_b32_e32 v37, 0xffff0000, v96
	v_lshlrev_b32_e32 v32, 16, v97
	v_and_b32_e32 v33, 0xffff0000, v97
	v_pk_fma_f32 v[14:15], v[172:173], v[32:33], v[14:15] op_sel_hi:[0,1,1]
	v_pk_fma_f32 v[12:13], v[172:173], v[36:37], v[12:13] op_sel_hi:[0,1,1]
	s_add_i32 s26, s23, 16
	s_max_i32 s26, s26, s16
	s_add_i32 s27, s23, 18
	s_min_i32 s27, s27, s17
	s_sub_i32 s26, s27, s26
	v_cvt_f32_i32_e32 v35, s26
	v_lshlrev_b32_e32 v44, 16, v96
	v_div_scale_f32 v16, s[10:11], v35, v35, 1.0
	v_rcp_f32_e32 v17, v16
	v_div_scale_f32 v38, vcc, 1.0, v35, 1.0
	v_fma_f32 v39, -v16, v17, 1.0
	v_fmac_f32_e32 v17, v39, v17
	v_mul_f32_e32 v39, v38, v17
	v_fma_f32 v43, -v16, v39, v38
	v_fmac_f32_e32 v39, v43, v17
	v_fma_f32 v16, -v16, v39, v38
	v_and_b32_e32 v45, 0xffff0000, v96
	v_lshlrev_b32_e32 v46, 16, v97
	v_div_fmas_f32 v17, v16, v17, v39
	v_and_b32_e32 v47, 0xffff0000, v97
	v_div_fixup_f32 v38, v17, v35, 1.0
	v_pk_mul_f32 v[46:47], v[172:173], v[46:47] op_sel_hi:[0,1]
	v_pk_mul_f32 v[44:45], v[172:173], v[44:45] op_sel_hi:[0,1]
	v_pk_fma_f32 v[44:45], v[38:39], v[12:13], v[44:45] op_sel_hi:[0,1,1] neg_lo:[0,0,1] neg_hi:[0,0,1]
	v_pk_fma_f32 v[46:47], v[38:39], v[14:15], v[46:47] op_sel_hi:[0,1,1] neg_lo:[0,0,1] neg_hi:[0,0,1]
	v_pk_mul_f32 v[44:45], v[52:53], v[44:45]
	v_pk_mul_f32 v[46:47], v[54:55], v[46:47]
	v_cvt_pk_bf16_f32 v50, v44, v45
	v_cvt_pk_bf16_f32 v51, v46, v47
	global_store_dwordx2 v41, v[50:51], s[46:47] offset:2048
	v_lshlrev_b32_e32 v36, 16, v94
	v_and_b32_e32 v37, 0xffff0000, v94
	v_lshlrev_b32_e32 v32, 16, v95
	v_and_b32_e32 v33, 0xffff0000, v95
	v_pk_fma_f32 v[14:15], v[170:171], v[32:33], v[14:15] op_sel:[1,0,0] op_sel_hi:[1,1,1] neg_lo:[1,0,0] neg_hi:[1,0,0]
	v_pk_fma_f32 v[12:13], v[170:171], v[36:37], v[12:13] op_sel:[1,0,0] op_sel_hi:[1,1,1] neg_lo:[1,0,0] neg_hi:[1,0,0]
	s_waitcnt vmcnt(31)
	v_lshlrev_b32_e32 v36, 16, v98
	v_and_b32_e32 v37, 0xffff0000, v98
	v_lshlrev_b32_e32 v32, 16, v99
	v_and_b32_e32 v33, 0xffff0000, v99
	v_pk_fma_f32 v[14:15], v[172:173], v[32:33], v[14:15] op_sel:[1,0,0] op_sel_hi:[1,1,1]
	v_pk_fma_f32 v[12:13], v[172:173], v[36:37], v[12:13] op_sel:[1,0,0] op_sel_hi:[1,1,1]
	s_add_i32 s26, s23, 17
	s_max_i32 s26, s26, s16
	s_add_i32 s27, s23, 19
	s_min_i32 s27, s27, s17
	s_sub_i32 s26, s27, s26
	v_cvt_f32_i32_e32 v35, s26
	v_lshlrev_b32_e32 v44, 16, v98
	v_div_scale_f32 v16, s[10:11], v35, v35, 1.0
	v_rcp_f32_e32 v17, v16
	v_div_scale_f32 v38, vcc, 1.0, v35, 1.0
	v_fma_f32 v39, -v16, v17, 1.0
	v_fmac_f32_e32 v17, v39, v17
	v_mul_f32_e32 v39, v38, v17
	v_fma_f32 v43, -v16, v39, v38
	v_fmac_f32_e32 v39, v43, v17
	v_fma_f32 v16, -v16, v39, v38
	v_and_b32_e32 v45, 0xffff0000, v98
	v_lshlrev_b32_e32 v46, 16, v99
	v_div_fmas_f32 v17, v16, v17, v39
	v_and_b32_e32 v47, 0xffff0000, v99
	v_div_fixup_f32 v38, v17, v35, 1.0
	v_pk_mul_f32 v[46:47], v[172:173], v[46:47] op_sel:[1,0] op_sel_hi:[1,1]
	v_pk_mul_f32 v[44:45], v[172:173], v[44:45] op_sel:[1,0] op_sel_hi:[1,1]
	v_pk_fma_f32 v[44:45], v[38:39], v[12:13], v[44:45] op_sel_hi:[0,1,1] neg_lo:[0,0,1] neg_hi:[0,0,1]
	v_pk_fma_f32 v[46:47], v[38:39], v[14:15], v[46:47] op_sel_hi:[0,1,1] neg_lo:[0,0,1] neg_hi:[0,0,1]
	v_pk_mul_f32 v[44:45], v[52:53], v[44:45]
	v_pk_mul_f32 v[46:47], v[54:55], v[46:47]
	v_cvt_pk_bf16_f32 v48, v44, v45
	v_cvt_pk_bf16_f32 v49, v46, v47
	s_add_u32 s48, s28, 36864
	s_addc_u32 s49, s29, 0
	global_store_dwordx2 v41, v[48:49], s[48:49]
	v_lshlrev_b32_e32 v36, 16, v96
	v_and_b32_e32 v37, 0xffff0000, v96
	v_lshlrev_b32_e32 v32, 16, v97
	v_and_b32_e32 v33, 0xffff0000, v97
	v_pk_fma_f32 v[14:15], v[172:173], v[32:33], v[14:15] op_sel_hi:[0,1,1] neg_lo:[1,0,0] neg_hi:[1,0,0]
	v_pk_fma_f32 v[12:13], v[172:173], v[36:37], v[12:13] op_sel_hi:[0,1,1] neg_lo:[1,0,0] neg_hi:[1,0,0]
	s_waitcnt vmcnt(31)
	v_lshlrev_b32_e32 v36, 16, v100
	v_and_b32_e32 v37, 0xffff0000, v100
	v_lshlrev_b32_e32 v32, 16, v101
	v_and_b32_e32 v33, 0xffff0000, v101
	v_pk_fma_f32 v[14:15], v[174:175], v[32:33], v[14:15] op_sel_hi:[0,1,1]
	v_pk_fma_f32 v[12:13], v[174:175], v[36:37], v[12:13] op_sel_hi:[0,1,1]
	s_add_i32 s26, s23, 18
	s_max_i32 s26, s26, s16
	s_add_i32 s27, s23, 20
	s_min_i32 s27, s27, s17
	s_sub_i32 s26, s27, s26
	v_cvt_f32_i32_e32 v35, s26
	v_lshlrev_b32_e32 v44, 16, v100
	v_div_scale_f32 v16, s[10:11], v35, v35, 1.0
	v_rcp_f32_e32 v17, v16
	v_div_scale_f32 v38, vcc, 1.0, v35, 1.0
	v_fma_f32 v39, -v16, v17, 1.0
	v_fmac_f32_e32 v17, v39, v17
	v_mul_f32_e32 v39, v38, v17
	v_fma_f32 v43, -v16, v39, v38
	v_fmac_f32_e32 v39, v43, v17
	v_fma_f32 v16, -v16, v39, v38
	v_and_b32_e32 v45, 0xffff0000, v100
	v_lshlrev_b32_e32 v46, 16, v101
	v_div_fmas_f32 v17, v16, v17, v39
	v_and_b32_e32 v47, 0xffff0000, v101
	v_div_fixup_f32 v38, v17, v35, 1.0
	v_pk_mul_f32 v[46:47], v[174:175], v[46:47] op_sel_hi:[0,1]
	v_pk_mul_f32 v[44:45], v[174:175], v[44:45] op_sel_hi:[0,1]
	v_pk_fma_f32 v[44:45], v[38:39], v[12:13], v[44:45] op_sel_hi:[0,1,1] neg_lo:[0,0,1] neg_hi:[0,0,1]
	v_pk_fma_f32 v[46:47], v[38:39], v[14:15], v[46:47] op_sel_hi:[0,1,1] neg_lo:[0,0,1] neg_hi:[0,0,1]
	v_pk_mul_f32 v[44:45], v[52:53], v[44:45]
	v_pk_mul_f32 v[46:47], v[54:55], v[46:47]
	v_cvt_pk_bf16_f32 v50, v44, v45
	v_cvt_pk_bf16_f32 v51, v46, v47
	global_store_dwordx2 v41, v[50:51], s[48:49] offset:2048
	v_lshlrev_b32_e32 v36, 16, v98
	v_and_b32_e32 v37, 0xffff0000, v98
	v_lshlrev_b32_e32 v32, 16, v99
	v_and_b32_e32 v33, 0xffff0000, v99
	v_pk_fma_f32 v[14:15], v[172:173], v[32:33], v[14:15] op_sel:[1,0,0] op_sel_hi:[1,1,1] neg_lo:[1,0,0] neg_hi:[1,0,0]
	v_pk_fma_f32 v[12:13], v[172:173], v[36:37], v[12:13] op_sel:[1,0,0] op_sel_hi:[1,1,1] neg_lo:[1,0,0] neg_hi:[1,0,0]
	s_waitcnt vmcnt(31)
; __device__ __forceinline__ unsigned pk2(float lo, float hi) { unsigned r; asm volatile("v_cvt_pk_bf16_f32 %0, %1, %2" : "=v"(r) : "v"(lo), "v"(hi)); return r; }
; __device__ __forceinline__ unsigned pk2(float lo, float hi) { return f2bf(lo) | (f2bf(hi) << 16); }
; #define LDX(tok) ({ const u32x2 _q = *(const u32x2*)(xb + (size_t)(tok) * D + cq * 4); (f32x4){bf_lo(_q.x), bf_hi(_q.x), bf_lo(_q.y), bf_hi(_q.y)} * rs[(tok) - t0 + 8]; })
; __global__ void __launch_bounds__(512, 2) fwd_megakernel(Params Pk) {
;     ...
;             for (int t = ta; t < ta + 32; ++t) {
;                 const int sin_ = t + hw - 1; if (sin_ < send) S += LDX(sin_);
;                 const int wl = (t - hw) > sbeg ? (t - hw) : sbeg, wh = (t + hw) < send ? (t + hw) : send; const float inv = 1.0f / (float)(wh - wl);
;                 const f32x4 xt = LDX(t);
;                 const f32x4 pv = (S * inv - xt) * gv;
;                 u32x2 w; w.x = pk2(pv[0], pv[1]); w.y = pk2(pv[2], pv[3]); *(u32x2*)(pbuf + (size_t)t * D + cq * 4) = w;
;                 const int sout = t - hw; if (sout >= sbeg) S -= LDX(sout);
;             }
	v_lshlrev_b32_e32 v36, 16, v102
	v_and_b32_e32 v37, 0xffff0000, v102
	v_lshlrev_b32_e32 v32, 16, v103
	v_and_b32_e32 v33, 0xffff0000, v103
	v_pk_fma_f32 v[14:15], v[174:175], v[32:33], v[14:15] op_sel:[1,0,0] op_sel_hi:[1,1,1]
	v_pk_fma_f32 v[12:13], v[174:175], v[36:37], v[12:13] op_sel:[1,0,0] op_sel_hi:[1,1,1]
	s_add_i32 s26, s23, 19
	s_max_i32 s26, s26, s16
	s_add_i32 s27, s23, 21
	s_min_i32 s27, s27, s17
	s_sub_i32 s26, s27, s26
	v_cvt_f32_i32_e32 v35, s26
	v_lshlrev_b32_e32 v44, 16, v102
	v_div_scale_f32 v16, s[10:11], v35, v35, 1.0
	v_rcp_f32_e32 v17, v16
	v_div_scale_f32 v38, vcc, 1.0, v35, 1.0
	v_fma_f32 v39, -v16, v17, 1.0
	v_fmac_f32_e32 v17, v39, v17
	v_mul_f32_e32 v39, v38, v17
	v_fma_f32 v43, -v16, v39, v38
	v_fmac_f32_e32 v39, v43, v17
	v_fma_f32 v16, -v16, v39, v38
	v_and_b32_e32 v45, 0xffff0000, v102
	v_lshlrev_b32_e32 v46, 16, v103
	v_div_fmas_f32 v17, v16, v17, v39
	v_and_b32_e32 v47, 0xffff0000, v103
	v_div_fixup_f32 v38, v17, v35, 1.0
	v_pk_mul_f32 v[46:47], v[174:175], v[46:47] op_sel:[1,0] op_sel_hi:[1,1]
	v_pk_mul_f32 v[44:45], v[174:175], v[44:45] op_sel:[1,0] op_sel_hi:[1,1]
	v_pk_fma_f32 v[44:45], v[38:39], v[12:13], v[44:45] op_sel_hi:[0,1,1] neg_lo:[0,0,1] neg_hi:[0,0,1]
	v_pk_fma_f32 v[46:47], v[38:39], v[14:15], v[46:47] op_sel_hi:[0,1,1] neg_lo:[0,0,1] neg_hi:[0,0,1]
	v_pk_mul_f32 v[44:45], v[52:53], v[44:45]
	v_pk_mul_f32 v[46:47], v[54:55], v[46:47]
	v_cvt_pk_bf16_f32 v48, v44, v45
	v_cvt_pk_bf16_f32 v49, v46, v47
	s_add_u32 s50, s28, 40960
	s_addc_u32 s51, s29, 0
	global_store_dwordx2 v41, v[48:49], s[50:51]
	v_lshlrev_b32_e32 v36, 16, v100
	v_and_b32_e32 v37, 0xffff0000, v100
	v_lshlrev_b32_e32 v32, 16, v101
	v_and_b32_e32 v33, 0xffff0000, v101
	v_pk_fma_f32 v[14:15], v[174:175], v[32:33], v[14:15] op_sel_hi:[0,1,1] neg_lo:[1,0,0] neg_hi:[1,0,0]
	v_pk_fma_f32 v[12:13], v[174:175], v[36:37], v[12:13] op_sel_hi:[0,1,1] neg_lo:[1,0,0] neg_hi:[1,0,0]
	s_waitcnt vmcnt(31)
	v_lshlrev_b32_e32 v36, 16, v104
	v_and_b32_e32 v37, 0xffff0000, v104
	v_lshlrev_b32_e32 v32, 16, v105
	v_and_b32_e32 v33, 0xffff0000, v105
	v_pk_fma_f32 v[14:15], v[176:177], v[32:33], v[14:15] op_sel_hi:[0,1,1]
	v_pk_fma_f32 v[12:13], v[176:177], v[36:37], v[12:13] op_sel_hi:[0,1,1]
	s_add_i32 s26, s23, 20
	s_max_i32 s26, s26, s16
	s_add_i32 s27, s23, 22
	s_min_i32 s27, s27, s17
	s_sub_i32 s26, s27, s26
	v_cvt_f32_i32_e32 v35, s26
	v_lshlrev_b32_e32 v44, 16, v104
	v_div_scale_f32 v16, s[10:11], v35, v35, 1.0
	v_rcp_f32_e32 v17, v16
	v_div_scale_f32 v38, vcc, 1.0, v35, 1.0
	v_fma_f32 v39, -v16, v17, 1.0
	v_fmac_f32_e32 v17, v39, v17
	v_mul_f32_e32 v39, v38, v17
	v_fma_f32 v43, -v16, v39, v38
	v_fmac_f32_e32 v39, v43, v17
	v_fma_f32 v16, -v16, v39, v38
	v_and_b32_e32 v45, 0xffff0000, v104
	v_lshlrev_b32_e32 v46, 16, v105
	v_div_fmas_f32 v17, v16, v17, v39
	v_and_b32_e32 v47, 0xffff0000, v105
	v_div_fixup_f32 v38, v17, v35, 1.0
	v_pk_mul_f32 v[46:47], v[176:177], v[46:47] op_sel_hi:[0,1]
	v_pk_mul_f32 v[44:45], v[176:177], v[44:45] op_sel_hi:[0,1]
	v_pk_fma_f32 v[44:45], v[38:39], v[12:13], v[44:45] op_sel_hi:[0,1,1] neg_lo:[0,0,1] neg_hi:[0,0,1]
	v_pk_fma_f32 v[46:47], v[38:39], v[14:15], v[46:47] op_sel_hi:[0,1,1] neg_lo:[0,0,1] neg_hi:[0,0,1]
	v_pk_mul_f32 v[44:45], v[52:53], v[44:45]
	v_pk_mul_f32 v[46:47], v[54:55], v[46:47]
	v_cvt_pk_bf16_f32 v50, v44, v45
	v_cvt_pk_bf16_f32 v51, v46, v47
	global_store_dwordx2 v41, v[50:51], s[50:51] offset:2048
	v_lshlrev_b32_e32 v36, 16, v102
	v_and_b32_e32 v37, 0xffff0000, v102
	v_lshlrev_b32_e32 v32, 16, v103
	v_and_b32_e32 v33, 0xffff0000, v103
	v_pk_fma_f32 v[14:15], v[174:175], v[32:33], v[14:15] op_sel:[1,0,0] op_sel_hi:[1,1,1] neg_lo:[1,0,0] neg_hi:[1,0,0]
	v_pk_fma_f32 v[12:13], v[174:175], v[36:37], v[12:13] op_sel:[1,0,0] op_sel_hi:[1,1,1] neg_lo:[1,0,0] neg_hi:[1,0,0]
	s_waitcnt vmcnt(31)
	v_lshlrev_b32_e32 v36, 16, v106
	v_and_b32_e32 v37, 0xffff0000, v106
	v_lshlrev_b32_e32 v32, 16, v107
	v_and_b32_e32 v33, 0xffff0000, v107
	v_pk_fma_f32 v[14:15], v[176:177], v[32:33], v[14:15] op_sel:[1,0,0] op_sel_hi:[1,1,1]
	v_pk_fma_f32 v[12:13], v[176:177], v[36:37], v[12:13] op_sel:[1,0,0] op_sel_hi:[1,1,1]
	s_add_i32 s26, s23, 21
	s_max_i32 s26, s26, s16
	s_add_i32 s27, s23, 23
	s_min_i32 s27, s27, s17
	s_sub_i32 s26, s27, s26
	v_cvt_f32_i32_e32 v35, s26
	v_lshlrev_b32_e32 v44, 16, v106
	v_div_scale_f32 v16, s[10:11], v35, v35, 1.0
	v_rcp_f32_e32 v17, v16
	v_div_scale_f32 v38, vcc, 1.0, v35, 1.0
	v_fma_f32 v39, -v16, v17, 1.0
	v_fmac_f32_e32 v17, v39, v17
	v_mul_f32_e32 v39, v38, v17
	v_fma_f32 v43, -v16, v39, v38
	v_fmac_f32_e32 v39, v43, v17
	v_fma_f32 v16, -v16, v39, v38
	v_and_b32_e32 v45, 0xffff0000, v106
	v_lshlrev_b32_e32 v46, 16, v107
	v_div_fmas_f32 v17, v16, v17, v39
	v_and_b32_e32 v47, 0xffff0000, v107
	v_div_fixup_f32 v38, v17, v35, 1.0
	v_pk_mul_f32 v[46:47], v[176:177], v[46:47] op_sel:[1,0] op_sel_hi:[1,1]
	v_pk_mul_f32 v[44:45], v[176:177], v[44:45] op_sel:[1,0] op_sel_hi:[1,1]
	v_pk_fma_f32 v[44:45], v[38:39], v[12:13], v[44:45] op_sel_hi:[0,1,1] neg_lo:[0,0,1] neg_hi:[0,0,1]
	v_pk_fma_f32 v[46:47], v[38:39], v[14:15], v[46:47] op_sel_hi:[0,1,1] neg_lo:[0,0,1] neg_hi:[0,0,1]
	v_pk_mul_f32 v[44:45], v[52:53], v[44:45]
	v_pk_mul_f32 v[46:47], v[54:55], v[46:47]
	v_cvt_pk_bf16_f32 v48, v44, v45
	v_cvt_pk_bf16_f32 v49, v46, v47
	s_add_u32 s52, s28, 45056
	s_addc_u32 s53, s29, 0
	global_store_dwordx2 v41, v[48:49], s[52:53]
	v_lshlrev_b32_e32 v36, 16, v104
	v_and_b32_e32 v37, 0xffff0000, v104
	v_lshlrev_b32_e32 v32, 16, v105
	v_and_b32_e32 v33, 0xffff0000, v105
	v_pk_fma_f32 v[14:15], v[176:177], v[32:33], v[14:15] op_sel_hi:[0,1,1] neg_lo:[1,0,0] neg_hi:[1,0,0]
	v_pk_fma_f32 v[12:13], v[176:177], v[36:37], v[12:13] op_sel_hi:[0,1,1] neg_lo:[1,0,0] neg_hi:[1,0,0]
	s_waitcnt vmcnt(31)
; __device__ __forceinline__ unsigned pk2(float lo, float hi) { unsigned r; asm volatile("v_cvt_pk_bf16_f32 %0, %1, %2" : "=v"(r) : "v"(lo), "v"(hi)); return r; }
; __device__ __forceinline__ unsigned pk2(float lo, float hi) { return f2bf(lo) | (f2bf(hi) << 16); }
; #define LDX(tok) ({ const u32x2 _q = *(const u32x2*)(xb + (size_t)(tok) * D + cq * 4); (f32x4){bf_lo(_q.x), bf_hi(_q.x), bf_lo(_q.y), bf_hi(_q.y)} * rs[(tok) - t0 + 8]; })
; __global__ void __launch_bounds__(512, 2) fwd_megakernel(Params Pk) {
;     ...
;             for (int t = ta; t < ta + 32; ++t) {
;                 const int sin_ = t + hw - 1; if (sin_ < send) S += LDX(sin_);
;                 const int wl = (t - hw) > sbeg ? (t - hw) : sbeg, wh = (t + hw) < send ? (t + hw) : send; const float inv = 1.0f / (float)(wh - wl);
;                 const f32x4 xt = LDX(t);
;                 const f32x4 pv = (S * inv - xt) * gv;
;                 u32x2 w; w.x = pk2(pv[0], pv[1]); w.y = pk2(pv[2], pv[3]); *(u32x2*)(pbuf + (size_t)t * D + cq * 4) = w;
;                 const int sout = t - hw; if (sout >= sbeg) S -= LDX(sout);
;             }
	v_lshlrev_b32_e32 v36, 16, v108
	v_and_b32_e32 v37, 0xffff0000, v108
	v_lshlrev_b32_e32 v32, 16, v109
	v_and_b32_e32 v33, 0xffff0000, v109
	v_pk_fma_f32 v[14:15], v[178:179], v[32:33], v[14:15] op_sel_hi:[0,1,1]
	v_pk_fma_f32 v[12:13], v[178:179], v[36:37], v[12:13] op_sel_hi:[0,1,1]
	s_add_i32 s26, s23, 22
	s_max_i32 s26, s26, s16
	s_add_i32 s27, s23, 24
	s_min_i32 s27, s27, s17
	s_sub_i32 s26, s27, s26
	v_cvt_f32_i32_e32 v35, s26
	v_lshlrev_b32_e32 v44, 16, v108
	v_div_scale_f32 v16, s[10:11], v35, v35, 1.0
	v_rcp_f32_e32 v17, v16
	v_div_scale_f32 v38, vcc, 1.0, v35, 1.0
	v_fma_f32 v39, -v16, v17, 1.0
	v_fmac_f32_e32 v17, v39, v17
	v_mul_f32_e32 v39, v38, v17
	v_fma_f32 v43, -v16, v39, v38
	v_fmac_f32_e32 v39, v43, v17
	v_fma_f32 v16, -v16, v39, v38
	v_and_b32_e32 v45, 0xffff0000, v108
	v_lshlrev_b32_e32 v46, 16, v109
	v_div_fmas_f32 v17, v16, v17, v39
	v_and_b32_e32 v47, 0xffff0000, v109
	v_div_fixup_f32 v38, v17, v35, 1.0
	v_pk_mul_f32 v[46:47], v[178:179], v[46:47] op_sel_hi:[0,1]
	v_pk_mul_f32 v[44:45], v[178:179], v[44:45] op_sel_hi:[0,1]
	v_pk_fma_f32 v[44:45], v[38:39], v[12:13], v[44:45] op_sel_hi:[0,1,1] neg_lo:[0,0,1] neg_hi:[0,0,1]
	v_pk_fma_f32 v[46:47], v[38:39], v[14:15], v[46:47] op_sel_hi:[0,1,1] neg_lo:[0,0,1] neg_hi:[0,0,1]
	v_pk_mul_f32 v[44:45], v[52:53], v[44:45]
	v_pk_mul_f32 v[46:47], v[54:55], v[46:47]
	v_cvt_pk_bf16_f32 v50, v44, v45
	v_cvt_pk_bf16_f32 v51, v46, v47
	global_store_dwordx2 v41, v[50:51], s[52:53] offset:2048
	v_lshlrev_b32_e32 v36, 16, v106
	v_and_b32_e32 v37, 0xffff0000, v106
	v_lshlrev_b32_e32 v32, 16, v107
	v_and_b32_e32 v33, 0xffff0000, v107
	v_pk_fma_f32 v[14:15], v[176:177], v[32:33], v[14:15] op_sel:[1,0,0] op_sel_hi:[1,1,1] neg_lo:[1,0,0] neg_hi:[1,0,0]
	v_pk_fma_f32 v[12:13], v[176:177], v[36:37], v[12:13] op_sel:[1,0,0] op_sel_hi:[1,1,1] neg_lo:[1,0,0] neg_hi:[1,0,0]
	s_waitcnt vmcnt(31)
	v_lshlrev_b32_e32 v36, 16, v110
	v_and_b32_e32 v37, 0xffff0000, v110
	v_lshlrev_b32_e32 v32, 16, v111
	v_and_b32_e32 v33, 0xffff0000, v111
	v_pk_fma_f32 v[14:15], v[178:179], v[32:33], v[14:15] op_sel:[1,0,0] op_sel_hi:[1,1,1]
	v_pk_fma_f32 v[12:13], v[178:179], v[36:37], v[12:13] op_sel:[1,0,0] op_sel_hi:[1,1,1]
	s_add_i32 s26, s23, 23
	s_max_i32 s26, s26, s16
	s_add_i32 s27, s23, 25
	s_min_i32 s27, s27, s17
	s_sub_i32 s26, s27, s26
	v_cvt_f32_i32_e32 v35, s26
	v_lshlrev_b32_e32 v44, 16, v110
	v_div_scale_f32 v16, s[10:11], v35, v35, 1.0
	v_rcp_f32_e32 v17, v16
	v_div_scale_f32 v38, vcc, 1.0, v35, 1.0
	v_fma_f32 v39, -v16, v17, 1.0
	v_fmac_f32_e32 v17, v39, v17
	v_mul_f32_e32 v39, v38, v17
	v_fma_f32 v43, -v16, v39, v38
	v_fmac_f32_e32 v39, v43, v17
	v_fma_f32 v16, -v16, v39, v38
	v_and_b32_e32 v45, 0xffff0000, v110
	v_lshlrev_b32_e32 v46, 16, v111
	v_div_fmas_f32 v17, v16, v17, v39
	v_and_b32_e32 v47, 0xffff0000, v111
	v_div_fixup_f32 v38, v17, v35, 1.0
	v_pk_mul_f32 v[46:47], v[178:179], v[46:47] op_sel:[1,0] op_sel_hi:[1,1]
	v_pk_mul_f32 v[44:45], v[178:179], v[44:45] op_sel:[1,0] op_sel_hi:[1,1]
	v_pk_fma_f32 v[44:45], v[38:39], v[12:13], v[44:45] op_sel_hi:[0,1,1] neg_lo:[0,0,1] neg_hi:[0,0,1]
	v_pk_fma_f32 v[46:47], v[38:39], v[14:15], v[46:47] op_sel_hi:[0,1,1] neg_lo:[0,0,1] neg_hi:[0,0,1]
	v_pk_mul_f32 v[44:45], v[52:53], v[44:45]
	v_pk_mul_f32 v[46:47], v[54:55], v[46:47]
	v_cvt_pk_bf16_f32 v48, v44, v45
	v_cvt_pk_bf16_f32 v49, v46, v47
	s_add_u32 s46, s28, 49152
	s_addc_u32 s47, s29, 0
	global_store_dwordx2 v41, v[48:49], s[46:47]
	v_lshlrev_b32_e32 v36, 16, v108
	v_and_b32_e32 v37, 0xffff0000, v108
	v_lshlrev_b32_e32 v32, 16, v109
	v_and_b32_e32 v33, 0xffff0000, v109
	v_pk_fma_f32 v[14:15], v[178:179], v[32:33], v[14:15] op_sel_hi:[0,1,1] neg_lo:[1,0,0] neg_hi:[1,0,0]
	v_pk_fma_f32 v[12:13], v[178:179], v[36:37], v[12:13] op_sel_hi:[0,1,1] neg_lo:[1,0,0] neg_hi:[1,0,0]
	s_waitcnt vmcnt(31)
	v_lshlrev_b32_e32 v36, 16, v112
	v_and_b32_e32 v37, 0xffff0000, v112
	v_lshlrev_b32_e32 v32, 16, v113
	v_and_b32_e32 v33, 0xffff0000, v113
	v_pk_fma_f32 v[14:15], v[180:181], v[32:33], v[14:15] op_sel_hi:[0,1,1]
	v_pk_fma_f32 v[12:13], v[180:181], v[36:37], v[12:13] op_sel_hi:[0,1,1]
	s_add_i32 s26, s23, 24
	s_max_i32 s26, s26, s16
	s_add_i32 s27, s23, 26
	s_min_i32 s27, s27, s17
	s_sub_i32 s26, s27, s26
	v_cvt_f32_i32_e32 v35, s26
	v_lshlrev_b32_e32 v44, 16, v112
	v_div_scale_f32 v16, s[10:11], v35, v35, 1.0
	v_rcp_f32_e32 v17, v16
	v_div_scale_f32 v38, vcc, 1.0, v35, 1.0
	v_fma_f32 v39, -v16, v17, 1.0
	v_fmac_f32_e32 v17, v39, v17
	v_mul_f32_e32 v39, v38, v17
	v_fma_f32 v43, -v16, v39, v38
	v_fmac_f32_e32 v39, v43, v17
	v_fma_f32 v16, -v16, v39, v38
	v_and_b32_e32 v45, 0xffff0000, v112
	v_lshlrev_b32_e32 v46, 16, v113
	v_div_fmas_f32 v17, v16, v17, v39
	v_and_b32_e32 v47, 0xffff0000, v113
	v_div_fixup_f32 v38, v17, v35, 1.0
	v_pk_mul_f32 v[46:47], v[180:181], v[46:47] op_sel_hi:[0,1]
	v_pk_mul_f32 v[44:45], v[180:181], v[44:45] op_sel_hi:[0,1]
	v_pk_fma_f32 v[44:45], v[38:39], v[12:13], v[44:45] op_sel_hi:[0,1,1] neg_lo:[0,0,1] neg_hi:[0,0,1]
	v_pk_fma_f32 v[46:47], v[38:39], v[14:15], v[46:47] op_sel_hi:[0,1,1] neg_lo:[0,0,1] neg_hi:[0,0,1]
	v_pk_mul_f32 v[44:45], v[52:53], v[44:45]
	v_pk_mul_f32 v[46:47], v[54:55], v[46:47]
	v_cvt_pk_bf16_f32 v50, v44, v45
	v_cvt_pk_bf16_f32 v51, v46, v47
	global_store_dwordx2 v41, v[50:51], s[46:47] offset:2048
	v_lshlrev_b32_e32 v36, 16, v110
	v_and_b32_e32 v37, 0xffff0000, v110
	v_lshlrev_b32_e32 v32, 16, v111
	v_and_b32_e32 v33, 0xffff0000, v111
	v_pk_fma_f32 v[14:15], v[178:179], v[32:33], v[14:15] op_sel:[1,0,0] op_sel_hi:[1,1,1] neg_lo:[1,0,0] neg_hi:[1,0,0]
	v_pk_fma_f32 v[12:13], v[178:179], v[36:37], v[12:13] op_sel:[1,0,0] op_sel_hi:[1,1,1] neg_lo:[1,0,0] neg_hi:[1,0,0]
	s_waitcnt vmcnt(31)
; __device__ __forceinline__ unsigned pk2(float lo, float hi) { unsigned r; asm volatile("v_cvt_pk_bf16_f32 %0, %1, %2" : "=v"(r) : "v"(lo), "v"(hi)); return r; }
; __device__ __forceinline__ unsigned pk2(float lo, float hi) { return f2bf(lo) | (f2bf(hi) << 16); }
; #define LDX(tok) ({ const u32x2 _q = *(const u32x2*)(xb + (size_t)(tok) * D + cq * 4); (f32x4){bf_lo(_q.x), bf_hi(_q.x), bf_lo(_q.y), bf_hi(_q.y)} * rs[(tok) - t0 + 8]; })
; __global__ void __launch_bounds__(512, 2) fwd_megakernel(Params Pk) {
;     ...
;             for (int t = ta; t < ta + 32; ++t) {
;                 const int sin_ = t + hw - 1; if (sin_ < send) S += LDX(sin_);
;                 const int wl = (t - hw) > sbeg ? (t - hw) : sbeg, wh = (t + hw) < send ? (t + hw) : send; const float inv = 1.0f / (float)(wh - wl);
;                 const f32x4 xt = LDX(t);
;                 const f32x4 pv = (S * inv - xt) * gv;
;                 u32x2 w; w.x = pk2(pv[0], pv[1]); w.y = pk2(pv[2], pv[3]); *(u32x2*)(pbuf + (size_t)t * D + cq * 4) = w;
;                 const int sout = t - hw; if (sout >= sbeg) S -= LDX(sout);
;             }
	v_lshlrev_b32_e32 v36, 16, v114
	v_and_b32_e32 v37, 0xffff0000, v114
	v_lshlrev_b32_e32 v32, 16, v115
	v_and_b32_e32 v33, 0xffff0000, v115
	v_pk_fma_f32 v[14:15], v[180:181], v[32:33], v[14:15] op_sel:[1,0,0] op_sel_hi:[1,1,1]
	v_pk_fma_f32 v[12:13], v[180:181], v[36:37], v[12:13] op_sel:[1,0,0] op_sel_hi:[1,1,1]
	s_add_i32 s26, s23, 25
	s_max_i32 s26, s26, s16
	s_add_i32 s27, s23, 27
	s_min_i32 s27, s27, s17
	s_sub_i32 s26, s27, s26
	v_cvt_f32_i32_e32 v35, s26
	v_lshlrev_b32_e32 v44, 16, v114
	v_div_scale_f32 v16, s[10:11], v35, v35, 1.0
	v_rcp_f32_e32 v17, v16
	v_div_scale_f32 v38, vcc, 1.0, v35, 1.0
	v_fma_f32 v39, -v16, v17, 1.0
	v_fmac_f32_e32 v17, v39, v17
	v_mul_f32_e32 v39, v38, v17
	v_fma_f32 v43, -v16, v39, v38
	v_fmac_f32_e32 v39, v43, v17
	v_fma_f32 v16, -v16, v39, v38
	v_and_b32_e32 v45, 0xffff0000, v114
	v_lshlrev_b32_e32 v46, 16, v115
	v_div_fmas_f32 v17, v16, v17, v39
	v_and_b32_e32 v47, 0xffff0000, v115
	v_div_fixup_f32 v38, v17, v35, 1.0
	v_pk_mul_f32 v[46:47], v[180:181], v[46:47] op_sel:[1,0] op_sel_hi:[1,1]
	v_pk_mul_f32 v[44:45], v[180:181], v[44:45] op_sel:[1,0] op_sel_hi:[1,1]
	v_pk_fma_f32 v[44:45], v[38:39], v[12:13], v[44:45] op_sel_hi:[0,1,1] neg_lo:[0,0,1] neg_hi:[0,0,1]
	v_pk_fma_f32 v[46:47], v[38:39], v[14:15], v[46:47] op_sel_hi:[0,1,1] neg_lo:[0,0,1] neg_hi:[0,0,1]
	v_pk_mul_f32 v[44:45], v[52:53], v[44:45]
	v_pk_mul_f32 v[46:47], v[54:55], v[46:47]
	v_cvt_pk_bf16_f32 v48, v44, v45
	v_cvt_pk_bf16_f32 v49, v46, v47
	s_add_u32 s48, s28, 53248
	s_addc_u32 s49, s29, 0
	global_store_dwordx2 v41, v[48:49], s[48:49]
	v_lshlrev_b32_e32 v36, 16, v112
	v_and_b32_e32 v37, 0xffff0000, v112
	v_lshlrev_b32_e32 v32, 16, v113
	v_and_b32_e32 v33, 0xffff0000, v113
	v_pk_fma_f32 v[14:15], v[180:181], v[32:33], v[14:15] op_sel_hi:[0,1,1] neg_lo:[1,0,0] neg_hi:[1,0,0]
	v_pk_fma_f32 v[12:13], v[180:181], v[36:37], v[12:13] op_sel_hi:[0,1,1] neg_lo:[1,0,0] neg_hi:[1,0,0]
	s_waitcnt vmcnt(31)
	v_lshlrev_b32_e32 v36, 16, v116
	v_and_b32_e32 v37, 0xffff0000, v116
	v_lshlrev_b32_e32 v32, 16, v117
	v_and_b32_e32 v33, 0xffff0000, v117
	v_pk_fma_f32 v[14:15], v[182:183], v[32:33], v[14:15] op_sel_hi:[0,1,1]
	v_pk_fma_f32 v[12:13], v[182:183], v[36:37], v[12:13] op_sel_hi:[0,1,1]
	s_add_i32 s26, s23, 26
	s_max_i32 s26, s26, s16
	s_add_i32 s27, s23, 28
	s_min_i32 s27, s27, s17
	s_sub_i32 s26, s27, s26
	v_cvt_f32_i32_e32 v35, s26
	v_lshlrev_b32_e32 v44, 16, v116
	v_div_scale_f32 v16, s[10:11], v35, v35, 1.0
	v_rcp_f32_e32 v17, v16
	v_div_scale_f32 v38, vcc, 1.0, v35, 1.0
	v_fma_f32 v39, -v16, v17, 1.0
	v_fmac_f32_e32 v17, v39, v17
	v_mul_f32_e32 v39, v38, v17
	v_fma_f32 v43, -v16, v39, v38
	v_fmac_f32_e32 v39, v43, v17
	v_fma_f32 v16, -v16, v39, v38
	v_and_b32_e32 v45, 0xffff0000, v116
	v_lshlrev_b32_e32 v46, 16, v117
	v_div_fmas_f32 v17, v16, v17, v39
	v_and_b32_e32 v47, 0xffff0000, v117
	v_div_fixup_f32 v38, v17, v35, 1.0
	v_pk_mul_f32 v[46:47], v[182:183], v[46:47] op_sel_hi:[0,1]
	v_pk_mul_f32 v[44:45], v[182:183], v[44:45] op_sel_hi:[0,1]
	v_pk_fma_f32 v[44:45], v[38:39], v[12:13], v[44:45] op_sel_hi:[0,1,1] neg_lo:[0,0,1] neg_hi:[0,0,1]
	v_pk_fma_f32 v[46:47], v[38:39], v[14:15], v[46:47] op_sel_hi:[0,1,1] neg_lo:[0,0,1] neg_hi:[0,0,1]
	v_pk_mul_f32 v[44:45], v[52:53], v[44:45]
	v_pk_mul_f32 v[46:47], v[54:55], v[46:47]
	v_cvt_pk_bf16_f32 v50, v44, v45
	v_cvt_pk_bf16_f32 v51, v46, v47
	global_store_dwordx2 v41, v[50:51], s[48:49] offset:2048
	v_lshlrev_b32_e32 v36, 16, v114
	v_and_b32_e32 v37, 0xffff0000, v114
	v_lshlrev_b32_e32 v32, 16, v115
	v_and_b32_e32 v33, 0xffff0000, v115
	v_pk_fma_f32 v[14:15], v[180:181], v[32:33], v[14:15] op_sel:[1,0,0] op_sel_hi:[1,1,1] neg_lo:[1,0,0] neg_hi:[1,0,0]
	v_pk_fma_f32 v[12:13], v[180:181], v[36:37], v[12:13] op_sel:[1,0,0] op_sel_hi:[1,1,1] neg_lo:[1,0,0] neg_hi:[1,0,0]
	s_waitcnt vmcnt(31)
	v_lshlrev_b32_e32 v36, 16, v118
	v_and_b32_e32 v37, 0xffff0000, v118
	v_lshlrev_b32_e32 v32, 16, v119
	v_and_b32_e32 v33, 0xffff0000, v119
	v_pk_fma_f32 v[14:15], v[182:183], v[32:33], v[14:15] op_sel:[1,0,0] op_sel_hi:[1,1,1]
	v_pk_fma_f32 v[12:13], v[182:183], v[36:37], v[12:13] op_sel:[1,0,0] op_sel_hi:[1,1,1]
	s_add_i32 s26, s23, 27
	s_max_i32 s26, s26, s16
	s_add_i32 s27, s23, 29
	s_min_i32 s27, s27, s17
	s_sub_i32 s26, s27, s26
	v_cvt_f32_i32_e32 v35, s26
	v_lshlrev_b32_e32 v44, 16, v118
	v_div_scale_f32 v16, s[10:11], v35, v35, 1.0
	v_rcp_f32_e32 v17, v16
	v_div_scale_f32 v38, vcc, 1.0, v35, 1.0
	v_fma_f32 v39, -v16, v17, 1.0
	v_fmac_f32_e32 v17, v39, v17
	v_mul_f32_e32 v39, v38, v17
	v_fma_f32 v43, -v16, v39, v38
	v_fmac_f32_e32 v39, v43, v17
	v_fma_f32 v16, -v16, v39, v38
	v_and_b32_e32 v45, 0xffff0000, v118
	v_lshlrev_b32_e32 v46, 16, v119
	v_div_fmas_f32 v17, v16, v17, v39
	v_and_b32_e32 v47, 0xffff0000, v119
	v_div_fixup_f32 v38, v17, v35, 1.0
	v_pk_mul_f32 v[46:47], v[182:183], v[46:47] op_sel:[1,0] op_sel_hi:[1,1]
	v_pk_mul_f32 v[44:45], v[182:183], v[44:45] op_sel:[1,0] op_sel_hi:[1,1]
	v_pk_fma_f32 v[44:45], v[38:39], v[12:13], v[44:45] op_sel_hi:[0,1,1] neg_lo:[0,0,1] neg_hi:[0,0,1]
	v_pk_fma_f32 v[46:47], v[38:39], v[14:15], v[46:47] op_sel_hi:[0,1,1] neg_lo:[0,0,1] neg_hi:[0,0,1]
	v_pk_mul_f32 v[44:45], v[52:53], v[44:45]
	v_pk_mul_f32 v[46:47], v[54:55], v[46:47]
	v_cvt_pk_bf16_f32 v48, v44, v45
	v_cvt_pk_bf16_f32 v49, v46, v47
	s_add_u32 s50, s28, 57344
	s_addc_u32 s51, s29, 0
	global_store_dwordx2 v41, v[48:49], s[50:51]
	v_lshlrev_b32_e32 v36, 16, v116
	v_and_b32_e32 v37, 0xffff0000, v116
	v_lshlrev_b32_e32 v32, 16, v117
	v_and_b32_e32 v33, 0xffff0000, v117
	v_pk_fma_f32 v[14:15], v[182:183], v[32:33], v[14:15] op_sel_hi:[0,1,1] neg_lo:[1,0,0] neg_hi:[1,0,0]
	v_pk_fma_f32 v[12:13], v[182:183], v[36:37], v[12:13] op_sel_hi:[0,1,1] neg_lo:[1,0,0] neg_hi:[1,0,0]
	s_waitcnt vmcnt(31)
; __device__ __forceinline__ unsigned pk2(float lo, float hi) { unsigned r; asm volatile("v_cvt_pk_bf16_f32 %0, %1, %2" : "=v"(r) : "v"(lo), "v"(hi)); return r; }
; __device__ __forceinline__ unsigned pk2(float lo, float hi) { return f2bf(lo) | (f2bf(hi) << 16); }
; #define LDX(tok) ({ const u32x2 _q = *(const u32x2*)(xb + (size_t)(tok) * D + cq * 4); (f32x4){bf_lo(_q.x), bf_hi(_q.x), bf_lo(_q.y), bf_hi(_q.y)} * rs[(tok) - t0 + 8]; })
; __global__ void __launch_bounds__(512, 2) fwd_megakernel(Params Pk) {
;     ...
;             for (int t = ta; t < ta + 32; ++t) {
;                 const int sin_ = t + hw - 1; if (sin_ < send) S += LDX(sin_);
;                 const int wl = (t - hw) > sbeg ? (t - hw) : sbeg, wh = (t + hw) < send ? (t + hw) : send; const float inv = 1.0f / (float)(wh - wl);
;                 const f32x4 xt = LDX(t);
;                 const f32x4 pv = (S * inv - xt) * gv;
;                 u32x2 w; w.x = pk2(pv[0], pv[1]); w.y = pk2(pv[2], pv[3]); *(u32x2*)(pbuf + (size_t)t * D + cq * 4) = w;
;                 const int sout = t - hw; if (sout >= sbeg) S -= LDX(sout);
;             }
	v_lshlrev_b32_e32 v36, 16, v120
	v_and_b32_e32 v37, 0xffff0000, v120
	v_lshlrev_b32_e32 v32, 16, v121
	v_and_b32_e32 v33, 0xffff0000, v121
	v_pk_fma_f32 v[14:15], v[184:185], v[32:33], v[14:15] op_sel_hi:[0,1,1]
	v_pk_fma_f32 v[12:13], v[184:185], v[36:37], v[12:13] op_sel_hi:[0,1,1]
	s_add_i32 s26, s23, 28
	s_max_i32 s26, s26, s16
	s_add_i32 s27, s23, 30
	s_min_i32 s27, s27, s17
	s_sub_i32 s26, s27, s26
	v_cvt_f32_i32_e32 v35, s26
	v_lshlrev_b32_e32 v44, 16, v120
	v_div_scale_f32 v16, s[10:11], v35, v35, 1.0
	v_rcp_f32_e32 v17, v16
	v_div_scale_f32 v38, vcc, 1.0, v35, 1.0
	v_fma_f32 v39, -v16, v17, 1.0
	v_fmac_f32_e32 v17, v39, v17
	v_mul_f32_e32 v39, v38, v17
	v_fma_f32 v43, -v16, v39, v38
	v_fmac_f32_e32 v39, v43, v17
	v_fma_f32 v16, -v16, v39, v38
	v_and_b32_e32 v45, 0xffff0000, v120
	v_lshlrev_b32_e32 v46, 16, v121
	v_div_fmas_f32 v17, v16, v17, v39
	v_and_b32_e32 v47, 0xffff0000, v121
	v_div_fixup_f32 v38, v17, v35, 1.0
	v_pk_mul_f32 v[46:47], v[184:185], v[46:47] op_sel_hi:[0,1]
	v_pk_mul_f32 v[44:45], v[184:185], v[44:45] op_sel_hi:[0,1]
	v_pk_fma_f32 v[44:45], v[38:39], v[12:13], v[44:45] op_sel_hi:[0,1,1] neg_lo:[0,0,1] neg_hi:[0,0,1]
	v_pk_fma_f32 v[46:47], v[38:39], v[14:15], v[46:47] op_sel_hi:[0,1,1] neg_lo:[0,0,1] neg_hi:[0,0,1]
	v_pk_mul_f32 v[44:45], v[52:53], v[44:45]
	v_pk_mul_f32 v[46:47], v[54:55], v[46:47]
	v_cvt_pk_bf16_f32 v50, v44, v45
	v_cvt_pk_bf16_f32 v51, v46, v47
	global_store_dwordx2 v41, v[50:51], s[50:51] offset:2048
	v_lshlrev_b32_e32 v36, 16, v118
	v_and_b32_e32 v37, 0xffff0000, v118
	v_lshlrev_b32_e32 v32, 16, v119
	v_and_b32_e32 v33, 0xffff0000, v119
	v_pk_fma_f32 v[14:15], v[182:183], v[32:33], v[14:15] op_sel:[1,0,0] op_sel_hi:[1,1,1] neg_lo:[1,0,0] neg_hi:[1,0,0]
	v_pk_fma_f32 v[12:13], v[182:183], v[36:37], v[12:13] op_sel:[1,0,0] op_sel_hi:[1,1,1] neg_lo:[1,0,0] neg_hi:[1,0,0]
	s_waitcnt vmcnt(31)
	v_lshlrev_b32_e32 v36, 16, v122
	v_and_b32_e32 v37, 0xffff0000, v122
	v_lshlrev_b32_e32 v32, 16, v123
	v_and_b32_e32 v33, 0xffff0000, v123
	v_pk_fma_f32 v[14:15], v[184:185], v[32:33], v[14:15] op_sel:[1,0,0] op_sel_hi:[1,1,1]
	v_pk_fma_f32 v[12:13], v[184:185], v[36:37], v[12:13] op_sel:[1,0,0] op_sel_hi:[1,1,1]
	s_add_i32 s26, s23, 29
	s_max_i32 s26, s26, s16
	s_add_i32 s27, s23, 31
	s_min_i32 s27, s27, s17
	s_sub_i32 s26, s27, s26
	v_cvt_f32_i32_e32 v35, s26
	v_lshlrev_b32_e32 v44, 16, v122
	v_div_scale_f32 v16, s[10:11], v35, v35, 1.0
	v_rcp_f32_e32 v17, v16
	v_div_scale_f32 v38, vcc, 1.0, v35, 1.0
	v_fma_f32 v39, -v16, v17, 1.0
	v_fmac_f32_e32 v17, v39, v17
	v_mul_f32_e32 v39, v38, v17
	v_fma_f32 v43, -v16, v39, v38
	v_fmac_f32_e32 v39, v43, v17
	v_fma_f32 v16, -v16, v39, v38
	v_and_b32_e32 v45, 0xffff0000, v122
	v_lshlrev_b32_e32 v46, 16, v123
	v_div_fmas_f32 v17, v16, v17, v39
	v_and_b32_e32 v47, 0xffff0000, v123
	v_div_fixup_f32 v38, v17, v35, 1.0
	v_pk_mul_f32 v[46:47], v[184:185], v[46:47] op_sel:[1,0] op_sel_hi:[1,1]
	v_pk_mul_f32 v[44:45], v[184:185], v[44:45] op_sel:[1,0] op_sel_hi:[1,1]
	v_pk_fma_f32 v[44:45], v[38:39], v[12:13], v[44:45] op_sel_hi:[0,1,1] neg_lo:[0,0,1] neg_hi:[0,0,1]
	v_pk_fma_f32 v[46:47], v[38:39], v[14:15], v[46:47] op_sel_hi:[0,1,1] neg_lo:[0,0,1] neg_hi:[0,0,1]
	v_pk_mul_f32 v[44:45], v[52:53], v[44:45]
	v_pk_mul_f32 v[46:47], v[54:55], v[46:47]
	v_cvt_pk_bf16_f32 v48, v44, v45
	v_cvt_pk_bf16_f32 v49, v46, v47
	s_add_u32 s52, s28, 61440
	s_addc_u32 s53, s29, 0
	global_store_dwordx2 v41, v[48:49], s[52:53]
	v_lshlrev_b32_e32 v36, 16, v120
	v_and_b32_e32 v37, 0xffff0000, v120
	v_lshlrev_b32_e32 v32, 16, v121
	v_and_b32_e32 v33, 0xffff0000, v121
	v_pk_fma_f32 v[14:15], v[184:185], v[32:33], v[14:15] op_sel_hi:[0,1,1] neg_lo:[1,0,0] neg_hi:[1,0,0]
	v_pk_fma_f32 v[12:13], v[184:185], v[36:37], v[12:13] op_sel_hi:[0,1,1] neg_lo:[1,0,0] neg_hi:[1,0,0]
	s_waitcnt vmcnt(31)
	v_lshlrev_b32_e32 v36, 16, v124
	v_and_b32_e32 v37, 0xffff0000, v124
	v_lshlrev_b32_e32 v32, 16, v125
	v_and_b32_e32 v33, 0xffff0000, v125
	v_pk_fma_f32 v[14:15], v[186:187], v[32:33], v[14:15] op_sel_hi:[0,1,1]
	v_pk_fma_f32 v[12:13], v[186:187], v[36:37], v[12:13] op_sel_hi:[0,1,1]
	s_add_i32 s26, s23, 30
	s_max_i32 s26, s26, s16
	s_add_i32 s27, s23, 32
	s_min_i32 s27, s27, s17
	s_sub_i32 s26, s27, s26
	v_cvt_f32_i32_e32 v35, s26
	v_lshlrev_b32_e32 v44, 16, v124
	v_div_scale_f32 v16, s[10:11], v35, v35, 1.0
	v_rcp_f32_e32 v17, v16
	v_div_scale_f32 v38, vcc, 1.0, v35, 1.0
	v_fma_f32 v39, -v16, v17, 1.0
	v_fmac_f32_e32 v17, v39, v17
	v_mul_f32_e32 v39, v38, v17
	v_fma_f32 v43, -v16, v39, v38
	v_fmac_f32_e32 v39, v43, v17
	v_fma_f32 v16, -v16, v39, v38
	v_and_b32_e32 v45, 0xffff0000, v124
	v_lshlrev_b32_e32 v46, 16, v125
	v_div_fmas_f32 v17, v16, v17, v39
	v_and_b32_e32 v47, 0xffff0000, v125
	v_div_fixup_f32 v38, v17, v35, 1.0
	v_pk_mul_f32 v[46:47], v[186:187], v[46:47] op_sel_hi:[0,1]
	v_pk_mul_f32 v[44:45], v[186:187], v[44:45] op_sel_hi:[0,1]
	v_pk_fma_f32 v[44:45], v[38:39], v[12:13], v[44:45] op_sel_hi:[0,1,1] neg_lo:[0,0,1] neg_hi:[0,0,1]
	v_pk_fma_f32 v[46:47], v[38:39], v[14:15], v[46:47] op_sel_hi:[0,1,1] neg_lo:[0,0,1] neg_hi:[0,0,1]
	v_pk_mul_f32 v[44:45], v[52:53], v[44:45]
	v_pk_mul_f32 v[46:47], v[54:55], v[46:47]
	v_cvt_pk_bf16_f32 v50, v44, v45
	v_cvt_pk_bf16_f32 v51, v46, v47
	global_store_dwordx2 v41, v[50:51], s[52:53] offset:2048
	v_lshlrev_b32_e32 v36, 16, v122
	v_and_b32_e32 v37, 0xffff0000, v122
	v_lshlrev_b32_e32 v32, 16, v123
	v_and_b32_e32 v33, 0xffff0000, v123
	v_pk_fma_f32 v[14:15], v[184:185], v[32:33], v[14:15] op_sel:[1,0,0] op_sel_hi:[1,1,1] neg_lo:[1,0,0] neg_hi:[1,0,0]
	v_pk_fma_f32 v[12:13], v[184:185], v[36:37], v[12:13] op_sel:[1,0,0] op_sel_hi:[1,1,1] neg_lo:[1,0,0] neg_hi:[1,0,0]
	s_branch .Lp13_tail
; __device__ __forceinline__ unsigned pk2(float lo, float hi) { unsigned r; asm volatile("v_cvt_pk_bf16_f32 %0, %1, %2" : "=v"(r) : "v"(lo), "v"(hi)); return r; }
; __device__ __forceinline__ unsigned pk2(float lo, float hi) { return f2bf(lo) | (f2bf(hi) << 16); }
; #define LDX(tok) ({ const u32x2 _q = *(const u32x2*)(xb + (size_t)(tok) * D + cq * 4); (f32x4){bf_lo(_q.x), bf_hi(_q.x), bf_lo(_q.y), bf_hi(_q.y)} * rs[(tok) - t0 + 8]; })
; __global__ void __launch_bounds__(512, 2) fwd_megakernel(Params Pk) {
;     ...
;             for (int s = ta - hw; s <= ta + hw - 2; ++s) if (s >= sbeg && s < send) S += LDX(s);
;             for (int t = ta; t < ta + 32; ++t) {
;                 const int sin_ = t + hw - 1; if (sin_ < send) S += LDX(sin_);
;                 const int wl = (t - hw) > sbeg ? (t - hw) : sbeg, wh = (t + hw) < send ? (t + hw) : send; const float inv = 1.0f / (float)(wh - wl);
;                 const f32x4 xt = LDX(t);
;                 const f32x4 pv = (S * inv - xt) * gv;
;                 u32x2 w; w.x = pk2(pv[0], pv[1]); w.y = pk2(pv[2], pv[3]); *(u32x2*)(pbuf + (size_t)t * D + cq * 4) = w;
;                 const int sout = t - hw; if (sout >= sbeg) S -= LDX(sout);
;             }
.Lp13_hw2:
	ds_read_b32 v154, v42 offset:24
	ds_read_b32 v155, v42 offset:28
	ds_read_b32 v156, v42 offset:32
	ds_read_b32 v157, v42 offset:36
	ds_read_b32 v158, v42 offset:40
	ds_read_b32 v159, v42 offset:44
	ds_read_b32 v160, v42 offset:48
	ds_read_b32 v161, v42 offset:52
	ds_read_b32 v162, v42 offset:56
	ds_read_b32 v163, v42 offset:60
	ds_read_b32 v164, v42 offset:64
	ds_read_b32 v165, v42 offset:68
	ds_read_b32 v166, v42 offset:72
	ds_read_b32 v167, v42 offset:76
	ds_read_b32 v168, v42 offset:80
	ds_read_b32 v169, v42 offset:84
	ds_read_b32 v170, v42 offset:88
	ds_read_b32 v171, v42 offset:92
	ds_read_b32 v172, v42 offset:96
	ds_read_b32 v173, v42 offset:100
	ds_read_b32 v174, v42 offset:104
	ds_read_b32 v175, v42 offset:108
	ds_read_b32 v176, v42 offset:112
	ds_read_b32 v177, v42 offset:116
	ds_read_b32 v178, v42 offset:120
	ds_read_b32 v179, v42 offset:124
	ds_read_b32 v180, v42 offset:128
	ds_read_b32 v181, v42 offset:132
	ds_read_b32 v182, v42 offset:136
	ds_read_b32 v183, v42 offset:140
	ds_read_b32 v184, v42 offset:144
	ds_read_b32 v185, v42 offset:148
	ds_read_b32 v186, v42 offset:152
	ds_read_b32 v187, v42 offset:156
	ds_read_b32 v188, v42 offset:160
	v_mov_b32_e32 v12, 0
	v_mov_b32_e32 v13, 0
	v_mov_b32_e32 v14, 0
	v_mov_b32_e32 v15, 0
	s_waitcnt lgkmcnt(0)
	s_waitcnt vmcnt(34)
	v_lshlrev_b32_e32 v36, 16, v60
	v_and_b32_e32 v37, 0xffff0000, v60
	v_lshlrev_b32_e32 v32, 16, v61
	v_and_b32_e32 v33, 0xffff0000, v61
	v_pk_fma_f32 v[14:15], v[154:155], v[32:33], v[14:15] op_sel_hi:[0,1,1]
	v_pk_fma_f32 v[12:13], v[154:155], v[36:37], v[12:13] op_sel_hi:[0,1,1]
	s_waitcnt vmcnt(33)
	v_lshlrev_b32_e32 v36, 16, v62
	v_and_b32_e32 v37, 0xffff0000, v62
	v_lshlrev_b32_e32 v32, 16, v63
	v_and_b32_e32 v33, 0xffff0000, v63
	v_pk_fma_f32 v[14:15], v[154:155], v[32:33], v[14:15] op_sel:[1,0,0] op_sel_hi:[1,1,1]
	v_pk_fma_f32 v[12:13], v[154:155], v[36:37], v[12:13] op_sel:[1,0,0] op_sel_hi:[1,1,1]
	s_waitcnt vmcnt(32)
	v_lshlrev_b32_e32 v36, 16, v64
	v_and_b32_e32 v37, 0xffff0000, v64
	v_lshlrev_b32_e32 v32, 16, v65
	v_and_b32_e32 v33, 0xffff0000, v65
	v_pk_fma_f32 v[14:15], v[156:157], v[32:33], v[14:15] op_sel_hi:[0,1,1]
	v_pk_fma_f32 v[12:13], v[156:157], v[36:37], v[12:13] op_sel_hi:[0,1,1]
	s_waitcnt vmcnt(31)
	v_lshlrev_b32_e32 v36, 16, v66
	v_and_b32_e32 v37, 0xffff0000, v66
	v_lshlrev_b32_e32 v32, 16, v67
	v_and_b32_e32 v33, 0xffff0000, v67
	v_pk_fma_f32 v[14:15], v[156:157], v[32:33], v[14:15] op_sel:[1,0,0] op_sel_hi:[1,1,1]
	v_pk_fma_f32 v[12:13], v[156:157], v[36:37], v[12:13] op_sel:[1,0,0] op_sel_hi:[1,1,1]
	s_add_i32 s26, s23, -2
	s_max_i32 s26, s26, s16
	s_add_i32 s27, s23, 2
	s_min_i32 s27, s27, s17
	s_sub_i32 s26, s27, s26
	v_cvt_f32_i32_e32 v35, s26
	v_lshlrev_b32_e32 v44, 16, v64
	v_div_scale_f32 v16, s[10:11], v35, v35, 1.0
	v_rcp_f32_e32 v17, v16
	v_div_scale_f32 v38, vcc, 1.0, v35, 1.0
	v_fma_f32 v39, -v16, v17, 1.0
	v_fmac_f32_e32 v17, v39, v17
	v_mul_f32_e32 v39, v38, v17
	v_fma_f32 v43, -v16, v39, v38
	v_fmac_f32_e32 v39, v43, v17
	v_fma_f32 v16, -v16, v39, v38
	v_and_b32_e32 v45, 0xffff0000, v64
	v_lshlrev_b32_e32 v46, 16, v65
	v_div_fmas_f32 v17, v16, v17, v39
	v_and_b32_e32 v47, 0xffff0000, v65
	v_div_fixup_f32 v38, v17, v35, 1.0
	v_pk_mul_f32 v[46:47], v[156:157], v[46:47] op_sel_hi:[0,1]
	v_pk_mul_f32 v[44:45], v[156:157], v[44:45] op_sel_hi:[0,1]
	v_pk_fma_f32 v[44:45], v[38:39], v[12:13], v[44:45] op_sel_hi:[0,1,1] neg_lo:[0,0,1] neg_hi:[0,0,1]
	v_pk_fma_f32 v[46:47], v[38:39], v[14:15], v[46:47] op_sel_hi:[0,1,1] neg_lo:[0,0,1] neg_hi:[0,0,1]
	v_pk_mul_f32 v[44:45], v[52:53], v[44:45]
	v_pk_mul_f32 v[46:47], v[54:55], v[46:47]
	v_cvt_pk_bf16_f32 v48, v44, v45
	v_cvt_pk_bf16_f32 v49, v46, v47
	s_add_u32 s46, s28, 0
	s_addc_u32 s47, s29, 0
	global_store_dwordx2 v41, v[48:49], s[46:47]
	v_lshlrev_b32_e32 v36, 16, v60
	v_and_b32_e32 v37, 0xffff0000, v60
	v_lshlrev_b32_e32 v32, 16, v61
	v_and_b32_e32 v33, 0xffff0000, v61
	v_pk_fma_f32 v[14:15], v[154:155], v[32:33], v[14:15] op_sel_hi:[0,1,1] neg_lo:[1,0,0] neg_hi:[1,0,0]
	v_pk_fma_f32 v[12:13], v[154:155], v[36:37], v[12:13] op_sel_hi:[0,1,1] neg_lo:[1,0,0] neg_hi:[1,0,0]
	s_waitcnt vmcnt(31)
	v_lshlrev_b32_e32 v36, 16, v68
	v_and_b32_e32 v37, 0xffff0000, v68
	v_lshlrev_b32_e32 v32, 16, v69
	v_and_b32_e32 v33, 0xffff0000, v69
	v_pk_fma_f32 v[14:15], v[158:159], v[32:33], v[14:15] op_sel_hi:[0,1,1]
	v_pk_fma_f32 v[12:13], v[158:159], v[36:37], v[12:13] op_sel_hi:[0,1,1]
	s_add_i32 s26, s23, -1
	s_max_i32 s26, s26, s16
	s_add_i32 s27, s23, 3
	s_min_i32 s27, s27, s17
	s_sub_i32 s26, s27, s26
	v_cvt_f32_i32_e32 v35, s26
	v_lshlrev_b32_e32 v44, 16, v66
	v_div_scale_f32 v16, s[10:11], v35, v35, 1.0
	v_rcp_f32_e32 v17, v16
	v_div_scale_f32 v38, vcc, 1.0, v35, 1.0
	v_fma_f32 v39, -v16, v17, 1.0
	v_fmac_f32_e32 v17, v39, v17
	v_mul_f32_e32 v39, v38, v17
	v_fma_f32 v43, -v16, v39, v38
	v_fmac_f32_e32 v39, v43, v17
	v_fma_f32 v16, -v16, v39, v38
	v_and_b32_e32 v45, 0xffff0000, v66
	v_lshlrev_b32_e32 v46, 16, v67
	v_div_fmas_f32 v17, v16, v17, v39
	v_and_b32_e32 v47, 0xffff0000, v67
	v_div_fixup_f32 v38, v17, v35, 1.0
	v_pk_mul_f32 v[46:47], v[156:157], v[46:47] op_sel:[1,0] op_sel_hi:[1,1]
	v_pk_mul_f32 v[44:45], v[156:157], v[44:45] op_sel:[1,0] op_sel_hi:[1,1]
	v_pk_fma_f32 v[44:45], v[38:39], v[12:13], v[44:45] op_sel_hi:[0,1,1] neg_lo:[0,0,1] neg_hi:[0,0,1]
	v_pk_fma_f32 v[46:47], v[38:39], v[14:15], v[46:47] op_sel_hi:[0,1,1] neg_lo:[0,0,1] neg_hi:[0,0,1]
	v_pk_mul_f32 v[44:45], v[52:53], v[44:45]
	v_pk_mul_f32 v[46:47], v[54:55], v[46:47]
	v_cvt_pk_bf16_f32 v50, v44, v45
	v_cvt_pk_bf16_f32 v51, v46, v47
	global_store_dwordx2 v41, v[50:51], s[46:47] offset:2048
	v_lshlrev_b32_e32 v36, 16, v62
	v_and_b32_e32 v37, 0xffff0000, v62
	v_lshlrev_b32_e32 v32, 16, v63
	v_and_b32_e32 v33, 0xffff0000, v63
	v_pk_fma_f32 v[14:15], v[154:155], v[32:33], v[14:15] op_sel:[1,0,0] op_sel_hi:[1,1,1] neg_lo:[1,0,0] neg_hi:[1,0,0]
	v_pk_fma_f32 v[12:13], v[154:155], v[36:37], v[12:13] op_sel:[1,0,0] op_sel_hi:[1,1,1] neg_lo:[1,0,0] neg_hi:[1,0,0]
	s_waitcnt vmcnt(31)
; __device__ __forceinline__ unsigned pk2(float lo, float hi) { unsigned r; asm volatile("v_cvt_pk_bf16_f32 %0, %1, %2" : "=v"(r) : "v"(lo), "v"(hi)); return r; }
; __device__ __forceinline__ unsigned pk2(float lo, float hi) { return f2bf(lo) | (f2bf(hi) << 16); }
; #define LDX(tok) ({ const u32x2 _q = *(const u32x2*)(xb + (size_t)(tok) * D + cq * 4); (f32x4){bf_lo(_q.x), bf_hi(_q.x), bf_lo(_q.y), bf_hi(_q.y)} * rs[(tok) - t0 + 8]; })
; __global__ void __launch_bounds__(512, 2) fwd_megakernel(Params Pk) {
;     ...
;             for (int t = ta; t < ta + 32; ++t) {
;                 const int sin_ = t + hw - 1; if (sin_ < send) S += LDX(sin_);
;                 const int wl = (t - hw) > sbeg ? (t - hw) : sbeg, wh = (t + hw) < send ? (t + hw) : send; const float inv = 1.0f / (float)(wh - wl);
;                 const f32x4 xt = LDX(t);
;                 const f32x4 pv = (S * inv - xt) * gv;
;                 u32x2 w; w.x = pk2(pv[0], pv[1]); w.y = pk2(pv[2], pv[3]); *(u32x2*)(pbuf + (size_t)t * D + cq * 4) = w;
;                 const int sout = t - hw; if (sout >= sbeg) S -= LDX(sout);
;             }
	v_lshlrev_b32_e32 v36, 16, v70
	v_and_b32_e32 v37, 0xffff0000, v70
	v_lshlrev_b32_e32 v32, 16, v71
	v_and_b32_e32 v33, 0xffff0000, v71
	v_pk_fma_f32 v[14:15], v[158:159], v[32:33], v[14:15] op_sel:[1,0,0] op_sel_hi:[1,1,1]
	v_pk_fma_f32 v[12:13], v[158:159], v[36:37], v[12:13] op_sel:[1,0,0] op_sel_hi:[1,1,1]
	s_add_i32 s26, s23, 0
	s_max_i32 s26, s26, s16
	s_add_i32 s27, s23, 4
	s_min_i32 s27, s27, s17
	s_sub_i32 s26, s27, s26
	v_cvt_f32_i32_e32 v35, s26
	v_lshlrev_b32_e32 v44, 16, v68
	v_div_scale_f32 v16, s[10:11], v35, v35, 1.0
	v_rcp_f32_e32 v17, v16
	v_div_scale_f32 v38, vcc, 1.0, v35, 1.0
	v_fma_f32 v39, -v16, v17, 1.0
	v_fmac_f32_e32 v17, v39, v17
	v_mul_f32_e32 v39, v38, v17
	v_fma_f32 v43, -v16, v39, v38
	v_fmac_f32_e32 v39, v43, v17
	v_fma_f32 v16, -v16, v39, v38
	v_and_b32_e32 v45, 0xffff0000, v68
	v_lshlrev_b32_e32 v46, 16, v69
	v_div_fmas_f32 v17, v16, v17, v39
	v_and_b32_e32 v47, 0xffff0000, v69
	v_div_fixup_f32 v38, v17, v35, 1.0
	v_pk_mul_f32 v[46:47], v[158:159], v[46:47] op_sel_hi:[0,1]
	v_pk_mul_f32 v[44:45], v[158:159], v[44:45] op_sel_hi:[0,1]
	v_pk_fma_f32 v[44:45], v[38:39], v[12:13], v[44:45] op_sel_hi:[0,1,1] neg_lo:[0,0,1] neg_hi:[0,0,1]
	v_pk_fma_f32 v[46:47], v[38:39], v[14:15], v[46:47] op_sel_hi:[0,1,1] neg_lo:[0,0,1] neg_hi:[0,0,1]
	v_pk_mul_f32 v[44:45], v[52:53], v[44:45]
	v_pk_mul_f32 v[46:47], v[54:55], v[46:47]
	v_cvt_pk_bf16_f32 v48, v44, v45
	v_cvt_pk_bf16_f32 v49, v46, v47
	s_add_u32 s48, s28, 4096
	s_addc_u32 s49, s29, 0
	global_store_dwordx2 v41, v[48:49], s[48:49]
	v_lshlrev_b32_e32 v36, 16, v64
	v_and_b32_e32 v37, 0xffff0000, v64
	v_lshlrev_b32_e32 v32, 16, v65
	v_and_b32_e32 v33, 0xffff0000, v65
	v_pk_fma_f32 v[14:15], v[156:157], v[32:33], v[14:15] op_sel_hi:[0,1,1] neg_lo:[1,0,0] neg_hi:[1,0,0]
	v_pk_fma_f32 v[12:13], v[156:157], v[36:37], v[12:13] op_sel_hi:[0,1,1] neg_lo:[1,0,0] neg_hi:[1,0,0]
	s_waitcnt vmcnt(31)
	v_lshlrev_b32_e32 v36, 16, v72
	v_and_b32_e32 v37, 0xffff0000, v72
	v_lshlrev_b32_e32 v32, 16, v73
	v_and_b32_e32 v33, 0xffff0000, v73
	v_pk_fma_f32 v[14:15], v[160:161], v[32:33], v[14:15] op_sel_hi:[0,1,1]
	v_pk_fma_f32 v[12:13], v[160:161], v[36:37], v[12:13] op_sel_hi:[0,1,1]
	s_add_i32 s26, s23, 1
	s_max_i32 s26, s26, s16
	s_add_i32 s27, s23, 5
	s_min_i32 s27, s27, s17
	s_sub_i32 s26, s27, s26
	v_cvt_f32_i32_e32 v35, s26
	v_lshlrev_b32_e32 v44, 16, v70
	v_div_scale_f32 v16, s[10:11], v35, v35, 1.0
	v_rcp_f32_e32 v17, v16
	v_div_scale_f32 v38, vcc, 1.0, v35, 1.0
	v_fma_f32 v39, -v16, v17, 1.0
	v_fmac_f32_e32 v17, v39, v17
	v_mul_f32_e32 v39, v38, v17
	v_fma_f32 v43, -v16, v39, v38
	v_fmac_f32_e32 v39, v43, v17
	v_fma_f32 v16, -v16, v39, v38
	v_and_b32_e32 v45, 0xffff0000, v70
	v_lshlrev_b32_e32 v46, 16, v71
	v_div_fmas_f32 v17, v16, v17, v39
	v_and_b32_e32 v47, 0xffff0000, v71
	v_div_fixup_f32 v38, v17, v35, 1.0
	v_pk_mul_f32 v[46:47], v[158:159], v[46:47] op_sel:[1,0] op_sel_hi:[1,1]
	v_pk_mul_f32 v[44:45], v[158:159], v[44:45] op_sel:[1,0] op_sel_hi:[1,1]
	v_pk_fma_f32 v[44:45], v[38:39], v[12:13], v[44:45] op_sel_hi:[0,1,1] neg_lo:[0,0,1] neg_hi:[0,0,1]
	v_pk_fma_f32 v[46:47], v[38:39], v[14:15], v[46:47] op_sel_hi:[0,1,1] neg_lo:[0,0,1] neg_hi:[0,0,1]
	v_pk_mul_f32 v[44:45], v[52:53], v[44:45]
	v_pk_mul_f32 v[46:47], v[54:55], v[46:47]
	v_cvt_pk_bf16_f32 v50, v44, v45
	v_cvt_pk_bf16_f32 v51, v46, v47
	global_store_dwordx2 v41, v[50:51], s[48:49] offset:2048
	v_lshlrev_b32_e32 v36, 16, v66
	v_and_b32_e32 v37, 0xffff0000, v66
	v_lshlrev_b32_e32 v32, 16, v67
	v_and_b32_e32 v33, 0xffff0000, v67
	v_pk_fma_f32 v[14:15], v[156:157], v[32:33], v[14:15] op_sel:[1,0,0] op_sel_hi:[1,1,1] neg_lo:[1,0,0] neg_hi:[1,0,0]
	v_pk_fma_f32 v[12:13], v[156:157], v[36:37], v[12:13] op_sel:[1,0,0] op_sel_hi:[1,1,1] neg_lo:[1,0,0] neg_hi:[1,0,0]
	s_waitcnt vmcnt(31)
	v_lshlrev_b32_e32 v36, 16, v74
	v_and_b32_e32 v37, 0xffff0000, v74
	v_lshlrev_b32_e32 v32, 16, v75
	v_and_b32_e32 v33, 0xffff0000, v75
	v_pk_fma_f32 v[14:15], v[160:161], v[32:33], v[14:15] op_sel:[1,0,0] op_sel_hi:[1,1,1]
	v_pk_fma_f32 v[12:13], v[160:161], v[36:37], v[12:13] op_sel:[1,0,0] op_sel_hi:[1,1,1]
	s_add_i32 s26, s23, 2
	s_max_i32 s26, s26, s16
	s_add_i32 s27, s23, 6
	s_min_i32 s27, s27, s17
	s_sub_i32 s26, s27, s26
	v_cvt_f32_i32_e32 v35, s26
	v_lshlrev_b32_e32 v44, 16, v72
	v_div_scale_f32 v16, s[10:11], v35, v35, 1.0
	v_rcp_f32_e32 v17, v16
	v_div_scale_f32 v38, vcc, 1.0, v35, 1.0
	v_fma_f32 v39, -v16, v17, 1.0
	v_fmac_f32_e32 v17, v39, v17
	v_mul_f32_e32 v39, v38, v17
	v_fma_f32 v43, -v16, v39, v38
	v_fmac_f32_e32 v39, v43, v17
	v_fma_f32 v16, -v16, v39, v38
	v_and_b32_e32 v45, 0xffff0000, v72
	v_lshlrev_b32_e32 v46, 16, v73
	v_div_fmas_f32 v17, v16, v17, v39
	v_and_b32_e32 v47, 0xffff0000, v73
	v_div_fixup_f32 v38, v17, v35, 1.0
	v_pk_mul_f32 v[46:47], v[160:161], v[46:47] op_sel_hi:[0,1]
	v_pk_mul_f32 v[44:45], v[160:161], v[44:45] op_sel_hi:[0,1]
	v_pk_fma_f32 v[44:45], v[38:39], v[12:13], v[44:45] op_sel_hi:[0,1,1] neg_lo:[0,0,1] neg_hi:[0,0,1]
	v_pk_fma_f32 v[46:47], v[38:39], v[14:15], v[46:47] op_sel_hi:[0,1,1] neg_lo:[0,0,1] neg_hi:[0,0,1]
	v_pk_mul_f32 v[44:45], v[52:53], v[44:45]
	v_pk_mul_f32 v[46:47], v[54:55], v[46:47]
	v_cvt_pk_bf16_f32 v48, v44, v45
	v_cvt_pk_bf16_f32 v49, v46, v47
	s_add_u32 s50, s28, 8192
	s_addc_u32 s51, s29, 0
	global_store_dwordx2 v41, v[48:49], s[50:51]
	v_lshlrev_b32_e32 v36, 16, v68
	v_and_b32_e32 v37, 0xffff0000, v68
	v_lshlrev_b32_e32 v32, 16, v69
	v_and_b32_e32 v33, 0xffff0000, v69
	v_pk_fma_f32 v[14:15], v[158:159], v[32:33], v[14:15] op_sel_hi:[0,1,1] neg_lo:[1,0,0] neg_hi:[1,0,0]
	v_pk_fma_f32 v[12:13], v[158:159], v[36:37], v[12:13] op_sel_hi:[0,1,1] neg_lo:[1,0,0] neg_hi:[1,0,0]
	s_waitcnt vmcnt(31)
; __device__ __forceinline__ unsigned pk2(float lo, float hi) { unsigned r; asm volatile("v_cvt_pk_bf16_f32 %0, %1, %2" : "=v"(r) : "v"(lo), "v"(hi)); return r; }
; __device__ __forceinline__ unsigned pk2(float lo, float hi) { return f2bf(lo) | (f2bf(hi) << 16); }
; #define LDX(tok) ({ const u32x2 _q = *(const u32x2*)(xb + (size_t)(tok) * D + cq * 4); (f32x4){bf_lo(_q.x), bf_hi(_q.x), bf_lo(_q.y), bf_hi(_q.y)} * rs[(tok) - t0 + 8]; })
; __global__ void __launch_bounds__(512, 2) fwd_megakernel(Params Pk) {
;     ...
;             for (int s = ta - hw; s <= ta + hw - 2; ++s) if (s >= sbeg && s < send) S += LDX(s);
;             for (int t = ta; t < ta + 32; ++t) {
;                 const int sin_ = t + hw - 1; if (sin_ < send) S += LDX(sin_);
;                 const int wl = (t - hw) > sbeg ? (t - hw) : sbeg, wh = (t + hw) < send ? (t + hw) : send; const float inv = 1.0f / (float)(wh - wl);
;                 const f32x4 xt = LDX(t);
;                 const f32x4 pv = (S * inv - xt) * gv;
;                 u32x2 w; w.x = pk2(pv[0], pv[1]); w.y = pk2(pv[2], pv[3]); *(u32x2*)(pbuf + (size_t)t * D + cq * 4) = w;
;                 const int sout = t - hw; if (sout >= sbeg) S -= LDX(sout);
;             }
	v_lshlrev_b32_e32 v36, 16, v76
	v_and_b32_e32 v37, 0xffff0000, v76
	v_lshlrev_b32_e32 v32, 16, v77
	v_and_b32_e32 v33, 0xffff0000, v77
	v_pk_fma_f32 v[14:15], v[162:163], v[32:33], v[14:15] op_sel_hi:[0,1,1]
	v_pk_fma_f32 v[12:13], v[162:163], v[36:37], v[12:13] op_sel_hi:[0,1,1]
	s_add_i32 s26, s23, 3
	s_max_i32 s26, s26, s16
	s_add_i32 s27, s23, 7
	s_min_i32 s27, s27, s17
	s_sub_i32 s26, s27, s26
	v_cvt_f32_i32_e32 v35, s26
	v_lshlrev_b32_e32 v44, 16, v74
	v_div_scale_f32 v16, s[10:11], v35, v35, 1.0
	v_rcp_f32_e32 v17, v16
	v_div_scale_f32 v38, vcc, 1.0, v35, 1.0
	v_fma_f32 v39, -v16, v17, 1.0
	v_fmac_f32_e32 v17, v39, v17
	v_mul_f32_e32 v39, v38, v17
	v_fma_f32 v43, -v16, v39, v38
	v_fmac_f32_e32 v39, v43, v17
	v_fma_f32 v16, -v16, v39, v38
	v_and_b32_e32 v45, 0xffff0000, v74
	v_lshlrev_b32_e32 v46, 16, v75
	v_div_fmas_f32 v17, v16, v17, v39
	v_and_b32_e32 v47, 0xffff0000, v75
	v_div_fixup_f32 v38, v17, v35, 1.0
	v_pk_mul_f32 v[46:47], v[160:161], v[46:47] op_sel:[1,0] op_sel_hi:[1,1]
	v_pk_mul_f32 v[44:45], v[160:161], v[44:45] op_sel:[1,0] op_sel_hi:[1,1]
	v_pk_fma_f32 v[44:45], v[38:39], v[12:13], v[44:45] op_sel_hi:[0,1,1] neg_lo:[0,0,1] neg_hi:[0,0,1]
	v_pk_fma_f32 v[46:47], v[38:39], v[14:15], v[46:47] op_sel_hi:[0,1,1] neg_lo:[0,0,1] neg_hi:[0,0,1]
	v_pk_mul_f32 v[44:45], v[52:53], v[44:45]
	v_pk_mul_f32 v[46:47], v[54:55], v[46:47]
	v_cvt_pk_bf16_f32 v50, v44, v45
	v_cvt_pk_bf16_f32 v51, v46, v47
	global_store_dwordx2 v41, v[50:51], s[50:51] offset:2048
	v_lshlrev_b32_e32 v36, 16, v70
	v_and_b32_e32 v37, 0xffff0000, v70
	v_lshlrev_b32_e32 v32, 16, v71
	v_and_b32_e32 v33, 0xffff0000, v71
	v_pk_fma_f32 v[14:15], v[158:159], v[32:33], v[14:15] op_sel:[1,0,0] op_sel_hi:[1,1,1] neg_lo:[1,0,0] neg_hi:[1,0,0]
	v_pk_fma_f32 v[12:13], v[158:159], v[36:37], v[12:13] op_sel:[1,0,0] op_sel_hi:[1,1,1] neg_lo:[1,0,0] neg_hi:[1,0,0]
	s_waitcnt vmcnt(31)
	v_lshlrev_b32_e32 v36, 16, v78
	v_and_b32_e32 v37, 0xffff0000, v78
	v_lshlrev_b32_e32 v32, 16, v79
	v_and_b32_e32 v33, 0xffff0000, v79
	v_pk_fma_f32 v[14:15], v[162:163], v[32:33], v[14:15] op_sel:[1,0,0] op_sel_hi:[1,1,1]
	v_pk_fma_f32 v[12:13], v[162:163], v[36:37], v[12:13] op_sel:[1,0,0] op_sel_hi:[1,1,1]
	s_add_i32 s26, s23, 4
	s_max_i32 s26, s26, s16
	s_add_i32 s27, s23, 8
	s_min_i32 s27, s27, s17
	s_sub_i32 s26, s27, s26
	v_cvt_f32_i32_e32 v35, s26
	v_lshlrev_b32_e32 v44, 16, v76
	v_div_scale_f32 v16, s[10:11], v35, v35, 1.0
	v_rcp_f32_e32 v17, v16
	v_div_scale_f32 v38, vcc, 1.0, v35, 1.0
	v_fma_f32 v39, -v16, v17, 1.0
	v_fmac_f32_e32 v17, v39, v17
	v_mul_f32_e32 v39, v38, v17
	v_fma_f32 v43, -v16, v39, v38
	v_fmac_f32_e32 v39, v43, v17
	v_fma_f32 v16, -v16, v39, v38
	v_and_b32_e32 v45, 0xffff0000, v76
	v_lshlrev_b32_e32 v46, 16, v77
	v_div_fmas_f32 v17, v16, v17, v39
	v_and_b32_e32 v47, 0xffff0000, v77
	v_div_fixup_f32 v38, v17, v35, 1.0
	v_pk_mul_f32 v[46:47], v[162:163], v[46:47] op_sel_hi:[0,1]
	v_pk_mul_f32 v[44:45], v[162:163], v[44:45] op_sel_hi:[0,1]
	v_pk_fma_f32 v[44:45], v[38:39], v[12:13], v[44:45] op_sel_hi:[0,1,1] neg_lo:[0,0,1] neg_hi:[0,0,1]
	v_pk_fma_f32 v[46:47], v[38:39], v[14:15], v[46:47] op_sel_hi:[0,1,1] neg_lo:[0,0,1] neg_hi:[0,0,1]
	v_pk_mul_f32 v[44:45], v[52:53], v[44:45]
	v_pk_mul_f32 v[46:47], v[54:55], v[46:47]
	v_cvt_pk_bf16_f32 v48, v44, v45
	v_cvt_pk_bf16_f32 v49, v46, v47
	s_add_u32 s52, s28, 12288
	s_addc_u32 s53, s29, 0
	global_store_dwordx2 v41, v[48:49], s[52:53]
	v_lshlrev_b32_e32 v36, 16, v72
	v_and_b32_e32 v37, 0xffff0000, v72
	v_lshlrev_b32_e32 v32, 16, v73
	v_and_b32_e32 v33, 0xffff0000, v73
	v_pk_fma_f32 v[14:15], v[160:161], v[32:33], v[14:15] op_sel_hi:[0,1,1] neg_lo:[1,0,0] neg_hi:[1,0,0]
	v_pk_fma_f32 v[12:13], v[160:161], v[36:37], v[12:13] op_sel_hi:[0,1,1] neg_lo:[1,0,0] neg_hi:[1,0,0]
	s_waitcnt vmcnt(31)
	v_lshlrev_b32_e32 v36, 16, v80
	v_and_b32_e32 v37, 0xffff0000, v80
	v_lshlrev_b32_e32 v32, 16, v81
	v_and_b32_e32 v33, 0xffff0000, v81
	v_pk_fma_f32 v[14:15], v[164:165], v[32:33], v[14:15] op_sel_hi:[0,1,1]
	v_pk_fma_f32 v[12:13], v[164:165], v[36:37], v[12:13] op_sel_hi:[0,1,1]
	s_add_i32 s26, s23, 5
	s_max_i32 s26, s26, s16
	s_add_i32 s27, s23, 9
	s_min_i32 s27, s27, s17
	s_sub_i32 s26, s27, s26
	v_cvt_f32_i32_e32 v35, s26
	v_lshlrev_b32_e32 v44, 16, v78
	v_div_scale_f32 v16, s[10:11], v35, v35, 1.0
	v_rcp_f32_e32 v17, v16
	v_div_scale_f32 v38, vcc, 1.0, v35, 1.0
	v_fma_f32 v39, -v16, v17, 1.0
	v_fmac_f32_e32 v17, v39, v17
	v_mul_f32_e32 v39, v38, v17
	v_fma_f32 v43, -v16, v39, v38
	v_fmac_f32_e32 v39, v43, v17
	v_fma_f32 v16, -v16, v39, v38
	v_and_b32_e32 v45, 0xffff0000, v78
	v_lshlrev_b32_e32 v46, 16, v79
	v_div_fmas_f32 v17, v16, v17, v39
	v_and_b32_e32 v47, 0xffff0000, v79
	v_div_fixup_f32 v38, v17, v35, 1.0
	v_pk_mul_f32 v[46:47], v[162:163], v[46:47] op_sel:[1,0] op_sel_hi:[1,1]
	v_pk_mul_f32 v[44:45], v[162:163], v[44:45] op_sel:[1,0] op_sel_hi:[1,1]
	v_pk_fma_f32 v[44:45], v[38:39], v[12:13], v[44:45] op_sel_hi:[0,1,1] neg_lo:[0,0,1] neg_hi:[0,0,1]
	v_pk_fma_f32 v[46:47], v[38:39], v[14:15], v[46:47] op_sel_hi:[0,1,1] neg_lo:[0,0,1] neg_hi:[0,0,1]
	v_pk_mul_f32 v[44:45], v[52:53], v[44:45]
	v_pk_mul_f32 v[46:47], v[54:55], v[46:47]
	v_cvt_pk_bf16_f32 v50, v44, v45
	v_cvt_pk_bf16_f32 v51, v46, v47
	global_store_dwordx2 v41, v[50:51], s[52:53] offset:2048
	v_lshlrev_b32_e32 v36, 16, v74
	v_and_b32_e32 v37, 0xffff0000, v74
	v_lshlrev_b32_e32 v32, 16, v75
	v_and_b32_e32 v33, 0xffff0000, v75
	v_pk_fma_f32 v[14:15], v[160:161], v[32:33], v[14:15] op_sel:[1,0,0] op_sel_hi:[1,1,1] neg_lo:[1,0,0] neg_hi:[1,0,0]
	v_pk_fma_f32 v[12:13], v[160:161], v[36:37], v[12:13] op_sel:[1,0,0] op_sel_hi:[1,1,1] neg_lo:[1,0,0] neg_hi:[1,0,0]
	s_waitcnt vmcnt(31)
; __device__ __forceinline__ unsigned pk2(float lo, float hi) { unsigned r; asm volatile("v_cvt_pk_bf16_f32 %0, %1, %2" : "=v"(r) : "v"(lo), "v"(hi)); return r; }
; __device__ __forceinline__ unsigned pk2(float lo, float hi) { return f2bf(lo) | (f2bf(hi) << 16); }
; #define LDX(tok) ({ const u32x2 _q = *(const u32x2*)(xb + (size_t)(tok) * D + cq * 4); (f32x4){bf_lo(_q.x), bf_hi(_q.x), bf_lo(_q.y), bf_hi(_q.y)} * rs[(tok) - t0 + 8]; })
; __global__ void __launch_bounds__(512, 2) fwd_megakernel(Params Pk) {
;     ...
;             for (int s = ta - hw; s <= ta + hw - 2; ++s) if (s >= sbeg && s < send) S += LDX(s);
;             for (int t = ta; t < ta + 32; ++t) {
;                 const int sin_ = t + hw - 1; if (sin_ < send) S += LDX(sin_);
;                 const int wl = (t - hw) > sbeg ? (t - hw) : sbeg, wh = (t + hw) < send ? (t + hw) : send; const float inv = 1.0f / (float)(wh - wl);
;                 const f32x4 xt = LDX(t);
;                 const f32x4 pv = (S * inv - xt) * gv;
;                 u32x2 w; w.x = pk2(pv[0], pv[1]); w.y = pk2(pv[2], pv[3]); *(u32x2*)(pbuf + (size_t)t * D + cq * 4) = w;
;                 const int sout = t - hw; if (sout >= sbeg) S -= LDX(sout);
;             }
	v_lshlrev_b32_e32 v36, 16, v82
	v_and_b32_e32 v37, 0xffff0000, v82
	v_lshlrev_b32_e32 v32, 16, v83
	v_and_b32_e32 v33, 0xffff0000, v83
	v_pk_fma_f32 v[14:15], v[164:165], v[32:33], v[14:15] op_sel:[1,0,0] op_sel_hi:[1,1,1]
	v_pk_fma_f32 v[12:13], v[164:165], v[36:37], v[12:13] op_sel:[1,0,0] op_sel_hi:[1,1,1]
	s_add_i32 s26, s23, 6
	s_max_i32 s26, s26, s16
	s_add_i32 s27, s23, 10
	s_min_i32 s27, s27, s17
	s_sub_i32 s26, s27, s26
	v_cvt_f32_i32_e32 v35, s26
	v_lshlrev_b32_e32 v44, 16, v80
	v_div_scale_f32 v16, s[10:11], v35, v35, 1.0
	v_rcp_f32_e32 v17, v16
	v_div_scale_f32 v38, vcc, 1.0, v35, 1.0
	v_fma_f32 v39, -v16, v17, 1.0
	v_fmac_f32_e32 v17, v39, v17
	v_mul_f32_e32 v39, v38, v17
	v_fma_f32 v43, -v16, v39, v38
	v_fmac_f32_e32 v39, v43, v17
	v_fma_f32 v16, -v16, v39, v38
	v_and_b32_e32 v45, 0xffff0000, v80
	v_lshlrev_b32_e32 v46, 16, v81
	v_div_fmas_f32 v17, v16, v17, v39
	v_and_b32_e32 v47, 0xffff0000, v81
	v_div_fixup_f32 v38, v17, v35, 1.0
	v_pk_mul_f32 v[46:47], v[164:165], v[46:47] op_sel_hi:[0,1]
	v_pk_mul_f32 v[44:45], v[164:165], v[44:45] op_sel_hi:[0,1]
	v_pk_fma_f32 v[44:45], v[38:39], v[12:13], v[44:45] op_sel_hi:[0,1,1] neg_lo:[0,0,1] neg_hi:[0,0,1]
	v_pk_fma_f32 v[46:47], v[38:39], v[14:15], v[46:47] op_sel_hi:[0,1,1] neg_lo:[0,0,1] neg_hi:[0,0,1]
	v_pk_mul_f32 v[44:45], v[52:53], v[44:45]
	v_pk_mul_f32 v[46:47], v[54:55], v[46:47]
	v_cvt_pk_bf16_f32 v48, v44, v45
	v_cvt_pk_bf16_f32 v49, v46, v47
	s_add_u32 s46, s28, 16384
	s_addc_u32 s47, s29, 0
	global_store_dwordx2 v41, v[48:49], s[46:47]
	v_lshlrev_b32_e32 v36, 16, v76
	v_and_b32_e32 v37, 0xffff0000, v76
	v_lshlrev_b32_e32 v32, 16, v77
	v_and_b32_e32 v33, 0xffff0000, v77
	v_pk_fma_f32 v[14:15], v[162:163], v[32:33], v[14:15] op_sel_hi:[0,1,1] neg_lo:[1,0,0] neg_hi:[1,0,0]
	v_pk_fma_f32 v[12:13], v[162:163], v[36:37], v[12:13] op_sel_hi:[0,1,1] neg_lo:[1,0,0] neg_hi:[1,0,0]
	s_waitcnt vmcnt(31)
	v_lshlrev_b32_e32 v36, 16, v84
	v_and_b32_e32 v37, 0xffff0000, v84
	v_lshlrev_b32_e32 v32, 16, v85
	v_and_b32_e32 v33, 0xffff0000, v85
	v_pk_fma_f32 v[14:15], v[166:167], v[32:33], v[14:15] op_sel_hi:[0,1,1]
	v_pk_fma_f32 v[12:13], v[166:167], v[36:37], v[12:13] op_sel_hi:[0,1,1]
	s_add_i32 s26, s23, 7
	s_max_i32 s26, s26, s16
	s_add_i32 s27, s23, 11
	s_min_i32 s27, s27, s17
	s_sub_i32 s26, s27, s26
	v_cvt_f32_i32_e32 v35, s26
	v_lshlrev_b32_e32 v44, 16, v82
	v_div_scale_f32 v16, s[10:11], v35, v35, 1.0
	v_rcp_f32_e32 v17, v16
	v_div_scale_f32 v38, vcc, 1.0, v35, 1.0
	v_fma_f32 v39, -v16, v17, 1.0
	v_fmac_f32_e32 v17, v39, v17
	v_mul_f32_e32 v39, v38, v17
	v_fma_f32 v43, -v16, v39, v38
	v_fmac_f32_e32 v39, v43, v17
	v_fma_f32 v16, -v16, v39, v38
	v_and_b32_e32 v45, 0xffff0000, v82
	v_lshlrev_b32_e32 v46, 16, v83
	v_div_fmas_f32 v17, v16, v17, v39
	v_and_b32_e32 v47, 0xffff0000, v83
	v_div_fixup_f32 v38, v17, v35, 1.0
	v_pk_mul_f32 v[46:47], v[164:165], v[46:47] op_sel:[1,0] op_sel_hi:[1,1]
	v_pk_mul_f32 v[44:45], v[164:165], v[44:45] op_sel:[1,0] op_sel_hi:[1,1]
	v_pk_fma_f32 v[44:45], v[38:39], v[12:13], v[44:45] op_sel_hi:[0,1,1] neg_lo:[0,0,1] neg_hi:[0,0,1]
	v_pk_fma_f32 v[46:47], v[38:39], v[14:15], v[46:47] op_sel_hi:[0,1,1] neg_lo:[0,0,1] neg_hi:[0,0,1]
	v_pk_mul_f32 v[44:45], v[52:53], v[44:45]
	v_pk_mul_f32 v[46:47], v[54:55], v[46:47]
	v_cvt_pk_bf16_f32 v50, v44, v45
	v_cvt_pk_bf16_f32 v51, v46, v47
	global_store_dwordx2 v41, v[50:51], s[46:47] offset:2048
	v_lshlrev_b32_e32 v36, 16, v78
	v_and_b32_e32 v37, 0xffff0000, v78
	v_lshlrev_b32_e32 v32, 16, v79
	v_and_b32_e32 v33, 0xffff0000, v79
	v_pk_fma_f32 v[14:15], v[162:163], v[32:33], v[14:15] op_sel:[1,0,0] op_sel_hi:[1,1,1] neg_lo:[1,0,0] neg_hi:[1,0,0]
	v_pk_fma_f32 v[12:13], v[162:163], v[36:37], v[12:13] op_sel:[1,0,0] op_sel_hi:[1,1,1] neg_lo:[1,0,0] neg_hi:[1,0,0]
	s_waitcnt vmcnt(31)
	v_lshlrev_b32_e32 v36, 16, v86
	v_and_b32_e32 v37, 0xffff0000, v86
	v_lshlrev_b32_e32 v32, 16, v87
	v_and_b32_e32 v33, 0xffff0000, v87
	v_pk_fma_f32 v[14:15], v[166:167], v[32:33], v[14:15] op_sel:[1,0,0] op_sel_hi:[1,1,1]
	v_pk_fma_f32 v[12:13], v[166:167], v[36:37], v[12:13] op_sel:[1,0,0] op_sel_hi:[1,1,1]
	s_add_i32 s26, s23, 8
	s_max_i32 s26, s26, s16
	s_add_i32 s27, s23, 12
	s_min_i32 s27, s27, s17
	s_sub_i32 s26, s27, s26
	v_cvt_f32_i32_e32 v35, s26
	v_lshlrev_b32_e32 v44, 16, v84
	v_div_scale_f32 v16, s[10:11], v35, v35, 1.0
	v_rcp_f32_e32 v17, v16
	v_div_scale_f32 v38, vcc, 1.0, v35, 1.0
	v_fma_f32 v39, -v16, v17, 1.0
	v_fmac_f32_e32 v17, v39, v17
	v_mul_f32_e32 v39, v38, v17
	v_fma_f32 v43, -v16, v39, v38
	v_fmac_f32_e32 v39, v43, v17
	v_fma_f32 v16, -v16, v39, v38
	v_and_b32_e32 v45, 0xffff0000, v84
	v_lshlrev_b32_e32 v46, 16, v85
	v_div_fmas_f32 v17, v16, v17, v39
	v_and_b32_e32 v47, 0xffff0000, v85
	v_div_fixup_f32 v38, v17, v35, 1.0
	v_pk_mul_f32 v[46:47], v[166:167], v[46:47] op_sel_hi:[0,1]
	v_pk_mul_f32 v[44:45], v[166:167], v[44:45] op_sel_hi:[0,1]
	v_pk_fma_f32 v[44:45], v[38:39], v[12:13], v[44:45] op_sel_hi:[0,1,1] neg_lo:[0,0,1] neg_hi:[0,0,1]
	v_pk_fma_f32 v[46:47], v[38:39], v[14:15], v[46:47] op_sel_hi:[0,1,1] neg_lo:[0,0,1] neg_hi:[0,0,1]
	v_pk_mul_f32 v[44:45], v[52:53], v[44:45]
	v_pk_mul_f32 v[46:47], v[54:55], v[46:47]
	v_cvt_pk_bf16_f32 v48, v44, v45
	v_cvt_pk_bf16_f32 v49, v46, v47
	s_add_u32 s48, s28, 20480
	s_addc_u32 s49, s29, 0
	global_store_dwordx2 v41, v[48:49], s[48:49]
	v_lshlrev_b32_e32 v36, 16, v80
	v_and_b32_e32 v37, 0xffff0000, v80
	v_lshlrev_b32_e32 v32, 16, v81
	v_and_b32_e32 v33, 0xffff0000, v81
	v_pk_fma_f32 v[14:15], v[164:165], v[32:33], v[14:15] op_sel_hi:[0,1,1] neg_lo:[1,0,0] neg_hi:[1,0,0]
	v_pk_fma_f32 v[12:13], v[164:165], v[36:37], v[12:13] op_sel_hi:[0,1,1] neg_lo:[1,0,0] neg_hi:[1,0,0]
	s_waitcnt vmcnt(31)
; __device__ __forceinline__ unsigned pk2(float lo, float hi) { unsigned r; asm volatile("v_cvt_pk_bf16_f32 %0, %1, %2" : "=v"(r) : "v"(lo), "v"(hi)); return r; }
; __device__ __forceinline__ unsigned pk2(float lo, float hi) { return f2bf(lo) | (f2bf(hi) << 16); }
; #define LDX(tok) ({ const u32x2 _q = *(const u32x2*)(xb + (size_t)(tok) * D + cq * 4); (f32x4){bf_lo(_q.x), bf_hi(_q.x), bf_lo(_q.y), bf_hi(_q.y)} * rs[(tok) - t0 + 8]; })
; __global__ void __launch_bounds__(512, 2) fwd_megakernel(Params Pk) {
;     ...
;             for (int s = ta - hw; s <= ta + hw - 2; ++s) if (s >= sbeg && s < send) S += LDX(s);
;             for (int t = ta; t < ta + 32; ++t) {
;                 const int sin_ = t + hw - 1; if (sin_ < send) S += LDX(sin_);
;                 const int wl = (t - hw) > sbeg ? (t - hw) : sbeg, wh = (t + hw) < send ? (t + hw) : send; const float inv = 1.0f / (float)(wh - wl);
;                 const f32x4 xt = LDX(t);
;                 const f32x4 pv = (S * inv - xt) * gv;
;                 u32x2 w; w.x = pk2(pv[0], pv[1]); w.y = pk2(pv[2], pv[3]); *(u32x2*)(pbuf + (size_t)t * D + cq * 4) = w;
;                 const int sout = t - hw; if (sout >= sbeg) S -= LDX(sout);
;             }
	v_lshlrev_b32_e32 v36, 16, v88
	v_and_b32_e32 v37, 0xffff0000, v88
	v_lshlrev_b32_e32 v32, 16, v89
	v_and_b32_e32 v33, 0xffff0000, v89
	v_pk_fma_f32 v[14:15], v[168:169], v[32:33], v[14:15] op_sel_hi:[0,1,1]
	v_pk_fma_f32 v[12:13], v[168:169], v[36:37], v[12:13] op_sel_hi:[0,1,1]
	s_add_i32 s26, s23, 9
	s_max_i32 s26, s26, s16
	s_add_i32 s27, s23, 13
	s_min_i32 s27, s27, s17
	s_sub_i32 s26, s27, s26
	v_cvt_f32_i32_e32 v35, s26
	v_lshlrev_b32_e32 v44, 16, v86
	v_div_scale_f32 v16, s[10:11], v35, v35, 1.0
	v_rcp_f32_e32 v17, v16
	v_div_scale_f32 v38, vcc, 1.0, v35, 1.0
	v_fma_f32 v39, -v16, v17, 1.0
	v_fmac_f32_e32 v17, v39, v17
	v_mul_f32_e32 v39, v38, v17
	v_fma_f32 v43, -v16, v39, v38
	v_fmac_f32_e32 v39, v43, v17
	v_fma_f32 v16, -v16, v39, v38
	v_and_b32_e32 v45, 0xffff0000, v86
	v_lshlrev_b32_e32 v46, 16, v87
	v_div_fmas_f32 v17, v16, v17, v39
	v_and_b32_e32 v47, 0xffff0000, v87
	v_div_fixup_f32 v38, v17, v35, 1.0
	v_pk_mul_f32 v[46:47], v[166:167], v[46:47] op_sel:[1,0] op_sel_hi:[1,1]
	v_pk_mul_f32 v[44:45], v[166:167], v[44:45] op_sel:[1,0] op_sel_hi:[1,1]
	v_pk_fma_f32 v[44:45], v[38:39], v[12:13], v[44:45] op_sel_hi:[0,1,1] neg_lo:[0,0,1] neg_hi:[0,0,1]
	v_pk_fma_f32 v[46:47], v[38:39], v[14:15], v[46:47] op_sel_hi:[0,1,1] neg_lo:[0,0,1] neg_hi:[0,0,1]
	v_pk_mul_f32 v[44:45], v[52:53], v[44:45]
	v_pk_mul_f32 v[46:47], v[54:55], v[46:47]
	v_cvt_pk_bf16_f32 v50, v44, v45
	v_cvt_pk_bf16_f32 v51, v46, v47
	global_store_dwordx2 v41, v[50:51], s[48:49] offset:2048
	v_lshlrev_b32_e32 v36, 16, v82
	v_and_b32_e32 v37, 0xffff0000, v82
	v_lshlrev_b32_e32 v32, 16, v83
	v_and_b32_e32 v33, 0xffff0000, v83
	v_pk_fma_f32 v[14:15], v[164:165], v[32:33], v[14:15] op_sel:[1,0,0] op_sel_hi:[1,1,1] neg_lo:[1,0,0] neg_hi:[1,0,0]
	v_pk_fma_f32 v[12:13], v[164:165], v[36:37], v[12:13] op_sel:[1,0,0] op_sel_hi:[1,1,1] neg_lo:[1,0,0] neg_hi:[1,0,0]
	s_waitcnt vmcnt(31)
	v_lshlrev_b32_e32 v36, 16, v90
	v_and_b32_e32 v37, 0xffff0000, v90
	v_lshlrev_b32_e32 v32, 16, v91
	v_and_b32_e32 v33, 0xffff0000, v91
	v_pk_fma_f32 v[14:15], v[168:169], v[32:33], v[14:15] op_sel:[1,0,0] op_sel_hi:[1,1,1]
	v_pk_fma_f32 v[12:13], v[168:169], v[36:37], v[12:13] op_sel:[1,0,0] op_sel_hi:[1,1,1]
	s_add_i32 s26, s23, 10
	s_max_i32 s26, s26, s16
	s_add_i32 s27, s23, 14
	s_min_i32 s27, s27, s17
	s_sub_i32 s26, s27, s26
	v_cvt_f32_i32_e32 v35, s26
	v_lshlrev_b32_e32 v44, 16, v88
	v_div_scale_f32 v16, s[10:11], v35, v35, 1.0
	v_rcp_f32_e32 v17, v16
	v_div_scale_f32 v38, vcc, 1.0, v35, 1.0
	v_fma_f32 v39, -v16, v17, 1.0
	v_fmac_f32_e32 v17, v39, v17
	v_mul_f32_e32 v39, v38, v17
	v_fma_f32 v43, -v16, v39, v38
	v_fmac_f32_e32 v39, v43, v17
	v_fma_f32 v16, -v16, v39, v38
	v_and_b32_e32 v45, 0xffff0000, v88
	v_lshlrev_b32_e32 v46, 16, v89
	v_div_fmas_f32 v17, v16, v17, v39
	v_and_b32_e32 v47, 0xffff0000, v89
	v_div_fixup_f32 v38, v17, v35, 1.0
	v_pk_mul_f32 v[46:47], v[168:169], v[46:47] op_sel_hi:[0,1]
	v_pk_mul_f32 v[44:45], v[168:169], v[44:45] op_sel_hi:[0,1]
	v_pk_fma_f32 v[44:45], v[38:39], v[12:13], v[44:45] op_sel_hi:[0,1,1] neg_lo:[0,0,1] neg_hi:[0,0,1]
	v_pk_fma_f32 v[46:47], v[38:39], v[14:15], v[46:47] op_sel_hi:[0,1,1] neg_lo:[0,0,1] neg_hi:[0,0,1]
	v_pk_mul_f32 v[44:45], v[52:53], v[44:45]
	v_pk_mul_f32 v[46:47], v[54:55], v[46:47]
	v_cvt_pk_bf16_f32 v48, v44, v45
	v_cvt_pk_bf16_f32 v49, v46, v47
	s_add_u32 s50, s28, 24576
	s_addc_u32 s51, s29, 0
	global_store_dwordx2 v41, v[48:49], s[50:51]
	v_lshlrev_b32_e32 v36, 16, v84
	v_and_b32_e32 v37, 0xffff0000, v84
	v_lshlrev_b32_e32 v32, 16, v85
	v_and_b32_e32 v33, 0xffff0000, v85
	v_pk_fma_f32 v[14:15], v[166:167], v[32:33], v[14:15] op_sel_hi:[0,1,1] neg_lo:[1,0,0] neg_hi:[1,0,0]
	v_pk_fma_f32 v[12:13], v[166:167], v[36:37], v[12:13] op_sel_hi:[0,1,1] neg_lo:[1,0,0] neg_hi:[1,0,0]
	s_waitcnt vmcnt(31)
	v_lshlrev_b32_e32 v36, 16, v92
	v_and_b32_e32 v37, 0xffff0000, v92
	v_lshlrev_b32_e32 v32, 16, v93
	v_and_b32_e32 v33, 0xffff0000, v93
	v_pk_fma_f32 v[14:15], v[170:171], v[32:33], v[14:15] op_sel_hi:[0,1,1]
	v_pk_fma_f32 v[12:13], v[170:171], v[36:37], v[12:13] op_sel_hi:[0,1,1]
	s_add_i32 s26, s23, 11
	s_max_i32 s26, s26, s16
	s_add_i32 s27, s23, 15
	s_min_i32 s27, s27, s17
	s_sub_i32 s26, s27, s26
	v_cvt_f32_i32_e32 v35, s26
	v_lshlrev_b32_e32 v44, 16, v90
	v_div_scale_f32 v16, s[10:11], v35, v35, 1.0
	v_rcp_f32_e32 v17, v16
	v_div_scale_f32 v38, vcc, 1.0, v35, 1.0
	v_fma_f32 v39, -v16, v17, 1.0
	v_fmac_f32_e32 v17, v39, v17
	v_mul_f32_e32 v39, v38, v17
	v_fma_f32 v43, -v16, v39, v38
	v_fmac_f32_e32 v39, v43, v17
	v_fma_f32 v16, -v16, v39, v38
	v_and_b32_e32 v45, 0xffff0000, v90
	v_lshlrev_b32_e32 v46, 16, v91
	v_div_fmas_f32 v17, v16, v17, v39
	v_and_b32_e32 v47, 0xffff0000, v91
	v_div_fixup_f32 v38, v17, v35, 1.0
	v_pk_mul_f32 v[46:47], v[168:169], v[46:47] op_sel:[1,0] op_sel_hi:[1,1]
	v_pk_mul_f32 v[44:45], v[168:169], v[44:45] op_sel:[1,0] op_sel_hi:[1,1]
	v_pk_fma_f32 v[44:45], v[38:39], v[12:13], v[44:45] op_sel_hi:[0,1,1] neg_lo:[0,0,1] neg_hi:[0,0,1]
	v_pk_fma_f32 v[46:47], v[38:39], v[14:15], v[46:47] op_sel_hi:[0,1,1] neg_lo:[0,0,1] neg_hi:[0,0,1]
	v_pk_mul_f32 v[44:45], v[52:53], v[44:45]
	v_pk_mul_f32 v[46:47], v[54:55], v[46:47]
	v_cvt_pk_bf16_f32 v50, v44, v45
	v_cvt_pk_bf16_f32 v51, v46, v47
	global_store_dwordx2 v41, v[50:51], s[50:51] offset:2048
	v_lshlrev_b32_e32 v36, 16, v86
	v_and_b32_e32 v37, 0xffff0000, v86
	v_lshlrev_b32_e32 v32, 16, v87
	v_and_b32_e32 v33, 0xffff0000, v87
	v_pk_fma_f32 v[14:15], v[166:167], v[32:33], v[14:15] op_sel:[1,0,0] op_sel_hi:[1,1,1] neg_lo:[1,0,0] neg_hi:[1,0,0]
	v_pk_fma_f32 v[12:13], v[166:167], v[36:37], v[12:13] op_sel:[1,0,0] op_sel_hi:[1,1,1] neg_lo:[1,0,0] neg_hi:[1,0,0]
	s_waitcnt vmcnt(31)
; __device__ __forceinline__ unsigned pk2(float lo, float hi) { unsigned r; asm volatile("v_cvt_pk_bf16_f32 %0, %1, %2" : "=v"(r) : "v"(lo), "v"(hi)); return r; }
; __device__ __forceinline__ unsigned pk2(float lo, float hi) { return f2bf(lo) | (f2bf(hi) << 16); }
; #define LDX(tok) ({ const u32x2 _q = *(const u32x2*)(xb + (size_t)(tok) * D + cq * 4); (f32x4){bf_lo(_q.x), bf_hi(_q.x), bf_lo(_q.y), bf_hi(_q.y)} * rs[(tok) - t0 + 8]; })
; __global__ void __launch_bounds__(512, 2) fwd_megakernel(Params Pk) {
;     ...
;             for (int s = ta - hw; s <= ta + hw - 2; ++s) if (s >= sbeg && s < send) S += LDX(s);
;             for (int t = ta; t < ta + 32; ++t) {
;                 const int sin_ = t + hw - 1; if (sin_ < send) S += LDX(sin_);
;                 const int wl = (t - hw) > sbeg ? (t - hw) : sbeg, wh = (t + hw) < send ? (t + hw) : send; const float inv = 1.0f / (float)(wh - wl);
;                 const f32x4 xt = LDX(t);
;                 const f32x4 pv = (S * inv - xt) * gv;
;                 u32x2 w; w.x = pk2(pv[0], pv[1]); w.y = pk2(pv[2], pv[3]); *(u32x2*)(pbuf + (size_t)t * D + cq * 4) = w;
;                 const int sout = t - hw; if (sout >= sbeg) S -= LDX(sout);
;             }
	v_lshlrev_b32_e32 v36, 16, v94
	v_and_b32_e32 v37, 0xffff0000, v94
	v_lshlrev_b32_e32 v32, 16, v95
	v_and_b32_e32 v33, 0xffff0000, v95
	v_pk_fma_f32 v[14:15], v[170:171], v[32:33], v[14:15] op_sel:[1,0,0] op_sel_hi:[1,1,1]
	v_pk_fma_f32 v[12:13], v[170:171], v[36:37], v[12:13] op_sel:[1,0,0] op_sel_hi:[1,1,1]
	s_add_i32 s26, s23, 12
	s_max_i32 s26, s26, s16
	s_add_i32 s27, s23, 16
	s_min_i32 s27, s27, s17
	s_sub_i32 s26, s27, s26
	v_cvt_f32_i32_e32 v35, s26
	v_lshlrev_b32_e32 v44, 16, v92
	v_div_scale_f32 v16, s[10:11], v35, v35, 1.0
	v_rcp_f32_e32 v17, v16
	v_div_scale_f32 v38, vcc, 1.0, v35, 1.0
	v_fma_f32 v39, -v16, v17, 1.0
	v_fmac_f32_e32 v17, v39, v17
	v_mul_f32_e32 v39, v38, v17
	v_fma_f32 v43, -v16, v39, v38
	v_fmac_f32_e32 v39, v43, v17
	v_fma_f32 v16, -v16, v39, v38
	v_and_b32_e32 v45, 0xffff0000, v92
	v_lshlrev_b32_e32 v46, 16, v93
	v_div_fmas_f32 v17, v16, v17, v39
	v_and_b32_e32 v47, 0xffff0000, v93
	v_div_fixup_f32 v38, v17, v35, 1.0
	v_pk_mul_f32 v[46:47], v[170:171], v[46:47] op_sel_hi:[0,1]
	v_pk_mul_f32 v[44:45], v[170:171], v[44:45] op_sel_hi:[0,1]
	v_pk_fma_f32 v[44:45], v[38:39], v[12:13], v[44:45] op_sel_hi:[0,1,1] neg_lo:[0,0,1] neg_hi:[0,0,1]
	v_pk_fma_f32 v[46:47], v[38:39], v[14:15], v[46:47] op_sel_hi:[0,1,1] neg_lo:[0,0,1] neg_hi:[0,0,1]
	v_pk_mul_f32 v[44:45], v[52:53], v[44:45]
	v_pk_mul_f32 v[46:47], v[54:55], v[46:47]
	v_cvt_pk_bf16_f32 v48, v44, v45
	v_cvt_pk_bf16_f32 v49, v46, v47
	s_add_u32 s52, s28, 28672
	s_addc_u32 s53, s29, 0
	global_store_dwordx2 v41, v[48:49], s[52:53]
	v_lshlrev_b32_e32 v36, 16, v88
	v_and_b32_e32 v37, 0xffff0000, v88
	v_lshlrev_b32_e32 v32, 16, v89
	v_and_b32_e32 v33, 0xffff0000, v89
	v_pk_fma_f32 v[14:15], v[168:169], v[32:33], v[14:15] op_sel_hi:[0,1,1] neg_lo:[1,0,0] neg_hi:[1,0,0]
	v_pk_fma_f32 v[12:13], v[168:169], v[36:37], v[12:13] op_sel_hi:[0,1,1] neg_lo:[1,0,0] neg_hi:[1,0,0]
	s_waitcnt vmcnt(31)
	v_lshlrev_b32_e32 v36, 16, v96
	v_and_b32_e32 v37, 0xffff0000, v96
	v_lshlrev_b32_e32 v32, 16, v97
	v_and_b32_e32 v33, 0xffff0000, v97
	v_pk_fma_f32 v[14:15], v[172:173], v[32:33], v[14:15] op_sel_hi:[0,1,1]
	v_pk_fma_f32 v[12:13], v[172:173], v[36:37], v[12:13] op_sel_hi:[0,1,1]
	s_add_i32 s26, s23, 13
	s_max_i32 s26, s26, s16
	s_add_i32 s27, s23, 17
	s_min_i32 s27, s27, s17
	s_sub_i32 s26, s27, s26
	v_cvt_f32_i32_e32 v35, s26
	v_lshlrev_b32_e32 v44, 16, v94
	v_div_scale_f32 v16, s[10:11], v35, v35, 1.0
	v_rcp_f32_e32 v17, v16
	v_div_scale_f32 v38, vcc, 1.0, v35, 1.0
	v_fma_f32 v39, -v16, v17, 1.0
	v_fmac_f32_e32 v17, v39, v17
	v_mul_f32_e32 v39, v38, v17
	v_fma_f32 v43, -v16, v39, v38
	v_fmac_f32_e32 v39, v43, v17
	v_fma_f32 v16, -v16, v39, v38
	v_and_b32_e32 v45, 0xffff0000, v94
	v_lshlrev_b32_e32 v46, 16, v95
	v_div_fmas_f32 v17, v16, v17, v39
	v_and_b32_e32 v47, 0xffff0000, v95
	v_div_fixup_f32 v38, v17, v35, 1.0
	v_pk_mul_f32 v[46:47], v[170:171], v[46:47] op_sel:[1,0] op_sel_hi:[1,1]
	v_pk_mul_f32 v[44:45], v[170:171], v[44:45] op_sel:[1,0] op_sel_hi:[1,1]
	v_pk_fma_f32 v[44:45], v[38:39], v[12:13], v[44:45] op_sel_hi:[0,1,1] neg_lo:[0,0,1] neg_hi:[0,0,1]
	v_pk_fma_f32 v[46:47], v[38:39], v[14:15], v[46:47] op_sel_hi:[0,1,1] neg_lo:[0,0,1] neg_hi:[0,0,1]
	v_pk_mul_f32 v[44:45], v[52:53], v[44:45]
	v_pk_mul_f32 v[46:47], v[54:55], v[46:47]
	v_cvt_pk_bf16_f32 v50, v44, v45
	v_cvt_pk_bf16_f32 v51, v46, v47
	global_store_dwordx2 v41, v[50:51], s[52:53] offset:2048
	v_lshlrev_b32_e32 v36, 16, v90
	v_and_b32_e32 v37, 0xffff0000, v90
	v_lshlrev_b32_e32 v32, 16, v91
	v_and_b32_e32 v33, 0xffff0000, v91
	v_pk_fma_f32 v[14:15], v[168:169], v[32:33], v[14:15] op_sel:[1,0,0] op_sel_hi:[1,1,1] neg_lo:[1,0,0] neg_hi:[1,0,0]
	v_pk_fma_f32 v[12:13], v[168:169], v[36:37], v[12:13] op_sel:[1,0,0] op_sel_hi:[1,1,1] neg_lo:[1,0,0] neg_hi:[1,0,0]
	s_waitcnt vmcnt(31)
	v_lshlrev_b32_e32 v36, 16, v98
	v_and_b32_e32 v37, 0xffff0000, v98
	v_lshlrev_b32_e32 v32, 16, v99
	v_and_b32_e32 v33, 0xffff0000, v99
	v_pk_fma_f32 v[14:15], v[172:173], v[32:33], v[14:15] op_sel:[1,0,0] op_sel_hi:[1,1,1]
	v_pk_fma_f32 v[12:13], v[172:173], v[36:37], v[12:13] op_sel:[1,0,0] op_sel_hi:[1,1,1]
	s_add_i32 s26, s23, 14
	s_max_i32 s26, s26, s16
	s_add_i32 s27, s23, 18
	s_min_i32 s27, s27, s17
	s_sub_i32 s26, s27, s26
	v_cvt_f32_i32_e32 v35, s26
	v_lshlrev_b32_e32 v44, 16, v96
	v_div_scale_f32 v16, s[10:11], v35, v35, 1.0
	v_rcp_f32_e32 v17, v16
	v_div_scale_f32 v38, vcc, 1.0, v35, 1.0
	v_fma_f32 v39, -v16, v17, 1.0
	v_fmac_f32_e32 v17, v39, v17
	v_mul_f32_e32 v39, v38, v17
	v_fma_f32 v43, -v16, v39, v38
	v_fmac_f32_e32 v39, v43, v17
	v_fma_f32 v16, -v16, v39, v38
	v_and_b32_e32 v45, 0xffff0000, v96
	v_lshlrev_b32_e32 v46, 16, v97
	v_div_fmas_f32 v17, v16, v17, v39
	v_and_b32_e32 v47, 0xffff0000, v97
	v_div_fixup_f32 v38, v17, v35, 1.0
	v_pk_mul_f32 v[46:47], v[172:173], v[46:47] op_sel_hi:[0,1]
	v_pk_mul_f32 v[44:45], v[172:173], v[44:45] op_sel_hi:[0,1]
	v_pk_fma_f32 v[44:45], v[38:39], v[12:13], v[44:45] op_sel_hi:[0,1,1] neg_lo:[0,0,1] neg_hi:[0,0,1]
	v_pk_fma_f32 v[46:47], v[38:39], v[14:15], v[46:47] op_sel_hi:[0,1,1] neg_lo:[0,0,1] neg_hi:[0,0,1]
	v_pk_mul_f32 v[44:45], v[52:53], v[44:45]
	v_pk_mul_f32 v[46:47], v[54:55], v[46:47]
	v_cvt_pk_bf16_f32 v48, v44, v45
	v_cvt_pk_bf16_f32 v49, v46, v47
	s_add_u32 s46, s28, 32768
	s_addc_u32 s47, s29, 0
	global_store_dwordx2 v41, v[48:49], s[46:47]
	v_lshlrev_b32_e32 v36, 16, v92
	v_and_b32_e32 v37, 0xffff0000, v92
	v_lshlrev_b32_e32 v32, 16, v93
	v_and_b32_e32 v33, 0xffff0000, v93
	v_pk_fma_f32 v[14:15], v[170:171], v[32:33], v[14:15] op_sel_hi:[0,1,1] neg_lo:[1,0,0] neg_hi:[1,0,0]
	v_pk_fma_f32 v[12:13], v[170:171], v[36:37], v[12:13] op_sel_hi:[0,1,1] neg_lo:[1,0,0] neg_hi:[1,0,0]
	s_waitcnt vmcnt(31)
; __device__ __forceinline__ unsigned pk2(float lo, float hi) { unsigned r; asm volatile("v_cvt_pk_bf16_f32 %0, %1, %2" : "=v"(r) : "v"(lo), "v"(hi)); return r; }
; __device__ __forceinline__ unsigned pk2(float lo, float hi) { return f2bf(lo) | (f2bf(hi) << 16); }
; #define LDX(tok) ({ const u32x2 _q = *(const u32x2*)(xb + (size_t)(tok) * D + cq * 4); (f32x4){bf_lo(_q.x), bf_hi(_q.x), bf_lo(_q.y), bf_hi(_q.y)} * rs[(tok) - t0 + 8]; })
; __global__ void __launch_bounds__(512, 2) fwd_megakernel(Params Pk) {
;     ...
;             for (int s = ta - hw; s <= ta + hw - 2; ++s) if (s >= sbeg && s < send) S += LDX(s);
;             for (int t = ta; t < ta + 32; ++t) {
;                 const int sin_ = t + hw - 1; if (sin_ < send) S += LDX(sin_);
;                 const int wl = (t - hw) > sbeg ? (t - hw) : sbeg, wh = (t + hw) < send ? (t + hw) : send; const float inv = 1.0f / (float)(wh - wl);
;                 const f32x4 xt = LDX(t);
;                 const f32x4 pv = (S * inv - xt) * gv;
;                 u32x2 w; w.x = pk2(pv[0], pv[1]); w.y = pk2(pv[2], pv[3]); *(u32x2*)(pbuf + (size_t)t * D + cq * 4) = w;
;                 const int sout = t - hw; if (sout >= sbeg) S -= LDX(sout);
;             }
	v_lshlrev_b32_e32 v36, 16, v100
	v_and_b32_e32 v37, 0xffff0000, v100
	v_lshlrev_b32_e32 v32, 16, v101
	v_and_b32_e32 v33, 0xffff0000, v101
	v_pk_fma_f32 v[14:15], v[174:175], v[32:33], v[14:15] op_sel_hi:[0,1,1]
	v_pk_fma_f32 v[12:13], v[174:175], v[36:37], v[12:13] op_sel_hi:[0,1,1]
	s_add_i32 s26, s23, 15
	s_max_i32 s26, s26, s16
	s_add_i32 s27, s23, 19
	s_min_i32 s27, s27, s17
	s_sub_i32 s26, s27, s26
	v_cvt_f32_i32_e32 v35, s26
	v_lshlrev_b32_e32 v44, 16, v98
	v_div_scale_f32 v16, s[10:11], v35, v35, 1.0
	v_rcp_f32_e32 v17, v16
	v_div_scale_f32 v38, vcc, 1.0, v35, 1.0
	v_fma_f32 v39, -v16, v17, 1.0
	v_fmac_f32_e32 v17, v39, v17
	v_mul_f32_e32 v39, v38, v17
	v_fma_f32 v43, -v16, v39, v38
	v_fmac_f32_e32 v39, v43, v17
	v_fma_f32 v16, -v16, v39, v38
	v_and_b32_e32 v45, 0xffff0000, v98
	v_lshlrev_b32_e32 v46, 16, v99
	v_div_fmas_f32 v17, v16, v17, v39
	v_and_b32_e32 v47, 0xffff0000, v99
	v_div_fixup_f32 v38, v17, v35, 1.0
	v_pk_mul_f32 v[46:47], v[172:173], v[46:47] op_sel:[1,0] op_sel_hi:[1,1]
	v_pk_mul_f32 v[44:45], v[172:173], v[44:45] op_sel:[1,0] op_sel_hi:[1,1]
	v_pk_fma_f32 v[44:45], v[38:39], v[12:13], v[44:45] op_sel_hi:[0,1,1] neg_lo:[0,0,1] neg_hi:[0,0,1]
	v_pk_fma_f32 v[46:47], v[38:39], v[14:15], v[46:47] op_sel_hi:[0,1,1] neg_lo:[0,0,1] neg_hi:[0,0,1]
	v_pk_mul_f32 v[44:45], v[52:53], v[44:45]
	v_pk_mul_f32 v[46:47], v[54:55], v[46:47]
	v_cvt_pk_bf16_f32 v50, v44, v45
	v_cvt_pk_bf16_f32 v51, v46, v47
	global_store_dwordx2 v41, v[50:51], s[46:47] offset:2048
	v_lshlrev_b32_e32 v36, 16, v94
	v_and_b32_e32 v37, 0xffff0000, v94
	v_lshlrev_b32_e32 v32, 16, v95
	v_and_b32_e32 v33, 0xffff0000, v95
	v_pk_fma_f32 v[14:15], v[170:171], v[32:33], v[14:15] op_sel:[1,0,0] op_sel_hi:[1,1,1] neg_lo:[1,0,0] neg_hi:[1,0,0]
	v_pk_fma_f32 v[12:13], v[170:171], v[36:37], v[12:13] op_sel:[1,0,0] op_sel_hi:[1,1,1] neg_lo:[1,0,0] neg_hi:[1,0,0]
	s_waitcnt vmcnt(31)
	v_lshlrev_b32_e32 v36, 16, v102
	v_and_b32_e32 v37, 0xffff0000, v102
	v_lshlrev_b32_e32 v32, 16, v103
	v_and_b32_e32 v33, 0xffff0000, v103
	v_pk_fma_f32 v[14:15], v[174:175], v[32:33], v[14:15] op_sel:[1,0,0] op_sel_hi:[1,1,1]
	v_pk_fma_f32 v[12:13], v[174:175], v[36:37], v[12:13] op_sel:[1,0,0] op_sel_hi:[1,1,1]
	s_add_i32 s26, s23, 16
	s_max_i32 s26, s26, s16
	s_add_i32 s27, s23, 20
	s_min_i32 s27, s27, s17
	s_sub_i32 s26, s27, s26
	v_cvt_f32_i32_e32 v35, s26
	v_lshlrev_b32_e32 v44, 16, v100
	v_div_scale_f32 v16, s[10:11], v35, v35, 1.0
	v_rcp_f32_e32 v17, v16
	v_div_scale_f32 v38, vcc, 1.0, v35, 1.0
	v_fma_f32 v39, -v16, v17, 1.0
	v_fmac_f32_e32 v17, v39, v17
	v_mul_f32_e32 v39, v38, v17
	v_fma_f32 v43, -v16, v39, v38
	v_fmac_f32_e32 v39, v43, v17
	v_fma_f32 v16, -v16, v39, v38
	v_and_b32_e32 v45, 0xffff0000, v100
	v_lshlrev_b32_e32 v46, 16, v101
	v_div_fmas_f32 v17, v16, v17, v39
	v_and_b32_e32 v47, 0xffff0000, v101
	v_div_fixup_f32 v38, v17, v35, 1.0
	v_pk_mul_f32 v[46:47], v[174:175], v[46:47] op_sel_hi:[0,1]
	v_pk_mul_f32 v[44:45], v[174:175], v[44:45] op_sel_hi:[0,1]
	v_pk_fma_f32 v[44:45], v[38:39], v[12:13], v[44:45] op_sel_hi:[0,1,1] neg_lo:[0,0,1] neg_hi:[0,0,1]
	v_pk_fma_f32 v[46:47], v[38:39], v[14:15], v[46:47] op_sel_hi:[0,1,1] neg_lo:[0,0,1] neg_hi:[0,0,1]
	v_pk_mul_f32 v[44:45], v[52:53], v[44:45]
	v_pk_mul_f32 v[46:47], v[54:55], v[46:47]
	v_cvt_pk_bf16_f32 v48, v44, v45
	v_cvt_pk_bf16_f32 v49, v46, v47
	s_add_u32 s48, s28, 36864
	s_addc_u32 s49, s29, 0
	global_store_dwordx2 v41, v[48:49], s[48:49]
	v_lshlrev_b32_e32 v36, 16, v96
	v_and_b32_e32 v37, 0xffff0000, v96
	v_lshlrev_b32_e32 v32, 16, v97
	v_and_b32_e32 v33, 0xffff0000, v97
	v_pk_fma_f32 v[14:15], v[172:173], v[32:33], v[14:15] op_sel_hi:[0,1,1] neg_lo:[1,0,0] neg_hi:[1,0,0]
	v_pk_fma_f32 v[12:13], v[172:173], v[36:37], v[12:13] op_sel_hi:[0,1,1] neg_lo:[1,0,0] neg_hi:[1,0,0]
	s_waitcnt vmcnt(31)
	v_lshlrev_b32_e32 v36, 16, v104
	v_and_b32_e32 v37, 0xffff0000, v104
	v_lshlrev_b32_e32 v32, 16, v105
	v_and_b32_e32 v33, 0xffff0000, v105
	v_pk_fma_f32 v[14:15], v[176:177], v[32:33], v[14:15] op_sel_hi:[0,1,1]
	v_pk_fma_f32 v[12:13], v[176:177], v[36:37], v[12:13] op_sel_hi:[0,1,1]
	s_add_i32 s26, s23, 17
	s_max_i32 s26, s26, s16
	s_add_i32 s27, s23, 21
	s_min_i32 s27, s27, s17
	s_sub_i32 s26, s27, s26
	v_cvt_f32_i32_e32 v35, s26
	v_lshlrev_b32_e32 v44, 16, v102
	v_div_scale_f32 v16, s[10:11], v35, v35, 1.0
	v_rcp_f32_e32 v17, v16
	v_div_scale_f32 v38, vcc, 1.0, v35, 1.0
	v_fma_f32 v39, -v16, v17, 1.0
	v_fmac_f32_e32 v17, v39, v17
	v_mul_f32_e32 v39, v38, v17
	v_fma_f32 v43, -v16, v39, v38
	v_fmac_f32_e32 v39, v43, v17
	v_fma_f32 v16, -v16, v39, v38
	v_and_b32_e32 v45, 0xffff0000, v102
	v_lshlrev_b32_e32 v46, 16, v103
	v_div_fmas_f32 v17, v16, v17, v39
	v_and_b32_e32 v47, 0xffff0000, v103
	v_div_fixup_f32 v38, v17, v35, 1.0
	v_pk_mul_f32 v[46:47], v[174:175], v[46:47] op_sel:[1,0] op_sel_hi:[1,1]
	v_pk_mul_f32 v[44:45], v[174:175], v[44:45] op_sel:[1,0] op_sel_hi:[1,1]
	v_pk_fma_f32 v[44:45], v[38:39], v[12:13], v[44:45] op_sel_hi:[0,1,1] neg_lo:[0,0,1] neg_hi:[0,0,1]
	v_pk_fma_f32 v[46:47], v[38:39], v[14:15], v[46:47] op_sel_hi:[0,1,1] neg_lo:[0,0,1] neg_hi:[0,0,1]
	v_pk_mul_f32 v[44:45], v[52:53], v[44:45]
	v_pk_mul_f32 v[46:47], v[54:55], v[46:47]
	v_cvt_pk_bf16_f32 v50, v44, v45
	v_cvt_pk_bf16_f32 v51, v46, v47
	global_store_dwordx2 v41, v[50:51], s[48:49] offset:2048
	v_lshlrev_b32_e32 v36, 16, v98
	v_and_b32_e32 v37, 0xffff0000, v98
	v_lshlrev_b32_e32 v32, 16, v99
	v_and_b32_e32 v33, 0xffff0000, v99
	v_pk_fma_f32 v[14:15], v[172:173], v[32:33], v[14:15] op_sel:[1,0,0] op_sel_hi:[1,1,1] neg_lo:[1,0,0] neg_hi:[1,0,0]
	v_pk_fma_f32 v[12:13], v[172:173], v[36:37], v[12:13] op_sel:[1,0,0] op_sel_hi:[1,1,1] neg_lo:[1,0,0] neg_hi:[1,0,0]
	s_waitcnt vmcnt(31)
; __device__ __forceinline__ unsigned pk2(float lo, float hi) { unsigned r; asm volatile("v_cvt_pk_bf16_f32 %0, %1, %2" : "=v"(r) : "v"(lo), "v"(hi)); return r; }
; __device__ __forceinline__ unsigned pk2(float lo, float hi) { return f2bf(lo) | (f2bf(hi) << 16); }
; #define LDX(tok) ({ const u32x2 _q = *(const u32x2*)(xb + (size_t)(tok) * D + cq * 4); (f32x4){bf_lo(_q.x), bf_hi(_q.x), bf_lo(_q.y), bf_hi(_q.y)} * rs[(tok) - t0 + 8]; })
; __global__ void __launch_bounds__(512, 2) fwd_megakernel(Params Pk) {
;     ...
;             for (int s = ta - hw; s <= ta + hw - 2; ++s) if (s >= sbeg && s < send) S += LDX(s);
;             for (int t = ta; t < ta + 32; ++t) {
;                 const int sin_ = t + hw - 1; if (sin_ < send) S += LDX(sin_);
;                 const int wl = (t - hw) > sbeg ? (t - hw) : sbeg, wh = (t + hw) < send ? (t + hw) : send; const float inv = 1.0f / (float)(wh - wl);
;                 const f32x4 xt = LDX(t);
;                 const f32x4 pv = (S * inv - xt) * gv;
;                 u32x2 w; w.x = pk2(pv[0], pv[1]); w.y = pk2(pv[2], pv[3]); *(u32x2*)(pbuf + (size_t)t * D + cq * 4) = w;
;                 const int sout = t - hw; if (sout >= sbeg) S -= LDX(sout);
;             }
	v_lshlrev_b32_e32 v36, 16, v106
	v_and_b32_e32 v37, 0xffff0000, v106
	v_lshlrev_b32_e32 v32, 16, v107
	v_and_b32_e32 v33, 0xffff0000, v107
	v_pk_fma_f32 v[14:15], v[176:177], v[32:33], v[14:15] op_sel:[1,0,0] op_sel_hi:[1,1,1]
	v_pk_fma_f32 v[12:13], v[176:177], v[36:37], v[12:13] op_sel:[1,0,0] op_sel_hi:[1,1,1]
	s_add_i32 s26, s23, 18
	s_max_i32 s26, s26, s16
	s_add_i32 s27, s23, 22
	s_min_i32 s27, s27, s17
	s_sub_i32 s26, s27, s26
	v_cvt_f32_i32_e32 v35, s26
	v_lshlrev_b32_e32 v44, 16, v104
	v_div_scale_f32 v16, s[10:11], v35, v35, 1.0
	v_rcp_f32_e32 v17, v16
	v_div_scale_f32 v38, vcc, 1.0, v35, 1.0
	v_fma_f32 v39, -v16, v17, 1.0
	v_fmac_f32_e32 v17, v39, v17
	v_mul_f32_e32 v39, v38, v17
	v_fma_f32 v43, -v16, v39, v38
	v_fmac_f32_e32 v39, v43, v17
	v_fma_f32 v16, -v16, v39, v38
	v_and_b32_e32 v45, 0xffff0000, v104
	v_lshlrev_b32_e32 v46, 16, v105
	v_div_fmas_f32 v17, v16, v17, v39
	v_and_b32_e32 v47, 0xffff0000, v105
	v_div_fixup_f32 v38, v17, v35, 1.0
	v_pk_mul_f32 v[46:47], v[176:177], v[46:47] op_sel_hi:[0,1]
	v_pk_mul_f32 v[44:45], v[176:177], v[44:45] op_sel_hi:[0,1]
	v_pk_fma_f32 v[44:45], v[38:39], v[12:13], v[44:45] op_sel_hi:[0,1,1] neg_lo:[0,0,1] neg_hi:[0,0,1]
	v_pk_fma_f32 v[46:47], v[38:39], v[14:15], v[46:47] op_sel_hi:[0,1,1] neg_lo:[0,0,1] neg_hi:[0,0,1]
	v_pk_mul_f32 v[44:45], v[52:53], v[44:45]
	v_pk_mul_f32 v[46:47], v[54:55], v[46:47]
	v_cvt_pk_bf16_f32 v48, v44, v45
	v_cvt_pk_bf16_f32 v49, v46, v47
	s_add_u32 s50, s28, 40960
	s_addc_u32 s51, s29, 0
	global_store_dwordx2 v41, v[48:49], s[50:51]
	v_lshlrev_b32_e32 v36, 16, v100
	v_and_b32_e32 v37, 0xffff0000, v100
	v_lshlrev_b32_e32 v32, 16, v101
	v_and_b32_e32 v33, 0xffff0000, v101
	v_pk_fma_f32 v[14:15], v[174:175], v[32:33], v[14:15] op_sel_hi:[0,1,1] neg_lo:[1,0,0] neg_hi:[1,0,0]
	v_pk_fma_f32 v[12:13], v[174:175], v[36:37], v[12:13] op_sel_hi:[0,1,1] neg_lo:[1,0,0] neg_hi:[1,0,0]
	s_waitcnt vmcnt(31)
	v_lshlrev_b32_e32 v36, 16, v108
	v_and_b32_e32 v37, 0xffff0000, v108
	v_lshlrev_b32_e32 v32, 16, v109
	v_and_b32_e32 v33, 0xffff0000, v109
	v_pk_fma_f32 v[14:15], v[178:179], v[32:33], v[14:15] op_sel_hi:[0,1,1]
	v_pk_fma_f32 v[12:13], v[178:179], v[36:37], v[12:13] op_sel_hi:[0,1,1]
	s_add_i32 s26, s23, 19
	s_max_i32 s26, s26, s16
	s_add_i32 s27, s23, 23
	s_min_i32 s27, s27, s17
	s_sub_i32 s26, s27, s26
	v_cvt_f32_i32_e32 v35, s26
	v_lshlrev_b32_e32 v44, 16, v106
	v_div_scale_f32 v16, s[10:11], v35, v35, 1.0
	v_rcp_f32_e32 v17, v16
	v_div_scale_f32 v38, vcc, 1.0, v35, 1.0
	v_fma_f32 v39, -v16, v17, 1.0
	v_fmac_f32_e32 v17, v39, v17
	v_mul_f32_e32 v39, v38, v17
	v_fma_f32 v43, -v16, v39, v38
	v_fmac_f32_e32 v39, v43, v17
	v_fma_f32 v16, -v16, v39, v38
	v_and_b32_e32 v45, 0xffff0000, v106
	v_lshlrev_b32_e32 v46, 16, v107
	v_div_fmas_f32 v17, v16, v17, v39
	v_and_b32_e32 v47, 0xffff0000, v107
	v_div_fixup_f32 v38, v17, v35, 1.0
	v_pk_mul_f32 v[46:47], v[176:177], v[46:47] op_sel:[1,0] op_sel_hi:[1,1]
	v_pk_mul_f32 v[44:45], v[176:177], v[44:45] op_sel:[1,0] op_sel_hi:[1,1]
	v_pk_fma_f32 v[44:45], v[38:39], v[12:13], v[44:45] op_sel_hi:[0,1,1] neg_lo:[0,0,1] neg_hi:[0,0,1]
	v_pk_fma_f32 v[46:47], v[38:39], v[14:15], v[46:47] op_sel_hi:[0,1,1] neg_lo:[0,0,1] neg_hi:[0,0,1]
	v_pk_mul_f32 v[44:45], v[52:53], v[44:45]
	v_pk_mul_f32 v[46:47], v[54:55], v[46:47]
	v_cvt_pk_bf16_f32 v50, v44, v45
	v_cvt_pk_bf16_f32 v51, v46, v47
	global_store_dwordx2 v41, v[50:51], s[50:51] offset:2048
	v_lshlrev_b32_e32 v36, 16, v102
	v_and_b32_e32 v37, 0xffff0000, v102
	v_lshlrev_b32_e32 v32, 16, v103
	v_and_b32_e32 v33, 0xffff0000, v103
	v_pk_fma_f32 v[14:15], v[174:175], v[32:33], v[14:15] op_sel:[1,0,0] op_sel_hi:[1,1,1] neg_lo:[1,0,0] neg_hi:[1,0,0]
	v_pk_fma_f32 v[12:13], v[174:175], v[36:37], v[12:13] op_sel:[1,0,0] op_sel_hi:[1,1,1] neg_lo:[1,0,0] neg_hi:[1,0,0]
	s_waitcnt vmcnt(31)
	v_lshlrev_b32_e32 v36, 16, v110
	v_and_b32_e32 v37, 0xffff0000, v110
	v_lshlrev_b32_e32 v32, 16, v111
	v_and_b32_e32 v33, 0xffff0000, v111
	v_pk_fma_f32 v[14:15], v[178:179], v[32:33], v[14:15] op_sel:[1,0,0] op_sel_hi:[1,1,1]
	v_pk_fma_f32 v[12:13], v[178:179], v[36:37], v[12:13] op_sel:[1,0,0] op_sel_hi:[1,1,1]
	s_add_i32 s26, s23, 20
	s_max_i32 s26, s26, s16
	s_add_i32 s27, s23, 24
	s_min_i32 s27, s27, s17
	s_sub_i32 s26, s27, s26
	v_cvt_f32_i32_e32 v35, s26
	v_lshlrev_b32_e32 v44, 16, v108
	v_div_scale_f32 v16, s[10:11], v35, v35, 1.0
	v_rcp_f32_e32 v17, v16
	v_div_scale_f32 v38, vcc, 1.0, v35, 1.0
	v_fma_f32 v39, -v16, v17, 1.0
	v_fmac_f32_e32 v17, v39, v17
	v_mul_f32_e32 v39, v38, v17
	v_fma_f32 v43, -v16, v39, v38
	v_fmac_f32_e32 v39, v43, v17
	v_fma_f32 v16, -v16, v39, v38
	v_and_b32_e32 v45, 0xffff0000, v108
	v_lshlrev_b32_e32 v46, 16, v109
	v_div_fmas_f32 v17, v16, v17, v39
	v_and_b32_e32 v47, 0xffff0000, v109
	v_div_fixup_f32 v38, v17, v35, 1.0
	v_pk_mul_f32 v[46:47], v[178:179], v[46:47] op_sel_hi:[0,1]
	v_pk_mul_f32 v[44:45], v[178:179], v[44:45] op_sel_hi:[0,1]
	v_pk_fma_f32 v[44:45], v[38:39], v[12:13], v[44:45] op_sel_hi:[0,1,1] neg_lo:[0,0,1] neg_hi:[0,0,1]
	v_pk_fma_f32 v[46:47], v[38:39], v[14:15], v[46:47] op_sel_hi:[0,1,1] neg_lo:[0,0,1] neg_hi:[0,0,1]
	v_pk_mul_f32 v[44:45], v[52:53], v[44:45]
	v_pk_mul_f32 v[46:47], v[54:55], v[46:47]
	v_cvt_pk_bf16_f32 v48, v44, v45
	v_cvt_pk_bf16_f32 v49, v46, v47
	s_add_u32 s52, s28, 45056
	s_addc_u32 s53, s29, 0
	global_store_dwordx2 v41, v[48:49], s[52:53]
	v_lshlrev_b32_e32 v36, 16, v104
	v_and_b32_e32 v37, 0xffff0000, v104
	v_lshlrev_b32_e32 v32, 16, v105
	v_and_b32_e32 v33, 0xffff0000, v105
	v_pk_fma_f32 v[14:15], v[176:177], v[32:33], v[14:15] op_sel_hi:[0,1,1] neg_lo:[1,0,0] neg_hi:[1,0,0]
	v_pk_fma_f32 v[12:13], v[176:177], v[36:37], v[12:13] op_sel_hi:[0,1,1] neg_lo:[1,0,0] neg_hi:[1,0,0]
	s_waitcnt vmcnt(31)
; __device__ __forceinline__ unsigned pk2(float lo, float hi) { unsigned r; asm volatile("v_cvt_pk_bf16_f32 %0, %1, %2" : "=v"(r) : "v"(lo), "v"(hi)); return r; }
; __device__ __forceinline__ unsigned pk2(float lo, float hi) { return f2bf(lo) | (f2bf(hi) << 16); }
; #define LDX(tok) ({ const u32x2 _q = *(const u32x2*)(xb + (size_t)(tok) * D + cq * 4); (f32x4){bf_lo(_q.x), bf_hi(_q.x), bf_lo(_q.y), bf_hi(_q.y)} * rs[(tok) - t0 + 8]; })
; __global__ void __launch_bounds__(512, 2) fwd_megakernel(Params Pk) {
;     ...
;             for (int s = ta - hw; s <= ta + hw - 2; ++s) if (s >= sbeg && s < send) S += LDX(s);
;             for (int t = ta; t < ta + 32; ++t) {
;                 const int sin_ = t + hw - 1; if (sin_ < send) S += LDX(sin_);
;                 const int wl = (t - hw) > sbeg ? (t - hw) : sbeg, wh = (t + hw) < send ? (t + hw) : send; const float inv = 1.0f / (float)(wh - wl);
;                 const f32x4 xt = LDX(t);
;                 const f32x4 pv = (S * inv - xt) * gv;
;                 u32x2 w; w.x = pk2(pv[0], pv[1]); w.y = pk2(pv[2], pv[3]); *(u32x2*)(pbuf + (size_t)t * D + cq * 4) = w;
;                 const int sout = t - hw; if (sout >= sbeg) S -= LDX(sout);
;             }
	v_lshlrev_b32_e32 v36, 16, v112
	v_and_b32_e32 v37, 0xffff0000, v112
	v_lshlrev_b32_e32 v32, 16, v113
	v_and_b32_e32 v33, 0xffff0000, v113
	v_pk_fma_f32 v[14:15], v[180:181], v[32:33], v[14:15] op_sel_hi:[0,1,1]
	v_pk_fma_f32 v[12:13], v[180:181], v[36:37], v[12:13] op_sel_hi:[0,1,1]
	s_add_i32 s26, s23, 21
	s_max_i32 s26, s26, s16
	s_add_i32 s27, s23, 25
	s_min_i32 s27, s27, s17
	s_sub_i32 s26, s27, s26
	v_cvt_f32_i32_e32 v35, s26
	v_lshlrev_b32_e32 v44, 16, v110
	v_div_scale_f32 v16, s[10:11], v35, v35, 1.0
	v_rcp_f32_e32 v17, v16
	v_div_scale_f32 v38, vcc, 1.0, v35, 1.0
	v_fma_f32 v39, -v16, v17, 1.0
	v_fmac_f32_e32 v17, v39, v17
	v_mul_f32_e32 v39, v38, v17
	v_fma_f32 v43, -v16, v39, v38
	v_fmac_f32_e32 v39, v43, v17
	v_fma_f32 v16, -v16, v39, v38
	v_and_b32_e32 v45, 0xffff0000, v110
	v_lshlrev_b32_e32 v46, 16, v111
	v_div_fmas_f32 v17, v16, v17, v39
	v_and_b32_e32 v47, 0xffff0000, v111
	v_div_fixup_f32 v38, v17, v35, 1.0
	v_pk_mul_f32 v[46:47], v[178:179], v[46:47] op_sel:[1,0] op_sel_hi:[1,1]
	v_pk_mul_f32 v[44:45], v[178:179], v[44:45] op_sel:[1,0] op_sel_hi:[1,1]
	v_pk_fma_f32 v[44:45], v[38:39], v[12:13], v[44:45] op_sel_hi:[0,1,1] neg_lo:[0,0,1] neg_hi:[0,0,1]
	v_pk_fma_f32 v[46:47], v[38:39], v[14:15], v[46:47] op_sel_hi:[0,1,1] neg_lo:[0,0,1] neg_hi:[0,0,1]
	v_pk_mul_f32 v[44:45], v[52:53], v[44:45]
	v_pk_mul_f32 v[46:47], v[54:55], v[46:47]
	v_cvt_pk_bf16_f32 v50, v44, v45
	v_cvt_pk_bf16_f32 v51, v46, v47
	global_store_dwordx2 v41, v[50:51], s[52:53] offset:2048
	v_lshlrev_b32_e32 v36, 16, v106
	v_and_b32_e32 v37, 0xffff0000, v106
	v_lshlrev_b32_e32 v32, 16, v107
	v_and_b32_e32 v33, 0xffff0000, v107
	v_pk_fma_f32 v[14:15], v[176:177], v[32:33], v[14:15] op_sel:[1,0,0] op_sel_hi:[1,1,1] neg_lo:[1,0,0] neg_hi:[1,0,0]
	v_pk_fma_f32 v[12:13], v[176:177], v[36:37], v[12:13] op_sel:[1,0,0] op_sel_hi:[1,1,1] neg_lo:[1,0,0] neg_hi:[1,0,0]
	s_waitcnt vmcnt(31)
	v_lshlrev_b32_e32 v36, 16, v114
	v_and_b32_e32 v37, 0xffff0000, v114
	v_lshlrev_b32_e32 v32, 16, v115
	v_and_b32_e32 v33, 0xffff0000, v115
	v_pk_fma_f32 v[14:15], v[180:181], v[32:33], v[14:15] op_sel:[1,0,0] op_sel_hi:[1,1,1]
	v_pk_fma_f32 v[12:13], v[180:181], v[36:37], v[12:13] op_sel:[1,0,0] op_sel_hi:[1,1,1]
	s_add_i32 s26, s23, 22
	s_max_i32 s26, s26, s16
	s_add_i32 s27, s23, 26
	s_min_i32 s27, s27, s17
	s_sub_i32 s26, s27, s26
	v_cvt_f32_i32_e32 v35, s26
	v_lshlrev_b32_e32 v44, 16, v112
	v_div_scale_f32 v16, s[10:11], v35, v35, 1.0
	v_rcp_f32_e32 v17, v16
	v_div_scale_f32 v38, vcc, 1.0, v35, 1.0
	v_fma_f32 v39, -v16, v17, 1.0
	v_fmac_f32_e32 v17, v39, v17
	v_mul_f32_e32 v39, v38, v17
	v_fma_f32 v43, -v16, v39, v38
	v_fmac_f32_e32 v39, v43, v17
	v_fma_f32 v16, -v16, v39, v38
	v_and_b32_e32 v45, 0xffff0000, v112
	v_lshlrev_b32_e32 v46, 16, v113
	v_div_fmas_f32 v17, v16, v17, v39
	v_and_b32_e32 v47, 0xffff0000, v113
	v_div_fixup_f32 v38, v17, v35, 1.0
	v_pk_mul_f32 v[46:47], v[180:181], v[46:47] op_sel_hi:[0,1]
	v_pk_mul_f32 v[44:45], v[180:181], v[44:45] op_sel_hi:[0,1]
	v_pk_fma_f32 v[44:45], v[38:39], v[12:13], v[44:45] op_sel_hi:[0,1,1] neg_lo:[0,0,1] neg_hi:[0,0,1]
	v_pk_fma_f32 v[46:47], v[38:39], v[14:15], v[46:47] op_sel_hi:[0,1,1] neg_lo:[0,0,1] neg_hi:[0,0,1]
	v_pk_mul_f32 v[44:45], v[52:53], v[44:45]
	v_pk_mul_f32 v[46:47], v[54:55], v[46:47]
	v_cvt_pk_bf16_f32 v48, v44, v45
	v_cvt_pk_bf16_f32 v49, v46, v47
	s_add_u32 s46, s28, 49152
	s_addc_u32 s47, s29, 0
	global_store_dwordx2 v41, v[48:49], s[46:47]
	v_lshlrev_b32_e32 v36, 16, v108
	v_and_b32_e32 v37, 0xffff0000, v108
	v_lshlrev_b32_e32 v32, 16, v109
	v_and_b32_e32 v33, 0xffff0000, v109
	v_pk_fma_f32 v[14:15], v[178:179], v[32:33], v[14:15] op_sel_hi:[0,1,1] neg_lo:[1,0,0] neg_hi:[1,0,0]
	v_pk_fma_f32 v[12:13], v[178:179], v[36:37], v[12:13] op_sel_hi:[0,1,1] neg_lo:[1,0,0] neg_hi:[1,0,0]
	s_waitcnt vmcnt(31)
	v_lshlrev_b32_e32 v36, 16, v116
	v_and_b32_e32 v37, 0xffff0000, v116
	v_lshlrev_b32_e32 v32, 16, v117
	v_and_b32_e32 v33, 0xffff0000, v117
	v_pk_fma_f32 v[14:15], v[182:183], v[32:33], v[14:15] op_sel_hi:[0,1,1]
	v_pk_fma_f32 v[12:13], v[182:183], v[36:37], v[12:13] op_sel_hi:[0,1,1]
	s_add_i32 s26, s23, 23
	s_max_i32 s26, s26, s16
	s_add_i32 s27, s23, 27
	s_min_i32 s27, s27, s17
	s_sub_i32 s26, s27, s26
	v_cvt_f32_i32_e32 v35, s26
	v_lshlrev_b32_e32 v44, 16, v114
	v_div_scale_f32 v16, s[10:11], v35, v35, 1.0
	v_rcp_f32_e32 v17, v16
	v_div_scale_f32 v38, vcc, 1.0, v35, 1.0
	v_fma_f32 v39, -v16, v17, 1.0
	v_fmac_f32_e32 v17, v39, v17
	v_mul_f32_e32 v39, v38, v17
	v_fma_f32 v43, -v16, v39, v38
	v_fmac_f32_e32 v39, v43, v17
	v_fma_f32 v16, -v16, v39, v38
	v_and_b32_e32 v45, 0xffff0000, v114
	v_lshlrev_b32_e32 v46, 16, v115
	v_div_fmas_f32 v17, v16, v17, v39
	v_and_b32_e32 v47, 0xffff0000, v115
	v_div_fixup_f32 v38, v17, v35, 1.0
	v_pk_mul_f32 v[46:47], v[180:181], v[46:47] op_sel:[1,0] op_sel_hi:[1,1]
	v_pk_mul_f32 v[44:45], v[180:181], v[44:45] op_sel:[1,0] op_sel_hi:[1,1]
	v_pk_fma_f32 v[44:45], v[38:39], v[12:13], v[44:45] op_sel_hi:[0,1,1] neg_lo:[0,0,1] neg_hi:[0,0,1]
	v_pk_fma_f32 v[46:47], v[38:39], v[14:15], v[46:47] op_sel_hi:[0,1,1] neg_lo:[0,0,1] neg_hi:[0,0,1]
	v_pk_mul_f32 v[44:45], v[52:53], v[44:45]
	v_pk_mul_f32 v[46:47], v[54:55], v[46:47]
	v_cvt_pk_bf16_f32 v50, v44, v45
	v_cvt_pk_bf16_f32 v51, v46, v47
	global_store_dwordx2 v41, v[50:51], s[46:47] offset:2048
	v_lshlrev_b32_e32 v36, 16, v110
	v_and_b32_e32 v37, 0xffff0000, v110
	v_lshlrev_b32_e32 v32, 16, v111
	v_and_b32_e32 v33, 0xffff0000, v111
	v_pk_fma_f32 v[14:15], v[178:179], v[32:33], v[14:15] op_sel:[1,0,0] op_sel_hi:[1,1,1] neg_lo:[1,0,0] neg_hi:[1,0,0]
	v_pk_fma_f32 v[12:13], v[178:179], v[36:37], v[12:13] op_sel:[1,0,0] op_sel_hi:[1,1,1] neg_lo:[1,0,0] neg_hi:[1,0,0]
	s_waitcnt vmcnt(31)
; __device__ __forceinline__ unsigned pk2(float lo, float hi) { unsigned r; asm volatile("v_cvt_pk_bf16_f32 %0, %1, %2" : "=v"(r) : "v"(lo), "v"(hi)); return r; }
; __device__ __forceinline__ unsigned pk2(float lo, float hi) { return f2bf(lo) | (f2bf(hi) << 16); }
; #define LDX(tok) ({ const u32x2 _q = *(const u32x2*)(xb + (size_t)(tok) * D + cq * 4); (f32x4){bf_lo(_q.x), bf_hi(_q.x), bf_lo(_q.y), bf_hi(_q.y)} * rs[(tok) - t0 + 8]; })
; __global__ void __launch_bounds__(512, 2) fwd_megakernel(Params Pk) {
;     ...
;             for (int s = ta - hw; s <= ta + hw - 2; ++s) if (s >= sbeg && s < send) S += LDX(s);
;             for (int t = ta; t < ta + 32; ++t) {
;                 const int sin_ = t + hw - 1; if (sin_ < send) S += LDX(sin_);
;                 const int wl = (t - hw) > sbeg ? (t - hw) : sbeg, wh = (t + hw) < send ? (t + hw) : send; const float inv = 1.0f / (float)(wh - wl);
;                 const f32x4 xt = LDX(t);
;                 const f32x4 pv = (S * inv - xt) * gv;
;                 u32x2 w; w.x = pk2(pv[0], pv[1]); w.y = pk2(pv[2], pv[3]); *(u32x2*)(pbuf + (size_t)t * D + cq * 4) = w;
;                 const int sout = t - hw; if (sout >= sbeg) S -= LDX(sout);
;             }
	v_lshlrev_b32_e32 v36, 16, v118
	v_and_b32_e32 v37, 0xffff0000, v118
	v_lshlrev_b32_e32 v32, 16, v119
	v_and_b32_e32 v33, 0xffff0000, v119
	v_pk_fma_f32 v[14:15], v[182:183], v[32:33], v[14:15] op_sel:[1,0,0] op_sel_hi:[1,1,1]
	v_pk_fma_f32 v[12:13], v[182:183], v[36:37], v[12:13] op_sel:[1,0,0] op_sel_hi:[1,1,1]
	s_add_i32 s26, s23, 24
	s_max_i32 s26, s26, s16
	s_add_i32 s27, s23, 28
	s_min_i32 s27, s27, s17
	s_sub_i32 s26, s27, s26
	v_cvt_f32_i32_e32 v35, s26
	v_lshlrev_b32_e32 v44, 16, v116
	v_div_scale_f32 v16, s[10:11], v35, v35, 1.0
	v_rcp_f32_e32 v17, v16
	v_div_scale_f32 v38, vcc, 1.0, v35, 1.0
	v_fma_f32 v39, -v16, v17, 1.0
	v_fmac_f32_e32 v17, v39, v17
	v_mul_f32_e32 v39, v38, v17
	v_fma_f32 v43, -v16, v39, v38
	v_fmac_f32_e32 v39, v43, v17
	v_fma_f32 v16, -v16, v39, v38
	v_and_b32_e32 v45, 0xffff0000, v116
	v_lshlrev_b32_e32 v46, 16, v117
	v_div_fmas_f32 v17, v16, v17, v39
	v_and_b32_e32 v47, 0xffff0000, v117
	v_div_fixup_f32 v38, v17, v35, 1.0
	v_pk_mul_f32 v[46:47], v[182:183], v[46:47] op_sel_hi:[0,1]
	v_pk_mul_f32 v[44:45], v[182:183], v[44:45] op_sel_hi:[0,1]
	v_pk_fma_f32 v[44:45], v[38:39], v[12:13], v[44:45] op_sel_hi:[0,1,1] neg_lo:[0,0,1] neg_hi:[0,0,1]
	v_pk_fma_f32 v[46:47], v[38:39], v[14:15], v[46:47] op_sel_hi:[0,1,1] neg_lo:[0,0,1] neg_hi:[0,0,1]
	v_pk_mul_f32 v[44:45], v[52:53], v[44:45]
	v_pk_mul_f32 v[46:47], v[54:55], v[46:47]
	v_cvt_pk_bf16_f32 v48, v44, v45
	v_cvt_pk_bf16_f32 v49, v46, v47
	s_add_u32 s48, s28, 53248
	s_addc_u32 s49, s29, 0
	global_store_dwordx2 v41, v[48:49], s[48:49]
	v_lshlrev_b32_e32 v36, 16, v112
	v_and_b32_e32 v37, 0xffff0000, v112
	v_lshlrev_b32_e32 v32, 16, v113
	v_and_b32_e32 v33, 0xffff0000, v113
	v_pk_fma_f32 v[14:15], v[180:181], v[32:33], v[14:15] op_sel_hi:[0,1,1] neg_lo:[1,0,0] neg_hi:[1,0,0]
	v_pk_fma_f32 v[12:13], v[180:181], v[36:37], v[12:13] op_sel_hi:[0,1,1] neg_lo:[1,0,0] neg_hi:[1,0,0]
	s_waitcnt vmcnt(31)
	v_lshlrev_b32_e32 v36, 16, v120
	v_and_b32_e32 v37, 0xffff0000, v120
	v_lshlrev_b32_e32 v32, 16, v121
	v_and_b32_e32 v33, 0xffff0000, v121
	v_pk_fma_f32 v[14:15], v[184:185], v[32:33], v[14:15] op_sel_hi:[0,1,1]
	v_pk_fma_f32 v[12:13], v[184:185], v[36:37], v[12:13] op_sel_hi:[0,1,1]
	s_add_i32 s26, s23, 25
	s_max_i32 s26, s26, s16
	s_add_i32 s27, s23, 29
	s_min_i32 s27, s27, s17
	s_sub_i32 s26, s27, s26
	v_cvt_f32_i32_e32 v35, s26
	v_lshlrev_b32_e32 v44, 16, v118
	v_div_scale_f32 v16, s[10:11], v35, v35, 1.0
	v_rcp_f32_e32 v17, v16
	v_div_scale_f32 v38, vcc, 1.0, v35, 1.0
	v_fma_f32 v39, -v16, v17, 1.0
	v_fmac_f32_e32 v17, v39, v17
	v_mul_f32_e32 v39, v38, v17
	v_fma_f32 v43, -v16, v39, v38
	v_fmac_f32_e32 v39, v43, v17
	v_fma_f32 v16, -v16, v39, v38
	v_and_b32_e32 v45, 0xffff0000, v118
	v_lshlrev_b32_e32 v46, 16, v119
	v_div_fmas_f32 v17, v16, v17, v39
	v_and_b32_e32 v47, 0xffff0000, v119
	v_div_fixup_f32 v38, v17, v35, 1.0
	v_pk_mul_f32 v[46:47], v[182:183], v[46:47] op_sel:[1,0] op_sel_hi:[1,1]
	v_pk_mul_f32 v[44:45], v[182:183], v[44:45] op_sel:[1,0] op_sel_hi:[1,1]
	v_pk_fma_f32 v[44:45], v[38:39], v[12:13], v[44:45] op_sel_hi:[0,1,1] neg_lo:[0,0,1] neg_hi:[0,0,1]
	v_pk_fma_f32 v[46:47], v[38:39], v[14:15], v[46:47] op_sel_hi:[0,1,1] neg_lo:[0,0,1] neg_hi:[0,0,1]
	v_pk_mul_f32 v[44:45], v[52:53], v[44:45]
	v_pk_mul_f32 v[46:47], v[54:55], v[46:47]
	v_cvt_pk_bf16_f32 v50, v44, v45
	v_cvt_pk_bf16_f32 v51, v46, v47
	global_store_dwordx2 v41, v[50:51], s[48:49] offset:2048
	v_lshlrev_b32_e32 v36, 16, v114
	v_and_b32_e32 v37, 0xffff0000, v114
	v_lshlrev_b32_e32 v32, 16, v115
	v_and_b32_e32 v33, 0xffff0000, v115
	v_pk_fma_f32 v[14:15], v[180:181], v[32:33], v[14:15] op_sel:[1,0,0] op_sel_hi:[1,1,1] neg_lo:[1,0,0] neg_hi:[1,0,0]
	v_pk_fma_f32 v[12:13], v[180:181], v[36:37], v[12:13] op_sel:[1,0,0] op_sel_hi:[1,1,1] neg_lo:[1,0,0] neg_hi:[1,0,0]
	s_waitcnt vmcnt(31)
	v_lshlrev_b32_e32 v36, 16, v122
	v_and_b32_e32 v37, 0xffff0000, v122
	v_lshlrev_b32_e32 v32, 16, v123
	v_and_b32_e32 v33, 0xffff0000, v123
	v_pk_fma_f32 v[14:15], v[184:185], v[32:33], v[14:15] op_sel:[1,0,0] op_sel_hi:[1,1,1]
	v_pk_fma_f32 v[12:13], v[184:185], v[36:37], v[12:13] op_sel:[1,0,0] op_sel_hi:[1,1,1]
	s_add_i32 s26, s23, 26
	s_max_i32 s26, s26, s16
	s_add_i32 s27, s23, 30
	s_min_i32 s27, s27, s17
	s_sub_i32 s26, s27, s26
	v_cvt_f32_i32_e32 v35, s26
	v_lshlrev_b32_e32 v44, 16, v120
	v_div_scale_f32 v16, s[10:11], v35, v35, 1.0
	v_rcp_f32_e32 v17, v16
	v_div_scale_f32 v38, vcc, 1.0, v35, 1.0
	v_fma_f32 v39, -v16, v17, 1.0
	v_fmac_f32_e32 v17, v39, v17
	v_mul_f32_e32 v39, v38, v17
	v_fma_f32 v43, -v16, v39, v38
	v_fmac_f32_e32 v39, v43, v17
	v_fma_f32 v16, -v16, v39, v38
	v_and_b32_e32 v45, 0xffff0000, v120
	v_lshlrev_b32_e32 v46, 16, v121
	v_div_fmas_f32 v17, v16, v17, v39
	v_and_b32_e32 v47, 0xffff0000, v121
	v_div_fixup_f32 v38, v17, v35, 1.0
	v_pk_mul_f32 v[46:47], v[184:185], v[46:47] op_sel_hi:[0,1]
	v_pk_mul_f32 v[44:45], v[184:185], v[44:45] op_sel_hi:[0,1]
	v_pk_fma_f32 v[44:45], v[38:39], v[12:13], v[44:45] op_sel_hi:[0,1,1] neg_lo:[0,0,1] neg_hi:[0,0,1]
	v_pk_fma_f32 v[46:47], v[38:39], v[14:15], v[46:47] op_sel_hi:[0,1,1] neg_lo:[0,0,1] neg_hi:[0,0,1]
	v_pk_mul_f32 v[44:45], v[52:53], v[44:45]
	v_pk_mul_f32 v[46:47], v[54:55], v[46:47]
	v_cvt_pk_bf16_f32 v48, v44, v45
	v_cvt_pk_bf16_f32 v49, v46, v47
	s_add_u32 s50, s28, 57344
	s_addc_u32 s51, s29, 0
	global_store_dwordx2 v41, v[48:49], s[50:51]
	v_lshlrev_b32_e32 v36, 16, v116
	v_and_b32_e32 v37, 0xffff0000, v116
	v_lshlrev_b32_e32 v32, 16, v117
	v_and_b32_e32 v33, 0xffff0000, v117
	v_pk_fma_f32 v[14:15], v[182:183], v[32:33], v[14:15] op_sel_hi:[0,1,1] neg_lo:[1,0,0] neg_hi:[1,0,0]
	v_pk_fma_f32 v[12:13], v[182:183], v[36:37], v[12:13] op_sel_hi:[0,1,1] neg_lo:[1,0,0] neg_hi:[1,0,0]
	s_waitcnt vmcnt(31)
; __device__ __forceinline__ unsigned pk2(float lo, float hi) { unsigned r; asm volatile("v_cvt_pk_bf16_f32 %0, %1, %2" : "=v"(r) : "v"(lo), "v"(hi)); return r; }
; __device__ __forceinline__ unsigned pk2(float lo, float hi) { return f2bf(lo) | (f2bf(hi) << 16); }
; #define LDX(tok) ({ const u32x2 _q = *(const u32x2*)(xb + (size_t)(tok) * D + cq * 4); (f32x4){bf_lo(_q.x), bf_hi(_q.x), bf_lo(_q.y), bf_hi(_q.y)} * rs[(tok) - t0 + 8]; })
; __global__ void __launch_bounds__(512, 2) fwd_megakernel(Params Pk) {
;     ...
;             for (int s = ta - hw; s <= ta + hw - 2; ++s) if (s >= sbeg && s < send) S += LDX(s);
;             for (int t = ta; t < ta + 32; ++t) {
;                 const int sin_ = t + hw - 1; if (sin_ < send) S += LDX(sin_);
;                 const int wl = (t - hw) > sbeg ? (t - hw) : sbeg, wh = (t + hw) < send ? (t + hw) : send; const float inv = 1.0f / (float)(wh - wl);
;                 const f32x4 xt = LDX(t);
;                 const f32x4 pv = (S * inv - xt) * gv;
;                 u32x2 w; w.x = pk2(pv[0], pv[1]); w.y = pk2(pv[2], pv[3]); *(u32x2*)(pbuf + (size_t)t * D + cq * 4) = w;
;                 const int sout = t - hw; if (sout >= sbeg) S -= LDX(sout);
;             }
	v_lshlrev_b32_e32 v36, 16, v124
	v_and_b32_e32 v37, 0xffff0000, v124
	v_lshlrev_b32_e32 v32, 16, v125
	v_and_b32_e32 v33, 0xffff0000, v125
	v_pk_fma_f32 v[14:15], v[186:187], v[32:33], v[14:15] op_sel_hi:[0,1,1]
	v_pk_fma_f32 v[12:13], v[186:187], v[36:37], v[12:13] op_sel_hi:[0,1,1]
	s_add_i32 s26, s23, 27
	s_max_i32 s26, s26, s16
	s_add_i32 s27, s23, 31
	s_min_i32 s27, s27, s17
	s_sub_i32 s26, s27, s26
	v_cvt_f32_i32_e32 v35, s26
	v_lshlrev_b32_e32 v44, 16, v122
	v_div_scale_f32 v16, s[10:11], v35, v35, 1.0
	v_rcp_f32_e32 v17, v16
	v_div_scale_f32 v38, vcc, 1.0, v35, 1.0
	v_fma_f32 v39, -v16, v17, 1.0
	v_fmac_f32_e32 v17, v39, v17
	v_mul_f32_e32 v39, v38, v17
	v_fma_f32 v43, -v16, v39, v38
	v_fmac_f32_e32 v39, v43, v17
	v_fma_f32 v16, -v16, v39, v38
	v_and_b32_e32 v45, 0xffff0000, v122
	v_lshlrev_b32_e32 v46, 16, v123
	v_div_fmas_f32 v17, v16, v17, v39
	v_and_b32_e32 v47, 0xffff0000, v123
	v_div_fixup_f32 v38, v17, v35, 1.0
	v_pk_mul_f32 v[46:47], v[184:185], v[46:47] op_sel:[1,0] op_sel_hi:[1,1]
	v_pk_mul_f32 v[44:45], v[184:185], v[44:45] op_sel:[1,0] op_sel_hi:[1,1]
	v_pk_fma_f32 v[44:45], v[38:39], v[12:13], v[44:45] op_sel_hi:[0,1,1] neg_lo:[0,0,1] neg_hi:[0,0,1]
	v_pk_fma_f32 v[46:47], v[38:39], v[14:15], v[46:47] op_sel_hi:[0,1,1] neg_lo:[0,0,1] neg_hi:[0,0,1]
	v_pk_mul_f32 v[44:45], v[52:53], v[44:45]
	v_pk_mul_f32 v[46:47], v[54:55], v[46:47]
	v_cvt_pk_bf16_f32 v50, v44, v45
	v_cvt_pk_bf16_f32 v51, v46, v47
	global_store_dwordx2 v41, v[50:51], s[50:51] offset:2048
	v_lshlrev_b32_e32 v36, 16, v118
	v_and_b32_e32 v37, 0xffff0000, v118
	v_lshlrev_b32_e32 v32, 16, v119
	v_and_b32_e32 v33, 0xffff0000, v119
	v_pk_fma_f32 v[14:15], v[182:183], v[32:33], v[14:15] op_sel:[1,0,0] op_sel_hi:[1,1,1] neg_lo:[1,0,0] neg_hi:[1,0,0]
	v_pk_fma_f32 v[12:13], v[182:183], v[36:37], v[12:13] op_sel:[1,0,0] op_sel_hi:[1,1,1] neg_lo:[1,0,0] neg_hi:[1,0,0]
	s_waitcnt vmcnt(31)
	v_lshlrev_b32_e32 v36, 16, v126
	v_and_b32_e32 v37, 0xffff0000, v126
	v_lshlrev_b32_e32 v32, 16, v127
	v_and_b32_e32 v33, 0xffff0000, v127
	v_pk_fma_f32 v[14:15], v[186:187], v[32:33], v[14:15] op_sel:[1,0,0] op_sel_hi:[1,1,1]
	v_pk_fma_f32 v[12:13], v[186:187], v[36:37], v[12:13] op_sel:[1,0,0] op_sel_hi:[1,1,1]
	s_add_i32 s26, s23, 28
	s_max_i32 s26, s26, s16
	s_add_i32 s27, s23, 32
	s_min_i32 s27, s27, s17
	s_sub_i32 s26, s27, s26
	v_cvt_f32_i32_e32 v35, s26
	v_lshlrev_b32_e32 v44, 16, v124
	v_div_scale_f32 v16, s[10:11], v35, v35, 1.0
	v_rcp_f32_e32 v17, v16
	v_div_scale_f32 v38, vcc, 1.0, v35, 1.0
	v_fma_f32 v39, -v16, v17, 1.0
	v_fmac_f32_e32 v17, v39, v17
	v_mul_f32_e32 v39, v38, v17
	v_fma_f32 v43, -v16, v39, v38
	v_fmac_f32_e32 v39, v43, v17
	v_fma_f32 v16, -v16, v39, v38
	v_and_b32_e32 v45, 0xffff0000, v124
	v_lshlrev_b32_e32 v46, 16, v125
	v_div_fmas_f32 v17, v16, v17, v39
	v_and_b32_e32 v47, 0xffff0000, v125
	v_div_fixup_f32 v38, v17, v35, 1.0
	v_pk_mul_f32 v[46:47], v[186:187], v[46:47] op_sel_hi:[0,1]
	v_pk_mul_f32 v[44:45], v[186:187], v[44:45] op_sel_hi:[0,1]
	v_pk_fma_f32 v[44:45], v[38:39], v[12:13], v[44:45] op_sel_hi:[0,1,1] neg_lo:[0,0,1] neg_hi:[0,0,1]
	v_pk_fma_f32 v[46:47], v[38:39], v[14:15], v[46:47] op_sel_hi:[0,1,1] neg_lo:[0,0,1] neg_hi:[0,0,1]
	v_pk_mul_f32 v[44:45], v[52:53], v[44:45]
	v_pk_mul_f32 v[46:47], v[54:55], v[46:47]
	v_cvt_pk_bf16_f32 v48, v44, v45
	v_cvt_pk_bf16_f32 v49, v46, v47
	s_add_u32 s52, s28, 61440
	s_addc_u32 s53, s29, 0
	global_store_dwordx2 v41, v[48:49], s[52:53]
	v_lshlrev_b32_e32 v36, 16, v120
	v_and_b32_e32 v37, 0xffff0000, v120
	v_lshlrev_b32_e32 v32, 16, v121
	v_and_b32_e32 v33, 0xffff0000, v121
	v_pk_fma_f32 v[14:15], v[184:185], v[32:33], v[14:15] op_sel_hi:[0,1,1] neg_lo:[1,0,0] neg_hi:[1,0,0]
	v_pk_fma_f32 v[12:13], v[184:185], v[36:37], v[12:13] op_sel_hi:[0,1,1] neg_lo:[1,0,0] neg_hi:[1,0,0]
	s_waitcnt vmcnt(31)
	v_lshlrev_b32_e32 v36, 16, v128
	v_and_b32_e32 v37, 0xffff0000, v128
	v_lshlrev_b32_e32 v32, 16, v129
	v_and_b32_e32 v33, 0xffff0000, v129
	v_pk_fma_f32 v[14:15], v[188:189], v[32:33], v[14:15] op_sel_hi:[0,1,1]
	v_pk_fma_f32 v[12:13], v[188:189], v[36:37], v[12:13] op_sel_hi:[0,1,1]
	s_add_i32 s26, s23, 29
	s_max_i32 s26, s26, s16
	s_add_i32 s27, s23, 33
	s_min_i32 s27, s27, s17
	s_sub_i32 s26, s27, s26
	v_cvt_f32_i32_e32 v35, s26
	v_lshlrev_b32_e32 v44, 16, v126
	v_div_scale_f32 v16, s[10:11], v35, v35, 1.0
	v_rcp_f32_e32 v17, v16
	v_div_scale_f32 v38, vcc, 1.0, v35, 1.0
	v_fma_f32 v39, -v16, v17, 1.0
	v_fmac_f32_e32 v17, v39, v17
	v_mul_f32_e32 v39, v38, v17
	v_fma_f32 v43, -v16, v39, v38
	v_fmac_f32_e32 v39, v43, v17
	v_fma_f32 v16, -v16, v39, v38
	v_and_b32_e32 v45, 0xffff0000, v126
	v_lshlrev_b32_e32 v46, 16, v127
	v_div_fmas_f32 v17, v16, v17, v39
	v_and_b32_e32 v47, 0xffff0000, v127
	v_div_fixup_f32 v38, v17, v35, 1.0
	v_pk_mul_f32 v[46:47], v[186:187], v[46:47] op_sel:[1,0] op_sel_hi:[1,1]
	v_pk_mul_f32 v[44:45], v[186:187], v[44:45] op_sel:[1,0] op_sel_hi:[1,1]
	v_pk_fma_f32 v[44:45], v[38:39], v[12:13], v[44:45] op_sel_hi:[0,1,1] neg_lo:[0,0,1] neg_hi:[0,0,1]
	v_pk_fma_f32 v[46:47], v[38:39], v[14:15], v[46:47] op_sel_hi:[0,1,1] neg_lo:[0,0,1] neg_hi:[0,0,1]
	v_pk_mul_f32 v[44:45], v[52:53], v[44:45]
	v_pk_mul_f32 v[46:47], v[54:55], v[46:47]
	v_cvt_pk_bf16_f32 v50, v44, v45
	v_cvt_pk_bf16_f32 v51, v46, v47
	global_store_dwordx2 v41, v[50:51], s[52:53] offset:2048
	v_lshlrev_b32_e32 v36, 16, v122
	v_and_b32_e32 v37, 0xffff0000, v122
	v_lshlrev_b32_e32 v32, 16, v123
	v_and_b32_e32 v33, 0xffff0000, v123
	v_pk_fma_f32 v[14:15], v[184:185], v[32:33], v[14:15] op_sel:[1,0,0] op_sel_hi:[1,1,1] neg_lo:[1,0,0] neg_hi:[1,0,0]
	v_pk_fma_f32 v[12:13], v[184:185], v[36:37], v[12:13] op_sel:[1,0,0] op_sel_hi:[1,1,1] neg_lo:[1,0,0] neg_hi:[1,0,0]
	s_branch .Lp13_tail
; __device__ __forceinline__ unsigned pk2(float lo, float hi) { unsigned r; asm volatile("v_cvt_pk_bf16_f32 %0, %1, %2" : "=v"(r) : "v"(lo), "v"(hi)); return r; }
; __device__ __forceinline__ unsigned pk2(float lo, float hi) { return f2bf(lo) | (f2bf(hi) << 16); }
; #define LDX(tok) ({ const u32x2 _q = *(const u32x2*)(xb + (size_t)(tok) * D + cq * 4); (f32x4){bf_lo(_q.x), bf_hi(_q.x), bf_lo(_q.y), bf_hi(_q.y)} * rs[(tok) - t0 + 8]; })
; __global__ void __launch_bounds__(512, 2) fwd_megakernel(Params Pk) {
;     ...
;             for (int s = ta - hw; s <= ta + hw - 2; ++s) if (s >= sbeg && s < send) S += LDX(s);
;             for (int t = ta; t < ta + 32; ++t) {
;                 const int sin_ = t + hw - 1; if (sin_ < send) S += LDX(sin_);
;                 const int wl = (t - hw) > sbeg ? (t - hw) : sbeg, wh = (t + hw) < send ? (t + hw) : send; const float inv = 1.0f / (float)(wh - wl);
;                 const f32x4 xt = LDX(t);
;                 const f32x4 pv = (S * inv - xt) * gv;
;                 u32x2 w; w.x = pk2(pv[0], pv[1]); w.y = pk2(pv[2], pv[3]); *(u32x2*)(pbuf + (size_t)t * D + cq * 4) = w;
;                 const int sout = t - hw; if (sout >= sbeg) S -= LDX(sout);
;             }
.Lp13_hw4:
	ds_read_b32 v154, v42 offset:16
	ds_read_b32 v155, v42 offset:20
	ds_read_b32 v156, v42 offset:24
	ds_read_b32 v157, v42 offset:28
	ds_read_b32 v158, v42 offset:32
	ds_read_b32 v159, v42 offset:36
	ds_read_b32 v160, v42 offset:40
	ds_read_b32 v161, v42 offset:44
	ds_read_b32 v162, v42 offset:48
	ds_read_b32 v163, v42 offset:52
	ds_read_b32 v164, v42 offset:56
	ds_read_b32 v165, v42 offset:60
	ds_read_b32 v166, v42 offset:64
	ds_read_b32 v167, v42 offset:68
	ds_read_b32 v168, v42 offset:72
	ds_read_b32 v169, v42 offset:76
	ds_read_b32 v170, v42 offset:80
	ds_read_b32 v171, v42 offset:84
	ds_read_b32 v172, v42 offset:88
	ds_read_b32 v173, v42 offset:92
	ds_read_b32 v174, v42 offset:96
	ds_read_b32 v175, v42 offset:100
	ds_read_b32 v176, v42 offset:104
	ds_read_b32 v177, v42 offset:108
	ds_read_b32 v178, v42 offset:112
	ds_read_b32 v179, v42 offset:116
	ds_read_b32 v180, v42 offset:120
	ds_read_b32 v181, v42 offset:124
	ds_read_b32 v182, v42 offset:128
	ds_read_b32 v183, v42 offset:132
	ds_read_b32 v184, v42 offset:136
	ds_read_b32 v185, v42 offset:140
	ds_read_b32 v186, v42 offset:144
	ds_read_b32 v187, v42 offset:148
	ds_read_b32 v188, v42 offset:152
	ds_read_b32 v189, v42 offset:156
	ds_read_b32 v190, v42 offset:160
	ds_read_b32 v191, v42 offset:164
	ds_read_b32 v192, v42 offset:168
	v_mov_b32_e32 v12, 0
	v_mov_b32_e32 v13, 0
	v_mov_b32_e32 v14, 0
	v_mov_b32_e32 v15, 0
	s_waitcnt lgkmcnt(0)
	s_waitcnt vmcnt(38)
	v_lshlrev_b32_e32 v36, 16, v60
	v_and_b32_e32 v37, 0xffff0000, v60
	v_lshlrev_b32_e32 v32, 16, v61
	v_and_b32_e32 v33, 0xffff0000, v61
	v_pk_fma_f32 v[14:15], v[154:155], v[32:33], v[14:15] op_sel_hi:[0,1,1]
	v_pk_fma_f32 v[12:13], v[154:155], v[36:37], v[12:13] op_sel_hi:[0,1,1]
	s_waitcnt vmcnt(37)
	v_lshlrev_b32_e32 v36, 16, v62
	v_and_b32_e32 v37, 0xffff0000, v62
	v_lshlrev_b32_e32 v32, 16, v63
	v_and_b32_e32 v33, 0xffff0000, v63
	v_pk_fma_f32 v[14:15], v[154:155], v[32:33], v[14:15] op_sel:[1,0,0] op_sel_hi:[1,1,1]
	v_pk_fma_f32 v[12:13], v[154:155], v[36:37], v[12:13] op_sel:[1,0,0] op_sel_hi:[1,1,1]
	s_waitcnt vmcnt(36)
	v_lshlrev_b32_e32 v36, 16, v64
	v_and_b32_e32 v37, 0xffff0000, v64
	v_lshlrev_b32_e32 v32, 16, v65
	v_and_b32_e32 v33, 0xffff0000, v65
	v_pk_fma_f32 v[14:15], v[156:157], v[32:33], v[14:15] op_sel_hi:[0,1,1]
	v_pk_fma_f32 v[12:13], v[156:157], v[36:37], v[12:13] op_sel_hi:[0,1,1]
	s_waitcnt vmcnt(35)
	v_lshlrev_b32_e32 v36, 16, v66
	v_and_b32_e32 v37, 0xffff0000, v66
	v_lshlrev_b32_e32 v32, 16, v67
	v_and_b32_e32 v33, 0xffff0000, v67
	v_pk_fma_f32 v[14:15], v[156:157], v[32:33], v[14:15] op_sel:[1,0,0] op_sel_hi:[1,1,1]
	v_pk_fma_f32 v[12:13], v[156:157], v[36:37], v[12:13] op_sel:[1,0,0] op_sel_hi:[1,1,1]
	s_waitcnt vmcnt(34)
	v_lshlrev_b32_e32 v36, 16, v68
	v_and_b32_e32 v37, 0xffff0000, v68
	v_lshlrev_b32_e32 v32, 16, v69
	v_and_b32_e32 v33, 0xffff0000, v69
	v_pk_fma_f32 v[14:15], v[158:159], v[32:33], v[14:15] op_sel_hi:[0,1,1]
	v_pk_fma_f32 v[12:13], v[158:159], v[36:37], v[12:13] op_sel_hi:[0,1,1]
	s_waitcnt vmcnt(33)
	v_lshlrev_b32_e32 v36, 16, v70
	v_and_b32_e32 v37, 0xffff0000, v70
	v_lshlrev_b32_e32 v32, 16, v71
	v_and_b32_e32 v33, 0xffff0000, v71
	v_pk_fma_f32 v[14:15], v[158:159], v[32:33], v[14:15] op_sel:[1,0,0] op_sel_hi:[1,1,1]
	v_pk_fma_f32 v[12:13], v[158:159], v[36:37], v[12:13] op_sel:[1,0,0] op_sel_hi:[1,1,1]
	s_waitcnt vmcnt(32)
	v_lshlrev_b32_e32 v36, 16, v72
	v_and_b32_e32 v37, 0xffff0000, v72
	v_lshlrev_b32_e32 v32, 16, v73
	v_and_b32_e32 v33, 0xffff0000, v73
	v_pk_fma_f32 v[14:15], v[160:161], v[32:33], v[14:15] op_sel_hi:[0,1,1]
	v_pk_fma_f32 v[12:13], v[160:161], v[36:37], v[12:13] op_sel_hi:[0,1,1]
	s_waitcnt vmcnt(31)
	v_lshlrev_b32_e32 v36, 16, v74
	v_and_b32_e32 v37, 0xffff0000, v74
	v_lshlrev_b32_e32 v32, 16, v75
	v_and_b32_e32 v33, 0xffff0000, v75
	v_pk_fma_f32 v[14:15], v[160:161], v[32:33], v[14:15] op_sel:[1,0,0] op_sel_hi:[1,1,1]
	v_pk_fma_f32 v[12:13], v[160:161], v[36:37], v[12:13] op_sel:[1,0,0] op_sel_hi:[1,1,1]
	s_add_i32 s26, s23, -4
	s_max_i32 s26, s26, s16
	s_add_i32 s27, s23, 4
	s_min_i32 s27, s27, s17
	s_sub_i32 s26, s27, s26
	v_cvt_f32_i32_e32 v35, s26
	v_lshlrev_b32_e32 v44, 16, v68
	v_div_scale_f32 v16, s[10:11], v35, v35, 1.0
	v_rcp_f32_e32 v17, v16
	v_div_scale_f32 v38, vcc, 1.0, v35, 1.0
	v_fma_f32 v39, -v16, v17, 1.0
	v_fmac_f32_e32 v17, v39, v17
	v_mul_f32_e32 v39, v38, v17
	v_fma_f32 v43, -v16, v39, v38
	v_fmac_f32_e32 v39, v43, v17
	v_fma_f32 v16, -v16, v39, v38
	v_and_b32_e32 v45, 0xffff0000, v68
	v_lshlrev_b32_e32 v46, 16, v69
	v_div_fmas_f32 v17, v16, v17, v39
	v_and_b32_e32 v47, 0xffff0000, v69
	v_div_fixup_f32 v38, v17, v35, 1.0
	v_pk_mul_f32 v[46:47], v[158:159], v[46:47] op_sel_hi:[0,1]
	v_pk_mul_f32 v[44:45], v[158:159], v[44:45] op_sel_hi:[0,1]
	v_pk_fma_f32 v[44:45], v[38:39], v[12:13], v[44:45] op_sel_hi:[0,1,1] neg_lo:[0,0,1] neg_hi:[0,0,1]
	v_pk_fma_f32 v[46:47], v[38:39], v[14:15], v[46:47] op_sel_hi:[0,1,1] neg_lo:[0,0,1] neg_hi:[0,0,1]
	v_pk_mul_f32 v[44:45], v[52:53], v[44:45]
	v_pk_mul_f32 v[46:47], v[54:55], v[46:47]
	v_cvt_pk_bf16_f32 v48, v44, v45
	v_cvt_pk_bf16_f32 v49, v46, v47
	s_add_u32 s46, s28, 0
	s_addc_u32 s47, s29, 0
	global_store_dwordx2 v41, v[48:49], s[46:47]
	v_lshlrev_b32_e32 v36, 16, v60
	v_and_b32_e32 v37, 0xffff0000, v60
	v_lshlrev_b32_e32 v32, 16, v61
	v_and_b32_e32 v33, 0xffff0000, v61
	v_pk_fma_f32 v[14:15], v[154:155], v[32:33], v[14:15] op_sel_hi:[0,1,1] neg_lo:[1,0,0] neg_hi:[1,0,0]
	v_pk_fma_f32 v[12:13], v[154:155], v[36:37], v[12:13] op_sel_hi:[0,1,1] neg_lo:[1,0,0] neg_hi:[1,0,0]
	s_waitcnt vmcnt(31)
; __device__ __forceinline__ unsigned pk2(float lo, float hi) { unsigned r; asm volatile("v_cvt_pk_bf16_f32 %0, %1, %2" : "=v"(r) : "v"(lo), "v"(hi)); return r; }
; __device__ __forceinline__ unsigned pk2(float lo, float hi) { return f2bf(lo) | (f2bf(hi) << 16); }
; #define LDX(tok) ({ const u32x2 _q = *(const u32x2*)(xb + (size_t)(tok) * D + cq * 4); (f32x4){bf_lo(_q.x), bf_hi(_q.x), bf_lo(_q.y), bf_hi(_q.y)} * rs[(tok) - t0 + 8]; })
; __global__ void __launch_bounds__(512, 2) fwd_megakernel(Params Pk) {
;     ...
;             for (int s = ta - hw; s <= ta + hw - 2; ++s) if (s >= sbeg && s < send) S += LDX(s);
;             for (int t = ta; t < ta + 32; ++t) {
;                 const int sin_ = t + hw - 1; if (sin_ < send) S += LDX(sin_);
;                 const int wl = (t - hw) > sbeg ? (t - hw) : sbeg, wh = (t + hw) < send ? (t + hw) : send; const float inv = 1.0f / (float)(wh - wl);
;                 const f32x4 xt = LDX(t);
;                 const f32x4 pv = (S * inv - xt) * gv;
;                 u32x2 w; w.x = pk2(pv[0], pv[1]); w.y = pk2(pv[2], pv[3]); *(u32x2*)(pbuf + (size_t)t * D + cq * 4) = w;
;                 const int sout = t - hw; if (sout >= sbeg) S -= LDX(sout);
;             }
	v_lshlrev_b32_e32 v36, 16, v76
	v_and_b32_e32 v37, 0xffff0000, v76
	v_lshlrev_b32_e32 v32, 16, v77
	v_and_b32_e32 v33, 0xffff0000, v77
	v_pk_fma_f32 v[14:15], v[162:163], v[32:33], v[14:15] op_sel_hi:[0,1,1]
	v_pk_fma_f32 v[12:13], v[162:163], v[36:37], v[12:13] op_sel_hi:[0,1,1]
	s_add_i32 s26, s23, -3
	s_max_i32 s26, s26, s16
	s_add_i32 s27, s23, 5
	s_min_i32 s27, s27, s17
	s_sub_i32 s26, s27, s26
	v_cvt_f32_i32_e32 v35, s26
	v_lshlrev_b32_e32 v44, 16, v70
	v_div_scale_f32 v16, s[10:11], v35, v35, 1.0
	v_rcp_f32_e32 v17, v16
	v_div_scale_f32 v38, vcc, 1.0, v35, 1.0
	v_fma_f32 v39, -v16, v17, 1.0
	v_fmac_f32_e32 v17, v39, v17
	v_mul_f32_e32 v39, v38, v17
	v_fma_f32 v43, -v16, v39, v38
	v_fmac_f32_e32 v39, v43, v17
	v_fma_f32 v16, -v16, v39, v38
	v_and_b32_e32 v45, 0xffff0000, v70
	v_lshlrev_b32_e32 v46, 16, v71
	v_div_fmas_f32 v17, v16, v17, v39
	v_and_b32_e32 v47, 0xffff0000, v71
	v_div_fixup_f32 v38, v17, v35, 1.0
	v_pk_mul_f32 v[46:47], v[158:159], v[46:47] op_sel:[1,0] op_sel_hi:[1,1]
	v_pk_mul_f32 v[44:45], v[158:159], v[44:45] op_sel:[1,0] op_sel_hi:[1,1]
	v_pk_fma_f32 v[44:45], v[38:39], v[12:13], v[44:45] op_sel_hi:[0,1,1] neg_lo:[0,0,1] neg_hi:[0,0,1]
	v_pk_fma_f32 v[46:47], v[38:39], v[14:15], v[46:47] op_sel_hi:[0,1,1] neg_lo:[0,0,1] neg_hi:[0,0,1]
	v_pk_mul_f32 v[44:45], v[52:53], v[44:45]
	v_pk_mul_f32 v[46:47], v[54:55], v[46:47]
	v_cvt_pk_bf16_f32 v50, v44, v45
	v_cvt_pk_bf16_f32 v51, v46, v47
	global_store_dwordx2 v41, v[50:51], s[46:47] offset:2048
	v_lshlrev_b32_e32 v36, 16, v62
	v_and_b32_e32 v37, 0xffff0000, v62
	v_lshlrev_b32_e32 v32, 16, v63
	v_and_b32_e32 v33, 0xffff0000, v63
	v_pk_fma_f32 v[14:15], v[154:155], v[32:33], v[14:15] op_sel:[1,0,0] op_sel_hi:[1,1,1] neg_lo:[1,0,0] neg_hi:[1,0,0]
	v_pk_fma_f32 v[12:13], v[154:155], v[36:37], v[12:13] op_sel:[1,0,0] op_sel_hi:[1,1,1] neg_lo:[1,0,0] neg_hi:[1,0,0]
	s_waitcnt vmcnt(31)
	v_lshlrev_b32_e32 v36, 16, v78
	v_and_b32_e32 v37, 0xffff0000, v78
	v_lshlrev_b32_e32 v32, 16, v79
	v_and_b32_e32 v33, 0xffff0000, v79
	v_pk_fma_f32 v[14:15], v[162:163], v[32:33], v[14:15] op_sel:[1,0,0] op_sel_hi:[1,1,1]
	v_pk_fma_f32 v[12:13], v[162:163], v[36:37], v[12:13] op_sel:[1,0,0] op_sel_hi:[1,1,1]
	s_add_i32 s26, s23, -2
	s_max_i32 s26, s26, s16
	s_add_i32 s27, s23, 6
	s_min_i32 s27, s27, s17
	s_sub_i32 s26, s27, s26
	v_cvt_f32_i32_e32 v35, s26
	v_lshlrev_b32_e32 v44, 16, v72
	v_div_scale_f32 v16, s[10:11], v35, v35, 1.0
	v_rcp_f32_e32 v17, v16
	v_div_scale_f32 v38, vcc, 1.0, v35, 1.0
	v_fma_f32 v39, -v16, v17, 1.0
	v_fmac_f32_e32 v17, v39, v17
	v_mul_f32_e32 v39, v38, v17
	v_fma_f32 v43, -v16, v39, v38
	v_fmac_f32_e32 v39, v43, v17
	v_fma_f32 v16, -v16, v39, v38
	v_and_b32_e32 v45, 0xffff0000, v72
	v_lshlrev_b32_e32 v46, 16, v73
	v_div_fmas_f32 v17, v16, v17, v39
	v_and_b32_e32 v47, 0xffff0000, v73
	v_div_fixup_f32 v38, v17, v35, 1.0
	v_pk_mul_f32 v[46:47], v[160:161], v[46:47] op_sel_hi:[0,1]
	v_pk_mul_f32 v[44:45], v[160:161], v[44:45] op_sel_hi:[0,1]
	v_pk_fma_f32 v[44:45], v[38:39], v[12:13], v[44:45] op_sel_hi:[0,1,1] neg_lo:[0,0,1] neg_hi:[0,0,1]
	v_pk_fma_f32 v[46:47], v[38:39], v[14:15], v[46:47] op_sel_hi:[0,1,1] neg_lo:[0,0,1] neg_hi:[0,0,1]
	v_pk_mul_f32 v[44:45], v[52:53], v[44:45]
	v_pk_mul_f32 v[46:47], v[54:55], v[46:47]
	v_cvt_pk_bf16_f32 v48, v44, v45
	v_cvt_pk_bf16_f32 v49, v46, v47
	s_add_u32 s48, s28, 4096
	s_addc_u32 s49, s29, 0
	global_store_dwordx2 v41, v[48:49], s[48:49]
	v_lshlrev_b32_e32 v36, 16, v64
	v_and_b32_e32 v37, 0xffff0000, v64
	v_lshlrev_b32_e32 v32, 16, v65
	v_and_b32_e32 v33, 0xffff0000, v65
	v_pk_fma_f32 v[14:15], v[156:157], v[32:33], v[14:15] op_sel_hi:[0,1,1] neg_lo:[1,0,0] neg_hi:[1,0,0]
	v_pk_fma_f32 v[12:13], v[156:157], v[36:37], v[12:13] op_sel_hi:[0,1,1] neg_lo:[1,0,0] neg_hi:[1,0,0]
	s_waitcnt vmcnt(31)
	v_lshlrev_b32_e32 v36, 16, v80
	v_and_b32_e32 v37, 0xffff0000, v80
	v_lshlrev_b32_e32 v32, 16, v81
	v_and_b32_e32 v33, 0xffff0000, v81
	v_pk_fma_f32 v[14:15], v[164:165], v[32:33], v[14:15] op_sel_hi:[0,1,1]
	v_pk_fma_f32 v[12:13], v[164:165], v[36:37], v[12:13] op_sel_hi:[0,1,1]
	s_add_i32 s26, s23, -1
	s_max_i32 s26, s26, s16
	s_add_i32 s27, s23, 7
	s_min_i32 s27, s27, s17
	s_sub_i32 s26, s27, s26
	v_cvt_f32_i32_e32 v35, s26
	v_lshlrev_b32_e32 v44, 16, v74
	v_div_scale_f32 v16, s[10:11], v35, v35, 1.0
	v_rcp_f32_e32 v17, v16
	v_div_scale_f32 v38, vcc, 1.0, v35, 1.0
	v_fma_f32 v39, -v16, v17, 1.0
	v_fmac_f32_e32 v17, v39, v17
	v_mul_f32_e32 v39, v38, v17
	v_fma_f32 v43, -v16, v39, v38
	v_fmac_f32_e32 v39, v43, v17
	v_fma_f32 v16, -v16, v39, v38
	v_and_b32_e32 v45, 0xffff0000, v74
	v_lshlrev_b32_e32 v46, 16, v75
	v_div_fmas_f32 v17, v16, v17, v39
	v_and_b32_e32 v47, 0xffff0000, v75
	v_div_fixup_f32 v38, v17, v35, 1.0
	v_pk_mul_f32 v[46:47], v[160:161], v[46:47] op_sel:[1,0] op_sel_hi:[1,1]
	v_pk_mul_f32 v[44:45], v[160:161], v[44:45] op_sel:[1,0] op_sel_hi:[1,1]
	v_pk_fma_f32 v[44:45], v[38:39], v[12:13], v[44:45] op_sel_hi:[0,1,1] neg_lo:[0,0,1] neg_hi:[0,0,1]
	v_pk_fma_f32 v[46:47], v[38:39], v[14:15], v[46:47] op_sel_hi:[0,1,1] neg_lo:[0,0,1] neg_hi:[0,0,1]
	v_pk_mul_f32 v[44:45], v[52:53], v[44:45]
	v_pk_mul_f32 v[46:47], v[54:55], v[46:47]
	v_cvt_pk_bf16_f32 v50, v44, v45
	v_cvt_pk_bf16_f32 v51, v46, v47
	global_store_dwordx2 v41, v[50:51], s[48:49] offset:2048
	v_lshlrev_b32_e32 v36, 16, v66
	v_and_b32_e32 v37, 0xffff0000, v66
	v_lshlrev_b32_e32 v32, 16, v67
	v_and_b32_e32 v33, 0xffff0000, v67
	v_pk_fma_f32 v[14:15], v[156:157], v[32:33], v[14:15] op_sel:[1,0,0] op_sel_hi:[1,1,1] neg_lo:[1,0,0] neg_hi:[1,0,0]
	v_pk_fma_f32 v[12:13], v[156:157], v[36:37], v[12:13] op_sel:[1,0,0] op_sel_hi:[1,1,1] neg_lo:[1,0,0] neg_hi:[1,0,0]
	s_waitcnt vmcnt(31)
; __device__ __forceinline__ unsigned pk2(float lo, float hi) { unsigned r; asm volatile("v_cvt_pk_bf16_f32 %0, %1, %2" : "=v"(r) : "v"(lo), "v"(hi)); return r; }
; __device__ __forceinline__ unsigned pk2(float lo, float hi) { return f2bf(lo) | (f2bf(hi) << 16); }
; #define LDX(tok) ({ const u32x2 _q = *(const u32x2*)(xb + (size_t)(tok) * D + cq * 4); (f32x4){bf_lo(_q.x), bf_hi(_q.x), bf_lo(_q.y), bf_hi(_q.y)} * rs[(tok) - t0 + 8]; })
; __global__ void __launch_bounds__(512, 2) fwd_megakernel(Params Pk) {
;     ...
;             for (int s = ta - hw; s <= ta + hw - 2; ++s) if (s >= sbeg && s < send) S += LDX(s);
;             for (int t = ta; t < ta + 32; ++t) {
;                 const int sin_ = t + hw - 1; if (sin_ < send) S += LDX(sin_);
;                 const int wl = (t - hw) > sbeg ? (t - hw) : sbeg, wh = (t + hw) < send ? (t + hw) : send; const float inv = 1.0f / (float)(wh - wl);
;                 const f32x4 xt = LDX(t);
;                 const f32x4 pv = (S * inv - xt) * gv;
;                 u32x2 w; w.x = pk2(pv[0], pv[1]); w.y = pk2(pv[2], pv[3]); *(u32x2*)(pbuf + (size_t)t * D + cq * 4) = w;
;                 const int sout = t - hw; if (sout >= sbeg) S -= LDX(sout);
;             }
	v_lshlrev_b32_e32 v36, 16, v82
	v_and_b32_e32 v37, 0xffff0000, v82
	v_lshlrev_b32_e32 v32, 16, v83
	v_and_b32_e32 v33, 0xffff0000, v83
	v_pk_fma_f32 v[14:15], v[164:165], v[32:33], v[14:15] op_sel:[1,0,0] op_sel_hi:[1,1,1]
	v_pk_fma_f32 v[12:13], v[164:165], v[36:37], v[12:13] op_sel:[1,0,0] op_sel_hi:[1,1,1]
	s_add_i32 s26, s23, 0
	s_max_i32 s26, s26, s16
	s_add_i32 s27, s23, 8
	s_min_i32 s27, s27, s17
	s_sub_i32 s26, s27, s26
	v_cvt_f32_i32_e32 v35, s26
	v_lshlrev_b32_e32 v44, 16, v76
	v_div_scale_f32 v16, s[10:11], v35, v35, 1.0
	v_rcp_f32_e32 v17, v16
	v_div_scale_f32 v38, vcc, 1.0, v35, 1.0
	v_fma_f32 v39, -v16, v17, 1.0
	v_fmac_f32_e32 v17, v39, v17
	v_mul_f32_e32 v39, v38, v17
	v_fma_f32 v43, -v16, v39, v38
	v_fmac_f32_e32 v39, v43, v17
	v_fma_f32 v16, -v16, v39, v38
	v_and_b32_e32 v45, 0xffff0000, v76
	v_lshlrev_b32_e32 v46, 16, v77
	v_div_fmas_f32 v17, v16, v17, v39
	v_and_b32_e32 v47, 0xffff0000, v77
	v_div_fixup_f32 v38, v17, v35, 1.0
	v_pk_mul_f32 v[46:47], v[162:163], v[46:47] op_sel_hi:[0,1]
	v_pk_mul_f32 v[44:45], v[162:163], v[44:45] op_sel_hi:[0,1]
	v_pk_fma_f32 v[44:45], v[38:39], v[12:13], v[44:45] op_sel_hi:[0,1,1] neg_lo:[0,0,1] neg_hi:[0,0,1]
	v_pk_fma_f32 v[46:47], v[38:39], v[14:15], v[46:47] op_sel_hi:[0,1,1] neg_lo:[0,0,1] neg_hi:[0,0,1]
	v_pk_mul_f32 v[44:45], v[52:53], v[44:45]
	v_pk_mul_f32 v[46:47], v[54:55], v[46:47]
	v_cvt_pk_bf16_f32 v48, v44, v45
	v_cvt_pk_bf16_f32 v49, v46, v47
	s_add_u32 s50, s28, 8192
	s_addc_u32 s51, s29, 0
	global_store_dwordx2 v41, v[48:49], s[50:51]
	v_lshlrev_b32_e32 v36, 16, v68
	v_and_b32_e32 v37, 0xffff0000, v68
	v_lshlrev_b32_e32 v32, 16, v69
	v_and_b32_e32 v33, 0xffff0000, v69
	v_pk_fma_f32 v[14:15], v[158:159], v[32:33], v[14:15] op_sel_hi:[0,1,1] neg_lo:[1,0,0] neg_hi:[1,0,0]
	v_pk_fma_f32 v[12:13], v[158:159], v[36:37], v[12:13] op_sel_hi:[0,1,1] neg_lo:[1,0,0] neg_hi:[1,0,0]
	s_waitcnt vmcnt(31)
	v_lshlrev_b32_e32 v36, 16, v84
	v_and_b32_e32 v37, 0xffff0000, v84
	v_lshlrev_b32_e32 v32, 16, v85
	v_and_b32_e32 v33, 0xffff0000, v85
	v_pk_fma_f32 v[14:15], v[166:167], v[32:33], v[14:15] op_sel_hi:[0,1,1]
	v_pk_fma_f32 v[12:13], v[166:167], v[36:37], v[12:13] op_sel_hi:[0,1,1]
	s_add_i32 s26, s23, 1
	s_max_i32 s26, s26, s16
	s_add_i32 s27, s23, 9
	s_min_i32 s27, s27, s17
	s_sub_i32 s26, s27, s26
	v_cvt_f32_i32_e32 v35, s26
	v_lshlrev_b32_e32 v44, 16, v78
	v_div_scale_f32 v16, s[10:11], v35, v35, 1.0
	v_rcp_f32_e32 v17, v16
	v_div_scale_f32 v38, vcc, 1.0, v35, 1.0
	v_fma_f32 v39, -v16, v17, 1.0
	v_fmac_f32_e32 v17, v39, v17
	v_mul_f32_e32 v39, v38, v17
	v_fma_f32 v43, -v16, v39, v38
	v_fmac_f32_e32 v39, v43, v17
	v_fma_f32 v16, -v16, v39, v38
	v_and_b32_e32 v45, 0xffff0000, v78
	v_lshlrev_b32_e32 v46, 16, v79
	v_div_fmas_f32 v17, v16, v17, v39
	v_and_b32_e32 v47, 0xffff0000, v79
	v_div_fixup_f32 v38, v17, v35, 1.0
	v_pk_mul_f32 v[46:47], v[162:163], v[46:47] op_sel:[1,0] op_sel_hi:[1,1]
	v_pk_mul_f32 v[44:45], v[162:163], v[44:45] op_sel:[1,0] op_sel_hi:[1,1]
	v_pk_fma_f32 v[44:45], v[38:39], v[12:13], v[44:45] op_sel_hi:[0,1,1] neg_lo:[0,0,1] neg_hi:[0,0,1]
	v_pk_fma_f32 v[46:47], v[38:39], v[14:15], v[46:47] op_sel_hi:[0,1,1] neg_lo:[0,0,1] neg_hi:[0,0,1]
	v_pk_mul_f32 v[44:45], v[52:53], v[44:45]
	v_pk_mul_f32 v[46:47], v[54:55], v[46:47]
	v_cvt_pk_bf16_f32 v50, v44, v45
	v_cvt_pk_bf16_f32 v51, v46, v47
	global_store_dwordx2 v41, v[50:51], s[50:51] offset:2048
	v_lshlrev_b32_e32 v36, 16, v70
	v_and_b32_e32 v37, 0xffff0000, v70
	v_lshlrev_b32_e32 v32, 16, v71
	v_and_b32_e32 v33, 0xffff0000, v71
	v_pk_fma_f32 v[14:15], v[158:159], v[32:33], v[14:15] op_sel:[1,0,0] op_sel_hi:[1,1,1] neg_lo:[1,0,0] neg_hi:[1,0,0]
	v_pk_fma_f32 v[12:13], v[158:159], v[36:37], v[12:13] op_sel:[1,0,0] op_sel_hi:[1,1,1] neg_lo:[1,0,0] neg_hi:[1,0,0]
	s_waitcnt vmcnt(31)
	v_lshlrev_b32_e32 v36, 16, v86
	v_and_b32_e32 v37, 0xffff0000, v86
	v_lshlrev_b32_e32 v32, 16, v87
	v_and_b32_e32 v33, 0xffff0000, v87
	v_pk_fma_f32 v[14:15], v[166:167], v[32:33], v[14:15] op_sel:[1,0,0] op_sel_hi:[1,1,1]
	v_pk_fma_f32 v[12:13], v[166:167], v[36:37], v[12:13] op_sel:[1,0,0] op_sel_hi:[1,1,1]
	s_add_i32 s26, s23, 2
	s_max_i32 s26, s26, s16
	s_add_i32 s27, s23, 10
	s_min_i32 s27, s27, s17
	s_sub_i32 s26, s27, s26
	v_cvt_f32_i32_e32 v35, s26
	v_lshlrev_b32_e32 v44, 16, v80
	v_div_scale_f32 v16, s[10:11], v35, v35, 1.0
	v_rcp_f32_e32 v17, v16
	v_div_scale_f32 v38, vcc, 1.0, v35, 1.0
	v_fma_f32 v39, -v16, v17, 1.0
	v_fmac_f32_e32 v17, v39, v17
	v_mul_f32_e32 v39, v38, v17
	v_fma_f32 v43, -v16, v39, v38
	v_fmac_f32_e32 v39, v43, v17
	v_fma_f32 v16, -v16, v39, v38
	v_and_b32_e32 v45, 0xffff0000, v80
	v_lshlrev_b32_e32 v46, 16, v81
	v_div_fmas_f32 v17, v16, v17, v39
	v_and_b32_e32 v47, 0xffff0000, v81
	v_div_fixup_f32 v38, v17, v35, 1.0
	v_pk_mul_f32 v[46:47], v[164:165], v[46:47] op_sel_hi:[0,1]
	v_pk_mul_f32 v[44:45], v[164:165], v[44:45] op_sel_hi:[0,1]
	v_pk_fma_f32 v[44:45], v[38:39], v[12:13], v[44:45] op_sel_hi:[0,1,1] neg_lo:[0,0,1] neg_hi:[0,0,1]
	v_pk_fma_f32 v[46:47], v[38:39], v[14:15], v[46:47] op_sel_hi:[0,1,1] neg_lo:[0,0,1] neg_hi:[0,0,1]
	v_pk_mul_f32 v[44:45], v[52:53], v[44:45]
	v_pk_mul_f32 v[46:47], v[54:55], v[46:47]
	v_cvt_pk_bf16_f32 v48, v44, v45
	v_cvt_pk_bf16_f32 v49, v46, v47
	s_add_u32 s52, s28, 12288
	s_addc_u32 s53, s29, 0
	global_store_dwordx2 v41, v[48:49], s[52:53]
	v_lshlrev_b32_e32 v36, 16, v72
	v_and_b32_e32 v37, 0xffff0000, v72
	v_lshlrev_b32_e32 v32, 16, v73
	v_and_b32_e32 v33, 0xffff0000, v73
	v_pk_fma_f32 v[14:15], v[160:161], v[32:33], v[14:15] op_sel_hi:[0,1,1] neg_lo:[1,0,0] neg_hi:[1,0,0]
	v_pk_fma_f32 v[12:13], v[160:161], v[36:37], v[12:13] op_sel_hi:[0,1,1] neg_lo:[1,0,0] neg_hi:[1,0,0]
	s_waitcnt vmcnt(31)
; __device__ __forceinline__ unsigned pk2(float lo, float hi) { unsigned r; asm volatile("v_cvt_pk_bf16_f32 %0, %1, %2" : "=v"(r) : "v"(lo), "v"(hi)); return r; }
; __device__ __forceinline__ unsigned pk2(float lo, float hi) { return f2bf(lo) | (f2bf(hi) << 16); }
; #define LDX(tok) ({ const u32x2 _q = *(const u32x2*)(xb + (size_t)(tok) * D + cq * 4); (f32x4){bf_lo(_q.x), bf_hi(_q.x), bf_lo(_q.y), bf_hi(_q.y)} * rs[(tok) - t0 + 8]; })
; __global__ void __launch_bounds__(512, 2) fwd_megakernel(Params Pk) {
;     ...
;             for (int s = ta - hw; s <= ta + hw - 2; ++s) if (s >= sbeg && s < send) S += LDX(s);
;             for (int t = ta; t < ta + 32; ++t) {
;                 const int sin_ = t + hw - 1; if (sin_ < send) S += LDX(sin_);
;                 const int wl = (t - hw) > sbeg ? (t - hw) : sbeg, wh = (t + hw) < send ? (t + hw) : send; const float inv = 1.0f / (float)(wh - wl);
;                 const f32x4 xt = LDX(t);
;                 const f32x4 pv = (S * inv - xt) * gv;
;                 u32x2 w; w.x = pk2(pv[0], pv[1]); w.y = pk2(pv[2], pv[3]); *(u32x2*)(pbuf + (size_t)t * D + cq * 4) = w;
;                 const int sout = t - hw; if (sout >= sbeg) S -= LDX(sout);
;             }
	v_lshlrev_b32_e32 v36, 16, v88
	v_and_b32_e32 v37, 0xffff0000, v88
	v_lshlrev_b32_e32 v32, 16, v89
	v_and_b32_e32 v33, 0xffff0000, v89
	v_pk_fma_f32 v[14:15], v[168:169], v[32:33], v[14:15] op_sel_hi:[0,1,1]
	v_pk_fma_f32 v[12:13], v[168:169], v[36:37], v[12:13] op_sel_hi:[0,1,1]
	s_add_i32 s26, s23, 3
	s_max_i32 s26, s26, s16
	s_add_i32 s27, s23, 11
	s_min_i32 s27, s27, s17
	s_sub_i32 s26, s27, s26
	v_cvt_f32_i32_e32 v35, s26
	v_lshlrev_b32_e32 v44, 16, v82
	v_div_scale_f32 v16, s[10:11], v35, v35, 1.0
	v_rcp_f32_e32 v17, v16
	v_div_scale_f32 v38, vcc, 1.0, v35, 1.0
	v_fma_f32 v39, -v16, v17, 1.0
	v_fmac_f32_e32 v17, v39, v17
	v_mul_f32_e32 v39, v38, v17
	v_fma_f32 v43, -v16, v39, v38
	v_fmac_f32_e32 v39, v43, v17
	v_fma_f32 v16, -v16, v39, v38
	v_and_b32_e32 v45, 0xffff0000, v82
	v_lshlrev_b32_e32 v46, 16, v83
	v_div_fmas_f32 v17, v16, v17, v39
	v_and_b32_e32 v47, 0xffff0000, v83
	v_div_fixup_f32 v38, v17, v35, 1.0
	v_pk_mul_f32 v[46:47], v[164:165], v[46:47] op_sel:[1,0] op_sel_hi:[1,1]
	v_pk_mul_f32 v[44:45], v[164:165], v[44:45] op_sel:[1,0] op_sel_hi:[1,1]
	v_pk_fma_f32 v[44:45], v[38:39], v[12:13], v[44:45] op_sel_hi:[0,1,1] neg_lo:[0,0,1] neg_hi:[0,0,1]
	v_pk_fma_f32 v[46:47], v[38:39], v[14:15], v[46:47] op_sel_hi:[0,1,1] neg_lo:[0,0,1] neg_hi:[0,0,1]
	v_pk_mul_f32 v[44:45], v[52:53], v[44:45]
	v_pk_mul_f32 v[46:47], v[54:55], v[46:47]
	v_cvt_pk_bf16_f32 v50, v44, v45
	v_cvt_pk_bf16_f32 v51, v46, v47
	global_store_dwordx2 v41, v[50:51], s[52:53] offset:2048
	v_lshlrev_b32_e32 v36, 16, v74
	v_and_b32_e32 v37, 0xffff0000, v74
	v_lshlrev_b32_e32 v32, 16, v75
	v_and_b32_e32 v33, 0xffff0000, v75
	v_pk_fma_f32 v[14:15], v[160:161], v[32:33], v[14:15] op_sel:[1,0,0] op_sel_hi:[1,1,1] neg_lo:[1,0,0] neg_hi:[1,0,0]
	v_pk_fma_f32 v[12:13], v[160:161], v[36:37], v[12:13] op_sel:[1,0,0] op_sel_hi:[1,1,1] neg_lo:[1,0,0] neg_hi:[1,0,0]
	s_waitcnt vmcnt(31)
	v_lshlrev_b32_e32 v36, 16, v90
	v_and_b32_e32 v37, 0xffff0000, v90
	v_lshlrev_b32_e32 v32, 16, v91
	v_and_b32_e32 v33, 0xffff0000, v91
	v_pk_fma_f32 v[14:15], v[168:169], v[32:33], v[14:15] op_sel:[1,0,0] op_sel_hi:[1,1,1]
	v_pk_fma_f32 v[12:13], v[168:169], v[36:37], v[12:13] op_sel:[1,0,0] op_sel_hi:[1,1,1]
	s_add_i32 s26, s23, 4
	s_max_i32 s26, s26, s16
	s_add_i32 s27, s23, 12
	s_min_i32 s27, s27, s17
	s_sub_i32 s26, s27, s26
	v_cvt_f32_i32_e32 v35, s26
	v_lshlrev_b32_e32 v44, 16, v84
	v_div_scale_f32 v16, s[10:11], v35, v35, 1.0
	v_rcp_f32_e32 v17, v16
	v_div_scale_f32 v38, vcc, 1.0, v35, 1.0
	v_fma_f32 v39, -v16, v17, 1.0
	v_fmac_f32_e32 v17, v39, v17
	v_mul_f32_e32 v39, v38, v17
	v_fma_f32 v43, -v16, v39, v38
	v_fmac_f32_e32 v39, v43, v17
	v_fma_f32 v16, -v16, v39, v38
	v_and_b32_e32 v45, 0xffff0000, v84
	v_lshlrev_b32_e32 v46, 16, v85
	v_div_fmas_f32 v17, v16, v17, v39
	v_and_b32_e32 v47, 0xffff0000, v85
	v_div_fixup_f32 v38, v17, v35, 1.0
	v_pk_mul_f32 v[46:47], v[166:167], v[46:47] op_sel_hi:[0,1]
	v_pk_mul_f32 v[44:45], v[166:167], v[44:45] op_sel_hi:[0,1]
	v_pk_fma_f32 v[44:45], v[38:39], v[12:13], v[44:45] op_sel_hi:[0,1,1] neg_lo:[0,0,1] neg_hi:[0,0,1]
	v_pk_fma_f32 v[46:47], v[38:39], v[14:15], v[46:47] op_sel_hi:[0,1,1] neg_lo:[0,0,1] neg_hi:[0,0,1]
	v_pk_mul_f32 v[44:45], v[52:53], v[44:45]
	v_pk_mul_f32 v[46:47], v[54:55], v[46:47]
	v_cvt_pk_bf16_f32 v48, v44, v45
	v_cvt_pk_bf16_f32 v49, v46, v47
	s_add_u32 s46, s28, 16384
	s_addc_u32 s47, s29, 0
	global_store_dwordx2 v41, v[48:49], s[46:47]
	v_lshlrev_b32_e32 v36, 16, v76
	v_and_b32_e32 v37, 0xffff0000, v76
	v_lshlrev_b32_e32 v32, 16, v77
	v_and_b32_e32 v33, 0xffff0000, v77
	v_pk_fma_f32 v[14:15], v[162:163], v[32:33], v[14:15] op_sel_hi:[0,1,1] neg_lo:[1,0,0] neg_hi:[1,0,0]
	v_pk_fma_f32 v[12:13], v[162:163], v[36:37], v[12:13] op_sel_hi:[0,1,1] neg_lo:[1,0,0] neg_hi:[1,0,0]
	s_waitcnt vmcnt(31)
	v_lshlrev_b32_e32 v36, 16, v92
	v_and_b32_e32 v37, 0xffff0000, v92
	v_lshlrev_b32_e32 v32, 16, v93
	v_and_b32_e32 v33, 0xffff0000, v93
	v_pk_fma_f32 v[14:15], v[170:171], v[32:33], v[14:15] op_sel_hi:[0,1,1]
	v_pk_fma_f32 v[12:13], v[170:171], v[36:37], v[12:13] op_sel_hi:[0,1,1]
	s_add_i32 s26, s23, 5
	s_max_i32 s26, s26, s16
	s_add_i32 s27, s23, 13
	s_min_i32 s27, s27, s17
	s_sub_i32 s26, s27, s26
	v_cvt_f32_i32_e32 v35, s26
	v_lshlrev_b32_e32 v44, 16, v86
	v_div_scale_f32 v16, s[10:11], v35, v35, 1.0
	v_rcp_f32_e32 v17, v16
	v_div_scale_f32 v38, vcc, 1.0, v35, 1.0
	v_fma_f32 v39, -v16, v17, 1.0
	v_fmac_f32_e32 v17, v39, v17
	v_mul_f32_e32 v39, v38, v17
	v_fma_f32 v43, -v16, v39, v38
	v_fmac_f32_e32 v39, v43, v17
	v_fma_f32 v16, -v16, v39, v38
	v_and_b32_e32 v45, 0xffff0000, v86
	v_lshlrev_b32_e32 v46, 16, v87
	v_div_fmas_f32 v17, v16, v17, v39
	v_and_b32_e32 v47, 0xffff0000, v87
	v_div_fixup_f32 v38, v17, v35, 1.0
	v_pk_mul_f32 v[46:47], v[166:167], v[46:47] op_sel:[1,0] op_sel_hi:[1,1]
	v_pk_mul_f32 v[44:45], v[166:167], v[44:45] op_sel:[1,0] op_sel_hi:[1,1]
	v_pk_fma_f32 v[44:45], v[38:39], v[12:13], v[44:45] op_sel_hi:[0,1,1] neg_lo:[0,0,1] neg_hi:[0,0,1]
	v_pk_fma_f32 v[46:47], v[38:39], v[14:15], v[46:47] op_sel_hi:[0,1,1] neg_lo:[0,0,1] neg_hi:[0,0,1]
	v_pk_mul_f32 v[44:45], v[52:53], v[44:45]
	v_pk_mul_f32 v[46:47], v[54:55], v[46:47]
	v_cvt_pk_bf16_f32 v50, v44, v45
	v_cvt_pk_bf16_f32 v51, v46, v47
	global_store_dwordx2 v41, v[50:51], s[46:47] offset:2048
	v_lshlrev_b32_e32 v36, 16, v78
	v_and_b32_e32 v37, 0xffff0000, v78
	v_lshlrev_b32_e32 v32, 16, v79
	v_and_b32_e32 v33, 0xffff0000, v79
	v_pk_fma_f32 v[14:15], v[162:163], v[32:33], v[14:15] op_sel:[1,0,0] op_sel_hi:[1,1,1] neg_lo:[1,0,0] neg_hi:[1,0,0]
	v_pk_fma_f32 v[12:13], v[162:163], v[36:37], v[12:13] op_sel:[1,0,0] op_sel_hi:[1,1,1] neg_lo:[1,0,0] neg_hi:[1,0,0]
	s_waitcnt vmcnt(31)
; __device__ __forceinline__ unsigned pk2(float lo, float hi) { unsigned r; asm volatile("v_cvt_pk_bf16_f32 %0, %1, %2" : "=v"(r) : "v"(lo), "v"(hi)); return r; }
; __device__ __forceinline__ unsigned pk2(float lo, float hi) { return f2bf(lo) | (f2bf(hi) << 16); }
; #define LDX(tok) ({ const u32x2 _q = *(const u32x2*)(xb + (size_t)(tok) * D + cq * 4); (f32x4){bf_lo(_q.x), bf_hi(_q.x), bf_lo(_q.y), bf_hi(_q.y)} * rs[(tok) - t0 + 8]; })
; __global__ void __launch_bounds__(512, 2) fwd_megakernel(Params Pk) {
;     ...
;             for (int s = ta - hw; s <= ta + hw - 2; ++s) if (s >= sbeg && s < send) S += LDX(s);
;             for (int t = ta; t < ta + 32; ++t) {
;                 const int sin_ = t + hw - 1; if (sin_ < send) S += LDX(sin_);
;                 const int wl = (t - hw) > sbeg ? (t - hw) : sbeg, wh = (t + hw) < send ? (t + hw) : send; const float inv = 1.0f / (float)(wh - wl);
;                 const f32x4 xt = LDX(t);
;                 const f32x4 pv = (S * inv - xt) * gv;
;                 u32x2 w; w.x = pk2(pv[0], pv[1]); w.y = pk2(pv[2], pv[3]); *(u32x2*)(pbuf + (size_t)t * D + cq * 4) = w;
;                 const int sout = t - hw; if (sout >= sbeg) S -= LDX(sout);
;             }
	v_lshlrev_b32_e32 v36, 16, v94
	v_and_b32_e32 v37, 0xffff0000, v94
	v_lshlrev_b32_e32 v32, 16, v95
	v_and_b32_e32 v33, 0xffff0000, v95
	v_pk_fma_f32 v[14:15], v[170:171], v[32:33], v[14:15] op_sel:[1,0,0] op_sel_hi:[1,1,1]
	v_pk_fma_f32 v[12:13], v[170:171], v[36:37], v[12:13] op_sel:[1,0,0] op_sel_hi:[1,1,1]
	s_add_i32 s26, s23, 6
	s_max_i32 s26, s26, s16
	s_add_i32 s27, s23, 14
	s_min_i32 s27, s27, s17
	s_sub_i32 s26, s27, s26
	v_cvt_f32_i32_e32 v35, s26
	v_lshlrev_b32_e32 v44, 16, v88
	v_div_scale_f32 v16, s[10:11], v35, v35, 1.0
	v_rcp_f32_e32 v17, v16
	v_div_scale_f32 v38, vcc, 1.0, v35, 1.0
	v_fma_f32 v39, -v16, v17, 1.0
	v_fmac_f32_e32 v17, v39, v17
	v_mul_f32_e32 v39, v38, v17
	v_fma_f32 v43, -v16, v39, v38
	v_fmac_f32_e32 v39, v43, v17
	v_fma_f32 v16, -v16, v39, v38
	v_and_b32_e32 v45, 0xffff0000, v88
	v_lshlrev_b32_e32 v46, 16, v89
	v_div_fmas_f32 v17, v16, v17, v39
	v_and_b32_e32 v47, 0xffff0000, v89
	v_div_fixup_f32 v38, v17, v35, 1.0
	v_pk_mul_f32 v[46:47], v[168:169], v[46:47] op_sel_hi:[0,1]
	v_pk_mul_f32 v[44:45], v[168:169], v[44:45] op_sel_hi:[0,1]
	v_pk_fma_f32 v[44:45], v[38:39], v[12:13], v[44:45] op_sel_hi:[0,1,1] neg_lo:[0,0,1] neg_hi:[0,0,1]
	v_pk_fma_f32 v[46:47], v[38:39], v[14:15], v[46:47] op_sel_hi:[0,1,1] neg_lo:[0,0,1] neg_hi:[0,0,1]
	v_pk_mul_f32 v[44:45], v[52:53], v[44:45]
	v_pk_mul_f32 v[46:47], v[54:55], v[46:47]
	v_cvt_pk_bf16_f32 v48, v44, v45
	v_cvt_pk_bf16_f32 v49, v46, v47
	s_add_u32 s48, s28, 20480
	s_addc_u32 s49, s29, 0
	global_store_dwordx2 v41, v[48:49], s[48:49]
	v_lshlrev_b32_e32 v36, 16, v80
	v_and_b32_e32 v37, 0xffff0000, v80
	v_lshlrev_b32_e32 v32, 16, v81
	v_and_b32_e32 v33, 0xffff0000, v81
	v_pk_fma_f32 v[14:15], v[164:165], v[32:33], v[14:15] op_sel_hi:[0,1,1] neg_lo:[1,0,0] neg_hi:[1,0,0]
	v_pk_fma_f32 v[12:13], v[164:165], v[36:37], v[12:13] op_sel_hi:[0,1,1] neg_lo:[1,0,0] neg_hi:[1,0,0]
	s_waitcnt vmcnt(31)
	v_lshlrev_b32_e32 v36, 16, v96
	v_and_b32_e32 v37, 0xffff0000, v96
	v_lshlrev_b32_e32 v32, 16, v97
	v_and_b32_e32 v33, 0xffff0000, v97
	v_pk_fma_f32 v[14:15], v[172:173], v[32:33], v[14:15] op_sel_hi:[0,1,1]
	v_pk_fma_f32 v[12:13], v[172:173], v[36:37], v[12:13] op_sel_hi:[0,1,1]
	s_add_i32 s26, s23, 7
	s_max_i32 s26, s26, s16
	s_add_i32 s27, s23, 15
	s_min_i32 s27, s27, s17
	s_sub_i32 s26, s27, s26
	v_cvt_f32_i32_e32 v35, s26
	v_lshlrev_b32_e32 v44, 16, v90
	v_div_scale_f32 v16, s[10:11], v35, v35, 1.0
	v_rcp_f32_e32 v17, v16
	v_div_scale_f32 v38, vcc, 1.0, v35, 1.0
	v_fma_f32 v39, -v16, v17, 1.0
	v_fmac_f32_e32 v17, v39, v17
	v_mul_f32_e32 v39, v38, v17
	v_fma_f32 v43, -v16, v39, v38
	v_fmac_f32_e32 v39, v43, v17
	v_fma_f32 v16, -v16, v39, v38
	v_and_b32_e32 v45, 0xffff0000, v90
	v_lshlrev_b32_e32 v46, 16, v91
	v_div_fmas_f32 v17, v16, v17, v39
	v_and_b32_e32 v47, 0xffff0000, v91
	v_div_fixup_f32 v38, v17, v35, 1.0
	v_pk_mul_f32 v[46:47], v[168:169], v[46:47] op_sel:[1,0] op_sel_hi:[1,1]
	v_pk_mul_f32 v[44:45], v[168:169], v[44:45] op_sel:[1,0] op_sel_hi:[1,1]
	v_pk_fma_f32 v[44:45], v[38:39], v[12:13], v[44:45] op_sel_hi:[0,1,1] neg_lo:[0,0,1] neg_hi:[0,0,1]
	v_pk_fma_f32 v[46:47], v[38:39], v[14:15], v[46:47] op_sel_hi:[0,1,1] neg_lo:[0,0,1] neg_hi:[0,0,1]
	v_pk_mul_f32 v[44:45], v[52:53], v[44:45]
	v_pk_mul_f32 v[46:47], v[54:55], v[46:47]
	v_cvt_pk_bf16_f32 v50, v44, v45
	v_cvt_pk_bf16_f32 v51, v46, v47
	global_store_dwordx2 v41, v[50:51], s[48:49] offset:2048
	v_lshlrev_b32_e32 v36, 16, v82
	v_and_b32_e32 v37, 0xffff0000, v82
	v_lshlrev_b32_e32 v32, 16, v83
	v_and_b32_e32 v33, 0xffff0000, v83
	v_pk_fma_f32 v[14:15], v[164:165], v[32:33], v[14:15] op_sel:[1,0,0] op_sel_hi:[1,1,1] neg_lo:[1,0,0] neg_hi:[1,0,0]
	v_pk_fma_f32 v[12:13], v[164:165], v[36:37], v[12:13] op_sel:[1,0,0] op_sel_hi:[1,1,1] neg_lo:[1,0,0] neg_hi:[1,0,0]
	s_waitcnt vmcnt(31)
	v_lshlrev_b32_e32 v36, 16, v98
	v_and_b32_e32 v37, 0xffff0000, v98
	v_lshlrev_b32_e32 v32, 16, v99
	v_and_b32_e32 v33, 0xffff0000, v99
	v_pk_fma_f32 v[14:15], v[172:173], v[32:33], v[14:15] op_sel:[1,0,0] op_sel_hi:[1,1,1]
	v_pk_fma_f32 v[12:13], v[172:173], v[36:37], v[12:13] op_sel:[1,0,0] op_sel_hi:[1,1,1]
	s_add_i32 s26, s23, 8
	s_max_i32 s26, s26, s16
	s_add_i32 s27, s23, 16
	s_min_i32 s27, s27, s17
	s_sub_i32 s26, s27, s26
	v_cvt_f32_i32_e32 v35, s26
	v_lshlrev_b32_e32 v44, 16, v92
	v_div_scale_f32 v16, s[10:11], v35, v35, 1.0
	v_rcp_f32_e32 v17, v16
	v_div_scale_f32 v38, vcc, 1.0, v35, 1.0
	v_fma_f32 v39, -v16, v17, 1.0
	v_fmac_f32_e32 v17, v39, v17
	v_mul_f32_e32 v39, v38, v17
	v_fma_f32 v43, -v16, v39, v38
	v_fmac_f32_e32 v39, v43, v17
	v_fma_f32 v16, -v16, v39, v38
	v_and_b32_e32 v45, 0xffff0000, v92
	v_lshlrev_b32_e32 v46, 16, v93
	v_div_fmas_f32 v17, v16, v17, v39
	v_and_b32_e32 v47, 0xffff0000, v93
	v_div_fixup_f32 v38, v17, v35, 1.0
	v_pk_mul_f32 v[46:47], v[170:171], v[46:47] op_sel_hi:[0,1]
	v_pk_mul_f32 v[44:45], v[170:171], v[44:45] op_sel_hi:[0,1]
	v_pk_fma_f32 v[44:45], v[38:39], v[12:13], v[44:45] op_sel_hi:[0,1,1] neg_lo:[0,0,1] neg_hi:[0,0,1]
	v_pk_fma_f32 v[46:47], v[38:39], v[14:15], v[46:47] op_sel_hi:[0,1,1] neg_lo:[0,0,1] neg_hi:[0,0,1]
	v_pk_mul_f32 v[44:45], v[52:53], v[44:45]
	v_pk_mul_f32 v[46:47], v[54:55], v[46:47]
	v_cvt_pk_bf16_f32 v48, v44, v45
	v_cvt_pk_bf16_f32 v49, v46, v47
	s_add_u32 s50, s28, 24576
	s_addc_u32 s51, s29, 0
	global_store_dwordx2 v41, v[48:49], s[50:51]
	v_lshlrev_b32_e32 v36, 16, v84
	v_and_b32_e32 v37, 0xffff0000, v84
	v_lshlrev_b32_e32 v32, 16, v85
	v_and_b32_e32 v33, 0xffff0000, v85
	v_pk_fma_f32 v[14:15], v[166:167], v[32:33], v[14:15] op_sel_hi:[0,1,1] neg_lo:[1,0,0] neg_hi:[1,0,0]
	v_pk_fma_f32 v[12:13], v[166:167], v[36:37], v[12:13] op_sel_hi:[0,1,1] neg_lo:[1,0,0] neg_hi:[1,0,0]
	s_waitcnt vmcnt(31)
; __device__ __forceinline__ unsigned pk2(float lo, float hi) { unsigned r; asm volatile("v_cvt_pk_bf16_f32 %0, %1, %2" : "=v"(r) : "v"(lo), "v"(hi)); return r; }
; __device__ __forceinline__ unsigned pk2(float lo, float hi) { return f2bf(lo) | (f2bf(hi) << 16); }
; #define LDX(tok) ({ const u32x2 _q = *(const u32x2*)(xb + (size_t)(tok) * D + cq * 4); (f32x4){bf_lo(_q.x), bf_hi(_q.x), bf_lo(_q.y), bf_hi(_q.y)} * rs[(tok) - t0 + 8]; })
; __global__ void __launch_bounds__(512, 2) fwd_megakernel(Params Pk) {
;     ...
;             for (int s = ta - hw; s <= ta + hw - 2; ++s) if (s >= sbeg && s < send) S += LDX(s);
;             for (int t = ta; t < ta + 32; ++t) {
;                 const int sin_ = t + hw - 1; if (sin_ < send) S += LDX(sin_);
;                 const int wl = (t - hw) > sbeg ? (t - hw) : sbeg, wh = (t + hw) < send ? (t + hw) : send; const float inv = 1.0f / (float)(wh - wl);
;                 const f32x4 xt = LDX(t);
;                 const f32x4 pv = (S * inv - xt) * gv;
;                 u32x2 w; w.x = pk2(pv[0], pv[1]); w.y = pk2(pv[2], pv[3]); *(u32x2*)(pbuf + (size_t)t * D + cq * 4) = w;
;                 const int sout = t - hw; if (sout >= sbeg) S -= LDX(sout);
;             }
	v_lshlrev_b32_e32 v36, 16, v100
	v_and_b32_e32 v37, 0xffff0000, v100
	v_lshlrev_b32_e32 v32, 16, v101
	v_and_b32_e32 v33, 0xffff0000, v101
	v_pk_fma_f32 v[14:15], v[174:175], v[32:33], v[14:15] op_sel_hi:[0,1,1]
	v_pk_fma_f32 v[12:13], v[174:175], v[36:37], v[12:13] op_sel_hi:[0,1,1]
	s_add_i32 s26, s23, 9
	s_max_i32 s26, s26, s16
	s_add_i32 s27, s23, 17
	s_min_i32 s27, s27, s17
	s_sub_i32 s26, s27, s26
	v_cvt_f32_i32_e32 v35, s26
	v_lshlrev_b32_e32 v44, 16, v94
	v_div_scale_f32 v16, s[10:11], v35, v35, 1.0
	v_rcp_f32_e32 v17, v16
	v_div_scale_f32 v38, vcc, 1.0, v35, 1.0
	v_fma_f32 v39, -v16, v17, 1.0
	v_fmac_f32_e32 v17, v39, v17
	v_mul_f32_e32 v39, v38, v17
	v_fma_f32 v43, -v16, v39, v38
	v_fmac_f32_e32 v39, v43, v17
	v_fma_f32 v16, -v16, v39, v38
	v_and_b32_e32 v45, 0xffff0000, v94
	v_lshlrev_b32_e32 v46, 16, v95
	v_div_fmas_f32 v17, v16, v17, v39
	v_and_b32_e32 v47, 0xffff0000, v95
	v_div_fixup_f32 v38, v17, v35, 1.0
	v_pk_mul_f32 v[46:47], v[170:171], v[46:47] op_sel:[1,0] op_sel_hi:[1,1]
	v_pk_mul_f32 v[44:45], v[170:171], v[44:45] op_sel:[1,0] op_sel_hi:[1,1]
	v_pk_fma_f32 v[44:45], v[38:39], v[12:13], v[44:45] op_sel_hi:[0,1,1] neg_lo:[0,0,1] neg_hi:[0,0,1]
	v_pk_fma_f32 v[46:47], v[38:39], v[14:15], v[46:47] op_sel_hi:[0,1,1] neg_lo:[0,0,1] neg_hi:[0,0,1]
	v_pk_mul_f32 v[44:45], v[52:53], v[44:45]
	v_pk_mul_f32 v[46:47], v[54:55], v[46:47]
	v_cvt_pk_bf16_f32 v50, v44, v45
	v_cvt_pk_bf16_f32 v51, v46, v47
	global_store_dwordx2 v41, v[50:51], s[50:51] offset:2048
	v_lshlrev_b32_e32 v36, 16, v86
	v_and_b32_e32 v37, 0xffff0000, v86
	v_lshlrev_b32_e32 v32, 16, v87
	v_and_b32_e32 v33, 0xffff0000, v87
	v_pk_fma_f32 v[14:15], v[166:167], v[32:33], v[14:15] op_sel:[1,0,0] op_sel_hi:[1,1,1] neg_lo:[1,0,0] neg_hi:[1,0,0]
	v_pk_fma_f32 v[12:13], v[166:167], v[36:37], v[12:13] op_sel:[1,0,0] op_sel_hi:[1,1,1] neg_lo:[1,0,0] neg_hi:[1,0,0]
	s_waitcnt vmcnt(31)
	v_lshlrev_b32_e32 v36, 16, v102
	v_and_b32_e32 v37, 0xffff0000, v102
	v_lshlrev_b32_e32 v32, 16, v103
	v_and_b32_e32 v33, 0xffff0000, v103
	v_pk_fma_f32 v[14:15], v[174:175], v[32:33], v[14:15] op_sel:[1,0,0] op_sel_hi:[1,1,1]
	v_pk_fma_f32 v[12:13], v[174:175], v[36:37], v[12:13] op_sel:[1,0,0] op_sel_hi:[1,1,1]
	s_add_i32 s26, s23, 10
	s_max_i32 s26, s26, s16
	s_add_i32 s27, s23, 18
	s_min_i32 s27, s27, s17
	s_sub_i32 s26, s27, s26
	v_cvt_f32_i32_e32 v35, s26
	v_lshlrev_b32_e32 v44, 16, v96
	v_div_scale_f32 v16, s[10:11], v35, v35, 1.0
	v_rcp_f32_e32 v17, v16
	v_div_scale_f32 v38, vcc, 1.0, v35, 1.0
	v_fma_f32 v39, -v16, v17, 1.0
	v_fmac_f32_e32 v17, v39, v17
	v_mul_f32_e32 v39, v38, v17
	v_fma_f32 v43, -v16, v39, v38
	v_fmac_f32_e32 v39, v43, v17
	v_fma_f32 v16, -v16, v39, v38
	v_and_b32_e32 v45, 0xffff0000, v96
	v_lshlrev_b32_e32 v46, 16, v97
	v_div_fmas_f32 v17, v16, v17, v39
	v_and_b32_e32 v47, 0xffff0000, v97
	v_div_fixup_f32 v38, v17, v35, 1.0
	v_pk_mul_f32 v[46:47], v[172:173], v[46:47] op_sel_hi:[0,1]
	v_pk_mul_f32 v[44:45], v[172:173], v[44:45] op_sel_hi:[0,1]
	v_pk_fma_f32 v[44:45], v[38:39], v[12:13], v[44:45] op_sel_hi:[0,1,1] neg_lo:[0,0,1] neg_hi:[0,0,1]
	v_pk_fma_f32 v[46:47], v[38:39], v[14:15], v[46:47] op_sel_hi:[0,1,1] neg_lo:[0,0,1] neg_hi:[0,0,1]
	v_pk_mul_f32 v[44:45], v[52:53], v[44:45]
	v_pk_mul_f32 v[46:47], v[54:55], v[46:47]
	v_cvt_pk_bf16_f32 v48, v44, v45
	v_cvt_pk_bf16_f32 v49, v46, v47
	s_add_u32 s52, s28, 28672
	s_addc_u32 s53, s29, 0
	global_store_dwordx2 v41, v[48:49], s[52:53]
	v_lshlrev_b32_e32 v36, 16, v88
	v_and_b32_e32 v37, 0xffff0000, v88
	v_lshlrev_b32_e32 v32, 16, v89
	v_and_b32_e32 v33, 0xffff0000, v89
	v_pk_fma_f32 v[14:15], v[168:169], v[32:33], v[14:15] op_sel_hi:[0,1,1] neg_lo:[1,0,0] neg_hi:[1,0,0]
	v_pk_fma_f32 v[12:13], v[168:169], v[36:37], v[12:13] op_sel_hi:[0,1,1] neg_lo:[1,0,0] neg_hi:[1,0,0]
	s_waitcnt vmcnt(31)
	v_lshlrev_b32_e32 v36, 16, v104
	v_and_b32_e32 v37, 0xffff0000, v104
	v_lshlrev_b32_e32 v32, 16, v105
	v_and_b32_e32 v33, 0xffff0000, v105
	v_pk_fma_f32 v[14:15], v[176:177], v[32:33], v[14:15] op_sel_hi:[0,1,1]
	v_pk_fma_f32 v[12:13], v[176:177], v[36:37], v[12:13] op_sel_hi:[0,1,1]
	s_add_i32 s26, s23, 11
	s_max_i32 s26, s26, s16
	s_add_i32 s27, s23, 19
	s_min_i32 s27, s27, s17
	s_sub_i32 s26, s27, s26
	v_cvt_f32_i32_e32 v35, s26
	v_lshlrev_b32_e32 v44, 16, v98
	v_div_scale_f32 v16, s[10:11], v35, v35, 1.0
	v_rcp_f32_e32 v17, v16
	v_div_scale_f32 v38, vcc, 1.0, v35, 1.0
	v_fma_f32 v39, -v16, v17, 1.0
	v_fmac_f32_e32 v17, v39, v17
	v_mul_f32_e32 v39, v38, v17
	v_fma_f32 v43, -v16, v39, v38
	v_fmac_f32_e32 v39, v43, v17
	v_fma_f32 v16, -v16, v39, v38
	v_and_b32_e32 v45, 0xffff0000, v98
	v_lshlrev_b32_e32 v46, 16, v99
	v_div_fmas_f32 v17, v16, v17, v39
	v_and_b32_e32 v47, 0xffff0000, v99
	v_div_fixup_f32 v38, v17, v35, 1.0
	v_pk_mul_f32 v[46:47], v[172:173], v[46:47] op_sel:[1,0] op_sel_hi:[1,1]
	v_pk_mul_f32 v[44:45], v[172:173], v[44:45] op_sel:[1,0] op_sel_hi:[1,1]
	v_pk_fma_f32 v[44:45], v[38:39], v[12:13], v[44:45] op_sel_hi:[0,1,1] neg_lo:[0,0,1] neg_hi:[0,0,1]
	v_pk_fma_f32 v[46:47], v[38:39], v[14:15], v[46:47] op_sel_hi:[0,1,1] neg_lo:[0,0,1] neg_hi:[0,0,1]
	v_pk_mul_f32 v[44:45], v[52:53], v[44:45]
	v_pk_mul_f32 v[46:47], v[54:55], v[46:47]
	v_cvt_pk_bf16_f32 v50, v44, v45
	v_cvt_pk_bf16_f32 v51, v46, v47
	global_store_dwordx2 v41, v[50:51], s[52:53] offset:2048
	v_lshlrev_b32_e32 v36, 16, v90
	v_and_b32_e32 v37, 0xffff0000, v90
	v_lshlrev_b32_e32 v32, 16, v91
	v_and_b32_e32 v33, 0xffff0000, v91
	v_pk_fma_f32 v[14:15], v[168:169], v[32:33], v[14:15] op_sel:[1,0,0] op_sel_hi:[1,1,1] neg_lo:[1,0,0] neg_hi:[1,0,0]
	v_pk_fma_f32 v[12:13], v[168:169], v[36:37], v[12:13] op_sel:[1,0,0] op_sel_hi:[1,1,1] neg_lo:[1,0,0] neg_hi:[1,0,0]
	s_waitcnt vmcnt(31)
; __device__ __forceinline__ unsigned pk2(float lo, float hi) { unsigned r; asm volatile("v_cvt_pk_bf16_f32 %0, %1, %2" : "=v"(r) : "v"(lo), "v"(hi)); return r; }
; __device__ __forceinline__ unsigned pk2(float lo, float hi) { return f2bf(lo) | (f2bf(hi) << 16); }
; #define LDX(tok) ({ const u32x2 _q = *(const u32x2*)(xb + (size_t)(tok) * D + cq * 4); (f32x4){bf_lo(_q.x), bf_hi(_q.x), bf_lo(_q.y), bf_hi(_q.y)} * rs[(tok) - t0 + 8]; })
; __global__ void __launch_bounds__(512, 2) fwd_megakernel(Params Pk) {
;     ...
;             for (int s = ta - hw; s <= ta + hw - 2; ++s) if (s >= sbeg && s < send) S += LDX(s);
;             for (int t = ta; t < ta + 32; ++t) {
;                 const int sin_ = t + hw - 1; if (sin_ < send) S += LDX(sin_);
;                 const int wl = (t - hw) > sbeg ? (t - hw) : sbeg, wh = (t + hw) < send ? (t + hw) : send; const float inv = 1.0f / (float)(wh - wl);
;                 const f32x4 xt = LDX(t);
;                 const f32x4 pv = (S * inv - xt) * gv;
;                 u32x2 w; w.x = pk2(pv[0], pv[1]); w.y = pk2(pv[2], pv[3]); *(u32x2*)(pbuf + (size_t)t * D + cq * 4) = w;
;                 const int sout = t - hw; if (sout >= sbeg) S -= LDX(sout);
;             }
	v_lshlrev_b32_e32 v36, 16, v106
	v_and_b32_e32 v37, 0xffff0000, v106
	v_lshlrev_b32_e32 v32, 16, v107
	v_and_b32_e32 v33, 0xffff0000, v107
	v_pk_fma_f32 v[14:15], v[176:177], v[32:33], v[14:15] op_sel:[1,0,0] op_sel_hi:[1,1,1]
	v_pk_fma_f32 v[12:13], v[176:177], v[36:37], v[12:13] op_sel:[1,0,0] op_sel_hi:[1,1,1]
	s_add_i32 s26, s23, 12
	s_max_i32 s26, s26, s16
	s_add_i32 s27, s23, 20
	s_min_i32 s27, s27, s17
	s_sub_i32 s26, s27, s26
	v_cvt_f32_i32_e32 v35, s26
	v_lshlrev_b32_e32 v44, 16, v100
	v_div_scale_f32 v16, s[10:11], v35, v35, 1.0
	v_rcp_f32_e32 v17, v16
	v_div_scale_f32 v38, vcc, 1.0, v35, 1.0
	v_fma_f32 v39, -v16, v17, 1.0
	v_fmac_f32_e32 v17, v39, v17
	v_mul_f32_e32 v39, v38, v17
	v_fma_f32 v43, -v16, v39, v38
	v_fmac_f32_e32 v39, v43, v17
	v_fma_f32 v16, -v16, v39, v38
	v_and_b32_e32 v45, 0xffff0000, v100
	v_lshlrev_b32_e32 v46, 16, v101
	v_div_fmas_f32 v17, v16, v17, v39
	v_and_b32_e32 v47, 0xffff0000, v101
	v_div_fixup_f32 v38, v17, v35, 1.0
	v_pk_mul_f32 v[46:47], v[174:175], v[46:47] op_sel_hi:[0,1]
	v_pk_mul_f32 v[44:45], v[174:175], v[44:45] op_sel_hi:[0,1]
	v_pk_fma_f32 v[44:45], v[38:39], v[12:13], v[44:45] op_sel_hi:[0,1,1] neg_lo:[0,0,1] neg_hi:[0,0,1]
	v_pk_fma_f32 v[46:47], v[38:39], v[14:15], v[46:47] op_sel_hi:[0,1,1] neg_lo:[0,0,1] neg_hi:[0,0,1]
	v_pk_mul_f32 v[44:45], v[52:53], v[44:45]
	v_pk_mul_f32 v[46:47], v[54:55], v[46:47]
	v_cvt_pk_bf16_f32 v48, v44, v45
	v_cvt_pk_bf16_f32 v49, v46, v47
	s_add_u32 s46, s28, 32768
	s_addc_u32 s47, s29, 0
	global_store_dwordx2 v41, v[48:49], s[46:47]
	v_lshlrev_b32_e32 v36, 16, v92
	v_and_b32_e32 v37, 0xffff0000, v92
	v_lshlrev_b32_e32 v32, 16, v93
	v_and_b32_e32 v33, 0xffff0000, v93
	v_pk_fma_f32 v[14:15], v[170:171], v[32:33], v[14:15] op_sel_hi:[0,1,1] neg_lo:[1,0,0] neg_hi:[1,0,0]
	v_pk_fma_f32 v[12:13], v[170:171], v[36:37], v[12:13] op_sel_hi:[0,1,1] neg_lo:[1,0,0] neg_hi:[1,0,0]
	s_waitcnt vmcnt(31)
	v_lshlrev_b32_e32 v36, 16, v108
	v_and_b32_e32 v37, 0xffff0000, v108
	v_lshlrev_b32_e32 v32, 16, v109
	v_and_b32_e32 v33, 0xffff0000, v109
	v_pk_fma_f32 v[14:15], v[178:179], v[32:33], v[14:15] op_sel_hi:[0,1,1]
	v_pk_fma_f32 v[12:13], v[178:179], v[36:37], v[12:13] op_sel_hi:[0,1,1]
	s_add_i32 s26, s23, 13
	s_max_i32 s26, s26, s16
	s_add_i32 s27, s23, 21
	s_min_i32 s27, s27, s17
	s_sub_i32 s26, s27, s26
	v_cvt_f32_i32_e32 v35, s26
	v_lshlrev_b32_e32 v44, 16, v102
	v_div_scale_f32 v16, s[10:11], v35, v35, 1.0
	v_rcp_f32_e32 v17, v16
	v_div_scale_f32 v38, vcc, 1.0, v35, 1.0
	v_fma_f32 v39, -v16, v17, 1.0
	v_fmac_f32_e32 v17, v39, v17
	v_mul_f32_e32 v39, v38, v17
	v_fma_f32 v43, -v16, v39, v38
	v_fmac_f32_e32 v39, v43, v17
	v_fma_f32 v16, -v16, v39, v38
	v_and_b32_e32 v45, 0xffff0000, v102
	v_lshlrev_b32_e32 v46, 16, v103
	v_div_fmas_f32 v17, v16, v17, v39
	v_and_b32_e32 v47, 0xffff0000, v103
	v_div_fixup_f32 v38, v17, v35, 1.0
	v_pk_mul_f32 v[46:47], v[174:175], v[46:47] op_sel:[1,0] op_sel_hi:[1,1]
	v_pk_mul_f32 v[44:45], v[174:175], v[44:45] op_sel:[1,0] op_sel_hi:[1,1]
	v_pk_fma_f32 v[44:45], v[38:39], v[12:13], v[44:45] op_sel_hi:[0,1,1] neg_lo:[0,0,1] neg_hi:[0,0,1]
	v_pk_fma_f32 v[46:47], v[38:39], v[14:15], v[46:47] op_sel_hi:[0,1,1] neg_lo:[0,0,1] neg_hi:[0,0,1]
	v_pk_mul_f32 v[44:45], v[52:53], v[44:45]
	v_pk_mul_f32 v[46:47], v[54:55], v[46:47]
	v_cvt_pk_bf16_f32 v50, v44, v45
	v_cvt_pk_bf16_f32 v51, v46, v47
	global_store_dwordx2 v41, v[50:51], s[46:47] offset:2048
	v_lshlrev_b32_e32 v36, 16, v94
	v_and_b32_e32 v37, 0xffff0000, v94
	v_lshlrev_b32_e32 v32, 16, v95
	v_and_b32_e32 v33, 0xffff0000, v95
	v_pk_fma_f32 v[14:15], v[170:171], v[32:33], v[14:15] op_sel:[1,0,0] op_sel_hi:[1,1,1] neg_lo:[1,0,0] neg_hi:[1,0,0]
	v_pk_fma_f32 v[12:13], v[170:171], v[36:37], v[12:13] op_sel:[1,0,0] op_sel_hi:[1,1,1] neg_lo:[1,0,0] neg_hi:[1,0,0]
	s_waitcnt vmcnt(31)
	v_lshlrev_b32_e32 v36, 16, v110
	v_and_b32_e32 v37, 0xffff0000, v110
	v_lshlrev_b32_e32 v32, 16, v111
	v_and_b32_e32 v33, 0xffff0000, v111
	v_pk_fma_f32 v[14:15], v[178:179], v[32:33], v[14:15] op_sel:[1,0,0] op_sel_hi:[1,1,1]
	v_pk_fma_f32 v[12:13], v[178:179], v[36:37], v[12:13] op_sel:[1,0,0] op_sel_hi:[1,1,1]
	s_add_i32 s26, s23, 14
	s_max_i32 s26, s26, s16
	s_add_i32 s27, s23, 22
	s_min_i32 s27, s27, s17
	s_sub_i32 s26, s27, s26
	v_cvt_f32_i32_e32 v35, s26
	v_lshlrev_b32_e32 v44, 16, v104
	v_div_scale_f32 v16, s[10:11], v35, v35, 1.0
	v_rcp_f32_e32 v17, v16
	v_div_scale_f32 v38, vcc, 1.0, v35, 1.0
	v_fma_f32 v39, -v16, v17, 1.0
	v_fmac_f32_e32 v17, v39, v17
	v_mul_f32_e32 v39, v38, v17
	v_fma_f32 v43, -v16, v39, v38
	v_fmac_f32_e32 v39, v43, v17
	v_fma_f32 v16, -v16, v39, v38
	v_and_b32_e32 v45, 0xffff0000, v104
	v_lshlrev_b32_e32 v46, 16, v105
	v_div_fmas_f32 v17, v16, v17, v39
	v_and_b32_e32 v47, 0xffff0000, v105
	v_div_fixup_f32 v38, v17, v35, 1.0
	v_pk_mul_f32 v[46:47], v[176:177], v[46:47] op_sel_hi:[0,1]
	v_pk_mul_f32 v[44:45], v[176:177], v[44:45] op_sel_hi:[0,1]
	v_pk_fma_f32 v[44:45], v[38:39], v[12:13], v[44:45] op_sel_hi:[0,1,1] neg_lo:[0,0,1] neg_hi:[0,0,1]
	v_pk_fma_f32 v[46:47], v[38:39], v[14:15], v[46:47] op_sel_hi:[0,1,1] neg_lo:[0,0,1] neg_hi:[0,0,1]
	v_pk_mul_f32 v[44:45], v[52:53], v[44:45]
	v_pk_mul_f32 v[46:47], v[54:55], v[46:47]
	v_cvt_pk_bf16_f32 v48, v44, v45
	v_cvt_pk_bf16_f32 v49, v46, v47
	s_add_u32 s48, s28, 36864
	s_addc_u32 s49, s29, 0
	global_store_dwordx2 v41, v[48:49], s[48:49]
	v_lshlrev_b32_e32 v36, 16, v96
	v_and_b32_e32 v37, 0xffff0000, v96
	v_lshlrev_b32_e32 v32, 16, v97
	v_and_b32_e32 v33, 0xffff0000, v97
	v_pk_fma_f32 v[14:15], v[172:173], v[32:33], v[14:15] op_sel_hi:[0,1,1] neg_lo:[1,0,0] neg_hi:[1,0,0]
	v_pk_fma_f32 v[12:13], v[172:173], v[36:37], v[12:13] op_sel_hi:[0,1,1] neg_lo:[1,0,0] neg_hi:[1,0,0]
	s_waitcnt vmcnt(31)
; __device__ __forceinline__ unsigned pk2(float lo, float hi) { unsigned r; asm volatile("v_cvt_pk_bf16_f32 %0, %1, %2" : "=v"(r) : "v"(lo), "v"(hi)); return r; }
; __device__ __forceinline__ unsigned pk2(float lo, float hi) { return f2bf(lo) | (f2bf(hi) << 16); }
; #define LDX(tok) ({ const u32x2 _q = *(const u32x2*)(xb + (size_t)(tok) * D + cq * 4); (f32x4){bf_lo(_q.x), bf_hi(_q.x), bf_lo(_q.y), bf_hi(_q.y)} * rs[(tok) - t0 + 8]; })
; __global__ void __launch_bounds__(512, 2) fwd_megakernel(Params Pk) {
;     ...
;             for (int s = ta - hw; s <= ta + hw - 2; ++s) if (s >= sbeg && s < send) S += LDX(s);
;             for (int t = ta; t < ta + 32; ++t) {
;                 const int sin_ = t + hw - 1; if (sin_ < send) S += LDX(sin_);
;                 const int wl = (t - hw) > sbeg ? (t - hw) : sbeg, wh = (t + hw) < send ? (t + hw) : send; const float inv = 1.0f / (float)(wh - wl);
;                 const f32x4 xt = LDX(t);
;                 const f32x4 pv = (S * inv - xt) * gv;
;                 u32x2 w; w.x = pk2(pv[0], pv[1]); w.y = pk2(pv[2], pv[3]); *(u32x2*)(pbuf + (size_t)t * D + cq * 4) = w;
;                 const int sout = t - hw; if (sout >= sbeg) S -= LDX(sout);
;             }
	v_lshlrev_b32_e32 v36, 16, v112
	v_and_b32_e32 v37, 0xffff0000, v112
	v_lshlrev_b32_e32 v32, 16, v113
	v_and_b32_e32 v33, 0xffff0000, v113
	v_pk_fma_f32 v[14:15], v[180:181], v[32:33], v[14:15] op_sel_hi:[0,1,1]
	v_pk_fma_f32 v[12:13], v[180:181], v[36:37], v[12:13] op_sel_hi:[0,1,1]
	s_add_i32 s26, s23, 15
	s_max_i32 s26, s26, s16
	s_add_i32 s27, s23, 23
	s_min_i32 s27, s27, s17
	s_sub_i32 s26, s27, s26
	v_cvt_f32_i32_e32 v35, s26
	v_lshlrev_b32_e32 v44, 16, v106
	v_div_scale_f32 v16, s[10:11], v35, v35, 1.0
	v_rcp_f32_e32 v17, v16
	v_div_scale_f32 v38, vcc, 1.0, v35, 1.0
	v_fma_f32 v39, -v16, v17, 1.0
	v_fmac_f32_e32 v17, v39, v17
	v_mul_f32_e32 v39, v38, v17
	v_fma_f32 v43, -v16, v39, v38
	v_fmac_f32_e32 v39, v43, v17
	v_fma_f32 v16, -v16, v39, v38
	v_and_b32_e32 v45, 0xffff0000, v106
	v_lshlrev_b32_e32 v46, 16, v107
	v_div_fmas_f32 v17, v16, v17, v39
	v_and_b32_e32 v47, 0xffff0000, v107
	v_div_fixup_f32 v38, v17, v35, 1.0
	v_pk_mul_f32 v[46:47], v[176:177], v[46:47] op_sel:[1,0] op_sel_hi:[1,1]
	v_pk_mul_f32 v[44:45], v[176:177], v[44:45] op_sel:[1,0] op_sel_hi:[1,1]
	v_pk_fma_f32 v[44:45], v[38:39], v[12:13], v[44:45] op_sel_hi:[0,1,1] neg_lo:[0,0,1] neg_hi:[0,0,1]
	v_pk_fma_f32 v[46:47], v[38:39], v[14:15], v[46:47] op_sel_hi:[0,1,1] neg_lo:[0,0,1] neg_hi:[0,0,1]
	v_pk_mul_f32 v[44:45], v[52:53], v[44:45]
	v_pk_mul_f32 v[46:47], v[54:55], v[46:47]
	v_cvt_pk_bf16_f32 v50, v44, v45
	v_cvt_pk_bf16_f32 v51, v46, v47
	global_store_dwordx2 v41, v[50:51], s[48:49] offset:2048
	v_lshlrev_b32_e32 v36, 16, v98
	v_and_b32_e32 v37, 0xffff0000, v98
	v_lshlrev_b32_e32 v32, 16, v99
	v_and_b32_e32 v33, 0xffff0000, v99
	v_pk_fma_f32 v[14:15], v[172:173], v[32:33], v[14:15] op_sel:[1,0,0] op_sel_hi:[1,1,1] neg_lo:[1,0,0] neg_hi:[1,0,0]
	v_pk_fma_f32 v[12:13], v[172:173], v[36:37], v[12:13] op_sel:[1,0,0] op_sel_hi:[1,1,1] neg_lo:[1,0,0] neg_hi:[1,0,0]
	s_waitcnt vmcnt(31)
	v_lshlrev_b32_e32 v36, 16, v114
	v_and_b32_e32 v37, 0xffff0000, v114
	v_lshlrev_b32_e32 v32, 16, v115
	v_and_b32_e32 v33, 0xffff0000, v115
	v_pk_fma_f32 v[14:15], v[180:181], v[32:33], v[14:15] op_sel:[1,0,0] op_sel_hi:[1,1,1]
	v_pk_fma_f32 v[12:13], v[180:181], v[36:37], v[12:13] op_sel:[1,0,0] op_sel_hi:[1,1,1]
	s_add_i32 s26, s23, 16
	s_max_i32 s26, s26, s16
	s_add_i32 s27, s23, 24
	s_min_i32 s27, s27, s17
	s_sub_i32 s26, s27, s26
	v_cvt_f32_i32_e32 v35, s26
	v_lshlrev_b32_e32 v44, 16, v108
	v_div_scale_f32 v16, s[10:11], v35, v35, 1.0
	v_rcp_f32_e32 v17, v16
	v_div_scale_f32 v38, vcc, 1.0, v35, 1.0
	v_fma_f32 v39, -v16, v17, 1.0
	v_fmac_f32_e32 v17, v39, v17
	v_mul_f32_e32 v39, v38, v17
	v_fma_f32 v43, -v16, v39, v38
	v_fmac_f32_e32 v39, v43, v17
	v_fma_f32 v16, -v16, v39, v38
	v_and_b32_e32 v45, 0xffff0000, v108
	v_lshlrev_b32_e32 v46, 16, v109
	v_div_fmas_f32 v17, v16, v17, v39
	v_and_b32_e32 v47, 0xffff0000, v109
	v_div_fixup_f32 v38, v17, v35, 1.0
	v_pk_mul_f32 v[46:47], v[178:179], v[46:47] op_sel_hi:[0,1]
	v_pk_mul_f32 v[44:45], v[178:179], v[44:45] op_sel_hi:[0,1]
	v_pk_fma_f32 v[44:45], v[38:39], v[12:13], v[44:45] op_sel_hi:[0,1,1] neg_lo:[0,0,1] neg_hi:[0,0,1]
	v_pk_fma_f32 v[46:47], v[38:39], v[14:15], v[46:47] op_sel_hi:[0,1,1] neg_lo:[0,0,1] neg_hi:[0,0,1]
	v_pk_mul_f32 v[44:45], v[52:53], v[44:45]
	v_pk_mul_f32 v[46:47], v[54:55], v[46:47]
	v_cvt_pk_bf16_f32 v48, v44, v45
	v_cvt_pk_bf16_f32 v49, v46, v47
	s_add_u32 s50, s28, 40960
	s_addc_u32 s51, s29, 0
	global_store_dwordx2 v41, v[48:49], s[50:51]
	v_lshlrev_b32_e32 v36, 16, v100
	v_and_b32_e32 v37, 0xffff0000, v100
	v_lshlrev_b32_e32 v32, 16, v101
	v_and_b32_e32 v33, 0xffff0000, v101
	v_pk_fma_f32 v[14:15], v[174:175], v[32:33], v[14:15] op_sel_hi:[0,1,1] neg_lo:[1,0,0] neg_hi:[1,0,0]
	v_pk_fma_f32 v[12:13], v[174:175], v[36:37], v[12:13] op_sel_hi:[0,1,1] neg_lo:[1,0,0] neg_hi:[1,0,0]
	s_waitcnt vmcnt(31)
	v_lshlrev_b32_e32 v36, 16, v116
	v_and_b32_e32 v37, 0xffff0000, v116
	v_lshlrev_b32_e32 v32, 16, v117
	v_and_b32_e32 v33, 0xffff0000, v117
	v_pk_fma_f32 v[14:15], v[182:183], v[32:33], v[14:15] op_sel_hi:[0,1,1]
	v_pk_fma_f32 v[12:13], v[182:183], v[36:37], v[12:13] op_sel_hi:[0,1,1]
	s_add_i32 s26, s23, 17
	s_max_i32 s26, s26, s16
	s_add_i32 s27, s23, 25
	s_min_i32 s27, s27, s17
	s_sub_i32 s26, s27, s26
	v_cvt_f32_i32_e32 v35, s26
	v_lshlrev_b32_e32 v44, 16, v110
	v_div_scale_f32 v16, s[10:11], v35, v35, 1.0
	v_rcp_f32_e32 v17, v16
	v_div_scale_f32 v38, vcc, 1.0, v35, 1.0
	v_fma_f32 v39, -v16, v17, 1.0
	v_fmac_f32_e32 v17, v39, v17
	v_mul_f32_e32 v39, v38, v17
	v_fma_f32 v43, -v16, v39, v38
	v_fmac_f32_e32 v39, v43, v17
	v_fma_f32 v16, -v16, v39, v38
	v_and_b32_e32 v45, 0xffff0000, v110
	v_lshlrev_b32_e32 v46, 16, v111
	v_div_fmas_f32 v17, v16, v17, v39
	v_and_b32_e32 v47, 0xffff0000, v111
	v_div_fixup_f32 v38, v17, v35, 1.0
	v_pk_mul_f32 v[46:47], v[178:179], v[46:47] op_sel:[1,0] op_sel_hi:[1,1]
	v_pk_mul_f32 v[44:45], v[178:179], v[44:45] op_sel:[1,0] op_sel_hi:[1,1]
	v_pk_fma_f32 v[44:45], v[38:39], v[12:13], v[44:45] op_sel_hi:[0,1,1] neg_lo:[0,0,1] neg_hi:[0,0,1]
	v_pk_fma_f32 v[46:47], v[38:39], v[14:15], v[46:47] op_sel_hi:[0,1,1] neg_lo:[0,0,1] neg_hi:[0,0,1]
	v_pk_mul_f32 v[44:45], v[52:53], v[44:45]
	v_pk_mul_f32 v[46:47], v[54:55], v[46:47]
	v_cvt_pk_bf16_f32 v50, v44, v45
	v_cvt_pk_bf16_f32 v51, v46, v47
	global_store_dwordx2 v41, v[50:51], s[50:51] offset:2048
	v_lshlrev_b32_e32 v36, 16, v102
	v_and_b32_e32 v37, 0xffff0000, v102
	v_lshlrev_b32_e32 v32, 16, v103
	v_and_b32_e32 v33, 0xffff0000, v103
	v_pk_fma_f32 v[14:15], v[174:175], v[32:33], v[14:15] op_sel:[1,0,0] op_sel_hi:[1,1,1] neg_lo:[1,0,0] neg_hi:[1,0,0]
	v_pk_fma_f32 v[12:13], v[174:175], v[36:37], v[12:13] op_sel:[1,0,0] op_sel_hi:[1,1,1] neg_lo:[1,0,0] neg_hi:[1,0,0]
	s_waitcnt vmcnt(31)
; __device__ __forceinline__ unsigned pk2(float lo, float hi) { unsigned r; asm volatile("v_cvt_pk_bf16_f32 %0, %1, %2" : "=v"(r) : "v"(lo), "v"(hi)); return r; }
; __device__ __forceinline__ unsigned pk2(float lo, float hi) { return f2bf(lo) | (f2bf(hi) << 16); }
; #define LDX(tok) ({ const u32x2 _q = *(const u32x2*)(xb + (size_t)(tok) * D + cq * 4); (f32x4){bf_lo(_q.x), bf_hi(_q.x), bf_lo(_q.y), bf_hi(_q.y)} * rs[(tok) - t0 + 8]; })
; __global__ void __launch_bounds__(512, 2) fwd_megakernel(Params Pk) {
;     ...
;             for (int s = ta - hw; s <= ta + hw - 2; ++s) if (s >= sbeg && s < send) S += LDX(s);
;             for (int t = ta; t < ta + 32; ++t) {
;                 const int sin_ = t + hw - 1; if (sin_ < send) S += LDX(sin_);
;                 const int wl = (t - hw) > sbeg ? (t - hw) : sbeg, wh = (t + hw) < send ? (t + hw) : send; const float inv = 1.0f / (float)(wh - wl);
;                 const f32x4 xt = LDX(t);
;                 const f32x4 pv = (S * inv - xt) * gv;
;                 u32x2 w; w.x = pk2(pv[0], pv[1]); w.y = pk2(pv[2], pv[3]); *(u32x2*)(pbuf + (size_t)t * D + cq * 4) = w;
;                 const int sout = t - hw; if (sout >= sbeg) S -= LDX(sout);
;             }
	v_lshlrev_b32_e32 v36, 16, v118
	v_and_b32_e32 v37, 0xffff0000, v118
	v_lshlrev_b32_e32 v32, 16, v119
	v_and_b32_e32 v33, 0xffff0000, v119
	v_pk_fma_f32 v[14:15], v[182:183], v[32:33], v[14:15] op_sel:[1,0,0] op_sel_hi:[1,1,1]
	v_pk_fma_f32 v[12:13], v[182:183], v[36:37], v[12:13] op_sel:[1,0,0] op_sel_hi:[1,1,1]
	s_add_i32 s26, s23, 18
	s_max_i32 s26, s26, s16
	s_add_i32 s27, s23, 26
	s_min_i32 s27, s27, s17
	s_sub_i32 s26, s27, s26
	v_cvt_f32_i32_e32 v35, s26
	v_lshlrev_b32_e32 v44, 16, v112
	v_div_scale_f32 v16, s[10:11], v35, v35, 1.0
	v_rcp_f32_e32 v17, v16
	v_div_scale_f32 v38, vcc, 1.0, v35, 1.0
	v_fma_f32 v39, -v16, v17, 1.0
	v_fmac_f32_e32 v17, v39, v17
	v_mul_f32_e32 v39, v38, v17
	v_fma_f32 v43, -v16, v39, v38
	v_fmac_f32_e32 v39, v43, v17
	v_fma_f32 v16, -v16, v39, v38
	v_and_b32_e32 v45, 0xffff0000, v112
	v_lshlrev_b32_e32 v46, 16, v113
	v_div_fmas_f32 v17, v16, v17, v39
	v_and_b32_e32 v47, 0xffff0000, v113
	v_div_fixup_f32 v38, v17, v35, 1.0
	v_pk_mul_f32 v[46:47], v[180:181], v[46:47] op_sel_hi:[0,1]
	v_pk_mul_f32 v[44:45], v[180:181], v[44:45] op_sel_hi:[0,1]
	v_pk_fma_f32 v[44:45], v[38:39], v[12:13], v[44:45] op_sel_hi:[0,1,1] neg_lo:[0,0,1] neg_hi:[0,0,1]
	v_pk_fma_f32 v[46:47], v[38:39], v[14:15], v[46:47] op_sel_hi:[0,1,1] neg_lo:[0,0,1] neg_hi:[0,0,1]
	v_pk_mul_f32 v[44:45], v[52:53], v[44:45]
	v_pk_mul_f32 v[46:47], v[54:55], v[46:47]
	v_cvt_pk_bf16_f32 v48, v44, v45
	v_cvt_pk_bf16_f32 v49, v46, v47
	s_add_u32 s52, s28, 45056
	s_addc_u32 s53, s29, 0
	global_store_dwordx2 v41, v[48:49], s[52:53]
	v_lshlrev_b32_e32 v36, 16, v104
	v_and_b32_e32 v37, 0xffff0000, v104
	v_lshlrev_b32_e32 v32, 16, v105
	v_and_b32_e32 v33, 0xffff0000, v105
	v_pk_fma_f32 v[14:15], v[176:177], v[32:33], v[14:15] op_sel_hi:[0,1,1] neg_lo:[1,0,0] neg_hi:[1,0,0]
	v_pk_fma_f32 v[12:13], v[176:177], v[36:37], v[12:13] op_sel_hi:[0,1,1] neg_lo:[1,0,0] neg_hi:[1,0,0]
	s_waitcnt vmcnt(31)
	v_lshlrev_b32_e32 v36, 16, v120
	v_and_b32_e32 v37, 0xffff0000, v120
	v_lshlrev_b32_e32 v32, 16, v121
	v_and_b32_e32 v33, 0xffff0000, v121
	v_pk_fma_f32 v[14:15], v[184:185], v[32:33], v[14:15] op_sel_hi:[0,1,1]
	v_pk_fma_f32 v[12:13], v[184:185], v[36:37], v[12:13] op_sel_hi:[0,1,1]
	s_add_i32 s26, s23, 19
	s_max_i32 s26, s26, s16
	s_add_i32 s27, s23, 27
	s_min_i32 s27, s27, s17
	s_sub_i32 s26, s27, s26
	v_cvt_f32_i32_e32 v35, s26
	v_lshlrev_b32_e32 v44, 16, v114
	v_div_scale_f32 v16, s[10:11], v35, v35, 1.0
	v_rcp_f32_e32 v17, v16
	v_div_scale_f32 v38, vcc, 1.0, v35, 1.0
	v_fma_f32 v39, -v16, v17, 1.0
	v_fmac_f32_e32 v17, v39, v17
	v_mul_f32_e32 v39, v38, v17
	v_fma_f32 v43, -v16, v39, v38
	v_fmac_f32_e32 v39, v43, v17
	v_fma_f32 v16, -v16, v39, v38
	v_and_b32_e32 v45, 0xffff0000, v114
	v_lshlrev_b32_e32 v46, 16, v115
	v_div_fmas_f32 v17, v16, v17, v39
	v_and_b32_e32 v47, 0xffff0000, v115
	v_div_fixup_f32 v38, v17, v35, 1.0
	v_pk_mul_f32 v[46:47], v[180:181], v[46:47] op_sel:[1,0] op_sel_hi:[1,1]
	v_pk_mul_f32 v[44:45], v[180:181], v[44:45] op_sel:[1,0] op_sel_hi:[1,1]
	v_pk_fma_f32 v[44:45], v[38:39], v[12:13], v[44:45] op_sel_hi:[0,1,1] neg_lo:[0,0,1] neg_hi:[0,0,1]
	v_pk_fma_f32 v[46:47], v[38:39], v[14:15], v[46:47] op_sel_hi:[0,1,1] neg_lo:[0,0,1] neg_hi:[0,0,1]
	v_pk_mul_f32 v[44:45], v[52:53], v[44:45]
	v_pk_mul_f32 v[46:47], v[54:55], v[46:47]
	v_cvt_pk_bf16_f32 v50, v44, v45
	v_cvt_pk_bf16_f32 v51, v46, v47
	global_store_dwordx2 v41, v[50:51], s[52:53] offset:2048
	v_lshlrev_b32_e32 v36, 16, v106
	v_and_b32_e32 v37, 0xffff0000, v106
	v_lshlrev_b32_e32 v32, 16, v107
	v_and_b32_e32 v33, 0xffff0000, v107
	v_pk_fma_f32 v[14:15], v[176:177], v[32:33], v[14:15] op_sel:[1,0,0] op_sel_hi:[1,1,1] neg_lo:[1,0,0] neg_hi:[1,0,0]
	v_pk_fma_f32 v[12:13], v[176:177], v[36:37], v[12:13] op_sel:[1,0,0] op_sel_hi:[1,1,1] neg_lo:[1,0,0] neg_hi:[1,0,0]
	s_waitcnt vmcnt(31)
	v_lshlrev_b32_e32 v36, 16, v122
	v_and_b32_e32 v37, 0xffff0000, v122
	v_lshlrev_b32_e32 v32, 16, v123
	v_and_b32_e32 v33, 0xffff0000, v123
	v_pk_fma_f32 v[14:15], v[184:185], v[32:33], v[14:15] op_sel:[1,0,0] op_sel_hi:[1,1,1]
	v_pk_fma_f32 v[12:13], v[184:185], v[36:37], v[12:13] op_sel:[1,0,0] op_sel_hi:[1,1,1]
	s_add_i32 s26, s23, 20
	s_max_i32 s26, s26, s16
	s_add_i32 s27, s23, 28
	s_min_i32 s27, s27, s17
	s_sub_i32 s26, s27, s26
	v_cvt_f32_i32_e32 v35, s26
	v_lshlrev_b32_e32 v44, 16, v116
	v_div_scale_f32 v16, s[10:11], v35, v35, 1.0
	v_rcp_f32_e32 v17, v16
	v_div_scale_f32 v38, vcc, 1.0, v35, 1.0
	v_fma_f32 v39, -v16, v17, 1.0
	v_fmac_f32_e32 v17, v39, v17
	v_mul_f32_e32 v39, v38, v17
	v_fma_f32 v43, -v16, v39, v38
	v_fmac_f32_e32 v39, v43, v17
	v_fma_f32 v16, -v16, v39, v38
	v_and_b32_e32 v45, 0xffff0000, v116
	v_lshlrev_b32_e32 v46, 16, v117
	v_div_fmas_f32 v17, v16, v17, v39
	v_and_b32_e32 v47, 0xffff0000, v117
	v_div_fixup_f32 v38, v17, v35, 1.0
	v_pk_mul_f32 v[46:47], v[182:183], v[46:47] op_sel_hi:[0,1]
	v_pk_mul_f32 v[44:45], v[182:183], v[44:45] op_sel_hi:[0,1]
	v_pk_fma_f32 v[44:45], v[38:39], v[12:13], v[44:45] op_sel_hi:[0,1,1] neg_lo:[0,0,1] neg_hi:[0,0,1]
	v_pk_fma_f32 v[46:47], v[38:39], v[14:15], v[46:47] op_sel_hi:[0,1,1] neg_lo:[0,0,1] neg_hi:[0,0,1]
	v_pk_mul_f32 v[44:45], v[52:53], v[44:45]
	v_pk_mul_f32 v[46:47], v[54:55], v[46:47]
	v_cvt_pk_bf16_f32 v48, v44, v45
	v_cvt_pk_bf16_f32 v49, v46, v47
	s_add_u32 s46, s28, 49152
	s_addc_u32 s47, s29, 0
	global_store_dwordx2 v41, v[48:49], s[46:47]
	v_lshlrev_b32_e32 v36, 16, v108
	v_and_b32_e32 v37, 0xffff0000, v108
	v_lshlrev_b32_e32 v32, 16, v109
	v_and_b32_e32 v33, 0xffff0000, v109
	v_pk_fma_f32 v[14:15], v[178:179], v[32:33], v[14:15] op_sel_hi:[0,1,1] neg_lo:[1,0,0] neg_hi:[1,0,0]
	v_pk_fma_f32 v[12:13], v[178:179], v[36:37], v[12:13] op_sel_hi:[0,1,1] neg_lo:[1,0,0] neg_hi:[1,0,0]
	s_waitcnt vmcnt(31)
; __device__ __forceinline__ unsigned pk2(float lo, float hi) { unsigned r; asm volatile("v_cvt_pk_bf16_f32 %0, %1, %2" : "=v"(r) : "v"(lo), "v"(hi)); return r; }
; __device__ __forceinline__ unsigned pk2(float lo, float hi) { return f2bf(lo) | (f2bf(hi) << 16); }
; #define LDX(tok) ({ const u32x2 _q = *(const u32x2*)(xb + (size_t)(tok) * D + cq * 4); (f32x4){bf_lo(_q.x), bf_hi(_q.x), bf_lo(_q.y), bf_hi(_q.y)} * rs[(tok) - t0 + 8]; })
; __global__ void __launch_bounds__(512, 2) fwd_megakernel(Params Pk) {
;     ...
;             for (int s = ta - hw; s <= ta + hw - 2; ++s) if (s >= sbeg && s < send) S += LDX(s);
;             for (int t = ta; t < ta + 32; ++t) {
;                 const int sin_ = t + hw - 1; if (sin_ < send) S += LDX(sin_);
;                 const int wl = (t - hw) > sbeg ? (t - hw) : sbeg, wh = (t + hw) < send ? (t + hw) : send; const float inv = 1.0f / (float)(wh - wl);
;                 const f32x4 xt = LDX(t);
;                 const f32x4 pv = (S * inv - xt) * gv;
;                 u32x2 w; w.x = pk2(pv[0], pv[1]); w.y = pk2(pv[2], pv[3]); *(u32x2*)(pbuf + (size_t)t * D + cq * 4) = w;
;                 const int sout = t - hw; if (sout >= sbeg) S -= LDX(sout);
;             }
	v_lshlrev_b32_e32 v36, 16, v124
	v_and_b32_e32 v37, 0xffff0000, v124
	v_lshlrev_b32_e32 v32, 16, v125
	v_and_b32_e32 v33, 0xffff0000, v125
	v_pk_fma_f32 v[14:15], v[186:187], v[32:33], v[14:15] op_sel_hi:[0,1,1]
	v_pk_fma_f32 v[12:13], v[186:187], v[36:37], v[12:13] op_sel_hi:[0,1,1]
	s_add_i32 s26, s23, 21
	s_max_i32 s26, s26, s16
	s_add_i32 s27, s23, 29
	s_min_i32 s27, s27, s17
	s_sub_i32 s26, s27, s26
	v_cvt_f32_i32_e32 v35, s26
	v_lshlrev_b32_e32 v44, 16, v118
	v_div_scale_f32 v16, s[10:11], v35, v35, 1.0
	v_rcp_f32_e32 v17, v16
	v_div_scale_f32 v38, vcc, 1.0, v35, 1.0
	v_fma_f32 v39, -v16, v17, 1.0
	v_fmac_f32_e32 v17, v39, v17
	v_mul_f32_e32 v39, v38, v17
	v_fma_f32 v43, -v16, v39, v38
	v_fmac_f32_e32 v39, v43, v17
	v_fma_f32 v16, -v16, v39, v38
	v_and_b32_e32 v45, 0xffff0000, v118
	v_lshlrev_b32_e32 v46, 16, v119
	v_div_fmas_f32 v17, v16, v17, v39
	v_and_b32_e32 v47, 0xffff0000, v119
	v_div_fixup_f32 v38, v17, v35, 1.0
	v_pk_mul_f32 v[46:47], v[182:183], v[46:47] op_sel:[1,0] op_sel_hi:[1,1]
	v_pk_mul_f32 v[44:45], v[182:183], v[44:45] op_sel:[1,0] op_sel_hi:[1,1]
	v_pk_fma_f32 v[44:45], v[38:39], v[12:13], v[44:45] op_sel_hi:[0,1,1] neg_lo:[0,0,1] neg_hi:[0,0,1]
	v_pk_fma_f32 v[46:47], v[38:39], v[14:15], v[46:47] op_sel_hi:[0,1,1] neg_lo:[0,0,1] neg_hi:[0,0,1]
	v_pk_mul_f32 v[44:45], v[52:53], v[44:45]
	v_pk_mul_f32 v[46:47], v[54:55], v[46:47]
	v_cvt_pk_bf16_f32 v50, v44, v45
	v_cvt_pk_bf16_f32 v51, v46, v47
	global_store_dwordx2 v41, v[50:51], s[46:47] offset:2048
	v_lshlrev_b32_e32 v36, 16, v110
	v_and_b32_e32 v37, 0xffff0000, v110
	v_lshlrev_b32_e32 v32, 16, v111
	v_and_b32_e32 v33, 0xffff0000, v111
	v_pk_fma_f32 v[14:15], v[178:179], v[32:33], v[14:15] op_sel:[1,0,0] op_sel_hi:[1,1,1] neg_lo:[1,0,0] neg_hi:[1,0,0]
	v_pk_fma_f32 v[12:13], v[178:179], v[36:37], v[12:13] op_sel:[1,0,0] op_sel_hi:[1,1,1] neg_lo:[1,0,0] neg_hi:[1,0,0]
	s_waitcnt vmcnt(31)
	v_lshlrev_b32_e32 v36, 16, v126
	v_and_b32_e32 v37, 0xffff0000, v126
	v_lshlrev_b32_e32 v32, 16, v127
	v_and_b32_e32 v33, 0xffff0000, v127
	v_pk_fma_f32 v[14:15], v[186:187], v[32:33], v[14:15] op_sel:[1,0,0] op_sel_hi:[1,1,1]
	v_pk_fma_f32 v[12:13], v[186:187], v[36:37], v[12:13] op_sel:[1,0,0] op_sel_hi:[1,1,1]
	s_add_i32 s26, s23, 22
	s_max_i32 s26, s26, s16
	s_add_i32 s27, s23, 30
	s_min_i32 s27, s27, s17
	s_sub_i32 s26, s27, s26
	v_cvt_f32_i32_e32 v35, s26
	v_lshlrev_b32_e32 v44, 16, v120
	v_div_scale_f32 v16, s[10:11], v35, v35, 1.0
	v_rcp_f32_e32 v17, v16
	v_div_scale_f32 v38, vcc, 1.0, v35, 1.0
	v_fma_f32 v39, -v16, v17, 1.0
	v_fmac_f32_e32 v17, v39, v17
	v_mul_f32_e32 v39, v38, v17
	v_fma_f32 v43, -v16, v39, v38
	v_fmac_f32_e32 v39, v43, v17
	v_fma_f32 v16, -v16, v39, v38
	v_and_b32_e32 v45, 0xffff0000, v120
	v_lshlrev_b32_e32 v46, 16, v121
	v_div_fmas_f32 v17, v16, v17, v39
	v_and_b32_e32 v47, 0xffff0000, v121
	v_div_fixup_f32 v38, v17, v35, 1.0
	v_pk_mul_f32 v[46:47], v[184:185], v[46:47] op_sel_hi:[0,1]
	v_pk_mul_f32 v[44:45], v[184:185], v[44:45] op_sel_hi:[0,1]
	v_pk_fma_f32 v[44:45], v[38:39], v[12:13], v[44:45] op_sel_hi:[0,1,1] neg_lo:[0,0,1] neg_hi:[0,0,1]
	v_pk_fma_f32 v[46:47], v[38:39], v[14:15], v[46:47] op_sel_hi:[0,1,1] neg_lo:[0,0,1] neg_hi:[0,0,1]
	v_pk_mul_f32 v[44:45], v[52:53], v[44:45]
	v_pk_mul_f32 v[46:47], v[54:55], v[46:47]
	v_cvt_pk_bf16_f32 v48, v44, v45
	v_cvt_pk_bf16_f32 v49, v46, v47
	s_add_u32 s48, s28, 53248
	s_addc_u32 s49, s29, 0
	global_store_dwordx2 v41, v[48:49], s[48:49]
	v_lshlrev_b32_e32 v36, 16, v112
	v_and_b32_e32 v37, 0xffff0000, v112
	v_lshlrev_b32_e32 v32, 16, v113
	v_and_b32_e32 v33, 0xffff0000, v113
	v_pk_fma_f32 v[14:15], v[180:181], v[32:33], v[14:15] op_sel_hi:[0,1,1] neg_lo:[1,0,0] neg_hi:[1,0,0]
	v_pk_fma_f32 v[12:13], v[180:181], v[36:37], v[12:13] op_sel_hi:[0,1,1] neg_lo:[1,0,0] neg_hi:[1,0,0]
	s_waitcnt vmcnt(31)
	v_lshlrev_b32_e32 v36, 16, v128
	v_and_b32_e32 v37, 0xffff0000, v128
	v_lshlrev_b32_e32 v32, 16, v129
	v_and_b32_e32 v33, 0xffff0000, v129
	v_pk_fma_f32 v[14:15], v[188:189], v[32:33], v[14:15] op_sel_hi:[0,1,1]
	v_pk_fma_f32 v[12:13], v[188:189], v[36:37], v[12:13] op_sel_hi:[0,1,1]
	s_add_i32 s26, s23, 23
	s_max_i32 s26, s26, s16
	s_add_i32 s27, s23, 31
	s_min_i32 s27, s27, s17
	s_sub_i32 s26, s27, s26
	v_cvt_f32_i32_e32 v35, s26
	v_lshlrev_b32_e32 v44, 16, v122
	v_div_scale_f32 v16, s[10:11], v35, v35, 1.0
	v_rcp_f32_e32 v17, v16
	v_div_scale_f32 v38, vcc, 1.0, v35, 1.0
	v_fma_f32 v39, -v16, v17, 1.0
	v_fmac_f32_e32 v17, v39, v17
	v_mul_f32_e32 v39, v38, v17
	v_fma_f32 v43, -v16, v39, v38
	v_fmac_f32_e32 v39, v43, v17
	v_fma_f32 v16, -v16, v39, v38
	v_and_b32_e32 v45, 0xffff0000, v122
	v_lshlrev_b32_e32 v46, 16, v123
	v_div_fmas_f32 v17, v16, v17, v39
	v_and_b32_e32 v47, 0xffff0000, v123
	v_div_fixup_f32 v38, v17, v35, 1.0
	v_pk_mul_f32 v[46:47], v[184:185], v[46:47] op_sel:[1,0] op_sel_hi:[1,1]
	v_pk_mul_f32 v[44:45], v[184:185], v[44:45] op_sel:[1,0] op_sel_hi:[1,1]
	v_pk_fma_f32 v[44:45], v[38:39], v[12:13], v[44:45] op_sel_hi:[0,1,1] neg_lo:[0,0,1] neg_hi:[0,0,1]
	v_pk_fma_f32 v[46:47], v[38:39], v[14:15], v[46:47] op_sel_hi:[0,1,1] neg_lo:[0,0,1] neg_hi:[0,0,1]
	v_pk_mul_f32 v[44:45], v[52:53], v[44:45]
	v_pk_mul_f32 v[46:47], v[54:55], v[46:47]
	v_cvt_pk_bf16_f32 v50, v44, v45
	v_cvt_pk_bf16_f32 v51, v46, v47
	global_store_dwordx2 v41, v[50:51], s[48:49] offset:2048
	v_lshlrev_b32_e32 v36, 16, v114
	v_and_b32_e32 v37, 0xffff0000, v114
	v_lshlrev_b32_e32 v32, 16, v115
	v_and_b32_e32 v33, 0xffff0000, v115
	v_pk_fma_f32 v[14:15], v[180:181], v[32:33], v[14:15] op_sel:[1,0,0] op_sel_hi:[1,1,1] neg_lo:[1,0,0] neg_hi:[1,0,0]
	v_pk_fma_f32 v[12:13], v[180:181], v[36:37], v[12:13] op_sel:[1,0,0] op_sel_hi:[1,1,1] neg_lo:[1,0,0] neg_hi:[1,0,0]
	s_waitcnt vmcnt(31)
; __device__ __forceinline__ unsigned pk2(float lo, float hi) { unsigned r; asm volatile("v_cvt_pk_bf16_f32 %0, %1, %2" : "=v"(r) : "v"(lo), "v"(hi)); return r; }
; __device__ __forceinline__ unsigned pk2(float lo, float hi) { return f2bf(lo) | (f2bf(hi) << 16); }
; #define LDX(tok) ({ const u32x2 _q = *(const u32x2*)(xb + (size_t)(tok) * D + cq * 4); (f32x4){bf_lo(_q.x), bf_hi(_q.x), bf_lo(_q.y), bf_hi(_q.y)} * rs[(tok) - t0 + 8]; })
; __global__ void __launch_bounds__(512, 2) fwd_megakernel(Params Pk) {
;     ...
;             for (int s = ta - hw; s <= ta + hw - 2; ++s) if (s >= sbeg && s < send) S += LDX(s);
;             for (int t = ta; t < ta + 32; ++t) {
;                 const int sin_ = t + hw - 1; if (sin_ < send) S += LDX(sin_);
;                 const int wl = (t - hw) > sbeg ? (t - hw) : sbeg, wh = (t + hw) < send ? (t + hw) : send; const float inv = 1.0f / (float)(wh - wl);
;                 const f32x4 xt = LDX(t);
;                 const f32x4 pv = (S * inv - xt) * gv;
;                 u32x2 w; w.x = pk2(pv[0], pv[1]); w.y = pk2(pv[2], pv[3]); *(u32x2*)(pbuf + (size_t)t * D + cq * 4) = w;
;                 const int sout = t - hw; if (sout >= sbeg) S -= LDX(sout);
;             }
	v_lshlrev_b32_e32 v36, 16, v130
	v_and_b32_e32 v37, 0xffff0000, v130
	v_lshlrev_b32_e32 v32, 16, v131
	v_and_b32_e32 v33, 0xffff0000, v131
	v_pk_fma_f32 v[14:15], v[188:189], v[32:33], v[14:15] op_sel:[1,0,0] op_sel_hi:[1,1,1]
	v_pk_fma_f32 v[12:13], v[188:189], v[36:37], v[12:13] op_sel:[1,0,0] op_sel_hi:[1,1,1]
	s_add_i32 s26, s23, 24
	s_max_i32 s26, s26, s16
	s_add_i32 s27, s23, 32
	s_min_i32 s27, s27, s17
	s_sub_i32 s26, s27, s26
	v_cvt_f32_i32_e32 v35, s26
	v_lshlrev_b32_e32 v44, 16, v124
	v_div_scale_f32 v16, s[10:11], v35, v35, 1.0
	v_rcp_f32_e32 v17, v16
	v_div_scale_f32 v38, vcc, 1.0, v35, 1.0
	v_fma_f32 v39, -v16, v17, 1.0
	v_fmac_f32_e32 v17, v39, v17
	v_mul_f32_e32 v39, v38, v17
	v_fma_f32 v43, -v16, v39, v38
	v_fmac_f32_e32 v39, v43, v17
	v_fma_f32 v16, -v16, v39, v38
	v_and_b32_e32 v45, 0xffff0000, v124
	v_lshlrev_b32_e32 v46, 16, v125
	v_div_fmas_f32 v17, v16, v17, v39
	v_and_b32_e32 v47, 0xffff0000, v125
	v_div_fixup_f32 v38, v17, v35, 1.0
	v_pk_mul_f32 v[46:47], v[186:187], v[46:47] op_sel_hi:[0,1]
	v_pk_mul_f32 v[44:45], v[186:187], v[44:45] op_sel_hi:[0,1]
	v_pk_fma_f32 v[44:45], v[38:39], v[12:13], v[44:45] op_sel_hi:[0,1,1] neg_lo:[0,0,1] neg_hi:[0,0,1]
	v_pk_fma_f32 v[46:47], v[38:39], v[14:15], v[46:47] op_sel_hi:[0,1,1] neg_lo:[0,0,1] neg_hi:[0,0,1]
	v_pk_mul_f32 v[44:45], v[52:53], v[44:45]
	v_pk_mul_f32 v[46:47], v[54:55], v[46:47]
	v_cvt_pk_bf16_f32 v48, v44, v45
	v_cvt_pk_bf16_f32 v49, v46, v47
	s_add_u32 s50, s28, 57344
	s_addc_u32 s51, s29, 0
	global_store_dwordx2 v41, v[48:49], s[50:51]
	v_lshlrev_b32_e32 v36, 16, v116
	v_and_b32_e32 v37, 0xffff0000, v116
	v_lshlrev_b32_e32 v32, 16, v117
	v_and_b32_e32 v33, 0xffff0000, v117
	v_pk_fma_f32 v[14:15], v[182:183], v[32:33], v[14:15] op_sel_hi:[0,1,1] neg_lo:[1,0,0] neg_hi:[1,0,0]
	v_pk_fma_f32 v[12:13], v[182:183], v[36:37], v[12:13] op_sel_hi:[0,1,1] neg_lo:[1,0,0] neg_hi:[1,0,0]
	s_waitcnt vmcnt(31)
	v_lshlrev_b32_e32 v36, 16, v132
	v_and_b32_e32 v37, 0xffff0000, v132
	v_lshlrev_b32_e32 v32, 16, v133
	v_and_b32_e32 v33, 0xffff0000, v133
	v_pk_fma_f32 v[14:15], v[190:191], v[32:33], v[14:15] op_sel_hi:[0,1,1]
	v_pk_fma_f32 v[12:13], v[190:191], v[36:37], v[12:13] op_sel_hi:[0,1,1]
	s_add_i32 s26, s23, 25
	s_max_i32 s26, s26, s16
	s_add_i32 s27, s23, 33
	s_min_i32 s27, s27, s17
	s_sub_i32 s26, s27, s26
	v_cvt_f32_i32_e32 v35, s26
	v_lshlrev_b32_e32 v44, 16, v126
	v_div_scale_f32 v16, s[10:11], v35, v35, 1.0
	v_rcp_f32_e32 v17, v16
	v_div_scale_f32 v38, vcc, 1.0, v35, 1.0
	v_fma_f32 v39, -v16, v17, 1.0
	v_fmac_f32_e32 v17, v39, v17
	v_mul_f32_e32 v39, v38, v17
	v_fma_f32 v43, -v16, v39, v38
	v_fmac_f32_e32 v39, v43, v17
	v_fma_f32 v16, -v16, v39, v38
	v_and_b32_e32 v45, 0xffff0000, v126
	v_lshlrev_b32_e32 v46, 16, v127
	v_div_fmas_f32 v17, v16, v17, v39
	v_and_b32_e32 v47, 0xffff0000, v127
	v_div_fixup_f32 v38, v17, v35, 1.0
	v_pk_mul_f32 v[46:47], v[186:187], v[46:47] op_sel:[1,0] op_sel_hi:[1,1]
	v_pk_mul_f32 v[44:45], v[186:187], v[44:45] op_sel:[1,0] op_sel_hi:[1,1]
	v_pk_fma_f32 v[44:45], v[38:39], v[12:13], v[44:45] op_sel_hi:[0,1,1] neg_lo:[0,0,1] neg_hi:[0,0,1]
	v_pk_fma_f32 v[46:47], v[38:39], v[14:15], v[46:47] op_sel_hi:[0,1,1] neg_lo:[0,0,1] neg_hi:[0,0,1]
	v_pk_mul_f32 v[44:45], v[52:53], v[44:45]
	v_pk_mul_f32 v[46:47], v[54:55], v[46:47]
	v_cvt_pk_bf16_f32 v50, v44, v45
	v_cvt_pk_bf16_f32 v51, v46, v47
	global_store_dwordx2 v41, v[50:51], s[50:51] offset:2048
	v_lshlrev_b32_e32 v36, 16, v118
	v_and_b32_e32 v37, 0xffff0000, v118
	v_lshlrev_b32_e32 v32, 16, v119
	v_and_b32_e32 v33, 0xffff0000, v119
	v_pk_fma_f32 v[14:15], v[182:183], v[32:33], v[14:15] op_sel:[1,0,0] op_sel_hi:[1,1,1] neg_lo:[1,0,0] neg_hi:[1,0,0]
	v_pk_fma_f32 v[12:13], v[182:183], v[36:37], v[12:13] op_sel:[1,0,0] op_sel_hi:[1,1,1] neg_lo:[1,0,0] neg_hi:[1,0,0]
	s_waitcnt vmcnt(31)
	v_lshlrev_b32_e32 v36, 16, v134
	v_and_b32_e32 v37, 0xffff0000, v134
	v_lshlrev_b32_e32 v32, 16, v135
	v_and_b32_e32 v33, 0xffff0000, v135
	v_pk_fma_f32 v[14:15], v[190:191], v[32:33], v[14:15] op_sel:[1,0,0] op_sel_hi:[1,1,1]
	v_pk_fma_f32 v[12:13], v[190:191], v[36:37], v[12:13] op_sel:[1,0,0] op_sel_hi:[1,1,1]
	s_add_i32 s26, s23, 26
	s_max_i32 s26, s26, s16
	s_add_i32 s27, s23, 34
	s_min_i32 s27, s27, s17
	s_sub_i32 s26, s27, s26
	v_cvt_f32_i32_e32 v35, s26
	v_lshlrev_b32_e32 v44, 16, v128
	v_div_scale_f32 v16, s[10:11], v35, v35, 1.0
	v_rcp_f32_e32 v17, v16
	v_div_scale_f32 v38, vcc, 1.0, v35, 1.0
	v_fma_f32 v39, -v16, v17, 1.0
	v_fmac_f32_e32 v17, v39, v17
	v_mul_f32_e32 v39, v38, v17
	v_fma_f32 v43, -v16, v39, v38
	v_fmac_f32_e32 v39, v43, v17
	v_fma_f32 v16, -v16, v39, v38
	v_and_b32_e32 v45, 0xffff0000, v128
	v_lshlrev_b32_e32 v46, 16, v129
	v_div_fmas_f32 v17, v16, v17, v39
	v_and_b32_e32 v47, 0xffff0000, v129
	v_div_fixup_f32 v38, v17, v35, 1.0
	v_pk_mul_f32 v[46:47], v[188:189], v[46:47] op_sel_hi:[0,1]
	v_pk_mul_f32 v[44:45], v[188:189], v[44:45] op_sel_hi:[0,1]
	v_pk_fma_f32 v[44:45], v[38:39], v[12:13], v[44:45] op_sel_hi:[0,1,1] neg_lo:[0,0,1] neg_hi:[0,0,1]
	v_pk_fma_f32 v[46:47], v[38:39], v[14:15], v[46:47] op_sel_hi:[0,1,1] neg_lo:[0,0,1] neg_hi:[0,0,1]
	v_pk_mul_f32 v[44:45], v[52:53], v[44:45]
	v_pk_mul_f32 v[46:47], v[54:55], v[46:47]
	v_cvt_pk_bf16_f32 v48, v44, v45
	v_cvt_pk_bf16_f32 v49, v46, v47
	s_add_u32 s52, s28, 61440
	s_addc_u32 s53, s29, 0
	global_store_dwordx2 v41, v[48:49], s[52:53]
	v_lshlrev_b32_e32 v36, 16, v120
	v_and_b32_e32 v37, 0xffff0000, v120
	v_lshlrev_b32_e32 v32, 16, v121
	v_and_b32_e32 v33, 0xffff0000, v121
	v_pk_fma_f32 v[14:15], v[184:185], v[32:33], v[14:15] op_sel_hi:[0,1,1] neg_lo:[1,0,0] neg_hi:[1,0,0]
	v_pk_fma_f32 v[12:13], v[184:185], v[36:37], v[12:13] op_sel_hi:[0,1,1] neg_lo:[1,0,0] neg_hi:[1,0,0]
	s_waitcnt vmcnt(31)
; __device__ __forceinline__ unsigned pk2(float lo, float hi) { unsigned r; asm volatile("v_cvt_pk_bf16_f32 %0, %1, %2" : "=v"(r) : "v"(lo), "v"(hi)); return r; }
; __device__ __forceinline__ unsigned pk2(float lo, float hi) { return f2bf(lo) | (f2bf(hi) << 16); }
; #define LDX(tok) ({ const u32x2 _q = *(const u32x2*)(xb + (size_t)(tok) * D + cq * 4); (f32x4){bf_lo(_q.x), bf_hi(_q.x), bf_lo(_q.y), bf_hi(_q.y)} * rs[(tok) - t0 + 8]; })
; __global__ void __launch_bounds__(512, 2) fwd_megakernel(Params Pk) {
;     ...
;             for (int s = ta - hw; s <= ta + hw - 2; ++s) if (s >= sbeg && s < send) S += LDX(s);
;             for (int t = ta; t < ta + 32; ++t) {
;                 const int sin_ = t + hw - 1; if (sin_ < send) S += LDX(sin_);
;                 const int wl = (t - hw) > sbeg ? (t - hw) : sbeg, wh = (t + hw) < send ? (t + hw) : send; const float inv = 1.0f / (float)(wh - wl);
;                 const f32x4 xt = LDX(t);
;                 const f32x4 pv = (S * inv - xt) * gv;
;                 u32x2 w; w.x = pk2(pv[0], pv[1]); w.y = pk2(pv[2], pv[3]); *(u32x2*)(pbuf + (size_t)t * D + cq * 4) = w;
;                 const int sout = t - hw; if (sout >= sbeg) S -= LDX(sout);
;             }
	v_lshlrev_b32_e32 v36, 16, v136
	v_and_b32_e32 v37, 0xffff0000, v136
	v_lshlrev_b32_e32 v32, 16, v137
	v_and_b32_e32 v33, 0xffff0000, v137
	v_pk_fma_f32 v[14:15], v[192:193], v[32:33], v[14:15] op_sel_hi:[0,1,1]
	v_pk_fma_f32 v[12:13], v[192:193], v[36:37], v[12:13] op_sel_hi:[0,1,1]
	s_add_i32 s26, s23, 27
	s_max_i32 s26, s26, s16
	s_add_i32 s27, s23, 35
	s_min_i32 s27, s27, s17
	s_sub_i32 s26, s27, s26
	v_cvt_f32_i32_e32 v35, s26
	v_lshlrev_b32_e32 v44, 16, v130
	v_div_scale_f32 v16, s[10:11], v35, v35, 1.0
	v_rcp_f32_e32 v17, v16
	v_div_scale_f32 v38, vcc, 1.0, v35, 1.0
	v_fma_f32 v39, -v16, v17, 1.0
	v_fmac_f32_e32 v17, v39, v17
	v_mul_f32_e32 v39, v38, v17
	v_fma_f32 v43, -v16, v39, v38
	v_fmac_f32_e32 v39, v43, v17
	v_fma_f32 v16, -v16, v39, v38
	v_and_b32_e32 v45, 0xffff0000, v130
	v_lshlrev_b32_e32 v46, 16, v131
	v_div_fmas_f32 v17, v16, v17, v39
	v_and_b32_e32 v47, 0xffff0000, v131
	v_div_fixup_f32 v38, v17, v35, 1.0
	v_pk_mul_f32 v[46:47], v[188:189], v[46:47] op_sel:[1,0] op_sel_hi:[1,1]
	v_pk_mul_f32 v[44:45], v[188:189], v[44:45] op_sel:[1,0] op_sel_hi:[1,1]
	v_pk_fma_f32 v[44:45], v[38:39], v[12:13], v[44:45] op_sel_hi:[0,1,1] neg_lo:[0,0,1] neg_hi:[0,0,1]
	v_pk_fma_f32 v[46:47], v[38:39], v[14:15], v[46:47] op_sel_hi:[0,1,1] neg_lo:[0,0,1] neg_hi:[0,0,1]
	v_pk_mul_f32 v[44:45], v[52:53], v[44:45]
	v_pk_mul_f32 v[46:47], v[54:55], v[46:47]
	v_cvt_pk_bf16_f32 v50, v44, v45
	v_cvt_pk_bf16_f32 v51, v46, v47
	global_store_dwordx2 v41, v[50:51], s[52:53] offset:2048
	v_lshlrev_b32_e32 v36, 16, v122
	v_and_b32_e32 v37, 0xffff0000, v122
	v_lshlrev_b32_e32 v32, 16, v123
	v_and_b32_e32 v33, 0xffff0000, v123
	v_pk_fma_f32 v[14:15], v[184:185], v[32:33], v[14:15] op_sel:[1,0,0] op_sel_hi:[1,1,1] neg_lo:[1,0,0] neg_hi:[1,0,0]
	v_pk_fma_f32 v[12:13], v[184:185], v[36:37], v[12:13] op_sel:[1,0,0] op_sel_hi:[1,1,1] neg_lo:[1,0,0] neg_hi:[1,0,0]
	s_branch .Lp13_tail
.Lp13_hw8:
	ds_read_b32 v154, v42 offset:0
	ds_read_b32 v155, v42 offset:4
	ds_read_b32 v156, v42 offset:8
	ds_read_b32 v157, v42 offset:12
	ds_read_b32 v158, v42 offset:16
	ds_read_b32 v159, v42 offset:20
	ds_read_b32 v160, v42 offset:24
	ds_read_b32 v161, v42 offset:28
	ds_read_b32 v162, v42 offset:32
	ds_read_b32 v163, v42 offset:36
	ds_read_b32 v164, v42 offset:40
	ds_read_b32 v165, v42 offset:44
	ds_read_b32 v166, v42 offset:48
	ds_read_b32 v167, v42 offset:52
	ds_read_b32 v168, v42 offset:56
	ds_read_b32 v169, v42 offset:60
	ds_read_b32 v170, v42 offset:64
	ds_read_b32 v171, v42 offset:68
	ds_read_b32 v172, v42 offset:72
	ds_read_b32 v173, v42 offset:76
	ds_read_b32 v174, v42 offset:80
	ds_read_b32 v175, v42 offset:84
	ds_read_b32 v176, v42 offset:88
	ds_read_b32 v177, v42 offset:92
	ds_read_b32 v178, v42 offset:96
	ds_read_b32 v179, v42 offset:100
	ds_read_b32 v180, v42 offset:104
	ds_read_b32 v181, v42 offset:108
	ds_read_b32 v182, v42 offset:112
	ds_read_b32 v183, v42 offset:116
	ds_read_b32 v184, v42 offset:120
	ds_read_b32 v185, v42 offset:124
	ds_read_b32 v186, v42 offset:128
	ds_read_b32 v187, v42 offset:132
	ds_read_b32 v188, v42 offset:136
	ds_read_b32 v189, v42 offset:140
	ds_read_b32 v190, v42 offset:144
	ds_read_b32 v191, v42 offset:148
	ds_read_b32 v192, v42 offset:152
	ds_read_b32 v193, v42 offset:156
	ds_read_b32 v194, v42 offset:160
	ds_read_b32 v195, v42 offset:164
	ds_read_b32 v196, v42 offset:168
	ds_read_b32 v197, v42 offset:172
	ds_read_b32 v198, v42 offset:176
	ds_read_b32 v199, v42 offset:180
	ds_read_b32 v200, v42 offset:184
	v_mov_b32_e32 v12, 0
	v_mov_b32_e32 v13, 0
	v_mov_b32_e32 v14, 0
	v_mov_b32_e32 v15, 0
	s_waitcnt lgkmcnt(0)
	s_waitcnt vmcnt(46)
	v_lshlrev_b32_e32 v36, 16, v60
	v_and_b32_e32 v37, 0xffff0000, v60
	v_lshlrev_b32_e32 v32, 16, v61
	v_and_b32_e32 v33, 0xffff0000, v61
	v_pk_fma_f32 v[14:15], v[154:155], v[32:33], v[14:15] op_sel_hi:[0,1,1]
	v_pk_fma_f32 v[12:13], v[154:155], v[36:37], v[12:13] op_sel_hi:[0,1,1]
	s_waitcnt vmcnt(45)
	v_lshlrev_b32_e32 v36, 16, v62
	v_and_b32_e32 v37, 0xffff0000, v62
	v_lshlrev_b32_e32 v32, 16, v63
	v_and_b32_e32 v33, 0xffff0000, v63
	v_pk_fma_f32 v[14:15], v[154:155], v[32:33], v[14:15] op_sel:[1,0,0] op_sel_hi:[1,1,1]
	v_pk_fma_f32 v[12:13], v[154:155], v[36:37], v[12:13] op_sel:[1,0,0] op_sel_hi:[1,1,1]
	s_waitcnt vmcnt(44)
	v_lshlrev_b32_e32 v36, 16, v64
	v_and_b32_e32 v37, 0xffff0000, v64
	v_lshlrev_b32_e32 v32, 16, v65
	v_and_b32_e32 v33, 0xffff0000, v65
	v_pk_fma_f32 v[14:15], v[156:157], v[32:33], v[14:15] op_sel_hi:[0,1,1]
	v_pk_fma_f32 v[12:13], v[156:157], v[36:37], v[12:13] op_sel_hi:[0,1,1]
	s_waitcnt vmcnt(43)
	v_lshlrev_b32_e32 v36, 16, v66
	v_and_b32_e32 v37, 0xffff0000, v66
	v_lshlrev_b32_e32 v32, 16, v67
	v_and_b32_e32 v33, 0xffff0000, v67
	v_pk_fma_f32 v[14:15], v[156:157], v[32:33], v[14:15] op_sel:[1,0,0] op_sel_hi:[1,1,1]
	v_pk_fma_f32 v[12:13], v[156:157], v[36:37], v[12:13] op_sel:[1,0,0] op_sel_hi:[1,1,1]
	s_waitcnt vmcnt(42)
	v_lshlrev_b32_e32 v36, 16, v68
	v_and_b32_e32 v37, 0xffff0000, v68
	v_lshlrev_b32_e32 v32, 16, v69
	v_and_b32_e32 v33, 0xffff0000, v69
	v_pk_fma_f32 v[14:15], v[158:159], v[32:33], v[14:15] op_sel_hi:[0,1,1]
	v_pk_fma_f32 v[12:13], v[158:159], v[36:37], v[12:13] op_sel_hi:[0,1,1]
	s_waitcnt vmcnt(41)
	v_lshlrev_b32_e32 v36, 16, v70
	v_and_b32_e32 v37, 0xffff0000, v70
	v_lshlrev_b32_e32 v32, 16, v71
	v_and_b32_e32 v33, 0xffff0000, v71
	v_pk_fma_f32 v[14:15], v[158:159], v[32:33], v[14:15] op_sel:[1,0,0] op_sel_hi:[1,1,1]
	v_pk_fma_f32 v[12:13], v[158:159], v[36:37], v[12:13] op_sel:[1,0,0] op_sel_hi:[1,1,1]
	s_waitcnt vmcnt(40)
; __device__ __forceinline__ unsigned pk2(float lo, float hi) { unsigned r; asm volatile("v_cvt_pk_bf16_f32 %0, %1, %2" : "=v"(r) : "v"(lo), "v"(hi)); return r; }
; __device__ __forceinline__ unsigned pk2(float lo, float hi) { return f2bf(lo) | (f2bf(hi) << 16); }
; #define LDX(tok) ({ const u32x2 _q = *(const u32x2*)(xb + (size_t)(tok) * D + cq * 4); (f32x4){bf_lo(_q.x), bf_hi(_q.x), bf_lo(_q.y), bf_hi(_q.y)} * rs[(tok) - t0 + 8]; })
; __global__ void __launch_bounds__(512, 2) fwd_megakernel(Params Pk) {
;     ...
;             for (int s = ta - hw; s <= ta + hw - 2; ++s) if (s >= sbeg && s < send) S += LDX(s);
;             for (int t = ta; t < ta + 32; ++t) {
;                 const int sin_ = t + hw - 1; if (sin_ < send) S += LDX(sin_);
;                 const int wl = (t - hw) > sbeg ? (t - hw) : sbeg, wh = (t + hw) < send ? (t + hw) : send; const float inv = 1.0f / (float)(wh - wl);
;                 const f32x4 xt = LDX(t);
;                 const f32x4 pv = (S * inv - xt) * gv;
;                 u32x2 w; w.x = pk2(pv[0], pv[1]); w.y = pk2(pv[2], pv[3]); *(u32x2*)(pbuf + (size_t)t * D + cq * 4) = w;
;                 const int sout = t - hw; if (sout >= sbeg) S -= LDX(sout);
;             }
	v_lshlrev_b32_e32 v36, 16, v72
	v_and_b32_e32 v37, 0xffff0000, v72
	v_lshlrev_b32_e32 v32, 16, v73
	v_and_b32_e32 v33, 0xffff0000, v73
	v_pk_fma_f32 v[14:15], v[160:161], v[32:33], v[14:15] op_sel_hi:[0,1,1]
	v_pk_fma_f32 v[12:13], v[160:161], v[36:37], v[12:13] op_sel_hi:[0,1,1]
	s_waitcnt vmcnt(39)
	v_lshlrev_b32_e32 v36, 16, v74
	v_and_b32_e32 v37, 0xffff0000, v74
	v_lshlrev_b32_e32 v32, 16, v75
	v_and_b32_e32 v33, 0xffff0000, v75
	v_pk_fma_f32 v[14:15], v[160:161], v[32:33], v[14:15] op_sel:[1,0,0] op_sel_hi:[1,1,1]
	v_pk_fma_f32 v[12:13], v[160:161], v[36:37], v[12:13] op_sel:[1,0,0] op_sel_hi:[1,1,1]
	s_waitcnt vmcnt(38)
	v_lshlrev_b32_e32 v36, 16, v76
	v_and_b32_e32 v37, 0xffff0000, v76
	v_lshlrev_b32_e32 v32, 16, v77
	v_and_b32_e32 v33, 0xffff0000, v77
	v_pk_fma_f32 v[14:15], v[162:163], v[32:33], v[14:15] op_sel_hi:[0,1,1]
	v_pk_fma_f32 v[12:13], v[162:163], v[36:37], v[12:13] op_sel_hi:[0,1,1]
	s_waitcnt vmcnt(37)
	v_lshlrev_b32_e32 v36, 16, v78
	v_and_b32_e32 v37, 0xffff0000, v78
	v_lshlrev_b32_e32 v32, 16, v79
	v_and_b32_e32 v33, 0xffff0000, v79
	v_pk_fma_f32 v[14:15], v[162:163], v[32:33], v[14:15] op_sel:[1,0,0] op_sel_hi:[1,1,1]
	v_pk_fma_f32 v[12:13], v[162:163], v[36:37], v[12:13] op_sel:[1,0,0] op_sel_hi:[1,1,1]
	s_waitcnt vmcnt(36)
	v_lshlrev_b32_e32 v36, 16, v80
	v_and_b32_e32 v37, 0xffff0000, v80
	v_lshlrev_b32_e32 v32, 16, v81
	v_and_b32_e32 v33, 0xffff0000, v81
	v_pk_fma_f32 v[14:15], v[164:165], v[32:33], v[14:15] op_sel_hi:[0,1,1]
	v_pk_fma_f32 v[12:13], v[164:165], v[36:37], v[12:13] op_sel_hi:[0,1,1]
	s_waitcnt vmcnt(35)
	v_lshlrev_b32_e32 v36, 16, v82
	v_and_b32_e32 v37, 0xffff0000, v82
	v_lshlrev_b32_e32 v32, 16, v83
	v_and_b32_e32 v33, 0xffff0000, v83
	v_pk_fma_f32 v[14:15], v[164:165], v[32:33], v[14:15] op_sel:[1,0,0] op_sel_hi:[1,1,1]
	v_pk_fma_f32 v[12:13], v[164:165], v[36:37], v[12:13] op_sel:[1,0,0] op_sel_hi:[1,1,1]
	s_waitcnt vmcnt(34)
	v_lshlrev_b32_e32 v36, 16, v84
	v_and_b32_e32 v37, 0xffff0000, v84
	v_lshlrev_b32_e32 v32, 16, v85
	v_and_b32_e32 v33, 0xffff0000, v85
	v_pk_fma_f32 v[14:15], v[166:167], v[32:33], v[14:15] op_sel_hi:[0,1,1]
	v_pk_fma_f32 v[12:13], v[166:167], v[36:37], v[12:13] op_sel_hi:[0,1,1]
	s_waitcnt vmcnt(33)
	v_lshlrev_b32_e32 v36, 16, v86
	v_and_b32_e32 v37, 0xffff0000, v86
	v_lshlrev_b32_e32 v32, 16, v87
	v_and_b32_e32 v33, 0xffff0000, v87
	v_pk_fma_f32 v[14:15], v[166:167], v[32:33], v[14:15] op_sel:[1,0,0] op_sel_hi:[1,1,1]
	v_pk_fma_f32 v[12:13], v[166:167], v[36:37], v[12:13] op_sel:[1,0,0] op_sel_hi:[1,1,1]
	s_waitcnt vmcnt(32)
	v_lshlrev_b32_e32 v36, 16, v88
	v_and_b32_e32 v37, 0xffff0000, v88
	v_lshlrev_b32_e32 v32, 16, v89
	v_and_b32_e32 v33, 0xffff0000, v89
	v_pk_fma_f32 v[14:15], v[168:169], v[32:33], v[14:15] op_sel_hi:[0,1,1]
	v_pk_fma_f32 v[12:13], v[168:169], v[36:37], v[12:13] op_sel_hi:[0,1,1]
	s_waitcnt vmcnt(31)
	v_lshlrev_b32_e32 v36, 16, v90
	v_and_b32_e32 v37, 0xffff0000, v90
	v_lshlrev_b32_e32 v32, 16, v91
	v_and_b32_e32 v33, 0xffff0000, v91
	v_pk_fma_f32 v[14:15], v[168:169], v[32:33], v[14:15] op_sel:[1,0,0] op_sel_hi:[1,1,1]
	v_pk_fma_f32 v[12:13], v[168:169], v[36:37], v[12:13] op_sel:[1,0,0] op_sel_hi:[1,1,1]
	s_add_i32 s26, s23, -8
	s_max_i32 s26, s26, s16
	s_add_i32 s27, s23, 8
	s_min_i32 s27, s27, s17
	s_sub_i32 s26, s27, s26
	v_cvt_f32_i32_e32 v35, s26
	v_lshlrev_b32_e32 v44, 16, v76
	v_div_scale_f32 v16, s[10:11], v35, v35, 1.0
	v_rcp_f32_e32 v17, v16
	v_div_scale_f32 v38, vcc, 1.0, v35, 1.0
	v_fma_f32 v39, -v16, v17, 1.0
	v_fmac_f32_e32 v17, v39, v17
	v_mul_f32_e32 v39, v38, v17
	v_fma_f32 v43, -v16, v39, v38
	v_fmac_f32_e32 v39, v43, v17
	v_fma_f32 v16, -v16, v39, v38
	v_and_b32_e32 v45, 0xffff0000, v76
	v_lshlrev_b32_e32 v46, 16, v77
	v_div_fmas_f32 v17, v16, v17, v39
	v_and_b32_e32 v47, 0xffff0000, v77
	v_div_fixup_f32 v38, v17, v35, 1.0
	v_pk_mul_f32 v[46:47], v[162:163], v[46:47] op_sel_hi:[0,1]
	v_pk_mul_f32 v[44:45], v[162:163], v[44:45] op_sel_hi:[0,1]
	v_pk_fma_f32 v[44:45], v[38:39], v[12:13], v[44:45] op_sel_hi:[0,1,1] neg_lo:[0,0,1] neg_hi:[0,0,1]
	v_pk_fma_f32 v[46:47], v[38:39], v[14:15], v[46:47] op_sel_hi:[0,1,1] neg_lo:[0,0,1] neg_hi:[0,0,1]
	v_pk_mul_f32 v[44:45], v[52:53], v[44:45]
	v_pk_mul_f32 v[46:47], v[54:55], v[46:47]
	v_cvt_pk_bf16_f32 v48, v44, v45
	v_cvt_pk_bf16_f32 v49, v46, v47
	s_add_u32 s46, s28, 0
	s_addc_u32 s47, s29, 0
	global_store_dwordx2 v41, v[48:49], s[46:47]
	v_lshlrev_b32_e32 v36, 16, v60
	v_and_b32_e32 v37, 0xffff0000, v60
	v_lshlrev_b32_e32 v32, 16, v61
	v_and_b32_e32 v33, 0xffff0000, v61
	v_pk_fma_f32 v[14:15], v[154:155], v[32:33], v[14:15] op_sel_hi:[0,1,1] neg_lo:[1,0,0] neg_hi:[1,0,0]
	v_pk_fma_f32 v[12:13], v[154:155], v[36:37], v[12:13] op_sel_hi:[0,1,1] neg_lo:[1,0,0] neg_hi:[1,0,0]
	s_waitcnt vmcnt(31)
; __device__ __forceinline__ unsigned pk2(float lo, float hi) { unsigned r; asm volatile("v_cvt_pk_bf16_f32 %0, %1, %2" : "=v"(r) : "v"(lo), "v"(hi)); return r; }
; __device__ __forceinline__ unsigned pk2(float lo, float hi) { return f2bf(lo) | (f2bf(hi) << 16); }
; #define LDX(tok) ({ const u32x2 _q = *(const u32x2*)(xb + (size_t)(tok) * D + cq * 4); (f32x4){bf_lo(_q.x), bf_hi(_q.x), bf_lo(_q.y), bf_hi(_q.y)} * rs[(tok) - t0 + 8]; })
; __global__ void __launch_bounds__(512, 2) fwd_megakernel(Params Pk) {
;     ...
;             for (int s = ta - hw; s <= ta + hw - 2; ++s) if (s >= sbeg && s < send) S += LDX(s);
;             for (int t = ta; t < ta + 32; ++t) {
;                 const int sin_ = t + hw - 1; if (sin_ < send) S += LDX(sin_);
;                 const int wl = (t - hw) > sbeg ? (t - hw) : sbeg, wh = (t + hw) < send ? (t + hw) : send; const float inv = 1.0f / (float)(wh - wl);
;                 const f32x4 xt = LDX(t);
;                 const f32x4 pv = (S * inv - xt) * gv;
;                 u32x2 w; w.x = pk2(pv[0], pv[1]); w.y = pk2(pv[2], pv[3]); *(u32x2*)(pbuf + (size_t)t * D + cq * 4) = w;
;                 const int sout = t - hw; if (sout >= sbeg) S -= LDX(sout);
;             }
	v_lshlrev_b32_e32 v36, 16, v92
	v_and_b32_e32 v37, 0xffff0000, v92
	v_lshlrev_b32_e32 v32, 16, v93
	v_and_b32_e32 v33, 0xffff0000, v93
	v_pk_fma_f32 v[14:15], v[170:171], v[32:33], v[14:15] op_sel_hi:[0,1,1]
	v_pk_fma_f32 v[12:13], v[170:171], v[36:37], v[12:13] op_sel_hi:[0,1,1]
	s_add_i32 s26, s23, -7
	s_max_i32 s26, s26, s16
	s_add_i32 s27, s23, 9
	s_min_i32 s27, s27, s17
	s_sub_i32 s26, s27, s26
	v_cvt_f32_i32_e32 v35, s26
	v_lshlrev_b32_e32 v44, 16, v78
	v_div_scale_f32 v16, s[10:11], v35, v35, 1.0
	v_rcp_f32_e32 v17, v16
	v_div_scale_f32 v38, vcc, 1.0, v35, 1.0
	v_fma_f32 v39, -v16, v17, 1.0
	v_fmac_f32_e32 v17, v39, v17
	v_mul_f32_e32 v39, v38, v17
	v_fma_f32 v43, -v16, v39, v38
	v_fmac_f32_e32 v39, v43, v17
	v_fma_f32 v16, -v16, v39, v38
	v_and_b32_e32 v45, 0xffff0000, v78
	v_lshlrev_b32_e32 v46, 16, v79
	v_div_fmas_f32 v17, v16, v17, v39
	v_and_b32_e32 v47, 0xffff0000, v79
	v_div_fixup_f32 v38, v17, v35, 1.0
	v_pk_mul_f32 v[46:47], v[162:163], v[46:47] op_sel:[1,0] op_sel_hi:[1,1]
	v_pk_mul_f32 v[44:45], v[162:163], v[44:45] op_sel:[1,0] op_sel_hi:[1,1]
	v_pk_fma_f32 v[44:45], v[38:39], v[12:13], v[44:45] op_sel_hi:[0,1,1] neg_lo:[0,0,1] neg_hi:[0,0,1]
	v_pk_fma_f32 v[46:47], v[38:39], v[14:15], v[46:47] op_sel_hi:[0,1,1] neg_lo:[0,0,1] neg_hi:[0,0,1]
	v_pk_mul_f32 v[44:45], v[52:53], v[44:45]
	v_pk_mul_f32 v[46:47], v[54:55], v[46:47]
	v_cvt_pk_bf16_f32 v50, v44, v45
	v_cvt_pk_bf16_f32 v51, v46, v47
	global_store_dwordx2 v41, v[50:51], s[46:47] offset:2048
	v_lshlrev_b32_e32 v36, 16, v62
	v_and_b32_e32 v37, 0xffff0000, v62
	v_lshlrev_b32_e32 v32, 16, v63
	v_and_b32_e32 v33, 0xffff0000, v63
	v_pk_fma_f32 v[14:15], v[154:155], v[32:33], v[14:15] op_sel:[1,0,0] op_sel_hi:[1,1,1] neg_lo:[1,0,0] neg_hi:[1,0,0]
	v_pk_fma_f32 v[12:13], v[154:155], v[36:37], v[12:13] op_sel:[1,0,0] op_sel_hi:[1,1,1] neg_lo:[1,0,0] neg_hi:[1,0,0]
	s_waitcnt vmcnt(31)
	v_lshlrev_b32_e32 v36, 16, v94
	v_and_b32_e32 v37, 0xffff0000, v94
	v_lshlrev_b32_e32 v32, 16, v95
	v_and_b32_e32 v33, 0xffff0000, v95
	v_pk_fma_f32 v[14:15], v[170:171], v[32:33], v[14:15] op_sel:[1,0,0] op_sel_hi:[1,1,1]
	v_pk_fma_f32 v[12:13], v[170:171], v[36:37], v[12:13] op_sel:[1,0,0] op_sel_hi:[1,1,1]
	s_add_i32 s26, s23, -6
	s_max_i32 s26, s26, s16
	s_add_i32 s27, s23, 10
	s_min_i32 s27, s27, s17
	s_sub_i32 s26, s27, s26
	v_cvt_f32_i32_e32 v35, s26
	v_lshlrev_b32_e32 v44, 16, v80
	v_div_scale_f32 v16, s[10:11], v35, v35, 1.0
	v_rcp_f32_e32 v17, v16
	v_div_scale_f32 v38, vcc, 1.0, v35, 1.0
	v_fma_f32 v39, -v16, v17, 1.0
	v_fmac_f32_e32 v17, v39, v17
	v_mul_f32_e32 v39, v38, v17
	v_fma_f32 v43, -v16, v39, v38
	v_fmac_f32_e32 v39, v43, v17
	v_fma_f32 v16, -v16, v39, v38
	v_and_b32_e32 v45, 0xffff0000, v80
	v_lshlrev_b32_e32 v46, 16, v81
	v_div_fmas_f32 v17, v16, v17, v39
	v_and_b32_e32 v47, 0xffff0000, v81
	v_div_fixup_f32 v38, v17, v35, 1.0
	v_pk_mul_f32 v[46:47], v[164:165], v[46:47] op_sel_hi:[0,1]
	v_pk_mul_f32 v[44:45], v[164:165], v[44:45] op_sel_hi:[0,1]
	v_pk_fma_f32 v[44:45], v[38:39], v[12:13], v[44:45] op_sel_hi:[0,1,1] neg_lo:[0,0,1] neg_hi:[0,0,1]
	v_pk_fma_f32 v[46:47], v[38:39], v[14:15], v[46:47] op_sel_hi:[0,1,1] neg_lo:[0,0,1] neg_hi:[0,0,1]
	v_pk_mul_f32 v[44:45], v[52:53], v[44:45]
	v_pk_mul_f32 v[46:47], v[54:55], v[46:47]
	v_cvt_pk_bf16_f32 v48, v44, v45
	v_cvt_pk_bf16_f32 v49, v46, v47
	s_add_u32 s48, s28, 4096
	s_addc_u32 s49, s29, 0
	global_store_dwordx2 v41, v[48:49], s[48:49]
	v_lshlrev_b32_e32 v36, 16, v64
	v_and_b32_e32 v37, 0xffff0000, v64
	v_lshlrev_b32_e32 v32, 16, v65
	v_and_b32_e32 v33, 0xffff0000, v65
	v_pk_fma_f32 v[14:15], v[156:157], v[32:33], v[14:15] op_sel_hi:[0,1,1] neg_lo:[1,0,0] neg_hi:[1,0,0]
	v_pk_fma_f32 v[12:13], v[156:157], v[36:37], v[12:13] op_sel_hi:[0,1,1] neg_lo:[1,0,0] neg_hi:[1,0,0]
	s_waitcnt vmcnt(31)
	v_lshlrev_b32_e32 v36, 16, v96
	v_and_b32_e32 v37, 0xffff0000, v96
	v_lshlrev_b32_e32 v32, 16, v97
	v_and_b32_e32 v33, 0xffff0000, v97
	v_pk_fma_f32 v[14:15], v[172:173], v[32:33], v[14:15] op_sel_hi:[0,1,1]
	v_pk_fma_f32 v[12:13], v[172:173], v[36:37], v[12:13] op_sel_hi:[0,1,1]
	s_add_i32 s26, s23, -5
	s_max_i32 s26, s26, s16
	s_add_i32 s27, s23, 11
	s_min_i32 s27, s27, s17
	s_sub_i32 s26, s27, s26
	v_cvt_f32_i32_e32 v35, s26
	v_lshlrev_b32_e32 v44, 16, v82
	v_div_scale_f32 v16, s[10:11], v35, v35, 1.0
	v_rcp_f32_e32 v17, v16
	v_div_scale_f32 v38, vcc, 1.0, v35, 1.0
	v_fma_f32 v39, -v16, v17, 1.0
	v_fmac_f32_e32 v17, v39, v17
	v_mul_f32_e32 v39, v38, v17
	v_fma_f32 v43, -v16, v39, v38
	v_fmac_f32_e32 v39, v43, v17
	v_fma_f32 v16, -v16, v39, v38
	v_and_b32_e32 v45, 0xffff0000, v82
	v_lshlrev_b32_e32 v46, 16, v83
	v_div_fmas_f32 v17, v16, v17, v39
	v_and_b32_e32 v47, 0xffff0000, v83
	v_div_fixup_f32 v38, v17, v35, 1.0
	v_pk_mul_f32 v[46:47], v[164:165], v[46:47] op_sel:[1,0] op_sel_hi:[1,1]
	v_pk_mul_f32 v[44:45], v[164:165], v[44:45] op_sel:[1,0] op_sel_hi:[1,1]
	v_pk_fma_f32 v[44:45], v[38:39], v[12:13], v[44:45] op_sel_hi:[0,1,1] neg_lo:[0,0,1] neg_hi:[0,0,1]
	v_pk_fma_f32 v[46:47], v[38:39], v[14:15], v[46:47] op_sel_hi:[0,1,1] neg_lo:[0,0,1] neg_hi:[0,0,1]
	v_pk_mul_f32 v[44:45], v[52:53], v[44:45]
	v_pk_mul_f32 v[46:47], v[54:55], v[46:47]
	v_cvt_pk_bf16_f32 v50, v44, v45
	v_cvt_pk_bf16_f32 v51, v46, v47
	global_store_dwordx2 v41, v[50:51], s[48:49] offset:2048
	v_lshlrev_b32_e32 v36, 16, v66
	v_and_b32_e32 v37, 0xffff0000, v66
	v_lshlrev_b32_e32 v32, 16, v67
	v_and_b32_e32 v33, 0xffff0000, v67
	v_pk_fma_f32 v[14:15], v[156:157], v[32:33], v[14:15] op_sel:[1,0,0] op_sel_hi:[1,1,1] neg_lo:[1,0,0] neg_hi:[1,0,0]
	v_pk_fma_f32 v[12:13], v[156:157], v[36:37], v[12:13] op_sel:[1,0,0] op_sel_hi:[1,1,1] neg_lo:[1,0,0] neg_hi:[1,0,0]
	s_waitcnt vmcnt(31)
; __device__ __forceinline__ unsigned pk2(float lo, float hi) { unsigned r; asm volatile("v_cvt_pk_bf16_f32 %0, %1, %2" : "=v"(r) : "v"(lo), "v"(hi)); return r; }
; __device__ __forceinline__ unsigned pk2(float lo, float hi) { return f2bf(lo) | (f2bf(hi) << 16); }
; #define LDX(tok) ({ const u32x2 _q = *(const u32x2*)(xb + (size_t)(tok) * D + cq * 4); (f32x4){bf_lo(_q.x), bf_hi(_q.x), bf_lo(_q.y), bf_hi(_q.y)} * rs[(tok) - t0 + 8]; })
; __global__ void __launch_bounds__(512, 2) fwd_megakernel(Params Pk) {
;     ...
;             for (int s = ta - hw; s <= ta + hw - 2; ++s) if (s >= sbeg && s < send) S += LDX(s);
;             for (int t = ta; t < ta + 32; ++t) {
;                 const int sin_ = t + hw - 1; if (sin_ < send) S += LDX(sin_);
;                 const int wl = (t - hw) > sbeg ? (t - hw) : sbeg, wh = (t + hw) < send ? (t + hw) : send; const float inv = 1.0f / (float)(wh - wl);
;                 const f32x4 xt = LDX(t);
;                 const f32x4 pv = (S * inv - xt) * gv;
;                 u32x2 w; w.x = pk2(pv[0], pv[1]); w.y = pk2(pv[2], pv[3]); *(u32x2*)(pbuf + (size_t)t * D + cq * 4) = w;
;                 const int sout = t - hw; if (sout >= sbeg) S -= LDX(sout);
;             }
	v_lshlrev_b32_e32 v36, 16, v98
	v_and_b32_e32 v37, 0xffff0000, v98
	v_lshlrev_b32_e32 v32, 16, v99
	v_and_b32_e32 v33, 0xffff0000, v99
	v_pk_fma_f32 v[14:15], v[172:173], v[32:33], v[14:15] op_sel:[1,0,0] op_sel_hi:[1,1,1]
	v_pk_fma_f32 v[12:13], v[172:173], v[36:37], v[12:13] op_sel:[1,0,0] op_sel_hi:[1,1,1]
	s_add_i32 s26, s23, -4
	s_max_i32 s26, s26, s16
	s_add_i32 s27, s23, 12
	s_min_i32 s27, s27, s17
	s_sub_i32 s26, s27, s26
	v_cvt_f32_i32_e32 v35, s26
	v_lshlrev_b32_e32 v44, 16, v84
	v_div_scale_f32 v16, s[10:11], v35, v35, 1.0
	v_rcp_f32_e32 v17, v16
	v_div_scale_f32 v38, vcc, 1.0, v35, 1.0
	v_fma_f32 v39, -v16, v17, 1.0
	v_fmac_f32_e32 v17, v39, v17
	v_mul_f32_e32 v39, v38, v17
	v_fma_f32 v43, -v16, v39, v38
	v_fmac_f32_e32 v39, v43, v17
	v_fma_f32 v16, -v16, v39, v38
	v_and_b32_e32 v45, 0xffff0000, v84
	v_lshlrev_b32_e32 v46, 16, v85
	v_div_fmas_f32 v17, v16, v17, v39
	v_and_b32_e32 v47, 0xffff0000, v85
	v_div_fixup_f32 v38, v17, v35, 1.0
	v_pk_mul_f32 v[46:47], v[166:167], v[46:47] op_sel_hi:[0,1]
	v_pk_mul_f32 v[44:45], v[166:167], v[44:45] op_sel_hi:[0,1]
	v_pk_fma_f32 v[44:45], v[38:39], v[12:13], v[44:45] op_sel_hi:[0,1,1] neg_lo:[0,0,1] neg_hi:[0,0,1]
	v_pk_fma_f32 v[46:47], v[38:39], v[14:15], v[46:47] op_sel_hi:[0,1,1] neg_lo:[0,0,1] neg_hi:[0,0,1]
	v_pk_mul_f32 v[44:45], v[52:53], v[44:45]
	v_pk_mul_f32 v[46:47], v[54:55], v[46:47]
	v_cvt_pk_bf16_f32 v48, v44, v45
	v_cvt_pk_bf16_f32 v49, v46, v47
	s_add_u32 s50, s28, 8192
	s_addc_u32 s51, s29, 0
	global_store_dwordx2 v41, v[48:49], s[50:51]
	v_lshlrev_b32_e32 v36, 16, v68
	v_and_b32_e32 v37, 0xffff0000, v68
	v_lshlrev_b32_e32 v32, 16, v69
	v_and_b32_e32 v33, 0xffff0000, v69
	v_pk_fma_f32 v[14:15], v[158:159], v[32:33], v[14:15] op_sel_hi:[0,1,1] neg_lo:[1,0,0] neg_hi:[1,0,0]
	v_pk_fma_f32 v[12:13], v[158:159], v[36:37], v[12:13] op_sel_hi:[0,1,1] neg_lo:[1,0,0] neg_hi:[1,0,0]
	s_waitcnt vmcnt(31)
	v_lshlrev_b32_e32 v36, 16, v100
	v_and_b32_e32 v37, 0xffff0000, v100
	v_lshlrev_b32_e32 v32, 16, v101
	v_and_b32_e32 v33, 0xffff0000, v101
	v_pk_fma_f32 v[14:15], v[174:175], v[32:33], v[14:15] op_sel_hi:[0,1,1]
	v_pk_fma_f32 v[12:13], v[174:175], v[36:37], v[12:13] op_sel_hi:[0,1,1]
	s_add_i32 s26, s23, -3
	s_max_i32 s26, s26, s16
	s_add_i32 s27, s23, 13
	s_min_i32 s27, s27, s17
	s_sub_i32 s26, s27, s26
	v_cvt_f32_i32_e32 v35, s26
	v_lshlrev_b32_e32 v44, 16, v86
	v_div_scale_f32 v16, s[10:11], v35, v35, 1.0
	v_rcp_f32_e32 v17, v16
	v_div_scale_f32 v38, vcc, 1.0, v35, 1.0
	v_fma_f32 v39, -v16, v17, 1.0
	v_fmac_f32_e32 v17, v39, v17
	v_mul_f32_e32 v39, v38, v17
	v_fma_f32 v43, -v16, v39, v38
	v_fmac_f32_e32 v39, v43, v17
	v_fma_f32 v16, -v16, v39, v38
	v_and_b32_e32 v45, 0xffff0000, v86
	v_lshlrev_b32_e32 v46, 16, v87
	v_div_fmas_f32 v17, v16, v17, v39
	v_and_b32_e32 v47, 0xffff0000, v87
	v_div_fixup_f32 v38, v17, v35, 1.0
	v_pk_mul_f32 v[46:47], v[166:167], v[46:47] op_sel:[1,0] op_sel_hi:[1,1]
	v_pk_mul_f32 v[44:45], v[166:167], v[44:45] op_sel:[1,0] op_sel_hi:[1,1]
	v_pk_fma_f32 v[44:45], v[38:39], v[12:13], v[44:45] op_sel_hi:[0,1,1] neg_lo:[0,0,1] neg_hi:[0,0,1]
	v_pk_fma_f32 v[46:47], v[38:39], v[14:15], v[46:47] op_sel_hi:[0,1,1] neg_lo:[0,0,1] neg_hi:[0,0,1]
	v_pk_mul_f32 v[44:45], v[52:53], v[44:45]
	v_pk_mul_f32 v[46:47], v[54:55], v[46:47]
	v_cvt_pk_bf16_f32 v50, v44, v45
	v_cvt_pk_bf16_f32 v51, v46, v47
	global_store_dwordx2 v41, v[50:51], s[50:51] offset:2048
	v_lshlrev_b32_e32 v36, 16, v70
	v_and_b32_e32 v37, 0xffff0000, v70
	v_lshlrev_b32_e32 v32, 16, v71
	v_and_b32_e32 v33, 0xffff0000, v71
	v_pk_fma_f32 v[14:15], v[158:159], v[32:33], v[14:15] op_sel:[1,0,0] op_sel_hi:[1,1,1] neg_lo:[1,0,0] neg_hi:[1,0,0]
	v_pk_fma_f32 v[12:13], v[158:159], v[36:37], v[12:13] op_sel:[1,0,0] op_sel_hi:[1,1,1] neg_lo:[1,0,0] neg_hi:[1,0,0]
	s_waitcnt vmcnt(31)
	v_lshlrev_b32_e32 v36, 16, v102
	v_and_b32_e32 v37, 0xffff0000, v102
	v_lshlrev_b32_e32 v32, 16, v103
	v_and_b32_e32 v33, 0xffff0000, v103
	v_pk_fma_f32 v[14:15], v[174:175], v[32:33], v[14:15] op_sel:[1,0,0] op_sel_hi:[1,1,1]
	v_pk_fma_f32 v[12:13], v[174:175], v[36:37], v[12:13] op_sel:[1,0,0] op_sel_hi:[1,1,1]
	s_add_i32 s26, s23, -2
	s_max_i32 s26, s26, s16
	s_add_i32 s27, s23, 14
	s_min_i32 s27, s27, s17
	s_sub_i32 s26, s27, s26
	v_cvt_f32_i32_e32 v35, s26
	v_lshlrev_b32_e32 v44, 16, v88
	v_div_scale_f32 v16, s[10:11], v35, v35, 1.0
	v_rcp_f32_e32 v17, v16
	v_div_scale_f32 v38, vcc, 1.0, v35, 1.0
	v_fma_f32 v39, -v16, v17, 1.0
	v_fmac_f32_e32 v17, v39, v17
	v_mul_f32_e32 v39, v38, v17
	v_fma_f32 v43, -v16, v39, v38
	v_fmac_f32_e32 v39, v43, v17
	v_fma_f32 v16, -v16, v39, v38
	v_and_b32_e32 v45, 0xffff0000, v88
	v_lshlrev_b32_e32 v46, 16, v89
	v_div_fmas_f32 v17, v16, v17, v39
	v_and_b32_e32 v47, 0xffff0000, v89
	v_div_fixup_f32 v38, v17, v35, 1.0
	v_pk_mul_f32 v[46:47], v[168:169], v[46:47] op_sel_hi:[0,1]
	v_pk_mul_f32 v[44:45], v[168:169], v[44:45] op_sel_hi:[0,1]
	v_pk_fma_f32 v[44:45], v[38:39], v[12:13], v[44:45] op_sel_hi:[0,1,1] neg_lo:[0,0,1] neg_hi:[0,0,1]
	v_pk_fma_f32 v[46:47], v[38:39], v[14:15], v[46:47] op_sel_hi:[0,1,1] neg_lo:[0,0,1] neg_hi:[0,0,1]
	v_pk_mul_f32 v[44:45], v[52:53], v[44:45]
	v_pk_mul_f32 v[46:47], v[54:55], v[46:47]
	v_cvt_pk_bf16_f32 v48, v44, v45
	v_cvt_pk_bf16_f32 v49, v46, v47
	s_add_u32 s52, s28, 12288
	s_addc_u32 s53, s29, 0
	global_store_dwordx2 v41, v[48:49], s[52:53]
	v_lshlrev_b32_e32 v36, 16, v72
	v_and_b32_e32 v37, 0xffff0000, v72
	v_lshlrev_b32_e32 v32, 16, v73
	v_and_b32_e32 v33, 0xffff0000, v73
	v_pk_fma_f32 v[14:15], v[160:161], v[32:33], v[14:15] op_sel_hi:[0,1,1] neg_lo:[1,0,0] neg_hi:[1,0,0]
	v_pk_fma_f32 v[12:13], v[160:161], v[36:37], v[12:13] op_sel_hi:[0,1,1] neg_lo:[1,0,0] neg_hi:[1,0,0]
	s_waitcnt vmcnt(31)
; __device__ __forceinline__ unsigned pk2(float lo, float hi) { unsigned r; asm volatile("v_cvt_pk_bf16_f32 %0, %1, %2" : "=v"(r) : "v"(lo), "v"(hi)); return r; }
; __device__ __forceinline__ unsigned pk2(float lo, float hi) { return f2bf(lo) | (f2bf(hi) << 16); }
; #define LDX(tok) ({ const u32x2 _q = *(const u32x2*)(xb + (size_t)(tok) * D + cq * 4); (f32x4){bf_lo(_q.x), bf_hi(_q.x), bf_lo(_q.y), bf_hi(_q.y)} * rs[(tok) - t0 + 8]; })
; __global__ void __launch_bounds__(512, 2) fwd_megakernel(Params Pk) {
;     ...
;             for (int s = ta - hw; s <= ta + hw - 2; ++s) if (s >= sbeg && s < send) S += LDX(s);
;             for (int t = ta; t < ta + 32; ++t) {
;                 const int sin_ = t + hw - 1; if (sin_ < send) S += LDX(sin_);
;                 const int wl = (t - hw) > sbeg ? (t - hw) : sbeg, wh = (t + hw) < send ? (t + hw) : send; const float inv = 1.0f / (float)(wh - wl);
;                 const f32x4 xt = LDX(t);
;                 const f32x4 pv = (S * inv - xt) * gv;
;                 u32x2 w; w.x = pk2(pv[0], pv[1]); w.y = pk2(pv[2], pv[3]); *(u32x2*)(pbuf + (size_t)t * D + cq * 4) = w;
;                 const int sout = t - hw; if (sout >= sbeg) S -= LDX(sout);
;             }
	v_lshlrev_b32_e32 v36, 16, v104
	v_and_b32_e32 v37, 0xffff0000, v104
	v_lshlrev_b32_e32 v32, 16, v105
	v_and_b32_e32 v33, 0xffff0000, v105
	v_pk_fma_f32 v[14:15], v[176:177], v[32:33], v[14:15] op_sel_hi:[0,1,1]
	v_pk_fma_f32 v[12:13], v[176:177], v[36:37], v[12:13] op_sel_hi:[0,1,1]
	s_add_i32 s26, s23, -1
	s_max_i32 s26, s26, s16
	s_add_i32 s27, s23, 15
	s_min_i32 s27, s27, s17
	s_sub_i32 s26, s27, s26
	v_cvt_f32_i32_e32 v35, s26
	v_lshlrev_b32_e32 v44, 16, v90
	v_div_scale_f32 v16, s[10:11], v35, v35, 1.0
	v_rcp_f32_e32 v17, v16
	v_div_scale_f32 v38, vcc, 1.0, v35, 1.0
	v_fma_f32 v39, -v16, v17, 1.0
	v_fmac_f32_e32 v17, v39, v17
	v_mul_f32_e32 v39, v38, v17
	v_fma_f32 v43, -v16, v39, v38
	v_fmac_f32_e32 v39, v43, v17
	v_fma_f32 v16, -v16, v39, v38
	v_and_b32_e32 v45, 0xffff0000, v90
	v_lshlrev_b32_e32 v46, 16, v91
	v_div_fmas_f32 v17, v16, v17, v39
	v_and_b32_e32 v47, 0xffff0000, v91
	v_div_fixup_f32 v38, v17, v35, 1.0
	v_pk_mul_f32 v[46:47], v[168:169], v[46:47] op_sel:[1,0] op_sel_hi:[1,1]
	v_pk_mul_f32 v[44:45], v[168:169], v[44:45] op_sel:[1,0] op_sel_hi:[1,1]
	v_pk_fma_f32 v[44:45], v[38:39], v[12:13], v[44:45] op_sel_hi:[0,1,1] neg_lo:[0,0,1] neg_hi:[0,0,1]
	v_pk_fma_f32 v[46:47], v[38:39], v[14:15], v[46:47] op_sel_hi:[0,1,1] neg_lo:[0,0,1] neg_hi:[0,0,1]
	v_pk_mul_f32 v[44:45], v[52:53], v[44:45]
	v_pk_mul_f32 v[46:47], v[54:55], v[46:47]
	v_cvt_pk_bf16_f32 v50, v44, v45
	v_cvt_pk_bf16_f32 v51, v46, v47
	global_store_dwordx2 v41, v[50:51], s[52:53] offset:2048
	v_lshlrev_b32_e32 v36, 16, v74
	v_and_b32_e32 v37, 0xffff0000, v74
	v_lshlrev_b32_e32 v32, 16, v75
	v_and_b32_e32 v33, 0xffff0000, v75
	v_pk_fma_f32 v[14:15], v[160:161], v[32:33], v[14:15] op_sel:[1,0,0] op_sel_hi:[1,1,1] neg_lo:[1,0,0] neg_hi:[1,0,0]
	v_pk_fma_f32 v[12:13], v[160:161], v[36:37], v[12:13] op_sel:[1,0,0] op_sel_hi:[1,1,1] neg_lo:[1,0,0] neg_hi:[1,0,0]
	s_waitcnt vmcnt(31)
	v_lshlrev_b32_e32 v36, 16, v106
	v_and_b32_e32 v37, 0xffff0000, v106
	v_lshlrev_b32_e32 v32, 16, v107
	v_and_b32_e32 v33, 0xffff0000, v107
	v_pk_fma_f32 v[14:15], v[176:177], v[32:33], v[14:15] op_sel:[1,0,0] op_sel_hi:[1,1,1]
	v_pk_fma_f32 v[12:13], v[176:177], v[36:37], v[12:13] op_sel:[1,0,0] op_sel_hi:[1,1,1]
	s_add_i32 s26, s23, 0
	s_max_i32 s26, s26, s16
	s_add_i32 s27, s23, 16
	s_min_i32 s27, s27, s17
	s_sub_i32 s26, s27, s26
	v_cvt_f32_i32_e32 v35, s26
	v_lshlrev_b32_e32 v44, 16, v92
	v_div_scale_f32 v16, s[10:11], v35, v35, 1.0
	v_rcp_f32_e32 v17, v16
	v_div_scale_f32 v38, vcc, 1.0, v35, 1.0
	v_fma_f32 v39, -v16, v17, 1.0
	v_fmac_f32_e32 v17, v39, v17
	v_mul_f32_e32 v39, v38, v17
	v_fma_f32 v43, -v16, v39, v38
	v_fmac_f32_e32 v39, v43, v17
	v_fma_f32 v16, -v16, v39, v38
	v_and_b32_e32 v45, 0xffff0000, v92
	v_lshlrev_b32_e32 v46, 16, v93
	v_div_fmas_f32 v17, v16, v17, v39
	v_and_b32_e32 v47, 0xffff0000, v93
	v_div_fixup_f32 v38, v17, v35, 1.0
	v_pk_mul_f32 v[46:47], v[170:171], v[46:47] op_sel_hi:[0,1]
	v_pk_mul_f32 v[44:45], v[170:171], v[44:45] op_sel_hi:[0,1]
	v_pk_fma_f32 v[44:45], v[38:39], v[12:13], v[44:45] op_sel_hi:[0,1,1] neg_lo:[0,0,1] neg_hi:[0,0,1]
	v_pk_fma_f32 v[46:47], v[38:39], v[14:15], v[46:47] op_sel_hi:[0,1,1] neg_lo:[0,0,1] neg_hi:[0,0,1]
	v_pk_mul_f32 v[44:45], v[52:53], v[44:45]
	v_pk_mul_f32 v[46:47], v[54:55], v[46:47]
	v_cvt_pk_bf16_f32 v48, v44, v45
	v_cvt_pk_bf16_f32 v49, v46, v47
	s_add_u32 s46, s28, 16384
	s_addc_u32 s47, s29, 0
	global_store_dwordx2 v41, v[48:49], s[46:47]
	v_lshlrev_b32_e32 v36, 16, v76
	v_and_b32_e32 v37, 0xffff0000, v76
	v_lshlrev_b32_e32 v32, 16, v77
	v_and_b32_e32 v33, 0xffff0000, v77
	v_pk_fma_f32 v[14:15], v[162:163], v[32:33], v[14:15] op_sel_hi:[0,1,1] neg_lo:[1,0,0] neg_hi:[1,0,0]
	v_pk_fma_f32 v[12:13], v[162:163], v[36:37], v[12:13] op_sel_hi:[0,1,1] neg_lo:[1,0,0] neg_hi:[1,0,0]
	s_waitcnt vmcnt(31)
	v_lshlrev_b32_e32 v36, 16, v108
	v_and_b32_e32 v37, 0xffff0000, v108
	v_lshlrev_b32_e32 v32, 16, v109
	v_and_b32_e32 v33, 0xffff0000, v109
	v_pk_fma_f32 v[14:15], v[178:179], v[32:33], v[14:15] op_sel_hi:[0,1,1]
	v_pk_fma_f32 v[12:13], v[178:179], v[36:37], v[12:13] op_sel_hi:[0,1,1]
	s_add_i32 s26, s23, 1
	s_max_i32 s26, s26, s16
	s_add_i32 s27, s23, 17
	s_min_i32 s27, s27, s17
	s_sub_i32 s26, s27, s26
	v_cvt_f32_i32_e32 v35, s26
	v_lshlrev_b32_e32 v44, 16, v94
	v_div_scale_f32 v16, s[10:11], v35, v35, 1.0
	v_rcp_f32_e32 v17, v16
	v_div_scale_f32 v38, vcc, 1.0, v35, 1.0
	v_fma_f32 v39, -v16, v17, 1.0
	v_fmac_f32_e32 v17, v39, v17
	v_mul_f32_e32 v39, v38, v17
	v_fma_f32 v43, -v16, v39, v38
	v_fmac_f32_e32 v39, v43, v17
	v_fma_f32 v16, -v16, v39, v38
	v_and_b32_e32 v45, 0xffff0000, v94
	v_lshlrev_b32_e32 v46, 16, v95
	v_div_fmas_f32 v17, v16, v17, v39
	v_and_b32_e32 v47, 0xffff0000, v95
	v_div_fixup_f32 v38, v17, v35, 1.0
	v_pk_mul_f32 v[46:47], v[170:171], v[46:47] op_sel:[1,0] op_sel_hi:[1,1]
	v_pk_mul_f32 v[44:45], v[170:171], v[44:45] op_sel:[1,0] op_sel_hi:[1,1]
	v_pk_fma_f32 v[44:45], v[38:39], v[12:13], v[44:45] op_sel_hi:[0,1,1] neg_lo:[0,0,1] neg_hi:[0,0,1]
	v_pk_fma_f32 v[46:47], v[38:39], v[14:15], v[46:47] op_sel_hi:[0,1,1] neg_lo:[0,0,1] neg_hi:[0,0,1]
	v_pk_mul_f32 v[44:45], v[52:53], v[44:45]
	v_pk_mul_f32 v[46:47], v[54:55], v[46:47]
	v_cvt_pk_bf16_f32 v50, v44, v45
	v_cvt_pk_bf16_f32 v51, v46, v47
	global_store_dwordx2 v41, v[50:51], s[46:47] offset:2048
	v_lshlrev_b32_e32 v36, 16, v78
	v_and_b32_e32 v37, 0xffff0000, v78
	v_lshlrev_b32_e32 v32, 16, v79
	v_and_b32_e32 v33, 0xffff0000, v79
	v_pk_fma_f32 v[14:15], v[162:163], v[32:33], v[14:15] op_sel:[1,0,0] op_sel_hi:[1,1,1] neg_lo:[1,0,0] neg_hi:[1,0,0]
	v_pk_fma_f32 v[12:13], v[162:163], v[36:37], v[12:13] op_sel:[1,0,0] op_sel_hi:[1,1,1] neg_lo:[1,0,0] neg_hi:[1,0,0]
	s_waitcnt vmcnt(31)
; __device__ __forceinline__ unsigned pk2(float lo, float hi) { unsigned r; asm volatile("v_cvt_pk_bf16_f32 %0, %1, %2" : "=v"(r) : "v"(lo), "v"(hi)); return r; }
; __device__ __forceinline__ unsigned pk2(float lo, float hi) { return f2bf(lo) | (f2bf(hi) << 16); }
; #define LDX(tok) ({ const u32x2 _q = *(const u32x2*)(xb + (size_t)(tok) * D + cq * 4); (f32x4){bf_lo(_q.x), bf_hi(_q.x), bf_lo(_q.y), bf_hi(_q.y)} * rs[(tok) - t0 + 8]; })
; __global__ void __launch_bounds__(512, 2) fwd_megakernel(Params Pk) {
;     ...
;             for (int s = ta - hw; s <= ta + hw - 2; ++s) if (s >= sbeg && s < send) S += LDX(s);
;             for (int t = ta; t < ta + 32; ++t) {
;                 const int sin_ = t + hw - 1; if (sin_ < send) S += LDX(sin_);
;                 const int wl = (t - hw) > sbeg ? (t - hw) : sbeg, wh = (t + hw) < send ? (t + hw) : send; const float inv = 1.0f / (float)(wh - wl);
;                 const f32x4 xt = LDX(t);
;                 const f32x4 pv = (S * inv - xt) * gv;
;                 u32x2 w; w.x = pk2(pv[0], pv[1]); w.y = pk2(pv[2], pv[3]); *(u32x2*)(pbuf + (size_t)t * D + cq * 4) = w;
;                 const int sout = t - hw; if (sout >= sbeg) S -= LDX(sout);
;             }
	v_lshlrev_b32_e32 v36, 16, v110
	v_and_b32_e32 v37, 0xffff0000, v110
	v_lshlrev_b32_e32 v32, 16, v111
	v_and_b32_e32 v33, 0xffff0000, v111
	v_pk_fma_f32 v[14:15], v[178:179], v[32:33], v[14:15] op_sel:[1,0,0] op_sel_hi:[1,1,1]
	v_pk_fma_f32 v[12:13], v[178:179], v[36:37], v[12:13] op_sel:[1,0,0] op_sel_hi:[1,1,1]
	s_add_i32 s26, s23, 2
	s_max_i32 s26, s26, s16
	s_add_i32 s27, s23, 18
	s_min_i32 s27, s27, s17
	s_sub_i32 s26, s27, s26
	v_cvt_f32_i32_e32 v35, s26
	v_lshlrev_b32_e32 v44, 16, v96
	v_div_scale_f32 v16, s[10:11], v35, v35, 1.0
	v_rcp_f32_e32 v17, v16
	v_div_scale_f32 v38, vcc, 1.0, v35, 1.0
	v_fma_f32 v39, -v16, v17, 1.0
	v_fmac_f32_e32 v17, v39, v17
	v_mul_f32_e32 v39, v38, v17
	v_fma_f32 v43, -v16, v39, v38
	v_fmac_f32_e32 v39, v43, v17
	v_fma_f32 v16, -v16, v39, v38
	v_and_b32_e32 v45, 0xffff0000, v96
	v_lshlrev_b32_e32 v46, 16, v97
	v_div_fmas_f32 v17, v16, v17, v39
	v_and_b32_e32 v47, 0xffff0000, v97
	v_div_fixup_f32 v38, v17, v35, 1.0
	v_pk_mul_f32 v[46:47], v[172:173], v[46:47] op_sel_hi:[0,1]
	v_pk_mul_f32 v[44:45], v[172:173], v[44:45] op_sel_hi:[0,1]
	v_pk_fma_f32 v[44:45], v[38:39], v[12:13], v[44:45] op_sel_hi:[0,1,1] neg_lo:[0,0,1] neg_hi:[0,0,1]
	v_pk_fma_f32 v[46:47], v[38:39], v[14:15], v[46:47] op_sel_hi:[0,1,1] neg_lo:[0,0,1] neg_hi:[0,0,1]
	v_pk_mul_f32 v[44:45], v[52:53], v[44:45]
	v_pk_mul_f32 v[46:47], v[54:55], v[46:47]
	v_cvt_pk_bf16_f32 v48, v44, v45
	v_cvt_pk_bf16_f32 v49, v46, v47
	s_add_u32 s48, s28, 20480
	s_addc_u32 s49, s29, 0
	global_store_dwordx2 v41, v[48:49], s[48:49]
	v_lshlrev_b32_e32 v36, 16, v80
	v_and_b32_e32 v37, 0xffff0000, v80
	v_lshlrev_b32_e32 v32, 16, v81
	v_and_b32_e32 v33, 0xffff0000, v81
	v_pk_fma_f32 v[14:15], v[164:165], v[32:33], v[14:15] op_sel_hi:[0,1,1] neg_lo:[1,0,0] neg_hi:[1,0,0]
	v_pk_fma_f32 v[12:13], v[164:165], v[36:37], v[12:13] op_sel_hi:[0,1,1] neg_lo:[1,0,0] neg_hi:[1,0,0]
	s_waitcnt vmcnt(31)
	v_lshlrev_b32_e32 v36, 16, v112
	v_and_b32_e32 v37, 0xffff0000, v112
	v_lshlrev_b32_e32 v32, 16, v113
	v_and_b32_e32 v33, 0xffff0000, v113
	v_pk_fma_f32 v[14:15], v[180:181], v[32:33], v[14:15] op_sel_hi:[0,1,1]
	v_pk_fma_f32 v[12:13], v[180:181], v[36:37], v[12:13] op_sel_hi:[0,1,1]
	s_add_i32 s26, s23, 3
	s_max_i32 s26, s26, s16
	s_add_i32 s27, s23, 19
	s_min_i32 s27, s27, s17
	s_sub_i32 s26, s27, s26
	v_cvt_f32_i32_e32 v35, s26
	v_lshlrev_b32_e32 v44, 16, v98
	v_div_scale_f32 v16, s[10:11], v35, v35, 1.0
	v_rcp_f32_e32 v17, v16
	v_div_scale_f32 v38, vcc, 1.0, v35, 1.0
	v_fma_f32 v39, -v16, v17, 1.0
	v_fmac_f32_e32 v17, v39, v17
	v_mul_f32_e32 v39, v38, v17
	v_fma_f32 v43, -v16, v39, v38
	v_fmac_f32_e32 v39, v43, v17
	v_fma_f32 v16, -v16, v39, v38
	v_and_b32_e32 v45, 0xffff0000, v98
	v_lshlrev_b32_e32 v46, 16, v99
	v_div_fmas_f32 v17, v16, v17, v39
	v_and_b32_e32 v47, 0xffff0000, v99
	v_div_fixup_f32 v38, v17, v35, 1.0
	v_pk_mul_f32 v[46:47], v[172:173], v[46:47] op_sel:[1,0] op_sel_hi:[1,1]
	v_pk_mul_f32 v[44:45], v[172:173], v[44:45] op_sel:[1,0] op_sel_hi:[1,1]
	v_pk_fma_f32 v[44:45], v[38:39], v[12:13], v[44:45] op_sel_hi:[0,1,1] neg_lo:[0,0,1] neg_hi:[0,0,1]
	v_pk_fma_f32 v[46:47], v[38:39], v[14:15], v[46:47] op_sel_hi:[0,1,1] neg_lo:[0,0,1] neg_hi:[0,0,1]
	v_pk_mul_f32 v[44:45], v[52:53], v[44:45]
	v_pk_mul_f32 v[46:47], v[54:55], v[46:47]
	v_cvt_pk_bf16_f32 v50, v44, v45
	v_cvt_pk_bf16_f32 v51, v46, v47
	global_store_dwordx2 v41, v[50:51], s[48:49] offset:2048
	v_lshlrev_b32_e32 v36, 16, v82
	v_and_b32_e32 v37, 0xffff0000, v82
	v_lshlrev_b32_e32 v32, 16, v83
	v_and_b32_e32 v33, 0xffff0000, v83
	v_pk_fma_f32 v[14:15], v[164:165], v[32:33], v[14:15] op_sel:[1,0,0] op_sel_hi:[1,1,1] neg_lo:[1,0,0] neg_hi:[1,0,0]
	v_pk_fma_f32 v[12:13], v[164:165], v[36:37], v[12:13] op_sel:[1,0,0] op_sel_hi:[1,1,1] neg_lo:[1,0,0] neg_hi:[1,0,0]
	s_waitcnt vmcnt(31)
	v_lshlrev_b32_e32 v36, 16, v114
	v_and_b32_e32 v37, 0xffff0000, v114
	v_lshlrev_b32_e32 v32, 16, v115
	v_and_b32_e32 v33, 0xffff0000, v115
	v_pk_fma_f32 v[14:15], v[180:181], v[32:33], v[14:15] op_sel:[1,0,0] op_sel_hi:[1,1,1]
	v_pk_fma_f32 v[12:13], v[180:181], v[36:37], v[12:13] op_sel:[1,0,0] op_sel_hi:[1,1,1]
	s_add_i32 s26, s23, 4
	s_max_i32 s26, s26, s16
	s_add_i32 s27, s23, 20
	s_min_i32 s27, s27, s17
	s_sub_i32 s26, s27, s26
	v_cvt_f32_i32_e32 v35, s26
	v_lshlrev_b32_e32 v44, 16, v100
	v_div_scale_f32 v16, s[10:11], v35, v35, 1.0
	v_rcp_f32_e32 v17, v16
	v_div_scale_f32 v38, vcc, 1.0, v35, 1.0
	v_fma_f32 v39, -v16, v17, 1.0
	v_fmac_f32_e32 v17, v39, v17
	v_mul_f32_e32 v39, v38, v17
	v_fma_f32 v43, -v16, v39, v38
	v_fmac_f32_e32 v39, v43, v17
	v_fma_f32 v16, -v16, v39, v38
	v_and_b32_e32 v45, 0xffff0000, v100
	v_lshlrev_b32_e32 v46, 16, v101
	v_div_fmas_f32 v17, v16, v17, v39
	v_and_b32_e32 v47, 0xffff0000, v101
	v_div_fixup_f32 v38, v17, v35, 1.0
	v_pk_mul_f32 v[46:47], v[174:175], v[46:47] op_sel_hi:[0,1]
	v_pk_mul_f32 v[44:45], v[174:175], v[44:45] op_sel_hi:[0,1]
	v_pk_fma_f32 v[44:45], v[38:39], v[12:13], v[44:45] op_sel_hi:[0,1,1] neg_lo:[0,0,1] neg_hi:[0,0,1]
	v_pk_fma_f32 v[46:47], v[38:39], v[14:15], v[46:47] op_sel_hi:[0,1,1] neg_lo:[0,0,1] neg_hi:[0,0,1]
	v_pk_mul_f32 v[44:45], v[52:53], v[44:45]
	v_pk_mul_f32 v[46:47], v[54:55], v[46:47]
	v_cvt_pk_bf16_f32 v48, v44, v45
	v_cvt_pk_bf16_f32 v49, v46, v47
	s_add_u32 s50, s28, 24576
	s_addc_u32 s51, s29, 0
	global_store_dwordx2 v41, v[48:49], s[50:51]
	v_lshlrev_b32_e32 v36, 16, v84
	v_and_b32_e32 v37, 0xffff0000, v84
	v_lshlrev_b32_e32 v32, 16, v85
	v_and_b32_e32 v33, 0xffff0000, v85
	v_pk_fma_f32 v[14:15], v[166:167], v[32:33], v[14:15] op_sel_hi:[0,1,1] neg_lo:[1,0,0] neg_hi:[1,0,0]
	v_pk_fma_f32 v[12:13], v[166:167], v[36:37], v[12:13] op_sel_hi:[0,1,1] neg_lo:[1,0,0] neg_hi:[1,0,0]
	s_waitcnt vmcnt(31)
; __device__ __forceinline__ unsigned pk2(float lo, float hi) { unsigned r; asm volatile("v_cvt_pk_bf16_f32 %0, %1, %2" : "=v"(r) : "v"(lo), "v"(hi)); return r; }
; __device__ __forceinline__ unsigned pk2(float lo, float hi) { return f2bf(lo) | (f2bf(hi) << 16); }
; #define LDX(tok) ({ const u32x2 _q = *(const u32x2*)(xb + (size_t)(tok) * D + cq * 4); (f32x4){bf_lo(_q.x), bf_hi(_q.x), bf_lo(_q.y), bf_hi(_q.y)} * rs[(tok) - t0 + 8]; })
; __global__ void __launch_bounds__(512, 2) fwd_megakernel(Params Pk) {
;     ...
;             for (int s = ta - hw; s <= ta + hw - 2; ++s) if (s >= sbeg && s < send) S += LDX(s);
;             for (int t = ta; t < ta + 32; ++t) {
;                 const int sin_ = t + hw - 1; if (sin_ < send) S += LDX(sin_);
;                 const int wl = (t - hw) > sbeg ? (t - hw) : sbeg, wh = (t + hw) < send ? (t + hw) : send; const float inv = 1.0f / (float)(wh - wl);
;                 const f32x4 xt = LDX(t);
;                 const f32x4 pv = (S * inv - xt) * gv;
;                 u32x2 w; w.x = pk2(pv[0], pv[1]); w.y = pk2(pv[2], pv[3]); *(u32x2*)(pbuf + (size_t)t * D + cq * 4) = w;
;                 const int sout = t - hw; if (sout >= sbeg) S -= LDX(sout);
;             }
	v_lshlrev_b32_e32 v36, 16, v116
	v_and_b32_e32 v37, 0xffff0000, v116
	v_lshlrev_b32_e32 v32, 16, v117
	v_and_b32_e32 v33, 0xffff0000, v117
	v_pk_fma_f32 v[14:15], v[182:183], v[32:33], v[14:15] op_sel_hi:[0,1,1]
	v_pk_fma_f32 v[12:13], v[182:183], v[36:37], v[12:13] op_sel_hi:[0,1,1]
	s_add_i32 s26, s23, 5
	s_max_i32 s26, s26, s16
	s_add_i32 s27, s23, 21
	s_min_i32 s27, s27, s17
	s_sub_i32 s26, s27, s26
	v_cvt_f32_i32_e32 v35, s26
	v_lshlrev_b32_e32 v44, 16, v102
	v_div_scale_f32 v16, s[10:11], v35, v35, 1.0
	v_rcp_f32_e32 v17, v16
	v_div_scale_f32 v38, vcc, 1.0, v35, 1.0
	v_fma_f32 v39, -v16, v17, 1.0
	v_fmac_f32_e32 v17, v39, v17
	v_mul_f32_e32 v39, v38, v17
	v_fma_f32 v43, -v16, v39, v38
	v_fmac_f32_e32 v39, v43, v17
	v_fma_f32 v16, -v16, v39, v38
	v_and_b32_e32 v45, 0xffff0000, v102
	v_lshlrev_b32_e32 v46, 16, v103
	v_div_fmas_f32 v17, v16, v17, v39
	v_and_b32_e32 v47, 0xffff0000, v103
	v_div_fixup_f32 v38, v17, v35, 1.0
	v_pk_mul_f32 v[46:47], v[174:175], v[46:47] op_sel:[1,0] op_sel_hi:[1,1]
	v_pk_mul_f32 v[44:45], v[174:175], v[44:45] op_sel:[1,0] op_sel_hi:[1,1]
	v_pk_fma_f32 v[44:45], v[38:39], v[12:13], v[44:45] op_sel_hi:[0,1,1] neg_lo:[0,0,1] neg_hi:[0,0,1]
	v_pk_fma_f32 v[46:47], v[38:39], v[14:15], v[46:47] op_sel_hi:[0,1,1] neg_lo:[0,0,1] neg_hi:[0,0,1]
	v_pk_mul_f32 v[44:45], v[52:53], v[44:45]
	v_pk_mul_f32 v[46:47], v[54:55], v[46:47]
	v_cvt_pk_bf16_f32 v50, v44, v45
	v_cvt_pk_bf16_f32 v51, v46, v47
	global_store_dwordx2 v41, v[50:51], s[50:51] offset:2048
	v_lshlrev_b32_e32 v36, 16, v86
	v_and_b32_e32 v37, 0xffff0000, v86
	v_lshlrev_b32_e32 v32, 16, v87
	v_and_b32_e32 v33, 0xffff0000, v87
	v_pk_fma_f32 v[14:15], v[166:167], v[32:33], v[14:15] op_sel:[1,0,0] op_sel_hi:[1,1,1] neg_lo:[1,0,0] neg_hi:[1,0,0]
	v_pk_fma_f32 v[12:13], v[166:167], v[36:37], v[12:13] op_sel:[1,0,0] op_sel_hi:[1,1,1] neg_lo:[1,0,0] neg_hi:[1,0,0]
	s_waitcnt vmcnt(31)
	v_lshlrev_b32_e32 v36, 16, v118
	v_and_b32_e32 v37, 0xffff0000, v118
	v_lshlrev_b32_e32 v32, 16, v119
	v_and_b32_e32 v33, 0xffff0000, v119
	v_pk_fma_f32 v[14:15], v[182:183], v[32:33], v[14:15] op_sel:[1,0,0] op_sel_hi:[1,1,1]
	v_pk_fma_f32 v[12:13], v[182:183], v[36:37], v[12:13] op_sel:[1,0,0] op_sel_hi:[1,1,1]
	s_add_i32 s26, s23, 6
	s_max_i32 s26, s26, s16
	s_add_i32 s27, s23, 22
	s_min_i32 s27, s27, s17
	s_sub_i32 s26, s27, s26
	v_cvt_f32_i32_e32 v35, s26
	v_lshlrev_b32_e32 v44, 16, v104
	v_div_scale_f32 v16, s[10:11], v35, v35, 1.0
	v_rcp_f32_e32 v17, v16
	v_div_scale_f32 v38, vcc, 1.0, v35, 1.0
	v_fma_f32 v39, -v16, v17, 1.0
	v_fmac_f32_e32 v17, v39, v17
	v_mul_f32_e32 v39, v38, v17
	v_fma_f32 v43, -v16, v39, v38
	v_fmac_f32_e32 v39, v43, v17
	v_fma_f32 v16, -v16, v39, v38
	v_and_b32_e32 v45, 0xffff0000, v104
	v_lshlrev_b32_e32 v46, 16, v105
	v_div_fmas_f32 v17, v16, v17, v39
	v_and_b32_e32 v47, 0xffff0000, v105
	v_div_fixup_f32 v38, v17, v35, 1.0
	v_pk_mul_f32 v[46:47], v[176:177], v[46:47] op_sel_hi:[0,1]
	v_pk_mul_f32 v[44:45], v[176:177], v[44:45] op_sel_hi:[0,1]
	v_pk_fma_f32 v[44:45], v[38:39], v[12:13], v[44:45] op_sel_hi:[0,1,1] neg_lo:[0,0,1] neg_hi:[0,0,1]
	v_pk_fma_f32 v[46:47], v[38:39], v[14:15], v[46:47] op_sel_hi:[0,1,1] neg_lo:[0,0,1] neg_hi:[0,0,1]
	v_pk_mul_f32 v[44:45], v[52:53], v[44:45]
	v_pk_mul_f32 v[46:47], v[54:55], v[46:47]
	v_cvt_pk_bf16_f32 v48, v44, v45
	v_cvt_pk_bf16_f32 v49, v46, v47
	s_add_u32 s52, s28, 28672
	s_addc_u32 s53, s29, 0
	global_store_dwordx2 v41, v[48:49], s[52:53]
	v_lshlrev_b32_e32 v36, 16, v88
	v_and_b32_e32 v37, 0xffff0000, v88
	v_lshlrev_b32_e32 v32, 16, v89
	v_and_b32_e32 v33, 0xffff0000, v89
	v_pk_fma_f32 v[14:15], v[168:169], v[32:33], v[14:15] op_sel_hi:[0,1,1] neg_lo:[1,0,0] neg_hi:[1,0,0]
	v_pk_fma_f32 v[12:13], v[168:169], v[36:37], v[12:13] op_sel_hi:[0,1,1] neg_lo:[1,0,0] neg_hi:[1,0,0]
	s_waitcnt vmcnt(31)
	v_lshlrev_b32_e32 v36, 16, v120
	v_and_b32_e32 v37, 0xffff0000, v120
	v_lshlrev_b32_e32 v32, 16, v121
	v_and_b32_e32 v33, 0xffff0000, v121
	v_pk_fma_f32 v[14:15], v[184:185], v[32:33], v[14:15] op_sel_hi:[0,1,1]
	v_pk_fma_f32 v[12:13], v[184:185], v[36:37], v[12:13] op_sel_hi:[0,1,1]
	s_add_i32 s26, s23, 7
	s_max_i32 s26, s26, s16
	s_add_i32 s27, s23, 23
	s_min_i32 s27, s27, s17
	s_sub_i32 s26, s27, s26
	v_cvt_f32_i32_e32 v35, s26
	v_lshlrev_b32_e32 v44, 16, v106
	v_div_scale_f32 v16, s[10:11], v35, v35, 1.0
	v_rcp_f32_e32 v17, v16
	v_div_scale_f32 v38, vcc, 1.0, v35, 1.0
	v_fma_f32 v39, -v16, v17, 1.0
	v_fmac_f32_e32 v17, v39, v17
	v_mul_f32_e32 v39, v38, v17
	v_fma_f32 v43, -v16, v39, v38
	v_fmac_f32_e32 v39, v43, v17
	v_fma_f32 v16, -v16, v39, v38
	v_and_b32_e32 v45, 0xffff0000, v106
	v_lshlrev_b32_e32 v46, 16, v107
	v_div_fmas_f32 v17, v16, v17, v39
	v_and_b32_e32 v47, 0xffff0000, v107
	v_div_fixup_f32 v38, v17, v35, 1.0
	v_pk_mul_f32 v[46:47], v[176:177], v[46:47] op_sel:[1,0] op_sel_hi:[1,1]
	v_pk_mul_f32 v[44:45], v[176:177], v[44:45] op_sel:[1,0] op_sel_hi:[1,1]
	v_pk_fma_f32 v[44:45], v[38:39], v[12:13], v[44:45] op_sel_hi:[0,1,1] neg_lo:[0,0,1] neg_hi:[0,0,1]
	v_pk_fma_f32 v[46:47], v[38:39], v[14:15], v[46:47] op_sel_hi:[0,1,1] neg_lo:[0,0,1] neg_hi:[0,0,1]
	v_pk_mul_f32 v[44:45], v[52:53], v[44:45]
	v_pk_mul_f32 v[46:47], v[54:55], v[46:47]
	v_cvt_pk_bf16_f32 v50, v44, v45
	v_cvt_pk_bf16_f32 v51, v46, v47
	global_store_dwordx2 v41, v[50:51], s[52:53] offset:2048
	v_lshlrev_b32_e32 v36, 16, v90
	v_and_b32_e32 v37, 0xffff0000, v90
	v_lshlrev_b32_e32 v32, 16, v91
	v_and_b32_e32 v33, 0xffff0000, v91
	v_pk_fma_f32 v[14:15], v[168:169], v[32:33], v[14:15] op_sel:[1,0,0] op_sel_hi:[1,1,1] neg_lo:[1,0,0] neg_hi:[1,0,0]
	v_pk_fma_f32 v[12:13], v[168:169], v[36:37], v[12:13] op_sel:[1,0,0] op_sel_hi:[1,1,1] neg_lo:[1,0,0] neg_hi:[1,0,0]
	s_waitcnt vmcnt(31)
; __device__ __forceinline__ unsigned pk2(float lo, float hi) { unsigned r; asm volatile("v_cvt_pk_bf16_f32 %0, %1, %2" : "=v"(r) : "v"(lo), "v"(hi)); return r; }
; __device__ __forceinline__ unsigned pk2(float lo, float hi) { return f2bf(lo) | (f2bf(hi) << 16); }
; #define LDX(tok) ({ const u32x2 _q = *(const u32x2*)(xb + (size_t)(tok) * D + cq * 4); (f32x4){bf_lo(_q.x), bf_hi(_q.x), bf_lo(_q.y), bf_hi(_q.y)} * rs[(tok) - t0 + 8]; })
; __global__ void __launch_bounds__(512, 2) fwd_megakernel(Params Pk) {
;     ...
;             for (int s = ta - hw; s <= ta + hw - 2; ++s) if (s >= sbeg && s < send) S += LDX(s);
;             for (int t = ta; t < ta + 32; ++t) {
;                 const int sin_ = t + hw - 1; if (sin_ < send) S += LDX(sin_);
;                 const int wl = (t - hw) > sbeg ? (t - hw) : sbeg, wh = (t + hw) < send ? (t + hw) : send; const float inv = 1.0f / (float)(wh - wl);
;                 const f32x4 xt = LDX(t);
;                 const f32x4 pv = (S * inv - xt) * gv;
;                 u32x2 w; w.x = pk2(pv[0], pv[1]); w.y = pk2(pv[2], pv[3]); *(u32x2*)(pbuf + (size_t)t * D + cq * 4) = w;
;                 const int sout = t - hw; if (sout >= sbeg) S -= LDX(sout);
;             }
	v_lshlrev_b32_e32 v36, 16, v122
	v_and_b32_e32 v37, 0xffff0000, v122
	v_lshlrev_b32_e32 v32, 16, v123
	v_and_b32_e32 v33, 0xffff0000, v123
	v_pk_fma_f32 v[14:15], v[184:185], v[32:33], v[14:15] op_sel:[1,0,0] op_sel_hi:[1,1,1]
	v_pk_fma_f32 v[12:13], v[184:185], v[36:37], v[12:13] op_sel:[1,0,0] op_sel_hi:[1,1,1]
	s_add_i32 s26, s23, 8
	s_max_i32 s26, s26, s16
	s_add_i32 s27, s23, 24
	s_min_i32 s27, s27, s17
	s_sub_i32 s26, s27, s26
	v_cvt_f32_i32_e32 v35, s26
	v_lshlrev_b32_e32 v44, 16, v108
	v_div_scale_f32 v16, s[10:11], v35, v35, 1.0
	v_rcp_f32_e32 v17, v16
	v_div_scale_f32 v38, vcc, 1.0, v35, 1.0
	v_fma_f32 v39, -v16, v17, 1.0
	v_fmac_f32_e32 v17, v39, v17
	v_mul_f32_e32 v39, v38, v17
	v_fma_f32 v43, -v16, v39, v38
	v_fmac_f32_e32 v39, v43, v17
	v_fma_f32 v16, -v16, v39, v38
	v_and_b32_e32 v45, 0xffff0000, v108
	v_lshlrev_b32_e32 v46, 16, v109
	v_div_fmas_f32 v17, v16, v17, v39
	v_and_b32_e32 v47, 0xffff0000, v109
	v_div_fixup_f32 v38, v17, v35, 1.0
	v_pk_mul_f32 v[46:47], v[178:179], v[46:47] op_sel_hi:[0,1]
	v_pk_mul_f32 v[44:45], v[178:179], v[44:45] op_sel_hi:[0,1]
	v_pk_fma_f32 v[44:45], v[38:39], v[12:13], v[44:45] op_sel_hi:[0,1,1] neg_lo:[0,0,1] neg_hi:[0,0,1]
	v_pk_fma_f32 v[46:47], v[38:39], v[14:15], v[46:47] op_sel_hi:[0,1,1] neg_lo:[0,0,1] neg_hi:[0,0,1]
	v_pk_mul_f32 v[44:45], v[52:53], v[44:45]
	v_pk_mul_f32 v[46:47], v[54:55], v[46:47]
	v_cvt_pk_bf16_f32 v48, v44, v45
	v_cvt_pk_bf16_f32 v49, v46, v47
	s_add_u32 s46, s28, 32768
	s_addc_u32 s47, s29, 0
	global_store_dwordx2 v41, v[48:49], s[46:47]
	v_lshlrev_b32_e32 v36, 16, v92
	v_and_b32_e32 v37, 0xffff0000, v92
	v_lshlrev_b32_e32 v32, 16, v93
	v_and_b32_e32 v33, 0xffff0000, v93
	v_pk_fma_f32 v[14:15], v[170:171], v[32:33], v[14:15] op_sel_hi:[0,1,1] neg_lo:[1,0,0] neg_hi:[1,0,0]
	v_pk_fma_f32 v[12:13], v[170:171], v[36:37], v[12:13] op_sel_hi:[0,1,1] neg_lo:[1,0,0] neg_hi:[1,0,0]
	s_waitcnt vmcnt(31)
	v_lshlrev_b32_e32 v36, 16, v124
	v_and_b32_e32 v37, 0xffff0000, v124
	v_lshlrev_b32_e32 v32, 16, v125
	v_and_b32_e32 v33, 0xffff0000, v125
	v_pk_fma_f32 v[14:15], v[186:187], v[32:33], v[14:15] op_sel_hi:[0,1,1]
	v_pk_fma_f32 v[12:13], v[186:187], v[36:37], v[12:13] op_sel_hi:[0,1,1]
	s_add_i32 s26, s23, 9
	s_max_i32 s26, s26, s16
	s_add_i32 s27, s23, 25
	s_min_i32 s27, s27, s17
	s_sub_i32 s26, s27, s26
	v_cvt_f32_i32_e32 v35, s26
	v_lshlrev_b32_e32 v44, 16, v110
	v_div_scale_f32 v16, s[10:11], v35, v35, 1.0
	v_rcp_f32_e32 v17, v16
	v_div_scale_f32 v38, vcc, 1.0, v35, 1.0
	v_fma_f32 v39, -v16, v17, 1.0
	v_fmac_f32_e32 v17, v39, v17
	v_mul_f32_e32 v39, v38, v17
	v_fma_f32 v43, -v16, v39, v38
	v_fmac_f32_e32 v39, v43, v17
	v_fma_f32 v16, -v16, v39, v38
	v_and_b32_e32 v45, 0xffff0000, v110
	v_lshlrev_b32_e32 v46, 16, v111
	v_div_fmas_f32 v17, v16, v17, v39
	v_and_b32_e32 v47, 0xffff0000, v111
	v_div_fixup_f32 v38, v17, v35, 1.0
	v_pk_mul_f32 v[46:47], v[178:179], v[46:47] op_sel:[1,0] op_sel_hi:[1,1]
	v_pk_mul_f32 v[44:45], v[178:179], v[44:45] op_sel:[1,0] op_sel_hi:[1,1]
	v_pk_fma_f32 v[44:45], v[38:39], v[12:13], v[44:45] op_sel_hi:[0,1,1] neg_lo:[0,0,1] neg_hi:[0,0,1]
	v_pk_fma_f32 v[46:47], v[38:39], v[14:15], v[46:47] op_sel_hi:[0,1,1] neg_lo:[0,0,1] neg_hi:[0,0,1]
	v_pk_mul_f32 v[44:45], v[52:53], v[44:45]
	v_pk_mul_f32 v[46:47], v[54:55], v[46:47]
	v_cvt_pk_bf16_f32 v50, v44, v45
	v_cvt_pk_bf16_f32 v51, v46, v47
	global_store_dwordx2 v41, v[50:51], s[46:47] offset:2048
	v_lshlrev_b32_e32 v36, 16, v94
	v_and_b32_e32 v37, 0xffff0000, v94
	v_lshlrev_b32_e32 v32, 16, v95
	v_and_b32_e32 v33, 0xffff0000, v95
	v_pk_fma_f32 v[14:15], v[170:171], v[32:33], v[14:15] op_sel:[1,0,0] op_sel_hi:[1,1,1] neg_lo:[1,0,0] neg_hi:[1,0,0]
	v_pk_fma_f32 v[12:13], v[170:171], v[36:37], v[12:13] op_sel:[1,0,0] op_sel_hi:[1,1,1] neg_lo:[1,0,0] neg_hi:[1,0,0]
	s_waitcnt vmcnt(31)
	v_lshlrev_b32_e32 v36, 16, v126
	v_and_b32_e32 v37, 0xffff0000, v126
	v_lshlrev_b32_e32 v32, 16, v127
	v_and_b32_e32 v33, 0xffff0000, v127
	v_pk_fma_f32 v[14:15], v[186:187], v[32:33], v[14:15] op_sel:[1,0,0] op_sel_hi:[1,1,1]
	v_pk_fma_f32 v[12:13], v[186:187], v[36:37], v[12:13] op_sel:[1,0,0] op_sel_hi:[1,1,1]
	s_add_i32 s26, s23, 10
	s_max_i32 s26, s26, s16
	s_add_i32 s27, s23, 26
	s_min_i32 s27, s27, s17
	s_sub_i32 s26, s27, s26
	v_cvt_f32_i32_e32 v35, s26
	v_lshlrev_b32_e32 v44, 16, v112
	v_div_scale_f32 v16, s[10:11], v35, v35, 1.0
	v_rcp_f32_e32 v17, v16
	v_div_scale_f32 v38, vcc, 1.0, v35, 1.0
	v_fma_f32 v39, -v16, v17, 1.0
	v_fmac_f32_e32 v17, v39, v17
	v_mul_f32_e32 v39, v38, v17
	v_fma_f32 v43, -v16, v39, v38
	v_fmac_f32_e32 v39, v43, v17
	v_fma_f32 v16, -v16, v39, v38
	v_and_b32_e32 v45, 0xffff0000, v112
	v_lshlrev_b32_e32 v46, 16, v113
	v_div_fmas_f32 v17, v16, v17, v39
	v_and_b32_e32 v47, 0xffff0000, v113
	v_div_fixup_f32 v38, v17, v35, 1.0
	v_pk_mul_f32 v[46:47], v[180:181], v[46:47] op_sel_hi:[0,1]
	v_pk_mul_f32 v[44:45], v[180:181], v[44:45] op_sel_hi:[0,1]
	v_pk_fma_f32 v[44:45], v[38:39], v[12:13], v[44:45] op_sel_hi:[0,1,1] neg_lo:[0,0,1] neg_hi:[0,0,1]
	v_pk_fma_f32 v[46:47], v[38:39], v[14:15], v[46:47] op_sel_hi:[0,1,1] neg_lo:[0,0,1] neg_hi:[0,0,1]
	v_pk_mul_f32 v[44:45], v[52:53], v[44:45]
	v_pk_mul_f32 v[46:47], v[54:55], v[46:47]
	v_cvt_pk_bf16_f32 v48, v44, v45
	v_cvt_pk_bf16_f32 v49, v46, v47
	s_add_u32 s48, s28, 36864
	s_addc_u32 s49, s29, 0
	global_store_dwordx2 v41, v[48:49], s[48:49]
	v_lshlrev_b32_e32 v36, 16, v96
	v_and_b32_e32 v37, 0xffff0000, v96
	v_lshlrev_b32_e32 v32, 16, v97
	v_and_b32_e32 v33, 0xffff0000, v97
	v_pk_fma_f32 v[14:15], v[172:173], v[32:33], v[14:15] op_sel_hi:[0,1,1] neg_lo:[1,0,0] neg_hi:[1,0,0]
	v_pk_fma_f32 v[12:13], v[172:173], v[36:37], v[12:13] op_sel_hi:[0,1,1] neg_lo:[1,0,0] neg_hi:[1,0,0]
	s_waitcnt vmcnt(31)
; __device__ __forceinline__ unsigned pk2(float lo, float hi) { unsigned r; asm volatile("v_cvt_pk_bf16_f32 %0, %1, %2" : "=v"(r) : "v"(lo), "v"(hi)); return r; }
; __device__ __forceinline__ unsigned pk2(float lo, float hi) { return f2bf(lo) | (f2bf(hi) << 16); }
; #define LDX(tok) ({ const u32x2 _q = *(const u32x2*)(xb + (size_t)(tok) * D + cq * 4); (f32x4){bf_lo(_q.x), bf_hi(_q.x), bf_lo(_q.y), bf_hi(_q.y)} * rs[(tok) - t0 + 8]; })
; __global__ void __launch_bounds__(512, 2) fwd_megakernel(Params Pk) {
;     ...
;             for (int s = ta - hw; s <= ta + hw - 2; ++s) if (s >= sbeg && s < send) S += LDX(s);
;             for (int t = ta; t < ta + 32; ++t) {
;                 const int sin_ = t + hw - 1; if (sin_ < send) S += LDX(sin_);
;                 const int wl = (t - hw) > sbeg ? (t - hw) : sbeg, wh = (t + hw) < send ? (t + hw) : send; const float inv = 1.0f / (float)(wh - wl);
;                 const f32x4 xt = LDX(t);
;                 const f32x4 pv = (S * inv - xt) * gv;
;                 u32x2 w; w.x = pk2(pv[0], pv[1]); w.y = pk2(pv[2], pv[3]); *(u32x2*)(pbuf + (size_t)t * D + cq * 4) = w;
;                 const int sout = t - hw; if (sout >= sbeg) S -= LDX(sout);
;             }
	v_lshlrev_b32_e32 v36, 16, v128
	v_and_b32_e32 v37, 0xffff0000, v128
	v_lshlrev_b32_e32 v32, 16, v129
	v_and_b32_e32 v33, 0xffff0000, v129
	v_pk_fma_f32 v[14:15], v[188:189], v[32:33], v[14:15] op_sel_hi:[0,1,1]
	v_pk_fma_f32 v[12:13], v[188:189], v[36:37], v[12:13] op_sel_hi:[0,1,1]
	s_add_i32 s26, s23, 11
	s_max_i32 s26, s26, s16
	s_add_i32 s27, s23, 27
	s_min_i32 s27, s27, s17
	s_sub_i32 s26, s27, s26
	v_cvt_f32_i32_e32 v35, s26
	v_lshlrev_b32_e32 v44, 16, v114
	v_div_scale_f32 v16, s[10:11], v35, v35, 1.0
	v_rcp_f32_e32 v17, v16
	v_div_scale_f32 v38, vcc, 1.0, v35, 1.0
	v_fma_f32 v39, -v16, v17, 1.0
	v_fmac_f32_e32 v17, v39, v17
	v_mul_f32_e32 v39, v38, v17
	v_fma_f32 v43, -v16, v39, v38
	v_fmac_f32_e32 v39, v43, v17
	v_fma_f32 v16, -v16, v39, v38
	v_and_b32_e32 v45, 0xffff0000, v114
	v_lshlrev_b32_e32 v46, 16, v115
	v_div_fmas_f32 v17, v16, v17, v39
	v_and_b32_e32 v47, 0xffff0000, v115
	v_div_fixup_f32 v38, v17, v35, 1.0
	v_pk_mul_f32 v[46:47], v[180:181], v[46:47] op_sel:[1,0] op_sel_hi:[1,1]
	v_pk_mul_f32 v[44:45], v[180:181], v[44:45] op_sel:[1,0] op_sel_hi:[1,1]
	v_pk_fma_f32 v[44:45], v[38:39], v[12:13], v[44:45] op_sel_hi:[0,1,1] neg_lo:[0,0,1] neg_hi:[0,0,1]
	v_pk_fma_f32 v[46:47], v[38:39], v[14:15], v[46:47] op_sel_hi:[0,1,1] neg_lo:[0,0,1] neg_hi:[0,0,1]
	v_pk_mul_f32 v[44:45], v[52:53], v[44:45]
	v_pk_mul_f32 v[46:47], v[54:55], v[46:47]
	v_cvt_pk_bf16_f32 v50, v44, v45
	v_cvt_pk_bf16_f32 v51, v46, v47
	global_store_dwordx2 v41, v[50:51], s[48:49] offset:2048
	v_lshlrev_b32_e32 v36, 16, v98
	v_and_b32_e32 v37, 0xffff0000, v98
	v_lshlrev_b32_e32 v32, 16, v99
	v_and_b32_e32 v33, 0xffff0000, v99
	v_pk_fma_f32 v[14:15], v[172:173], v[32:33], v[14:15] op_sel:[1,0,0] op_sel_hi:[1,1,1] neg_lo:[1,0,0] neg_hi:[1,0,0]
	v_pk_fma_f32 v[12:13], v[172:173], v[36:37], v[12:13] op_sel:[1,0,0] op_sel_hi:[1,1,1] neg_lo:[1,0,0] neg_hi:[1,0,0]
	s_waitcnt vmcnt(31)
	v_lshlrev_b32_e32 v36, 16, v130
	v_and_b32_e32 v37, 0xffff0000, v130
	v_lshlrev_b32_e32 v32, 16, v131
	v_and_b32_e32 v33, 0xffff0000, v131
	v_pk_fma_f32 v[14:15], v[188:189], v[32:33], v[14:15] op_sel:[1,0,0] op_sel_hi:[1,1,1]
	v_pk_fma_f32 v[12:13], v[188:189], v[36:37], v[12:13] op_sel:[1,0,0] op_sel_hi:[1,1,1]
	s_add_i32 s26, s23, 12
	s_max_i32 s26, s26, s16
	s_add_i32 s27, s23, 28
	s_min_i32 s27, s27, s17
	s_sub_i32 s26, s27, s26
	v_cvt_f32_i32_e32 v35, s26
	v_lshlrev_b32_e32 v44, 16, v116
	v_div_scale_f32 v16, s[10:11], v35, v35, 1.0
	v_rcp_f32_e32 v17, v16
	v_div_scale_f32 v38, vcc, 1.0, v35, 1.0
	v_fma_f32 v39, -v16, v17, 1.0
	v_fmac_f32_e32 v17, v39, v17
	v_mul_f32_e32 v39, v38, v17
	v_fma_f32 v43, -v16, v39, v38
	v_fmac_f32_e32 v39, v43, v17
	v_fma_f32 v16, -v16, v39, v38
	v_and_b32_e32 v45, 0xffff0000, v116
	v_lshlrev_b32_e32 v46, 16, v117
	v_div_fmas_f32 v17, v16, v17, v39
	v_and_b32_e32 v47, 0xffff0000, v117
	v_div_fixup_f32 v38, v17, v35, 1.0
	v_pk_mul_f32 v[46:47], v[182:183], v[46:47] op_sel_hi:[0,1]
	v_pk_mul_f32 v[44:45], v[182:183], v[44:45] op_sel_hi:[0,1]
	v_pk_fma_f32 v[44:45], v[38:39], v[12:13], v[44:45] op_sel_hi:[0,1,1] neg_lo:[0,0,1] neg_hi:[0,0,1]
	v_pk_fma_f32 v[46:47], v[38:39], v[14:15], v[46:47] op_sel_hi:[0,1,1] neg_lo:[0,0,1] neg_hi:[0,0,1]
	v_pk_mul_f32 v[44:45], v[52:53], v[44:45]
	v_pk_mul_f32 v[46:47], v[54:55], v[46:47]
	v_cvt_pk_bf16_f32 v48, v44, v45
	v_cvt_pk_bf16_f32 v49, v46, v47
	s_add_u32 s50, s28, 40960
	s_addc_u32 s51, s29, 0
	global_store_dwordx2 v41, v[48:49], s[50:51]
	v_lshlrev_b32_e32 v36, 16, v100
	v_and_b32_e32 v37, 0xffff0000, v100
	v_lshlrev_b32_e32 v32, 16, v101
	v_and_b32_e32 v33, 0xffff0000, v101
	v_pk_fma_f32 v[14:15], v[174:175], v[32:33], v[14:15] op_sel_hi:[0,1,1] neg_lo:[1,0,0] neg_hi:[1,0,0]
	v_pk_fma_f32 v[12:13], v[174:175], v[36:37], v[12:13] op_sel_hi:[0,1,1] neg_lo:[1,0,0] neg_hi:[1,0,0]
	s_waitcnt vmcnt(31)
	v_lshlrev_b32_e32 v36, 16, v132
	v_and_b32_e32 v37, 0xffff0000, v132
	v_lshlrev_b32_e32 v32, 16, v133
	v_and_b32_e32 v33, 0xffff0000, v133
	v_pk_fma_f32 v[14:15], v[190:191], v[32:33], v[14:15] op_sel_hi:[0,1,1]
	v_pk_fma_f32 v[12:13], v[190:191], v[36:37], v[12:13] op_sel_hi:[0,1,1]
	s_add_i32 s26, s23, 13
	s_max_i32 s26, s26, s16
	s_add_i32 s27, s23, 29
	s_min_i32 s27, s27, s17
	s_sub_i32 s26, s27, s26
	v_cvt_f32_i32_e32 v35, s26
	v_lshlrev_b32_e32 v44, 16, v118
	v_div_scale_f32 v16, s[10:11], v35, v35, 1.0
	v_rcp_f32_e32 v17, v16
	v_div_scale_f32 v38, vcc, 1.0, v35, 1.0
	v_fma_f32 v39, -v16, v17, 1.0
	v_fmac_f32_e32 v17, v39, v17
	v_mul_f32_e32 v39, v38, v17
	v_fma_f32 v43, -v16, v39, v38
	v_fmac_f32_e32 v39, v43, v17
	v_fma_f32 v16, -v16, v39, v38
	v_and_b32_e32 v45, 0xffff0000, v118
	v_lshlrev_b32_e32 v46, 16, v119
	v_div_fmas_f32 v17, v16, v17, v39
	v_and_b32_e32 v47, 0xffff0000, v119
	v_div_fixup_f32 v38, v17, v35, 1.0
	v_pk_mul_f32 v[46:47], v[182:183], v[46:47] op_sel:[1,0] op_sel_hi:[1,1]
	v_pk_mul_f32 v[44:45], v[182:183], v[44:45] op_sel:[1,0] op_sel_hi:[1,1]
	v_pk_fma_f32 v[44:45], v[38:39], v[12:13], v[44:45] op_sel_hi:[0,1,1] neg_lo:[0,0,1] neg_hi:[0,0,1]
	v_pk_fma_f32 v[46:47], v[38:39], v[14:15], v[46:47] op_sel_hi:[0,1,1] neg_lo:[0,0,1] neg_hi:[0,0,1]
	v_pk_mul_f32 v[44:45], v[52:53], v[44:45]
	v_pk_mul_f32 v[46:47], v[54:55], v[46:47]
	v_cvt_pk_bf16_f32 v50, v44, v45
	v_cvt_pk_bf16_f32 v51, v46, v47
	global_store_dwordx2 v41, v[50:51], s[50:51] offset:2048
	v_lshlrev_b32_e32 v36, 16, v102
	v_and_b32_e32 v37, 0xffff0000, v102
	v_lshlrev_b32_e32 v32, 16, v103
	v_and_b32_e32 v33, 0xffff0000, v103
	v_pk_fma_f32 v[14:15], v[174:175], v[32:33], v[14:15] op_sel:[1,0,0] op_sel_hi:[1,1,1] neg_lo:[1,0,0] neg_hi:[1,0,0]
	v_pk_fma_f32 v[12:13], v[174:175], v[36:37], v[12:13] op_sel:[1,0,0] op_sel_hi:[1,1,1] neg_lo:[1,0,0] neg_hi:[1,0,0]
	s_waitcnt vmcnt(31)
; __device__ __forceinline__ unsigned pk2(float lo, float hi) { unsigned r; asm volatile("v_cvt_pk_bf16_f32 %0, %1, %2" : "=v"(r) : "v"(lo), "v"(hi)); return r; }
; __device__ __forceinline__ unsigned pk2(float lo, float hi) { return f2bf(lo) | (f2bf(hi) << 16); }
; #define LDX(tok) ({ const u32x2 _q = *(const u32x2*)(xb + (size_t)(tok) * D + cq * 4); (f32x4){bf_lo(_q.x), bf_hi(_q.x), bf_lo(_q.y), bf_hi(_q.y)} * rs[(tok) - t0 + 8]; })
; __global__ void __launch_bounds__(512, 2) fwd_megakernel(Params Pk) {
;     ...
;             for (int s = ta - hw; s <= ta + hw - 2; ++s) if (s >= sbeg && s < send) S += LDX(s);
;             for (int t = ta; t < ta + 32; ++t) {
;                 const int sin_ = t + hw - 1; if (sin_ < send) S += LDX(sin_);
;                 const int wl = (t - hw) > sbeg ? (t - hw) : sbeg, wh = (t + hw) < send ? (t + hw) : send; const float inv = 1.0f / (float)(wh - wl);
;                 const f32x4 xt = LDX(t);
;                 const f32x4 pv = (S * inv - xt) * gv;
;                 u32x2 w; w.x = pk2(pv[0], pv[1]); w.y = pk2(pv[2], pv[3]); *(u32x2*)(pbuf + (size_t)t * D + cq * 4) = w;
;                 const int sout = t - hw; if (sout >= sbeg) S -= LDX(sout);
;             }
	v_lshlrev_b32_e32 v36, 16, v134
	v_and_b32_e32 v37, 0xffff0000, v134
	v_lshlrev_b32_e32 v32, 16, v135
	v_and_b32_e32 v33, 0xffff0000, v135
	v_pk_fma_f32 v[14:15], v[190:191], v[32:33], v[14:15] op_sel:[1,0,0] op_sel_hi:[1,1,1]
	v_pk_fma_f32 v[12:13], v[190:191], v[36:37], v[12:13] op_sel:[1,0,0] op_sel_hi:[1,1,1]
	s_add_i32 s26, s23, 14
	s_max_i32 s26, s26, s16
	s_add_i32 s27, s23, 30
	s_min_i32 s27, s27, s17
	s_sub_i32 s26, s27, s26
	v_cvt_f32_i32_e32 v35, s26
	v_lshlrev_b32_e32 v44, 16, v120
	v_div_scale_f32 v16, s[10:11], v35, v35, 1.0
	v_rcp_f32_e32 v17, v16
	v_div_scale_f32 v38, vcc, 1.0, v35, 1.0
	v_fma_f32 v39, -v16, v17, 1.0
	v_fmac_f32_e32 v17, v39, v17
	v_mul_f32_e32 v39, v38, v17
	v_fma_f32 v43, -v16, v39, v38
	v_fmac_f32_e32 v39, v43, v17
	v_fma_f32 v16, -v16, v39, v38
	v_and_b32_e32 v45, 0xffff0000, v120
	v_lshlrev_b32_e32 v46, 16, v121
	v_div_fmas_f32 v17, v16, v17, v39
	v_and_b32_e32 v47, 0xffff0000, v121
	v_div_fixup_f32 v38, v17, v35, 1.0
	v_pk_mul_f32 v[46:47], v[184:185], v[46:47] op_sel_hi:[0,1]
	v_pk_mul_f32 v[44:45], v[184:185], v[44:45] op_sel_hi:[0,1]
	v_pk_fma_f32 v[44:45], v[38:39], v[12:13], v[44:45] op_sel_hi:[0,1,1] neg_lo:[0,0,1] neg_hi:[0,0,1]
	v_pk_fma_f32 v[46:47], v[38:39], v[14:15], v[46:47] op_sel_hi:[0,1,1] neg_lo:[0,0,1] neg_hi:[0,0,1]
	v_pk_mul_f32 v[44:45], v[52:53], v[44:45]
	v_pk_mul_f32 v[46:47], v[54:55], v[46:47]
	v_cvt_pk_bf16_f32 v48, v44, v45
	v_cvt_pk_bf16_f32 v49, v46, v47
	s_add_u32 s52, s28, 45056
	s_addc_u32 s53, s29, 0
	global_store_dwordx2 v41, v[48:49], s[52:53]
	v_lshlrev_b32_e32 v36, 16, v104
	v_and_b32_e32 v37, 0xffff0000, v104
	v_lshlrev_b32_e32 v32, 16, v105
	v_and_b32_e32 v33, 0xffff0000, v105
	v_pk_fma_f32 v[14:15], v[176:177], v[32:33], v[14:15] op_sel_hi:[0,1,1] neg_lo:[1,0,0] neg_hi:[1,0,0]
	v_pk_fma_f32 v[12:13], v[176:177], v[36:37], v[12:13] op_sel_hi:[0,1,1] neg_lo:[1,0,0] neg_hi:[1,0,0]
	s_waitcnt vmcnt(31)
	v_lshlrev_b32_e32 v36, 16, v136
	v_and_b32_e32 v37, 0xffff0000, v136
	v_lshlrev_b32_e32 v32, 16, v137
	v_and_b32_e32 v33, 0xffff0000, v137
	v_pk_fma_f32 v[14:15], v[192:193], v[32:33], v[14:15] op_sel_hi:[0,1,1]
	v_pk_fma_f32 v[12:13], v[192:193], v[36:37], v[12:13] op_sel_hi:[0,1,1]
	s_add_i32 s26, s23, 15
	s_max_i32 s26, s26, s16
	s_add_i32 s27, s23, 31
	s_min_i32 s27, s27, s17
	s_sub_i32 s26, s27, s26
	v_cvt_f32_i32_e32 v35, s26
	v_lshlrev_b32_e32 v44, 16, v122
	v_div_scale_f32 v16, s[10:11], v35, v35, 1.0
	v_rcp_f32_e32 v17, v16
	v_div_scale_f32 v38, vcc, 1.0, v35, 1.0
	v_fma_f32 v39, -v16, v17, 1.0
	v_fmac_f32_e32 v17, v39, v17
	v_mul_f32_e32 v39, v38, v17
	v_fma_f32 v43, -v16, v39, v38
	v_fmac_f32_e32 v39, v43, v17
	v_fma_f32 v16, -v16, v39, v38
	v_and_b32_e32 v45, 0xffff0000, v122
	v_lshlrev_b32_e32 v46, 16, v123
	v_div_fmas_f32 v17, v16, v17, v39
	v_and_b32_e32 v47, 0xffff0000, v123
	v_div_fixup_f32 v38, v17, v35, 1.0
	v_pk_mul_f32 v[46:47], v[184:185], v[46:47] op_sel:[1,0] op_sel_hi:[1,1]
	v_pk_mul_f32 v[44:45], v[184:185], v[44:45] op_sel:[1,0] op_sel_hi:[1,1]
	v_pk_fma_f32 v[44:45], v[38:39], v[12:13], v[44:45] op_sel_hi:[0,1,1] neg_lo:[0,0,1] neg_hi:[0,0,1]
	v_pk_fma_f32 v[46:47], v[38:39], v[14:15], v[46:47] op_sel_hi:[0,1,1] neg_lo:[0,0,1] neg_hi:[0,0,1]
	v_pk_mul_f32 v[44:45], v[52:53], v[44:45]
	v_pk_mul_f32 v[46:47], v[54:55], v[46:47]
	v_cvt_pk_bf16_f32 v50, v44, v45
	v_cvt_pk_bf16_f32 v51, v46, v47
	global_store_dwordx2 v41, v[50:51], s[52:53] offset:2048
	v_lshlrev_b32_e32 v36, 16, v106
	v_and_b32_e32 v37, 0xffff0000, v106
	v_lshlrev_b32_e32 v32, 16, v107
	v_and_b32_e32 v33, 0xffff0000, v107
	v_pk_fma_f32 v[14:15], v[176:177], v[32:33], v[14:15] op_sel:[1,0,0] op_sel_hi:[1,1,1] neg_lo:[1,0,0] neg_hi:[1,0,0]
	v_pk_fma_f32 v[12:13], v[176:177], v[36:37], v[12:13] op_sel:[1,0,0] op_sel_hi:[1,1,1] neg_lo:[1,0,0] neg_hi:[1,0,0]
	s_waitcnt vmcnt(31)
	v_lshlrev_b32_e32 v36, 16, v138
	v_and_b32_e32 v37, 0xffff0000, v138
	v_lshlrev_b32_e32 v32, 16, v139
	v_and_b32_e32 v33, 0xffff0000, v139
	v_pk_fma_f32 v[14:15], v[192:193], v[32:33], v[14:15] op_sel:[1,0,0] op_sel_hi:[1,1,1]
	v_pk_fma_f32 v[12:13], v[192:193], v[36:37], v[12:13] op_sel:[1,0,0] op_sel_hi:[1,1,1]
	s_add_i32 s26, s23, 16
	s_max_i32 s26, s26, s16
	s_add_i32 s27, s23, 32
	s_min_i32 s27, s27, s17
	s_sub_i32 s26, s27, s26
	v_cvt_f32_i32_e32 v35, s26
	v_lshlrev_b32_e32 v44, 16, v124
	v_div_scale_f32 v16, s[10:11], v35, v35, 1.0
	v_rcp_f32_e32 v17, v16
	v_div_scale_f32 v38, vcc, 1.0, v35, 1.0
	v_fma_f32 v39, -v16, v17, 1.0
	v_fmac_f32_e32 v17, v39, v17
	v_mul_f32_e32 v39, v38, v17
	v_fma_f32 v43, -v16, v39, v38
	v_fmac_f32_e32 v39, v43, v17
	v_fma_f32 v16, -v16, v39, v38
	v_and_b32_e32 v45, 0xffff0000, v124
	v_lshlrev_b32_e32 v46, 16, v125
	v_div_fmas_f32 v17, v16, v17, v39
	v_and_b32_e32 v47, 0xffff0000, v125
	v_div_fixup_f32 v38, v17, v35, 1.0
	v_pk_mul_f32 v[46:47], v[186:187], v[46:47] op_sel_hi:[0,1]
	v_pk_mul_f32 v[44:45], v[186:187], v[44:45] op_sel_hi:[0,1]
	v_pk_fma_f32 v[44:45], v[38:39], v[12:13], v[44:45] op_sel_hi:[0,1,1] neg_lo:[0,0,1] neg_hi:[0,0,1]
	v_pk_fma_f32 v[46:47], v[38:39], v[14:15], v[46:47] op_sel_hi:[0,1,1] neg_lo:[0,0,1] neg_hi:[0,0,1]
	v_pk_mul_f32 v[44:45], v[52:53], v[44:45]
	v_pk_mul_f32 v[46:47], v[54:55], v[46:47]
	v_cvt_pk_bf16_f32 v48, v44, v45
	v_cvt_pk_bf16_f32 v49, v46, v47
	s_add_u32 s46, s28, 49152
	s_addc_u32 s47, s29, 0
	global_store_dwordx2 v41, v[48:49], s[46:47]
	v_lshlrev_b32_e32 v36, 16, v108
	v_and_b32_e32 v37, 0xffff0000, v108
	v_lshlrev_b32_e32 v32, 16, v109
	v_and_b32_e32 v33, 0xffff0000, v109
	v_pk_fma_f32 v[14:15], v[178:179], v[32:33], v[14:15] op_sel_hi:[0,1,1] neg_lo:[1,0,0] neg_hi:[1,0,0]
	v_pk_fma_f32 v[12:13], v[178:179], v[36:37], v[12:13] op_sel_hi:[0,1,1] neg_lo:[1,0,0] neg_hi:[1,0,0]
	s_waitcnt vmcnt(31)
; __device__ __forceinline__ unsigned pk2(float lo, float hi) { unsigned r; asm volatile("v_cvt_pk_bf16_f32 %0, %1, %2" : "=v"(r) : "v"(lo), "v"(hi)); return r; }
; __device__ __forceinline__ unsigned pk2(float lo, float hi) { return f2bf(lo) | (f2bf(hi) << 16); }
; #define LDX(tok) ({ const u32x2 _q = *(const u32x2*)(xb + (size_t)(tok) * D + cq * 4); (f32x4){bf_lo(_q.x), bf_hi(_q.x), bf_lo(_q.y), bf_hi(_q.y)} * rs[(tok) - t0 + 8]; })
; __global__ void __launch_bounds__(512, 2) fwd_megakernel(Params Pk) {
;     ...
;             for (int s = ta - hw; s <= ta + hw - 2; ++s) if (s >= sbeg && s < send) S += LDX(s);
;             for (int t = ta; t < ta + 32; ++t) {
;                 const int sin_ = t + hw - 1; if (sin_ < send) S += LDX(sin_);
;                 const int wl = (t - hw) > sbeg ? (t - hw) : sbeg, wh = (t + hw) < send ? (t + hw) : send; const float inv = 1.0f / (float)(wh - wl);
;                 const f32x4 xt = LDX(t);
;                 const f32x4 pv = (S * inv - xt) * gv;
;                 u32x2 w; w.x = pk2(pv[0], pv[1]); w.y = pk2(pv[2], pv[3]); *(u32x2*)(pbuf + (size_t)t * D + cq * 4) = w;
;                 const int sout = t - hw; if (sout >= sbeg) S -= LDX(sout);
;             }
	v_lshlrev_b32_e32 v36, 16, v140
	v_and_b32_e32 v37, 0xffff0000, v140
	v_lshlrev_b32_e32 v32, 16, v141
	v_and_b32_e32 v33, 0xffff0000, v141
	v_pk_fma_f32 v[14:15], v[194:195], v[32:33], v[14:15] op_sel_hi:[0,1,1]
	v_pk_fma_f32 v[12:13], v[194:195], v[36:37], v[12:13] op_sel_hi:[0,1,1]
	s_add_i32 s26, s23, 17
	s_max_i32 s26, s26, s16
	s_add_i32 s27, s23, 33
	s_min_i32 s27, s27, s17
	s_sub_i32 s26, s27, s26
	v_cvt_f32_i32_e32 v35, s26
	v_lshlrev_b32_e32 v44, 16, v126
	v_div_scale_f32 v16, s[10:11], v35, v35, 1.0
	v_rcp_f32_e32 v17, v16
	v_div_scale_f32 v38, vcc, 1.0, v35, 1.0
	v_fma_f32 v39, -v16, v17, 1.0
	v_fmac_f32_e32 v17, v39, v17
	v_mul_f32_e32 v39, v38, v17
	v_fma_f32 v43, -v16, v39, v38
	v_fmac_f32_e32 v39, v43, v17
	v_fma_f32 v16, -v16, v39, v38
	v_and_b32_e32 v45, 0xffff0000, v126
	v_lshlrev_b32_e32 v46, 16, v127
	v_div_fmas_f32 v17, v16, v17, v39
	v_and_b32_e32 v47, 0xffff0000, v127
	v_div_fixup_f32 v38, v17, v35, 1.0
	v_pk_mul_f32 v[46:47], v[186:187], v[46:47] op_sel:[1,0] op_sel_hi:[1,1]
	v_pk_mul_f32 v[44:45], v[186:187], v[44:45] op_sel:[1,0] op_sel_hi:[1,1]
	v_pk_fma_f32 v[44:45], v[38:39], v[12:13], v[44:45] op_sel_hi:[0,1,1] neg_lo:[0,0,1] neg_hi:[0,0,1]
	v_pk_fma_f32 v[46:47], v[38:39], v[14:15], v[46:47] op_sel_hi:[0,1,1] neg_lo:[0,0,1] neg_hi:[0,0,1]
	v_pk_mul_f32 v[44:45], v[52:53], v[44:45]
	v_pk_mul_f32 v[46:47], v[54:55], v[46:47]
	v_cvt_pk_bf16_f32 v50, v44, v45
	v_cvt_pk_bf16_f32 v51, v46, v47
	global_store_dwordx2 v41, v[50:51], s[46:47] offset:2048
	v_lshlrev_b32_e32 v36, 16, v110
	v_and_b32_e32 v37, 0xffff0000, v110
	v_lshlrev_b32_e32 v32, 16, v111
	v_and_b32_e32 v33, 0xffff0000, v111
	v_pk_fma_f32 v[14:15], v[178:179], v[32:33], v[14:15] op_sel:[1,0,0] op_sel_hi:[1,1,1] neg_lo:[1,0,0] neg_hi:[1,0,0]
	v_pk_fma_f32 v[12:13], v[178:179], v[36:37], v[12:13] op_sel:[1,0,0] op_sel_hi:[1,1,1] neg_lo:[1,0,0] neg_hi:[1,0,0]
	s_waitcnt vmcnt(31)
	v_lshlrev_b32_e32 v36, 16, v142
	v_and_b32_e32 v37, 0xffff0000, v142
	v_lshlrev_b32_e32 v32, 16, v143
	v_and_b32_e32 v33, 0xffff0000, v143
	v_pk_fma_f32 v[14:15], v[194:195], v[32:33], v[14:15] op_sel:[1,0,0] op_sel_hi:[1,1,1]
	v_pk_fma_f32 v[12:13], v[194:195], v[36:37], v[12:13] op_sel:[1,0,0] op_sel_hi:[1,1,1]
	s_add_i32 s26, s23, 18
	s_max_i32 s26, s26, s16
	s_add_i32 s27, s23, 34
	s_min_i32 s27, s27, s17
	s_sub_i32 s26, s27, s26
	v_cvt_f32_i32_e32 v35, s26
	v_lshlrev_b32_e32 v44, 16, v128
	v_div_scale_f32 v16, s[10:11], v35, v35, 1.0
	v_rcp_f32_e32 v17, v16
	v_div_scale_f32 v38, vcc, 1.0, v35, 1.0
	v_fma_f32 v39, -v16, v17, 1.0
	v_fmac_f32_e32 v17, v39, v17
	v_mul_f32_e32 v39, v38, v17
	v_fma_f32 v43, -v16, v39, v38
	v_fmac_f32_e32 v39, v43, v17
	v_fma_f32 v16, -v16, v39, v38
	v_and_b32_e32 v45, 0xffff0000, v128
	v_lshlrev_b32_e32 v46, 16, v129
	v_div_fmas_f32 v17, v16, v17, v39
	v_and_b32_e32 v47, 0xffff0000, v129
	v_div_fixup_f32 v38, v17, v35, 1.0
	v_pk_mul_f32 v[46:47], v[188:189], v[46:47] op_sel_hi:[0,1]
	v_pk_mul_f32 v[44:45], v[188:189], v[44:45] op_sel_hi:[0,1]
	v_pk_fma_f32 v[44:45], v[38:39], v[12:13], v[44:45] op_sel_hi:[0,1,1] neg_lo:[0,0,1] neg_hi:[0,0,1]
	v_pk_fma_f32 v[46:47], v[38:39], v[14:15], v[46:47] op_sel_hi:[0,1,1] neg_lo:[0,0,1] neg_hi:[0,0,1]
	v_pk_mul_f32 v[44:45], v[52:53], v[44:45]
	v_pk_mul_f32 v[46:47], v[54:55], v[46:47]
	v_cvt_pk_bf16_f32 v48, v44, v45
	v_cvt_pk_bf16_f32 v49, v46, v47
	s_add_u32 s48, s28, 53248
	s_addc_u32 s49, s29, 0
	global_store_dwordx2 v41, v[48:49], s[48:49]
	v_lshlrev_b32_e32 v36, 16, v112
	v_and_b32_e32 v37, 0xffff0000, v112
	v_lshlrev_b32_e32 v32, 16, v113
	v_and_b32_e32 v33, 0xffff0000, v113
	v_pk_fma_f32 v[14:15], v[180:181], v[32:33], v[14:15] op_sel_hi:[0,1,1] neg_lo:[1,0,0] neg_hi:[1,0,0]
	v_pk_fma_f32 v[12:13], v[180:181], v[36:37], v[12:13] op_sel_hi:[0,1,1] neg_lo:[1,0,0] neg_hi:[1,0,0]
	s_waitcnt vmcnt(31)
	v_lshlrev_b32_e32 v36, 16, v144
	v_and_b32_e32 v37, 0xffff0000, v144
	v_lshlrev_b32_e32 v32, 16, v145
	v_and_b32_e32 v33, 0xffff0000, v145
	v_pk_fma_f32 v[14:15], v[196:197], v[32:33], v[14:15] op_sel_hi:[0,1,1]
	v_pk_fma_f32 v[12:13], v[196:197], v[36:37], v[12:13] op_sel_hi:[0,1,1]
	s_add_i32 s26, s23, 19
	s_max_i32 s26, s26, s16
	s_add_i32 s27, s23, 35
	s_min_i32 s27, s27, s17
	s_sub_i32 s26, s27, s26
	v_cvt_f32_i32_e32 v35, s26
	v_lshlrev_b32_e32 v44, 16, v130
	v_div_scale_f32 v16, s[10:11], v35, v35, 1.0
	v_rcp_f32_e32 v17, v16
	v_div_scale_f32 v38, vcc, 1.0, v35, 1.0
	v_fma_f32 v39, -v16, v17, 1.0
	v_fmac_f32_e32 v17, v39, v17
	v_mul_f32_e32 v39, v38, v17
	v_fma_f32 v43, -v16, v39, v38
	v_fmac_f32_e32 v39, v43, v17
	v_fma_f32 v16, -v16, v39, v38
	v_and_b32_e32 v45, 0xffff0000, v130
	v_lshlrev_b32_e32 v46, 16, v131
	v_div_fmas_f32 v17, v16, v17, v39
	v_and_b32_e32 v47, 0xffff0000, v131
	v_div_fixup_f32 v38, v17, v35, 1.0
	v_pk_mul_f32 v[46:47], v[188:189], v[46:47] op_sel:[1,0] op_sel_hi:[1,1]
	v_pk_mul_f32 v[44:45], v[188:189], v[44:45] op_sel:[1,0] op_sel_hi:[1,1]
	v_pk_fma_f32 v[44:45], v[38:39], v[12:13], v[44:45] op_sel_hi:[0,1,1] neg_lo:[0,0,1] neg_hi:[0,0,1]
	v_pk_fma_f32 v[46:47], v[38:39], v[14:15], v[46:47] op_sel_hi:[0,1,1] neg_lo:[0,0,1] neg_hi:[0,0,1]
	v_pk_mul_f32 v[44:45], v[52:53], v[44:45]
	v_pk_mul_f32 v[46:47], v[54:55], v[46:47]
	v_cvt_pk_bf16_f32 v50, v44, v45
	v_cvt_pk_bf16_f32 v51, v46, v47
	global_store_dwordx2 v41, v[50:51], s[48:49] offset:2048
	v_lshlrev_b32_e32 v36, 16, v114
	v_and_b32_e32 v37, 0xffff0000, v114
	v_lshlrev_b32_e32 v32, 16, v115
	v_and_b32_e32 v33, 0xffff0000, v115
	v_pk_fma_f32 v[14:15], v[180:181], v[32:33], v[14:15] op_sel:[1,0,0] op_sel_hi:[1,1,1] neg_lo:[1,0,0] neg_hi:[1,0,0]
	v_pk_fma_f32 v[12:13], v[180:181], v[36:37], v[12:13] op_sel:[1,0,0] op_sel_hi:[1,1,1] neg_lo:[1,0,0] neg_hi:[1,0,0]
	s_waitcnt vmcnt(31)
; __device__ __forceinline__ unsigned pk2(float lo, float hi) { unsigned r; asm volatile("v_cvt_pk_bf16_f32 %0, %1, %2" : "=v"(r) : "v"(lo), "v"(hi)); return r; }
; __device__ __forceinline__ unsigned pk2(float lo, float hi) { return f2bf(lo) | (f2bf(hi) << 16); }
; #define LDX(tok) ({ const u32x2 _q = *(const u32x2*)(xb + (size_t)(tok) * D + cq * 4); (f32x4){bf_lo(_q.x), bf_hi(_q.x), bf_lo(_q.y), bf_hi(_q.y)} * rs[(tok) - t0 + 8]; })
; __global__ void __launch_bounds__(512, 2) fwd_megakernel(Params Pk) {
;     ...
;             for (int s = ta - hw; s <= ta + hw - 2; ++s) if (s >= sbeg && s < send) S += LDX(s);
;             for (int t = ta; t < ta + 32; ++t) {
;                 const int sin_ = t + hw - 1; if (sin_ < send) S += LDX(sin_);
;                 const int wl = (t - hw) > sbeg ? (t - hw) : sbeg, wh = (t + hw) < send ? (t + hw) : send; const float inv = 1.0f / (float)(wh - wl);
;                 const f32x4 xt = LDX(t);
;                 const f32x4 pv = (S * inv - xt) * gv;
;                 u32x2 w; w.x = pk2(pv[0], pv[1]); w.y = pk2(pv[2], pv[3]); *(u32x2*)(pbuf + (size_t)t * D + cq * 4) = w;
;                 const int sout = t - hw; if (sout >= sbeg) S -= LDX(sout);
;             }
	v_lshlrev_b32_e32 v36, 16, v146
	v_and_b32_e32 v37, 0xffff0000, v146
	v_lshlrev_b32_e32 v32, 16, v147
	v_and_b32_e32 v33, 0xffff0000, v147
	v_pk_fma_f32 v[14:15], v[196:197], v[32:33], v[14:15] op_sel:[1,0,0] op_sel_hi:[1,1,1]
	v_pk_fma_f32 v[12:13], v[196:197], v[36:37], v[12:13] op_sel:[1,0,0] op_sel_hi:[1,1,1]
	s_add_i32 s26, s23, 20
	s_max_i32 s26, s26, s16
	s_add_i32 s27, s23, 36
	s_min_i32 s27, s27, s17
	s_sub_i32 s26, s27, s26
	v_cvt_f32_i32_e32 v35, s26
	v_lshlrev_b32_e32 v44, 16, v132
	v_div_scale_f32 v16, s[10:11], v35, v35, 1.0
	v_rcp_f32_e32 v17, v16
	v_div_scale_f32 v38, vcc, 1.0, v35, 1.0
	v_fma_f32 v39, -v16, v17, 1.0
	v_fmac_f32_e32 v17, v39, v17
	v_mul_f32_e32 v39, v38, v17
	v_fma_f32 v43, -v16, v39, v38
	v_fmac_f32_e32 v39, v43, v17
	v_fma_f32 v16, -v16, v39, v38
	v_and_b32_e32 v45, 0xffff0000, v132
	v_lshlrev_b32_e32 v46, 16, v133
	v_div_fmas_f32 v17, v16, v17, v39
	v_and_b32_e32 v47, 0xffff0000, v133
	v_div_fixup_f32 v38, v17, v35, 1.0
	v_pk_mul_f32 v[46:47], v[190:191], v[46:47] op_sel_hi:[0,1]
	v_pk_mul_f32 v[44:45], v[190:191], v[44:45] op_sel_hi:[0,1]
	v_pk_fma_f32 v[44:45], v[38:39], v[12:13], v[44:45] op_sel_hi:[0,1,1] neg_lo:[0,0,1] neg_hi:[0,0,1]
	v_pk_fma_f32 v[46:47], v[38:39], v[14:15], v[46:47] op_sel_hi:[0,1,1] neg_lo:[0,0,1] neg_hi:[0,0,1]
	v_pk_mul_f32 v[44:45], v[52:53], v[44:45]
	v_pk_mul_f32 v[46:47], v[54:55], v[46:47]
	v_cvt_pk_bf16_f32 v48, v44, v45
	v_cvt_pk_bf16_f32 v49, v46, v47
	s_add_u32 s50, s28, 57344
	s_addc_u32 s51, s29, 0
	global_store_dwordx2 v41, v[48:49], s[50:51]
	v_lshlrev_b32_e32 v36, 16, v116
	v_and_b32_e32 v37, 0xffff0000, v116
	v_lshlrev_b32_e32 v32, 16, v117
	v_and_b32_e32 v33, 0xffff0000, v117
	v_pk_fma_f32 v[14:15], v[182:183], v[32:33], v[14:15] op_sel_hi:[0,1,1] neg_lo:[1,0,0] neg_hi:[1,0,0]
	v_pk_fma_f32 v[12:13], v[182:183], v[36:37], v[12:13] op_sel_hi:[0,1,1] neg_lo:[1,0,0] neg_hi:[1,0,0]
	s_waitcnt vmcnt(31)
	v_lshlrev_b32_e32 v36, 16, v148
	v_and_b32_e32 v37, 0xffff0000, v148
	v_lshlrev_b32_e32 v32, 16, v149
	v_and_b32_e32 v33, 0xffff0000, v149
	v_pk_fma_f32 v[14:15], v[198:199], v[32:33], v[14:15] op_sel_hi:[0,1,1]
	v_pk_fma_f32 v[12:13], v[198:199], v[36:37], v[12:13] op_sel_hi:[0,1,1]
	s_add_i32 s26, s23, 21
	s_max_i32 s26, s26, s16
	s_add_i32 s27, s23, 37
	s_min_i32 s27, s27, s17
	s_sub_i32 s26, s27, s26
	v_cvt_f32_i32_e32 v35, s26
	v_lshlrev_b32_e32 v44, 16, v134
	v_div_scale_f32 v16, s[10:11], v35, v35, 1.0
	v_rcp_f32_e32 v17, v16
	v_div_scale_f32 v38, vcc, 1.0, v35, 1.0
	v_fma_f32 v39, -v16, v17, 1.0
	v_fmac_f32_e32 v17, v39, v17
	v_mul_f32_e32 v39, v38, v17
	v_fma_f32 v43, -v16, v39, v38
	v_fmac_f32_e32 v39, v43, v17
	v_fma_f32 v16, -v16, v39, v38
	v_and_b32_e32 v45, 0xffff0000, v134
	v_lshlrev_b32_e32 v46, 16, v135
	v_div_fmas_f32 v17, v16, v17, v39
	v_and_b32_e32 v47, 0xffff0000, v135
	v_div_fixup_f32 v38, v17, v35, 1.0
	v_pk_mul_f32 v[46:47], v[190:191], v[46:47] op_sel:[1,0] op_sel_hi:[1,1]
	v_pk_mul_f32 v[44:45], v[190:191], v[44:45] op_sel:[1,0] op_sel_hi:[1,1]
	v_pk_fma_f32 v[44:45], v[38:39], v[12:13], v[44:45] op_sel_hi:[0,1,1] neg_lo:[0,0,1] neg_hi:[0,0,1]
	v_pk_fma_f32 v[46:47], v[38:39], v[14:15], v[46:47] op_sel_hi:[0,1,1] neg_lo:[0,0,1] neg_hi:[0,0,1]
	v_pk_mul_f32 v[44:45], v[52:53], v[44:45]
	v_pk_mul_f32 v[46:47], v[54:55], v[46:47]
	v_cvt_pk_bf16_f32 v50, v44, v45
	v_cvt_pk_bf16_f32 v51, v46, v47
	global_store_dwordx2 v41, v[50:51], s[50:51] offset:2048
	v_lshlrev_b32_e32 v36, 16, v118
	v_and_b32_e32 v37, 0xffff0000, v118
	v_lshlrev_b32_e32 v32, 16, v119
	v_and_b32_e32 v33, 0xffff0000, v119
	v_pk_fma_f32 v[14:15], v[182:183], v[32:33], v[14:15] op_sel:[1,0,0] op_sel_hi:[1,1,1] neg_lo:[1,0,0] neg_hi:[1,0,0]
	v_pk_fma_f32 v[12:13], v[182:183], v[36:37], v[12:13] op_sel:[1,0,0] op_sel_hi:[1,1,1] neg_lo:[1,0,0] neg_hi:[1,0,0]
	s_waitcnt vmcnt(31)
; __device__ __forceinline__ unsigned pk2(float lo, float hi) { unsigned r; asm volatile("v_cvt_pk_bf16_f32 %0, %1, %2" : "=v"(r) : "v"(lo), "v"(hi)); return r; }
; __device__ __forceinline__ unsigned pk2(float lo, float hi) { return f2bf(lo) | (f2bf(hi) << 16); }
; #define LDX(tok) ({ const u32x2 _q = *(const u32x2*)(xb + (size_t)(tok) * D + cq * 4); (f32x4){bf_lo(_q.x), bf_hi(_q.x), bf_lo(_q.y), bf_hi(_q.y)} * rs[(tok) - t0 + 8]; })
; __global__ void __launch_bounds__(512, 2) fwd_megakernel(Params Pk) {
;     ...
;             for (int s = ta - hw; s <= ta + hw - 2; ++s) if (s >= sbeg && s < send) S += LDX(s);
;             for (int t = ta; t < ta + 32; ++t) {
;                 const int sin_ = t + hw - 1; if (sin_ < send) S += LDX(sin_);
;                 const int wl = (t - hw) > sbeg ? (t - hw) : sbeg, wh = (t + hw) < send ? (t + hw) : send; const float inv = 1.0f / (float)(wh - wl);
;                 const f32x4 xt = LDX(t);
;                 const f32x4 pv = (S * inv - xt) * gv;
;                 u32x2 w; w.x = pk2(pv[0], pv[1]); w.y = pk2(pv[2], pv[3]); *(u32x2*)(pbuf + (size_t)t * D + cq * 4) = w;
;                 const int sout = t - hw; if (sout >= sbeg) S -= LDX(sout);
;             }
	v_lshlrev_b32_e32 v36, 16, v150
	v_and_b32_e32 v37, 0xffff0000, v150
	v_lshlrev_b32_e32 v32, 16, v151
	v_and_b32_e32 v33, 0xffff0000, v151
	v_pk_fma_f32 v[14:15], v[198:199], v[32:33], v[14:15] op_sel:[1,0,0] op_sel_hi:[1,1,1]
	v_pk_fma_f32 v[12:13], v[198:199], v[36:37], v[12:13] op_sel:[1,0,0] op_sel_hi:[1,1,1]
	s_add_i32 s26, s23, 22
	s_max_i32 s26, s26, s16
	s_add_i32 s27, s23, 38
	s_min_i32 s27, s27, s17
	s_sub_i32 s26, s27, s26
	v_cvt_f32_i32_e32 v35, s26
	v_lshlrev_b32_e32 v44, 16, v136
	v_div_scale_f32 v16, s[10:11], v35, v35, 1.0
	v_rcp_f32_e32 v17, v16
	v_div_scale_f32 v38, vcc, 1.0, v35, 1.0
	v_fma_f32 v39, -v16, v17, 1.0
	v_fmac_f32_e32 v17, v39, v17
	v_mul_f32_e32 v39, v38, v17
	v_fma_f32 v43, -v16, v39, v38
	v_fmac_f32_e32 v39, v43, v17
	v_fma_f32 v16, -v16, v39, v38
	v_and_b32_e32 v45, 0xffff0000, v136
	v_lshlrev_b32_e32 v46, 16, v137
	v_div_fmas_f32 v17, v16, v17, v39
	v_and_b32_e32 v47, 0xffff0000, v137
	v_div_fixup_f32 v38, v17, v35, 1.0
	v_pk_mul_f32 v[46:47], v[192:193], v[46:47] op_sel_hi:[0,1]
	v_pk_mul_f32 v[44:45], v[192:193], v[44:45] op_sel_hi:[0,1]
	v_pk_fma_f32 v[44:45], v[38:39], v[12:13], v[44:45] op_sel_hi:[0,1,1] neg_lo:[0,0,1] neg_hi:[0,0,1]
	v_pk_fma_f32 v[46:47], v[38:39], v[14:15], v[46:47] op_sel_hi:[0,1,1] neg_lo:[0,0,1] neg_hi:[0,0,1]
	v_pk_mul_f32 v[44:45], v[52:53], v[44:45]
	v_pk_mul_f32 v[46:47], v[54:55], v[46:47]
	v_cvt_pk_bf16_f32 v48, v44, v45
	v_cvt_pk_bf16_f32 v49, v46, v47
	s_add_u32 s52, s28, 61440
	s_addc_u32 s53, s29, 0
	global_store_dwordx2 v41, v[48:49], s[52:53]
	v_lshlrev_b32_e32 v36, 16, v120
	v_and_b32_e32 v37, 0xffff0000, v120
	v_lshlrev_b32_e32 v32, 16, v121
	v_and_b32_e32 v33, 0xffff0000, v121
	v_pk_fma_f32 v[14:15], v[184:185], v[32:33], v[14:15] op_sel_hi:[0,1,1] neg_lo:[1,0,0] neg_hi:[1,0,0]
	v_pk_fma_f32 v[12:13], v[184:185], v[36:37], v[12:13] op_sel_hi:[0,1,1] neg_lo:[1,0,0] neg_hi:[1,0,0]
	s_waitcnt vmcnt(31)
	v_lshlrev_b32_e32 v36, 16, v152
	v_and_b32_e32 v37, 0xffff0000, v152
	v_lshlrev_b32_e32 v32, 16, v153
	v_and_b32_e32 v33, 0xffff0000, v153
	v_pk_fma_f32 v[14:15], v[200:201], v[32:33], v[14:15] op_sel_hi:[0,1,1]
	v_pk_fma_f32 v[12:13], v[200:201], v[36:37], v[12:13] op_sel_hi:[0,1,1]
	s_add_i32 s26, s23, 23
	s_max_i32 s26, s26, s16
	s_add_i32 s27, s23, 39
	s_min_i32 s27, s27, s17
	s_sub_i32 s26, s27, s26
	v_cvt_f32_i32_e32 v35, s26
	v_lshlrev_b32_e32 v44, 16, v138
	v_div_scale_f32 v16, s[10:11], v35, v35, 1.0
	v_rcp_f32_e32 v17, v16
	v_div_scale_f32 v38, vcc, 1.0, v35, 1.0
	v_fma_f32 v39, -v16, v17, 1.0
	v_fmac_f32_e32 v17, v39, v17
	v_mul_f32_e32 v39, v38, v17
	v_fma_f32 v43, -v16, v39, v38
	v_fmac_f32_e32 v39, v43, v17
	v_fma_f32 v16, -v16, v39, v38
	v_and_b32_e32 v45, 0xffff0000, v138
	v_lshlrev_b32_e32 v46, 16, v139
	v_div_fmas_f32 v17, v16, v17, v39
	v_and_b32_e32 v47, 0xffff0000, v139
	v_div_fixup_f32 v38, v17, v35, 1.0
	v_pk_mul_f32 v[46:47], v[192:193], v[46:47] op_sel:[1,0] op_sel_hi:[1,1]
	v_pk_mul_f32 v[44:45], v[192:193], v[44:45] op_sel:[1,0] op_sel_hi:[1,1]
	v_pk_fma_f32 v[44:45], v[38:39], v[12:13], v[44:45] op_sel_hi:[0,1,1] neg_lo:[0,0,1] neg_hi:[0,0,1]
	v_pk_fma_f32 v[46:47], v[38:39], v[14:15], v[46:47] op_sel_hi:[0,1,1] neg_lo:[0,0,1] neg_hi:[0,0,1]
	v_pk_mul_f32 v[44:45], v[52:53], v[44:45]
	v_pk_mul_f32 v[46:47], v[54:55], v[46:47]
	v_cvt_pk_bf16_f32 v50, v44, v45
	v_cvt_pk_bf16_f32 v51, v46, v47
	global_store_dwordx2 v41, v[50:51], s[52:53] offset:2048
	v_lshlrev_b32_e32 v36, 16, v122
	v_and_b32_e32 v37, 0xffff0000, v122
	v_lshlrev_b32_e32 v32, 16, v123
	v_and_b32_e32 v33, 0xffff0000, v123
	v_pk_fma_f32 v[14:15], v[184:185], v[32:33], v[14:15] op_sel:[1,0,0] op_sel_hi:[1,1,1] neg_lo:[1,0,0] neg_hi:[1,0,0]
	v_pk_fma_f32 v[12:13], v[184:185], v[36:37], v[12:13] op_sel:[1,0,0] op_sel_hi:[1,1,1] neg_lo:[1,0,0] neg_hi:[1,0,0]
	s_branch .Lp13_tail
